# write-through (sc1) stores for the P1/P7/P8/P9/P10 outputs to shorten the L2 write-back at the grid barriers
# speedup vs baseline: 1.0083x; 1.0083x over previous
.LBB0_125:
	v_lshl_add_u32 v154, s26, 8, v1
	v_or_b32_e32 v160, 16, v154
	v_ashrrev_i32_e32 v155, 31, v154
	v_ashrrev_i32_e32 v161, 31, v160
	v_lshl_add_u64 v[156:157], v[154:155], 2, s[12:13]
	v_lshl_add_u64 v[162:163], v[160:161], 2, s[12:13]
	v_or_b32_e32 v164, 32, v154
	global_load_dword v158, v[156:157], off
	v_ashrrev_i32_e32 v165, 31, v164
	global_load_dword v162, v[162:163], off
	v_lshl_add_u64 v[166:167], v[164:165], 2, s[12:13]
	global_load_dword v166, v[166:167], off
	v_or_b32_e32 v168, 48, v154
	v_ashrrev_i32_e32 v169, 31, v168
	v_lshl_add_u64 v[170:171], v[168:169], 2, s[12:13]
	global_load_dword v170, v[170:171], off
	s_nop 0
	global_load_dword v172, v[156:157], off offset:512
	global_load_dword v150, v[156:157], off offset:576
	global_load_dword v148, v[156:157], off offset:640
	global_load_dword v146, v[156:157], off offset:704
	s_lshl_b32 s19, s86, 8
	s_add_i32 s21, s19, 0xffffec00
	s_cmp_lt_i32 s86, 20
	s_cselect_b32 s21, s19, s21
	s_cselect_b32 s26, s84, 0xc900000
	s_cselect_b32 s19, s85, 0x1000
	s_add_u32 s28, s70, s26
	v_or_b32_e32 v156, s21, v149
	v_add_u32_e32 v163, 0x80, v154
	s_addc_u32 s29, s71, 0
	v_ashrrev_i32_e32 v157, 31, v156
	v_add_u32_e32 v167, 0x90, v154
	v_add_u32_e32 v173, 0xa0, v154
	v_add_u32_e32 v176, 0xb0, v154
	v_mad_i64_i32 v[154:155], s[30:31], s19, v154, 0
	v_mad_i64_i32 v[160:161], s[30:31], s19, v160, 0
	v_lshl_add_u64 v[156:157], v[156:157], 1, s[28:29]
	v_lshl_add_u64 v[154:155], v[154:155], 1, v[156:157]
	v_lshl_add_u64 v[160:161], v[160:161], 1, v[156:157]
	v_mad_i64_i32 v[164:165], s[30:31], s19, v164, 0
	v_lshl_add_u64 v[164:165], v[164:165], 1, v[156:157]
	s_andn2_b64 vcc, exec, s[6:7]
	s_mov_b64 s[6:7], -1
	s_waitcnt vmcnt(0)
	v_pk_mul_f32 v[128:129], v[128:129], v[158:159] op_sel_hi:[1,0]
	v_pk_mul_f32 v[126:127], v[126:127], v[158:159] op_sel_hi:[1,0]
	v_pk_mul_f32 v[124:125], v[124:125], v[158:159] op_sel_hi:[1,0]
	v_pk_mul_f32 v[122:123], v[122:123], v[158:159] op_sel_hi:[1,0]
	v_pk_mul_f32 v[120:121], v[120:121], v[162:163] op_sel_hi:[1,0]
	v_pk_mul_f32 v[118:119], v[118:119], v[162:163] op_sel_hi:[1,0]
	v_pk_mul_f32 v[116:117], v[116:117], v[162:163] op_sel_hi:[1,0]
	v_pk_mul_f32 v[114:115], v[114:115], v[162:163] op_sel_hi:[1,0]
	v_pk_mul_f32 v[112:113], v[112:113], v[158:159] op_sel_hi:[1,0]
	v_pk_mul_f32 v[110:111], v[110:111], v[158:159] op_sel_hi:[1,0]
	v_pk_mul_f32 v[174:175], v[108:109], v[158:159] op_sel_hi:[1,0]
	v_pk_mul_f32 v[158:159], v[106:107], v[158:159] op_sel_hi:[1,0]
	v_cvt_pk_bf16_f32 v106, v126, v127
	v_cvt_pk_bf16_f32 v107, v128, v129
	v_cvt_pk_bf16_f32 v108, v122, v123
	v_cvt_pk_bf16_f32 v109, v124, v125
	v_pk_mul_f32 v[96:97], v[96:97], v[162:163] op_sel_hi:[1,0]
	v_pk_mul_f32 v[94:95], v[94:95], v[162:163] op_sel_hi:[1,0]
	v_pk_mul_f32 v[122:123], v[92:93], v[162:163] op_sel_hi:[1,0]
	v_pk_mul_f32 v[124:125], v[90:91], v[162:163] op_sel_hi:[1,0]
	v_cvt_pk_bf16_f32 v90, v118, v119
	v_cvt_pk_bf16_f32 v91, v120, v121
	v_cvt_pk_bf16_f32 v92, v114, v115
	v_cvt_pk_bf16_f32 v93, v116, v117
	v_cvt_pk_bf16_f32 v110, v110, v111
	v_cvt_pk_bf16_f32 v111, v112, v113
	v_cvt_pk_bf16_f32 v112, v158, v159
	v_cvt_pk_bf16_f32 v113, v174, v175
	global_store_dwordx4 v[154:155], v[106:109], off sc1
	global_store_dwordx4 v[154:155], v[110:113], off offset:256 sc1
	v_cvt_pk_bf16_f32 v94, v94, v95
	v_cvt_pk_bf16_f32 v95, v96, v97
	v_cvt_pk_bf16_f32 v96, v124, v125
	v_cvt_pk_bf16_f32 v97, v122, v123
	global_store_dwordx4 v[160:161], v[90:93], off sc1
	global_store_dwordx4 v[160:161], v[94:97], off offset:256 sc1
	v_pk_mul_f32 v[84:85], v[84:85], v[166:167] op_sel_hi:[1,0]
	v_pk_mul_f32 v[82:83], v[82:83], v[166:167] op_sel_hi:[1,0]
	v_pk_mul_f32 v[90:91], v[76:77], v[166:167] op_sel_hi:[1,0]
	v_pk_mul_f32 v[76:77], v[74:75], v[166:167] op_sel_hi:[1,0]
	v_cvt_pk_bf16_f32 v74, v82, v83
	v_cvt_pk_bf16_f32 v75, v84, v85
	v_cvt_pk_bf16_f32 v76, v76, v77
	v_cvt_pk_bf16_f32 v77, v90, v91
	global_store_dwordx4 v[164:165], v[74:77], off offset:256 sc1
	v_pk_mul_f32 v[104:105], v[104:105], v[166:167] op_sel_hi:[1,0]
	v_pk_mul_f32 v[102:103], v[102:103], v[166:167] op_sel_hi:[1,0]
	v_mad_i64_i32 v[74:75], s[28:29], s19, v168, 0
	v_pk_mul_f32 v[126:127], v[100:101], v[166:167] op_sel_hi:[1,0]
	v_pk_mul_f32 v[100:101], v[98:99], v[166:167] op_sel_hi:[1,0]
	v_lshl_add_u64 v[82:83], v[74:75], 1, v[156:157]
	v_pk_mul_f32 v[76:77], v[88:89], v[170:171] op_sel_hi:[1,0]
	v_pk_mul_f32 v[74:75], v[86:87], v[170:171] op_sel_hi:[1,0]
	v_pk_mul_f32 v[80:81], v[80:81], v[170:171] op_sel_hi:[1,0]
	v_pk_mul_f32 v[78:79], v[78:79], v[170:171] op_sel_hi:[1,0]
	v_cvt_pk_bf16_f32 v98, v102, v103
	v_cvt_pk_bf16_f32 v99, v104, v105
	v_cvt_pk_bf16_f32 v100, v100, v101
	v_cvt_pk_bf16_f32 v101, v126, v127
	v_cvt_pk_bf16_f32 v74, v74, v75
	v_cvt_pk_bf16_f32 v75, v76, v77
	v_cvt_pk_bf16_f32 v76, v78, v79
	v_cvt_pk_bf16_f32 v77, v80, v81
	global_store_dwordx4 v[164:165], v[98:101], off sc1
	global_store_dwordx4 v[82:83], v[74:77], off sc1
	v_pk_mul_f32 v[72:73], v[72:73], v[170:171] op_sel_hi:[1,0]
	v_pk_mul_f32 v[70:71], v[70:71], v[170:171] op_sel_hi:[1,0]
	v_pk_mul_f32 v[74:75], v[68:69], v[170:171] op_sel_hi:[1,0]
	v_pk_mul_f32 v[68:69], v[66:67], v[170:171] op_sel_hi:[1,0]
	v_cvt_pk_bf16_f32 v66, v70, v71
	v_cvt_pk_bf16_f32 v67, v72, v73
	v_cvt_pk_bf16_f32 v68, v68, v69
	v_cvt_pk_bf16_f32 v69, v74, v75
	global_store_dwordx4 v[82:83], v[66:69], off offset:256 sc1
	v_pk_mul_f32 v[64:65], v[64:65], v[172:173] op_sel_hi:[1,0]
	v_pk_mul_f32 v[62:63], v[62:63], v[172:173] op_sel_hi:[1,0]
	v_mad_i64_i32 v[66:67], s[28:29], s19, v163, 0
	v_pk_mul_f32 v[68:69], v[60:61], v[172:173] op_sel_hi:[1,0]
	v_pk_mul_f32 v[60:61], v[58:59], v[172:173] op_sel_hi:[1,0]
	v_lshl_add_u64 v[66:67], v[66:67], 1, v[156:157]
	v_cvt_pk_bf16_f32 v58, v62, v63
	v_cvt_pk_bf16_f32 v59, v64, v65
	v_cvt_pk_bf16_f32 v60, v60, v61
	v_cvt_pk_bf16_f32 v61, v68, v69
	global_store_dwordx4 v[66:67], v[58:61], off sc1
	v_pk_mul_f32 v[52:53], v[52:53], v[172:173] op_sel_hi:[1,0]
	v_pk_mul_f32 v[50:51], v[50:51], v[172:173] op_sel_hi:[1,0]
	v_pk_mul_f32 v[58:59], v[44:45], v[172:173] op_sel_hi:[1,0]
	v_pk_mul_f32 v[44:45], v[42:43], v[172:173] op_sel_hi:[1,0]
	v_cvt_pk_bf16_f32 v42, v50, v51
	v_cvt_pk_bf16_f32 v43, v52, v53
	v_cvt_pk_bf16_f32 v44, v44, v45
	v_cvt_pk_bf16_f32 v45, v58, v59
	global_store_dwordx4 v[66:67], v[42:45], off offset:256 sc1
	v_pk_mul_f32 v[48:49], v[48:49], v[150:151] op_sel_hi:[1,0]
	v_pk_mul_f32 v[46:47], v[46:47], v[150:151] op_sel_hi:[1,0]
	v_mad_i64_i32 v[42:43], s[28:29], s19, v167, 0
	v_lshl_add_u64 v[50:51], v[42:43], 1, v[156:157]
	v_pk_mul_f32 v[44:45], v[56:57], v[150:151] op_sel_hi:[1,0]
	v_pk_mul_f32 v[42:43], v[54:55], v[150:151] op_sel_hi:[1,0]
	v_pk_mul_f32 v[36:37], v[36:37], v[150:151] op_sel_hi:[1,0]
	v_cvt_pk_bf16_f32 v42, v42, v43
	v_cvt_pk_bf16_f32 v43, v44, v45
	v_cvt_pk_bf16_f32 v44, v46, v47
	v_cvt_pk_bf16_f32 v45, v48, v49
	global_store_dwordx4 v[50:51], v[42:45], off sc1
	v_pk_mul_f32 v[34:35], v[34:35], v[150:151] op_sel_hi:[1,0]
	v_pk_mul_f32 v[32:33], v[32:33], v[148:149] op_sel_hi:[1,0]
	v_pk_mul_f32 v[42:43], v[28:29], v[150:151] op_sel_hi:[1,0]
	v_pk_mul_f32 v[28:29], v[26:27], v[150:151] op_sel_hi:[1,0]
	v_cvt_pk_bf16_f32 v26, v34, v35
	v_cvt_pk_bf16_f32 v27, v36, v37
	v_cvt_pk_bf16_f32 v28, v28, v29
	v_cvt_pk_bf16_f32 v29, v42, v43
	global_store_dwordx4 v[50:51], v[26:29], off offset:256 sc1
	v_pk_mul_f32 v[30:31], v[30:31], v[148:149] op_sel_hi:[1,0]
	v_pk_mul_f32 v[20:21], v[20:21], v[148:149] op_sel_hi:[1,0]
	v_mad_i64_i32 v[26:27], s[28:29], s19, v173, 0
	v_lshl_add_u64 v[34:35], v[26:27], 1, v[156:157]
	v_pk_mul_f32 v[28:29], v[40:41], v[148:149] op_sel_hi:[1,0]
	v_pk_mul_f32 v[26:27], v[38:39], v[148:149] op_sel_hi:[1,0]
	v_pk_mul_f32 v[18:19], v[18:19], v[148:149] op_sel_hi:[1,0]
	v_cvt_pk_bf16_f32 v26, v26, v27
	v_cvt_pk_bf16_f32 v27, v28, v29
	v_cvt_pk_bf16_f32 v28, v30, v31
	v_cvt_pk_bf16_f32 v29, v32, v33
	global_store_dwordx4 v[34:35], v[26:29], off sc1
	v_pk_mul_f32 v[16:17], v[16:17], v[146:147] op_sel_hi:[1,0]
	v_pk_mul_f32 v[14:15], v[14:15], v[146:147] op_sel_hi:[1,0]
	v_pk_mul_f32 v[26:27], v[12:13], v[148:149] op_sel_hi:[1,0]
	v_pk_mul_f32 v[12:13], v[10:11], v[148:149] op_sel_hi:[1,0]
	v_cvt_pk_bf16_f32 v10, v18, v19
	v_cvt_pk_bf16_f32 v11, v20, v21
	v_cvt_pk_bf16_f32 v12, v12, v13
	v_cvt_pk_bf16_f32 v13, v26, v27
	global_store_dwordx4 v[34:35], v[10:13], off offset:256 sc1
	v_pk_mul_f32 v[8:9], v[8:9], v[146:147] op_sel_hi:[1,0]
	v_pk_mul_f32 v[6:7], v[6:7], v[146:147] op_sel_hi:[1,0]
	v_mad_i64_i32 v[10:11], s[28:29], s19, v176, 0
	v_lshl_add_u64 v[18:19], v[10:11], 1, v[156:157]
	v_pk_mul_f32 v[12:13], v[24:25], v[146:147] op_sel_hi:[1,0]
	v_pk_mul_f32 v[10:11], v[22:23], v[146:147] op_sel_hi:[1,0]
	s_nop 0
	v_cvt_pk_bf16_f32 v10, v10, v11
	v_cvt_pk_bf16_f32 v11, v12, v13
	v_cvt_pk_bf16_f32 v12, v14, v15
	v_cvt_pk_bf16_f32 v13, v16, v17
	global_store_dwordx4 v[18:19], v[10:13], off sc1
	s_nop 1
	v_pk_mul_f32 v[10:11], v[4:5], v[146:147] op_sel_hi:[1,0]
	v_pk_mul_f32 v[4:5], v[2:3], v[146:147] op_sel_hi:[1,0]
	v_cvt_pk_bf16_f32 v2, v6, v7
	v_cvt_pk_bf16_f32 v3, v8, v9
	v_cvt_pk_bf16_f32 v4, v4, v5
	v_cvt_pk_bf16_f32 v5, v10, v11
	global_store_dwordx4 v[18:19], v[2:5], off offset:256 sc1
	s_cbranch_vccnz .LBB0_118
	s_andn2_b64 vcc, exec, s[10:11]
	s_cbranch_vccnz .LBB0_117
	s_barrier
	s_branch .LBB0_117

.LBB0_705:
	v_lshl_add_u32 v152, s8, 8, v173
	v_lshl_or_b32 v130, s9, 8, v175
	v_ashrrev_i32_e32 v153, 31, v152
	v_lshlrev_b64 v[132:133], 13, v[152:153]
	v_ashrrev_i32_e32 v131, 31, v130
	v_lshl_add_u64 v[132:133], s[20:21], 0, v[132:133]
	v_lshlrev_b64 v[150:151], 1, v[130:131]
	v_lshl_add_u64 v[130:131], v[132:133], 0, v[150:151]
	global_load_dwordx4 v[180:183], v[130:131], off
	global_load_dwordx4 v[138:141], v[130:131], off offset:256
	v_or_b32_e32 v162, 16, v152
	v_ashrrev_i32_e32 v163, 31, v162
	v_lshlrev_b64 v[132:133], 13, v[162:163]
	v_lshl_add_u64 v[132:133], s[20:21], 0, v[132:133]
	v_lshl_add_u64 v[130:131], v[132:133], 0, v[150:151]
	v_lshlrev_b64 v[164:165], 12, v[152:153]
	s_waitcnt vmcnt(0)
	v_lshlrev_b32_e32 v132, 16, v180
	v_and_b32_e32 v133, 0xffff0000, v180
	v_mul_f32_e32 v132, 0xbfb8aa3b, v132
	v_mul_f32_e32 v133, 0xbfb8aa3b, v133
	v_lshlrev_b32_e32 v134, 16, v181
	v_and_b32_e32 v135, 0xffff0000, v181
	v_exp_f32_e32 v180, v132
	v_exp_f32_e32 v181, v133
	v_mul_f32_e32 v134, 0xbfb8aa3b, v134
	v_mul_f32_e32 v135, 0xbfb8aa3b, v135
	v_exp_f32_e32 v184, v134
	v_exp_f32_e32 v185, v135
	v_pk_add_f32 v[180:181], v[180:181], 1.0 op_sel_hi:[1,0]
	v_lshlrev_b32_e32 v136, 16, v182
	v_div_scale_f32 v153, s[8:9], v181, v181, 1.0
	v_and_b32_e32 v137, 0xffff0000, v182
	v_pk_add_f32 v[184:185], v[184:185], 1.0 op_sel_hi:[1,0]
	v_div_scale_f32 v182, s[8:9], v180, v180, 1.0
	v_rcp_f32_e32 v195, v153
	v_mul_f32_e32 v136, 0xbfb8aa3b, v136
	v_mul_f32_e32 v137, 0xbfb8aa3b, v137
	v_div_scale_f32 v189, s[10:11], v185, v185, 1.0
	v_rcp_f32_e32 v196, v182
	v_exp_f32_e32 v186, v136
	v_exp_f32_e32 v187, v137
	v_div_scale_f32 v191, s[12:13], v184, v184, 1.0
	v_rcp_f32_e32 v197, v189
	v_rcp_f32_e32 v198, v191
	v_fma_f32 v200, -v153, v195, 1.0
	v_div_scale_f32 v179, vcc, 1.0, v181, 1.0
	v_fma_f32 v201, -v182, v196, 1.0
	v_fmac_f32_e32 v195, v200, v195
	v_pk_add_f32 v[186:187], v[186:187], 1.0 op_sel_hi:[1,0]
	v_div_scale_f32 v188, s[8:9], 1.0, v180, 1.0
	v_fma_f32 v202, -v189, v197, 1.0
	v_fmac_f32_e32 v196, v201, v196
	v_mul_f32_e32 v200, v179, v195
	v_div_scale_f32 v190, s[10:11], 1.0, v185, 1.0
	v_div_scale_f32 v193, s[14:15], v187, v187, 1.0
	v_fma_f32 v203, -v191, v198, 1.0
	v_fmac_f32_e32 v197, v202, v197
	v_mul_f32_e32 v201, v188, v196
	v_fma_f32 v205, -v153, v200, v179
	v_div_scale_f32 v192, s[12:13], 1.0, v184, 1.0
	v_rcp_f32_e32 v199, v193
	v_fmac_f32_e32 v198, v203, v198
	v_mul_f32_e32 v202, v190, v197
	v_fma_f32 v206, -v182, v201, v188
	v_fmac_f32_e32 v200, v205, v195
	v_mul_f32_e32 v203, v192, v198
	v_fma_f32 v207, -v189, v202, v190
	v_fmac_f32_e32 v201, v206, v196
	v_fma_f32 v153, -v153, v200, v179
	v_fma_f32 v208, -v191, v203, v192
	v_fmac_f32_e32 v202, v207, v197
	v_fma_f32 v179, -v182, v201, v188
	v_div_fmas_f32 v153, v153, v195, v200
	s_mov_b64 vcc, s[8:9]
	v_fmac_f32_e32 v203, v208, v198
	v_fma_f32 v182, -v189, v202, v190
	v_div_fixup_f32 v181, v153, v181, 1.0
	v_div_fmas_f32 v153, v179, v196, v201
	s_mov_b64 vcc, s[10:11]
	v_fma_f32 v204, -v193, v199, 1.0
	v_fma_f32 v188, -v191, v203, v192
	v_div_fixup_f32 v180, v153, v180, 1.0
	v_div_fmas_f32 v153, v182, v197, v202
	s_mov_b64 vcc, s[12:13]
	v_div_scale_f32 v194, s[14:15], 1.0, v187, 1.0
	v_fmac_f32_e32 v199, v204, v199
	v_pk_mul_f32 v[126:127], v[126:127], v[180:181]
	v_div_fixup_f32 v181, v153, v185, 1.0
	v_div_fmas_f32 v153, v188, v198, v203
	v_mul_f32_e32 v204, v194, v199
	v_div_fixup_f32 v180, v153, v184, 1.0
	v_div_scale_f32 v153, s[8:9], v186, v186, 1.0
	v_fma_f32 v209, -v193, v204, v194
	v_rcp_f32_e32 v179, v153
	v_fmac_f32_e32 v204, v209, v199
	v_lshlrev_b32_e32 v182, 16, v183
	v_and_b32_e32 v183, 0xffff0000, v183
	v_fma_f32 v189, -v193, v204, v194
	s_mov_b64 vcc, s[14:15]
	v_mul_f32_e32 v182, 0xbfb8aa3b, v182
	v_mul_f32_e32 v183, 0xbfb8aa3b, v183
	v_pk_mul_f32 v[128:129], v[128:129], v[180:181]
	v_div_fmas_f32 v180, v189, v199, v204
	v_exp_f32_e32 v182, v182
	v_exp_f32_e32 v183, v183
	v_div_fixup_f32 v181, v180, v187, 1.0
	v_fma_f32 v180, -v153, v179, 1.0
	v_fmac_f32_e32 v179, v180, v179
	v_div_scale_f32 v180, vcc, 1.0, v186, 1.0
	v_mul_f32_e32 v184, v180, v179
	v_fma_f32 v185, -v153, v184, v180
	v_pk_add_f32 v[182:183], v[182:183], 1.0 op_sel_hi:[1,0]
	v_fmac_f32_e32 v184, v185, v179
	v_div_scale_f32 v185, s[8:9], v183, v183, 1.0
	v_rcp_f32_e32 v187, v185
	v_fma_f32 v153, -v153, v184, v180
	v_div_fmas_f32 v153, v153, v179, v184
	v_div_fixup_f32 v180, v153, v186, 1.0
	v_pk_mul_f32 v[180:181], v[122:123], v[180:181]
	v_fma_f32 v122, -v185, v187, 1.0
	v_fmac_f32_e32 v187, v122, v187
	v_div_scale_f32 v122, vcc, 1.0, v183, 1.0
	v_mul_f32_e32 v123, v122, v187
	v_fma_f32 v153, -v185, v123, v122
	v_fmac_f32_e32 v123, v153, v187
	v_div_scale_f32 v153, s[8:9], v182, v182, 1.0
	v_rcp_f32_e32 v179, v153
	v_fma_f32 v122, -v185, v123, v122
	v_div_fmas_f32 v122, v122, v187, v123
	v_div_fixup_f32 v123, v122, v183, 1.0
	v_fma_f32 v122, -v153, v179, 1.0
	v_fmac_f32_e32 v179, v122, v179
	v_div_scale_f32 v122, vcc, 1.0, v182, 1.0
	v_mul_f32_e32 v183, v122, v179
	v_fma_f32 v184, -v153, v183, v122
	v_fmac_f32_e32 v183, v184, v179
	v_fma_f32 v122, -v153, v183, v122
	v_div_fmas_f32 v122, v122, v179, v183
	v_div_fixup_f32 v122, v122, v182, 1.0
	v_pk_mul_f32 v[182:183], v[124:125], v[122:123]
	v_lshlrev_b32_e32 v123, 16, v138
	v_mul_f32_e32 v123, 0xbfb8aa3b, v123
	v_cvt_pk_bf16_f32 v122, v126, v127
	v_exp_f32_e32 v126, v123
	v_and_b32_e32 v123, 0xffff0000, v138
	v_mul_f32_e32 v123, 0xbfb8aa3b, v123
	v_exp_f32_e32 v127, v123
	v_cvt_pk_bf16_f32 v123, v128, v129
	v_lshl_add_u64 v[128:129], s[18:19], 0, v[164:165]
	v_cvt_pk_bf16_f32 v124, v180, v181
	v_pk_add_f32 v[126:127], v[126:127], 1.0 op_sel_hi:[1,0]
	v_cvt_pk_bf16_f32 v125, v182, v183
	v_div_scale_f32 v138, s[8:9], v127, v127, 1.0
	v_rcp_f32_e32 v153, v138
	v_lshl_add_u64 v[128:129], v[128:129], 0, v[150:151]
	global_load_dwordx4 v[134:137], v[130:131], off
	s_nop 0
	global_load_dwordx4 v[130:133], v[130:131], off offset:256
	s_nop 0
	global_store_dwordx4 v[128:129], v[122:125], off sc1
	s_nop 1
	v_fma_f32 v122, -v138, v153, 1.0
	v_fmac_f32_e32 v153, v122, v153
	v_div_scale_f32 v122, vcc, 1.0, v127, 1.0
	v_mul_f32_e32 v123, v122, v153
	v_fma_f32 v124, -v138, v123, v122
	v_fmac_f32_e32 v123, v124, v153
	v_fma_f32 v122, -v138, v123, v122
	v_div_scale_f32 v138, s[8:9], v126, v126, 1.0
	v_rcp_f32_e32 v164, v138
	v_lshlrev_b32_e32 v124, 16, v139
	v_and_b32_e32 v125, 0xffff0000, v139
	v_div_fmas_f32 v122, v122, v153, v123
	v_mul_f32_e32 v124, 0xbfb8aa3b, v124
	v_mul_f32_e32 v125, 0xbfb8aa3b, v125
	v_div_fixup_f32 v123, v122, v127, 1.0
	v_fma_f32 v122, -v138, v164, 1.0
	v_exp_f32_e32 v124, v124
	v_exp_f32_e32 v125, v125
	v_fmac_f32_e32 v164, v122, v164
	v_div_scale_f32 v122, vcc, 1.0, v126, 1.0
	v_mul_f32_e32 v127, v122, v164
	v_fma_f32 v139, -v138, v127, v122
	v_fmac_f32_e32 v127, v139, v164
	v_pk_add_f32 v[124:125], v[124:125], 1.0 op_sel_hi:[1,0]
	v_fma_f32 v122, -v138, v127, v122
	v_div_scale_f32 v138, s[8:9], v125, v125, 1.0
	v_rcp_f32_e32 v139, v138
	v_div_fmas_f32 v122, v122, v164, v127
	v_div_fixup_f32 v122, v122, v126, 1.0
	v_pk_mul_f32 v[118:119], v[118:119], v[122:123]
	v_fma_f32 v122, -v138, v139, 1.0
	v_fmac_f32_e32 v139, v122, v139
	v_div_scale_f32 v122, vcc, 1.0, v125, 1.0
	v_mul_f32_e32 v123, v122, v139
	v_fma_f32 v126, -v138, v123, v122
	v_fmac_f32_e32 v123, v126, v139
	v_fma_f32 v122, -v138, v123, v122
	v_div_scale_f32 v138, s[8:9], v124, v124, 1.0
	v_rcp_f32_e32 v153, v138
	v_lshlrev_b32_e32 v126, 16, v140
	v_and_b32_e32 v127, 0xffff0000, v140
	v_div_fmas_f32 v122, v122, v139, v123
	v_mul_f32_e32 v126, 0xbfb8aa3b, v126
	v_mul_f32_e32 v127, 0xbfb8aa3b, v127
	v_div_fixup_f32 v123, v122, v125, 1.0
	v_fma_f32 v122, -v138, v153, 1.0
	v_exp_f32_e32 v126, v126
	v_exp_f32_e32 v127, v127
	v_fmac_f32_e32 v153, v122, v153
	v_div_scale_f32 v122, vcc, 1.0, v124, 1.0
	v_mul_f32_e32 v125, v122, v153
	v_fma_f32 v139, -v138, v125, v122
	v_fmac_f32_e32 v125, v139, v153
	v_pk_add_f32 v[126:127], v[126:127], 1.0 op_sel_hi:[1,0]
	v_fma_f32 v122, -v138, v125, v122
	v_div_scale_f32 v138, s[8:9], v127, v127, 1.0
	v_rcp_f32_e32 v139, v138
	v_div_fmas_f32 v122, v122, v153, v125
	v_div_fixup_f32 v122, v122, v124, 1.0
	v_pk_mul_f32 v[120:121], v[120:121], v[122:123]
	v_fma_f32 v122, -v138, v139, 1.0
	v_fmac_f32_e32 v139, v122, v139
	v_div_scale_f32 v122, vcc, 1.0, v127, 1.0
	v_mul_f32_e32 v123, v122, v139
	v_fma_f32 v124, -v138, v123, v122
	v_fmac_f32_e32 v123, v124, v139
	v_fma_f32 v122, -v138, v123, v122
	v_div_scale_f32 v138, s[8:9], v126, v126, 1.0
	v_rcp_f32_e32 v140, v138
	v_lshlrev_b32_e32 v124, 16, v141
	v_and_b32_e32 v125, 0xffff0000, v141
	v_div_fmas_f32 v122, v122, v139, v123
	v_mul_f32_e32 v124, 0xbfb8aa3b, v124
	v_mul_f32_e32 v125, 0xbfb8aa3b, v125
	v_div_fixup_f32 v123, v122, v127, 1.0
	v_fma_f32 v122, -v138, v140, 1.0
	v_exp_f32_e32 v124, v124
	v_exp_f32_e32 v125, v125
	v_fmac_f32_e32 v140, v122, v140
	v_div_scale_f32 v122, vcc, 1.0, v126, 1.0
	v_mul_f32_e32 v127, v122, v140
	v_fma_f32 v139, -v138, v127, v122
	v_fmac_f32_e32 v127, v139, v140
	v_pk_add_f32 v[124:125], v[124:125], 1.0 op_sel_hi:[1,0]
	v_fma_f32 v122, -v138, v127, v122
	v_div_scale_f32 v138, s[8:9], v125, v125, 1.0
	v_rcp_f32_e32 v139, v138
	v_div_fmas_f32 v122, v122, v140, v127
	v_div_fixup_f32 v122, v122, v126, 1.0
	v_pk_mul_f32 v[122:123], v[114:115], v[122:123]
	v_fma_f32 v114, -v138, v139, 1.0
	v_fmac_f32_e32 v139, v114, v139
	v_div_scale_f32 v114, vcc, 1.0, v125, 1.0
	v_mul_f32_e32 v115, v114, v139
	v_fma_f32 v126, -v138, v115, v114
	v_fmac_f32_e32 v115, v126, v139
	v_div_scale_f32 v126, s[8:9], v124, v124, 1.0
	v_rcp_f32_e32 v127, v126
	v_fma_f32 v114, -v138, v115, v114
	v_div_fmas_f32 v114, v114, v139, v115
	v_div_fixup_f32 v115, v114, v125, 1.0
	v_fma_f32 v114, -v126, v127, 1.0
	v_fmac_f32_e32 v127, v114, v127
	v_div_scale_f32 v114, vcc, 1.0, v124, 1.0
	v_mul_f32_e32 v125, v114, v127
	v_fma_f32 v138, -v126, v125, v114
	v_fmac_f32_e32 v125, v138, v127
	v_fma_f32 v114, -v126, v125, v114
	v_div_fmas_f32 v114, v114, v127, v125
	v_div_fixup_f32 v114, v114, v124, 1.0
	v_pk_mul_f32 v[124:125], v[116:117], v[114:115]
	v_cvt_pk_bf16_f32 v114, v118, v119
	v_cvt_pk_bf16_f32 v115, v120, v121
	v_cvt_pk_bf16_f32 v116, v122, v123
	v_cvt_pk_bf16_f32 v117, v124, v125
	global_store_dwordx4 v[128:129], v[114:117], off offset:256 sc1
	v_or_b32_e32 v122, 32, v152
	v_ashrrev_i32_e32 v123, 31, v122
	s_waitcnt vmcnt(3)
	v_lshlrev_b32_e32 v114, 16, v134
	v_and_b32_e32 v115, 0xffff0000, v134
	v_mul_f32_e32 v114, 0xbfb8aa3b, v114
	v_mul_f32_e32 v115, 0xbfb8aa3b, v115
	v_exp_f32_e32 v114, v114
	v_exp_f32_e32 v115, v115
	v_lshlrev_b64 v[116:117], 13, v[122:123]
	v_lshlrev_b64 v[126:127], 12, v[162:163]
	v_lshl_add_u64 v[116:117], s[20:21], 0, v[116:117]
	v_pk_add_f32 v[124:125], v[114:115], 1.0 op_sel_hi:[1,0]
	v_lshl_add_u64 v[116:117], v[116:117], 0, v[150:151]
	v_div_scale_f32 v128, s[8:9], v125, v125, 1.0
	v_rcp_f32_e32 v129, v128
	global_load_dwordx4 v[118:121], v[116:117], off
	s_nop 0
	global_load_dwordx4 v[114:117], v[116:117], off offset:256
	v_fma_f32 v134, -v128, v129, 1.0
	v_fmac_f32_e32 v129, v134, v129
	v_div_scale_f32 v134, vcc, 1.0, v125, 1.0
	v_mul_f32_e32 v138, v134, v129
	v_fma_f32 v139, -v128, v138, v134
	v_fmac_f32_e32 v138, v139, v129
	v_fma_f32 v128, -v128, v138, v134
	v_div_scale_f32 v134, s[8:9], v124, v124, 1.0
	v_rcp_f32_e32 v139, v134
	v_div_fmas_f32 v128, v128, v129, v138
	v_div_fixup_f32 v125, v128, v125, 1.0
	v_and_b32_e32 v129, 0xffff0000, v135
	v_fma_f32 v128, -v134, v139, 1.0
	v_fmac_f32_e32 v139, v128, v139
	v_lshlrev_b32_e32 v128, 16, v135
	v_mul_f32_e32 v128, 0xbfb8aa3b, v128
	v_mul_f32_e32 v129, 0xbfb8aa3b, v129
	v_exp_f32_e32 v128, v128
	v_exp_f32_e32 v129, v129
	v_div_scale_f32 v138, vcc, 1.0, v124, 1.0
	v_mul_f32_e32 v140, v138, v139
	v_fma_f32 v135, -v134, v140, v138
	v_pk_add_f32 v[128:129], v[128:129], 1.0 op_sel_hi:[1,0]
	v_fmac_f32_e32 v140, v135, v139
	v_div_scale_f32 v135, s[8:9], v129, v129, 1.0
	v_fma_f32 v134, -v134, v140, v138
	v_rcp_f32_e32 v138, v135
	v_div_fmas_f32 v134, v134, v139, v140
	v_div_fixup_f32 v124, v134, v124, 1.0
	v_pk_mul_f32 v[110:111], v[110:111], v[124:125]
	v_fma_f32 v124, -v135, v138, 1.0
	v_fmac_f32_e32 v138, v124, v138
	v_div_scale_f32 v124, vcc, 1.0, v129, 1.0
	v_mul_f32_e32 v125, v124, v138
	v_fma_f32 v134, -v135, v125, v124
	v_div_scale_f32 v139, s[8:9], v128, v128, 1.0
	v_fmac_f32_e32 v125, v134, v138
	v_rcp_f32_e32 v140, v139
	v_fma_f32 v124, -v135, v125, v124
	v_lshlrev_b32_e32 v134, 16, v136
	v_and_b32_e32 v135, 0xffff0000, v136
	v_mul_f32_e32 v134, 0xbfb8aa3b, v134
	v_mul_f32_e32 v135, 0xbfb8aa3b, v135
	v_div_fmas_f32 v124, v124, v138, v125
	v_exp_f32_e32 v134, v134
	v_exp_f32_e32 v135, v135
	v_div_fixup_f32 v125, v124, v129, 1.0
	v_fma_f32 v124, -v139, v140, 1.0
	v_fmac_f32_e32 v140, v124, v140
	v_div_scale_f32 v124, vcc, 1.0, v128, 1.0
	v_mul_f32_e32 v129, v124, v140
	v_fma_f32 v136, -v139, v129, v124
	v_pk_add_f32 v[134:135], v[134:135], 1.0 op_sel_hi:[1,0]
	v_fmac_f32_e32 v129, v136, v140
	v_div_scale_f32 v136, s[8:9], v135, v135, 1.0
	v_rcp_f32_e32 v138, v136
	v_fma_f32 v124, -v139, v129, v124
	v_div_fmas_f32 v124, v124, v140, v129
	v_div_fixup_f32 v124, v124, v128, 1.0
	v_pk_mul_f32 v[112:113], v[112:113], v[124:125]
	v_fma_f32 v124, -v136, v138, 1.0
	v_fmac_f32_e32 v138, v124, v138
	v_div_scale_f32 v124, vcc, 1.0, v135, 1.0
	v_mul_f32_e32 v125, v124, v138
	v_fma_f32 v128, -v136, v125, v124
	v_fmac_f32_e32 v125, v128, v138
	v_fma_f32 v124, -v136, v125, v124
	v_div_scale_f32 v136, s[8:9], v134, v134, 1.0
	v_rcp_f32_e32 v139, v136
	v_lshlrev_b32_e32 v128, 16, v137
	v_and_b32_e32 v129, 0xffff0000, v137
	v_div_fmas_f32 v124, v124, v138, v125
	v_mul_f32_e32 v128, 0xbfb8aa3b, v128
	v_mul_f32_e32 v129, 0xbfb8aa3b, v129
	v_div_fixup_f32 v125, v124, v135, 1.0
	v_fma_f32 v124, -v136, v139, 1.0
	v_exp_f32_e32 v128, v128
	v_exp_f32_e32 v129, v129
	v_fmac_f32_e32 v139, v124, v139
	v_div_scale_f32 v124, vcc, 1.0, v134, 1.0
	v_mul_f32_e32 v135, v124, v139
	v_fma_f32 v137, -v136, v135, v124
	v_fmac_f32_e32 v135, v137, v139
	v_pk_add_f32 v[128:129], v[128:129], 1.0 op_sel_hi:[1,0]
	v_fma_f32 v124, -v136, v135, v124
	v_div_scale_f32 v136, s[8:9], v129, v129, 1.0
	v_rcp_f32_e32 v137, v136
	v_div_fmas_f32 v124, v124, v139, v135
	v_div_fixup_f32 v124, v124, v134, 1.0
	v_pk_mul_f32 v[124:125], v[106:107], v[124:125]
	v_fma_f32 v106, -v136, v137, 1.0
	v_fmac_f32_e32 v137, v106, v137
	v_div_scale_f32 v106, vcc, 1.0, v129, 1.0
	v_mul_f32_e32 v107, v106, v137
	v_fma_f32 v134, -v136, v107, v106
	v_fmac_f32_e32 v107, v134, v137
	v_div_scale_f32 v134, s[8:9], v128, v128, 1.0
	v_rcp_f32_e32 v135, v134
	v_fma_f32 v106, -v136, v107, v106
	v_div_fmas_f32 v106, v106, v137, v107
	v_div_fixup_f32 v107, v106, v129, 1.0
	v_fma_f32 v106, -v134, v135, 1.0
	v_fmac_f32_e32 v135, v106, v135
	v_div_scale_f32 v106, vcc, 1.0, v128, 1.0
	v_mul_f32_e32 v129, v106, v135
	v_fma_f32 v136, -v134, v129, v106
	v_fmac_f32_e32 v129, v136, v135
	v_fma_f32 v106, -v134, v129, v106
	v_div_fmas_f32 v106, v106, v135, v129
	v_div_fixup_f32 v106, v106, v128, 1.0
	v_pk_mul_f32 v[128:129], v[108:109], v[106:107]
	s_waitcnt vmcnt(4)
	v_lshlrev_b32_e32 v107, 16, v130
	v_mul_f32_e32 v107, 0xbfb8aa3b, v107
	v_cvt_pk_bf16_f32 v106, v110, v111
	v_exp_f32_e32 v110, v107
	v_and_b32_e32 v107, 0xffff0000, v130
	v_mul_f32_e32 v107, 0xbfb8aa3b, v107
	v_exp_f32_e32 v111, v107
	v_cvt_pk_bf16_f32 v108, v124, v125
	v_cvt_pk_bf16_f32 v107, v112, v113
	v_lshl_add_u64 v[112:113], s[18:19], 0, v[126:127]
	v_pk_add_f32 v[110:111], v[110:111], 1.0 op_sel_hi:[1,0]
	v_cvt_pk_bf16_f32 v109, v128, v129
	v_div_scale_f32 v124, s[8:9], v111, v111, 1.0
	v_rcp_f32_e32 v125, v124
	v_lshl_add_u64 v[112:113], v[112:113], 0, v[150:151]
	global_store_dwordx4 v[112:113], v[106:109], off sc1
	s_nop 1
	v_fma_f32 v106, -v124, v125, 1.0
	v_fmac_f32_e32 v125, v106, v125
	v_div_scale_f32 v106, vcc, 1.0, v111, 1.0
	v_mul_f32_e32 v107, v106, v125
	v_fma_f32 v108, -v124, v107, v106
	v_fmac_f32_e32 v107, v108, v125
	v_fma_f32 v106, -v124, v107, v106
	v_div_scale_f32 v124, s[8:9], v110, v110, 1.0
	v_rcp_f32_e32 v126, v124
	v_lshlrev_b32_e32 v108, 16, v131
	v_and_b32_e32 v109, 0xffff0000, v131
	v_div_fmas_f32 v106, v106, v125, v107
	v_mul_f32_e32 v108, 0xbfb8aa3b, v108
	v_mul_f32_e32 v109, 0xbfb8aa3b, v109
	v_div_fixup_f32 v107, v106, v111, 1.0
	v_fma_f32 v106, -v124, v126, 1.0
	v_exp_f32_e32 v108, v108
	v_exp_f32_e32 v109, v109
	v_fmac_f32_e32 v126, v106, v126
	v_div_scale_f32 v106, vcc, 1.0, v110, 1.0
	v_mul_f32_e32 v111, v106, v126
	v_fma_f32 v125, -v124, v111, v106
	v_fmac_f32_e32 v111, v125, v126
	v_pk_add_f32 v[108:109], v[108:109], 1.0 op_sel_hi:[1,0]
	v_fma_f32 v106, -v124, v111, v106
	v_div_scale_f32 v124, s[8:9], v109, v109, 1.0
	v_rcp_f32_e32 v125, v124
	v_div_fmas_f32 v106, v106, v126, v111
	v_div_fixup_f32 v106, v106, v110, 1.0
	v_pk_mul_f32 v[102:103], v[102:103], v[106:107]
	v_fma_f32 v106, -v124, v125, 1.0
	v_fmac_f32_e32 v125, v106, v125
	v_div_scale_f32 v106, vcc, 1.0, v109, 1.0
	v_mul_f32_e32 v107, v106, v125
	v_fma_f32 v110, -v124, v107, v106
	v_fmac_f32_e32 v107, v110, v125
	v_fma_f32 v106, -v124, v107, v106
	v_div_scale_f32 v124, s[8:9], v108, v108, 1.0
	v_rcp_f32_e32 v126, v124
	v_lshlrev_b32_e32 v110, 16, v132
	v_and_b32_e32 v111, 0xffff0000, v132
	v_div_fmas_f32 v106, v106, v125, v107
	v_mul_f32_e32 v110, 0xbfb8aa3b, v110
	v_mul_f32_e32 v111, 0xbfb8aa3b, v111
	v_div_fixup_f32 v107, v106, v109, 1.0
	v_fma_f32 v106, -v124, v126, 1.0
	v_exp_f32_e32 v110, v110
	v_exp_f32_e32 v111, v111
	v_fmac_f32_e32 v126, v106, v126
	v_div_scale_f32 v106, vcc, 1.0, v108, 1.0
	v_mul_f32_e32 v109, v106, v126
	v_fma_f32 v125, -v124, v109, v106
	v_fmac_f32_e32 v109, v125, v126
	v_pk_add_f32 v[110:111], v[110:111], 1.0 op_sel_hi:[1,0]
	v_fma_f32 v106, -v124, v109, v106
	v_div_scale_f32 v124, s[8:9], v111, v111, 1.0
	v_rcp_f32_e32 v125, v124
	v_div_fmas_f32 v106, v106, v126, v109
	v_div_fixup_f32 v106, v106, v108, 1.0
	v_pk_mul_f32 v[104:105], v[104:105], v[106:107]
	v_fma_f32 v106, -v124, v125, 1.0
	v_fmac_f32_e32 v125, v106, v125
	v_div_scale_f32 v106, vcc, 1.0, v111, 1.0
	v_mul_f32_e32 v107, v106, v125
	v_fma_f32 v108, -v124, v107, v106
	v_fmac_f32_e32 v107, v108, v125
	v_fma_f32 v106, -v124, v107, v106
	v_div_scale_f32 v124, s[8:9], v110, v110, 1.0
	v_rcp_f32_e32 v126, v124
	v_lshlrev_b32_e32 v108, 16, v133
	v_and_b32_e32 v109, 0xffff0000, v133
	v_div_fmas_f32 v106, v106, v125, v107
	v_mul_f32_e32 v108, 0xbfb8aa3b, v108
	v_mul_f32_e32 v109, 0xbfb8aa3b, v109
	v_div_fixup_f32 v107, v106, v111, 1.0
	v_fma_f32 v106, -v124, v126, 1.0
	v_exp_f32_e32 v108, v108
	v_exp_f32_e32 v109, v109
	v_fmac_f32_e32 v126, v106, v126
	v_div_scale_f32 v106, vcc, 1.0, v110, 1.0
	v_mul_f32_e32 v111, v106, v126
	v_fma_f32 v125, -v124, v111, v106
	v_fmac_f32_e32 v111, v125, v126
	v_pk_add_f32 v[108:109], v[108:109], 1.0 op_sel_hi:[1,0]
	v_fma_f32 v106, -v124, v111, v106
	v_div_scale_f32 v124, s[8:9], v109, v109, 1.0
	v_rcp_f32_e32 v125, v124
	v_div_fmas_f32 v106, v106, v126, v111
	v_div_fixup_f32 v106, v106, v110, 1.0
	v_pk_mul_f32 v[106:107], v[98:99], v[106:107]
	v_fma_f32 v98, -v124, v125, 1.0
	v_fmac_f32_e32 v125, v98, v125
	v_div_scale_f32 v98, vcc, 1.0, v109, 1.0
	v_mul_f32_e32 v99, v98, v125
	v_fma_f32 v110, -v124, v99, v98
	v_fmac_f32_e32 v99, v110, v125
	v_div_scale_f32 v110, s[8:9], v108, v108, 1.0
	v_rcp_f32_e32 v111, v110
	v_fma_f32 v98, -v124, v99, v98
	v_div_fmas_f32 v98, v98, v125, v99
	v_div_fixup_f32 v99, v98, v109, 1.0
	v_fma_f32 v98, -v110, v111, 1.0
	v_fmac_f32_e32 v111, v98, v111
	v_div_scale_f32 v98, vcc, 1.0, v108, 1.0
	v_mul_f32_e32 v109, v98, v111
	v_fma_f32 v124, -v110, v109, v98
	v_fmac_f32_e32 v109, v124, v111
	v_fma_f32 v98, -v110, v109, v98
	v_div_fmas_f32 v98, v98, v111, v109
	v_div_fixup_f32 v98, v98, v108, 1.0
	v_pk_mul_f32 v[108:109], v[100:101], v[98:99]
	v_cvt_pk_bf16_f32 v98, v102, v103
	v_cvt_pk_bf16_f32 v99, v104, v105
	v_cvt_pk_bf16_f32 v100, v106, v107
	v_cvt_pk_bf16_f32 v101, v108, v109
	global_store_dwordx4 v[112:113], v[98:101], off offset:256 sc1
	v_lshlrev_b64 v[110:111], 12, v[122:123]
	v_or_b32_e32 v106, 48, v152
	s_waitcnt vmcnt(3)
	v_lshlrev_b32_e32 v98, 16, v118
	v_and_b32_e32 v99, 0xffff0000, v118
	v_mul_f32_e32 v98, 0xbfb8aa3b, v98
	v_mul_f32_e32 v99, 0xbfb8aa3b, v99
	v_exp_f32_e32 v98, v98
	v_exp_f32_e32 v99, v99
	v_ashrrev_i32_e32 v107, 31, v106
	v_lshlrev_b64 v[100:101], 13, v[106:107]
	v_lshl_add_u64 v[100:101], s[20:21], 0, v[100:101]
	v_pk_add_f32 v[108:109], v[98:99], 1.0 op_sel_hi:[1,0]
	v_lshl_add_u64 v[100:101], v[100:101], 0, v[150:151]
	v_div_scale_f32 v112, s[8:9], v109, v109, 1.0
	v_rcp_f32_e32 v113, v112
	global_load_dwordx4 v[102:105], v[100:101], off
	s_nop 0
	global_load_dwordx4 v[98:101], v[100:101], off offset:256
	v_fma_f32 v118, -v112, v113, 1.0
	v_fmac_f32_e32 v113, v118, v113
	v_div_scale_f32 v118, vcc, 1.0, v109, 1.0
	v_mul_f32_e32 v122, v118, v113
	v_fma_f32 v123, -v112, v122, v118
	v_fmac_f32_e32 v122, v123, v113
	v_fma_f32 v112, -v112, v122, v118
	v_div_scale_f32 v118, s[8:9], v108, v108, 1.0
	v_rcp_f32_e32 v123, v118
	v_div_fmas_f32 v112, v112, v113, v122
	v_div_fixup_f32 v109, v112, v109, 1.0
	v_and_b32_e32 v113, 0xffff0000, v119
	v_fma_f32 v112, -v118, v123, 1.0
	v_fmac_f32_e32 v123, v112, v123
	v_lshlrev_b32_e32 v112, 16, v119
	v_mul_f32_e32 v112, 0xbfb8aa3b, v112
	v_mul_f32_e32 v113, 0xbfb8aa3b, v113
	v_exp_f32_e32 v112, v112
	v_exp_f32_e32 v113, v113
	v_div_scale_f32 v122, vcc, 1.0, v108, 1.0
	v_mul_f32_e32 v124, v122, v123
	v_fma_f32 v119, -v118, v124, v122
	v_pk_add_f32 v[112:113], v[112:113], 1.0 op_sel_hi:[1,0]
	v_fmac_f32_e32 v124, v119, v123
	v_div_scale_f32 v119, s[8:9], v113, v113, 1.0
	v_fma_f32 v118, -v118, v124, v122
	v_rcp_f32_e32 v122, v119
	v_div_fmas_f32 v118, v118, v123, v124
	v_div_fixup_f32 v108, v118, v108, 1.0
	v_pk_mul_f32 v[94:95], v[94:95], v[108:109]
	v_fma_f32 v108, -v119, v122, 1.0
	v_fmac_f32_e32 v122, v108, v122
	v_div_scale_f32 v108, vcc, 1.0, v113, 1.0
	v_mul_f32_e32 v109, v108, v122
	v_fma_f32 v118, -v119, v109, v108
	v_div_scale_f32 v123, s[8:9], v112, v112, 1.0
	v_fmac_f32_e32 v109, v118, v122
	v_rcp_f32_e32 v124, v123
	v_fma_f32 v108, -v119, v109, v108
	v_lshlrev_b32_e32 v118, 16, v120
	v_and_b32_e32 v119, 0xffff0000, v120
	v_mul_f32_e32 v118, 0xbfb8aa3b, v118
	v_mul_f32_e32 v119, 0xbfb8aa3b, v119
	v_div_fmas_f32 v108, v108, v122, v109
	v_exp_f32_e32 v118, v118
	v_exp_f32_e32 v119, v119
	v_div_fixup_f32 v109, v108, v113, 1.0
	v_fma_f32 v108, -v123, v124, 1.0
	v_fmac_f32_e32 v124, v108, v124
	v_div_scale_f32 v108, vcc, 1.0, v112, 1.0
	v_mul_f32_e32 v113, v108, v124
	v_fma_f32 v120, -v123, v113, v108
	v_pk_add_f32 v[118:119], v[118:119], 1.0 op_sel_hi:[1,0]
	v_fmac_f32_e32 v113, v120, v124
	v_div_scale_f32 v120, s[8:9], v119, v119, 1.0
	v_rcp_f32_e32 v122, v120
	v_fma_f32 v108, -v123, v113, v108
	v_div_fmas_f32 v108, v108, v124, v113
	v_div_fixup_f32 v108, v108, v112, 1.0
	v_pk_mul_f32 v[96:97], v[96:97], v[108:109]
	v_fma_f32 v108, -v120, v122, 1.0
	v_fmac_f32_e32 v122, v108, v122
	v_div_scale_f32 v108, vcc, 1.0, v119, 1.0
	v_mul_f32_e32 v109, v108, v122
	v_fma_f32 v112, -v120, v109, v108
	v_fmac_f32_e32 v109, v112, v122
	v_fma_f32 v108, -v120, v109, v108
	v_div_scale_f32 v120, s[8:9], v118, v118, 1.0
	v_rcp_f32_e32 v123, v120
	v_lshlrev_b32_e32 v112, 16, v121
	v_and_b32_e32 v113, 0xffff0000, v121
	v_div_fmas_f32 v108, v108, v122, v109
	v_mul_f32_e32 v112, 0xbfb8aa3b, v112
	v_mul_f32_e32 v113, 0xbfb8aa3b, v113
	v_div_fixup_f32 v109, v108, v119, 1.0
	v_fma_f32 v108, -v120, v123, 1.0
	v_exp_f32_e32 v112, v112
	v_exp_f32_e32 v113, v113
	v_fmac_f32_e32 v123, v108, v123
	v_div_scale_f32 v108, vcc, 1.0, v118, 1.0
	v_mul_f32_e32 v119, v108, v123
	v_fma_f32 v121, -v120, v119, v108
	v_fmac_f32_e32 v119, v121, v123
	v_pk_add_f32 v[112:113], v[112:113], 1.0 op_sel_hi:[1,0]
	v_fma_f32 v108, -v120, v119, v108
	v_div_scale_f32 v120, s[8:9], v113, v113, 1.0
	v_rcp_f32_e32 v121, v120
	v_div_fmas_f32 v108, v108, v123, v119
	v_div_fixup_f32 v108, v108, v118, 1.0
	v_pk_mul_f32 v[108:109], v[90:91], v[108:109]
	v_fma_f32 v90, -v120, v121, 1.0
	v_fmac_f32_e32 v121, v90, v121
	v_div_scale_f32 v90, vcc, 1.0, v113, 1.0
	v_mul_f32_e32 v91, v90, v121
	v_fma_f32 v118, -v120, v91, v90
	v_fmac_f32_e32 v91, v118, v121
	v_div_scale_f32 v118, s[8:9], v112, v112, 1.0
	v_rcp_f32_e32 v119, v118
	v_fma_f32 v90, -v120, v91, v90
	v_div_fmas_f32 v90, v90, v121, v91
	v_div_fixup_f32 v91, v90, v113, 1.0
	v_fma_f32 v90, -v118, v119, 1.0
	v_fmac_f32_e32 v119, v90, v119
	v_div_scale_f32 v90, vcc, 1.0, v112, 1.0
	v_mul_f32_e32 v113, v90, v119
	v_fma_f32 v120, -v118, v113, v90
	v_fmac_f32_e32 v113, v120, v119
	v_fma_f32 v90, -v118, v113, v90
	v_div_fmas_f32 v90, v90, v119, v113
	v_div_fixup_f32 v90, v90, v112, 1.0
	v_pk_mul_f32 v[112:113], v[92:93], v[90:91]
	s_waitcnt vmcnt(4)
	v_lshlrev_b32_e32 v91, 16, v114
	v_mul_f32_e32 v91, 0xbfb8aa3b, v91
	v_cvt_pk_bf16_f32 v90, v94, v95
	v_exp_f32_e32 v94, v91
	v_and_b32_e32 v91, 0xffff0000, v114
	v_mul_f32_e32 v91, 0xbfb8aa3b, v91
	v_exp_f32_e32 v95, v91
	v_cvt_pk_bf16_f32 v92, v108, v109
	v_cvt_pk_bf16_f32 v91, v96, v97
	v_lshl_add_u64 v[96:97], s[18:19], 0, v[110:111]
	v_pk_add_f32 v[94:95], v[94:95], 1.0 op_sel_hi:[1,0]
	v_cvt_pk_bf16_f32 v93, v112, v113
	v_div_scale_f32 v108, s[8:9], v95, v95, 1.0
	v_rcp_f32_e32 v109, v108
	v_lshl_add_u64 v[96:97], v[96:97], 0, v[150:151]
	global_store_dwordx4 v[96:97], v[90:93], off sc1
	s_nop 1
	v_fma_f32 v90, -v108, v109, 1.0
	v_fmac_f32_e32 v109, v90, v109
	v_div_scale_f32 v90, vcc, 1.0, v95, 1.0
	v_mul_f32_e32 v91, v90, v109
	v_fma_f32 v92, -v108, v91, v90
	v_fmac_f32_e32 v91, v92, v109
	v_fma_f32 v90, -v108, v91, v90
	v_div_scale_f32 v108, s[8:9], v94, v94, 1.0
	v_rcp_f32_e32 v110, v108
	v_lshlrev_b32_e32 v92, 16, v115
	v_and_b32_e32 v93, 0xffff0000, v115
	v_div_fmas_f32 v90, v90, v109, v91
	v_mul_f32_e32 v92, 0xbfb8aa3b, v92
	v_mul_f32_e32 v93, 0xbfb8aa3b, v93
	v_div_fixup_f32 v91, v90, v95, 1.0
	v_fma_f32 v90, -v108, v110, 1.0
	v_exp_f32_e32 v92, v92
	v_exp_f32_e32 v93, v93
	v_fmac_f32_e32 v110, v90, v110
	v_div_scale_f32 v90, vcc, 1.0, v94, 1.0
	v_mul_f32_e32 v95, v90, v110
	v_fma_f32 v109, -v108, v95, v90
	v_fmac_f32_e32 v95, v109, v110
	v_pk_add_f32 v[92:93], v[92:93], 1.0 op_sel_hi:[1,0]
	v_fma_f32 v90, -v108, v95, v90
	v_div_scale_f32 v108, s[8:9], v93, v93, 1.0
	v_rcp_f32_e32 v109, v108
	v_div_fmas_f32 v90, v90, v110, v95
	v_div_fixup_f32 v90, v90, v94, 1.0
	v_pk_mul_f32 v[86:87], v[86:87], v[90:91]
	v_fma_f32 v90, -v108, v109, 1.0
	v_fmac_f32_e32 v109, v90, v109
	v_div_scale_f32 v90, vcc, 1.0, v93, 1.0
	v_mul_f32_e32 v91, v90, v109
	v_fma_f32 v94, -v108, v91, v90
	v_fmac_f32_e32 v91, v94, v109
	v_fma_f32 v90, -v108, v91, v90
	v_div_scale_f32 v108, s[8:9], v92, v92, 1.0
	v_rcp_f32_e32 v110, v108
	v_lshlrev_b32_e32 v94, 16, v116
	v_and_b32_e32 v95, 0xffff0000, v116
	v_div_fmas_f32 v90, v90, v109, v91
	v_mul_f32_e32 v94, 0xbfb8aa3b, v94
	v_mul_f32_e32 v95, 0xbfb8aa3b, v95
	v_div_fixup_f32 v91, v90, v93, 1.0
	v_fma_f32 v90, -v108, v110, 1.0
	v_exp_f32_e32 v94, v94
	v_exp_f32_e32 v95, v95
	v_fmac_f32_e32 v110, v90, v110
	v_div_scale_f32 v90, vcc, 1.0, v92, 1.0
	v_mul_f32_e32 v93, v90, v110
	v_fma_f32 v109, -v108, v93, v90
	v_fmac_f32_e32 v93, v109, v110
	v_pk_add_f32 v[94:95], v[94:95], 1.0 op_sel_hi:[1,0]
	v_fma_f32 v90, -v108, v93, v90
	v_div_scale_f32 v108, s[8:9], v95, v95, 1.0
	v_rcp_f32_e32 v109, v108
	v_div_fmas_f32 v90, v90, v110, v93
	v_div_fixup_f32 v90, v90, v92, 1.0
	v_pk_mul_f32 v[88:89], v[88:89], v[90:91]
	v_fma_f32 v90, -v108, v109, 1.0
	v_fmac_f32_e32 v109, v90, v109
	v_div_scale_f32 v90, vcc, 1.0, v95, 1.0
	v_mul_f32_e32 v91, v90, v109
	v_fma_f32 v92, -v108, v91, v90
	v_fmac_f32_e32 v91, v92, v109
	v_fma_f32 v90, -v108, v91, v90
	v_div_scale_f32 v108, s[8:9], v94, v94, 1.0
	v_rcp_f32_e32 v110, v108
	v_lshlrev_b32_e32 v92, 16, v117
	v_and_b32_e32 v93, 0xffff0000, v117
	v_div_fmas_f32 v90, v90, v109, v91
	v_mul_f32_e32 v92, 0xbfb8aa3b, v92
	v_mul_f32_e32 v93, 0xbfb8aa3b, v93
	v_div_fixup_f32 v91, v90, v95, 1.0
	v_fma_f32 v90, -v108, v110, 1.0
	v_exp_f32_e32 v92, v92
	v_exp_f32_e32 v93, v93
	v_fmac_f32_e32 v110, v90, v110
	v_div_scale_f32 v90, vcc, 1.0, v94, 1.0
	v_mul_f32_e32 v95, v90, v110
	v_fma_f32 v109, -v108, v95, v90
	v_fmac_f32_e32 v95, v109, v110
	v_pk_add_f32 v[92:93], v[92:93], 1.0 op_sel_hi:[1,0]
	v_fma_f32 v90, -v108, v95, v90
	v_div_scale_f32 v108, s[8:9], v93, v93, 1.0
	v_rcp_f32_e32 v109, v108
	v_div_fmas_f32 v90, v90, v110, v95
	v_div_fixup_f32 v90, v90, v94, 1.0
	v_pk_mul_f32 v[90:91], v[82:83], v[90:91]
	v_fma_f32 v82, -v108, v109, 1.0
	v_fmac_f32_e32 v109, v82, v109
	v_div_scale_f32 v82, vcc, 1.0, v93, 1.0
	v_mul_f32_e32 v83, v82, v109
	v_fma_f32 v94, -v108, v83, v82
	v_fmac_f32_e32 v83, v94, v109
	v_div_scale_f32 v94, s[8:9], v92, v92, 1.0
	v_rcp_f32_e32 v95, v94
	v_fma_f32 v82, -v108, v83, v82
	v_div_fmas_f32 v82, v82, v109, v83
	v_div_fixup_f32 v83, v82, v93, 1.0
	v_fma_f32 v82, -v94, v95, 1.0
	v_fmac_f32_e32 v95, v82, v95
	v_div_scale_f32 v82, vcc, 1.0, v92, 1.0
	v_mul_f32_e32 v93, v82, v95
	v_fma_f32 v108, -v94, v93, v82
	v_fmac_f32_e32 v93, v108, v95
	v_fma_f32 v82, -v94, v93, v82
	v_div_fmas_f32 v82, v82, v95, v93
	v_div_fixup_f32 v82, v82, v92, 1.0
	v_pk_mul_f32 v[92:93], v[84:85], v[82:83]
	v_cvt_pk_bf16_f32 v82, v86, v87
	v_cvt_pk_bf16_f32 v83, v88, v89
	v_cvt_pk_bf16_f32 v84, v90, v91
	v_cvt_pk_bf16_f32 v85, v92, v93
	global_store_dwordx4 v[96:97], v[82:85], off offset:256 sc1
	v_lshlrev_b64 v[94:95], 12, v[106:107]
	v_add_u32_e32 v90, 0x80, v152
	s_waitcnt vmcnt(3)
	v_lshlrev_b32_e32 v82, 16, v102
	v_and_b32_e32 v83, 0xffff0000, v102
	v_mul_f32_e32 v82, 0xbfb8aa3b, v82
	v_mul_f32_e32 v83, 0xbfb8aa3b, v83
	v_exp_f32_e32 v82, v82
	v_exp_f32_e32 v83, v83
	v_ashrrev_i32_e32 v91, 31, v90
	v_lshlrev_b64 v[84:85], 13, v[90:91]
	v_lshl_add_u64 v[84:85], s[20:21], 0, v[84:85]
	v_pk_add_f32 v[92:93], v[82:83], 1.0 op_sel_hi:[1,0]
	v_lshl_add_u64 v[84:85], v[84:85], 0, v[150:151]
	v_div_scale_f32 v96, s[8:9], v93, v93, 1.0
	v_rcp_f32_e32 v97, v96
	global_load_dwordx4 v[86:89], v[84:85], off
	s_nop 0
	global_load_dwordx4 v[82:85], v[84:85], off offset:256
	v_fma_f32 v102, -v96, v97, 1.0
	v_fmac_f32_e32 v97, v102, v97
	v_div_scale_f32 v102, vcc, 1.0, v93, 1.0
	v_mul_f32_e32 v106, v102, v97
	v_fma_f32 v107, -v96, v106, v102
	v_fmac_f32_e32 v106, v107, v97
	v_fma_f32 v96, -v96, v106, v102
	v_div_scale_f32 v102, s[8:9], v92, v92, 1.0
	v_rcp_f32_e32 v107, v102
	v_div_fmas_f32 v96, v96, v97, v106
	v_div_fixup_f32 v93, v96, v93, 1.0
	v_and_b32_e32 v97, 0xffff0000, v103
	v_fma_f32 v96, -v102, v107, 1.0
	v_fmac_f32_e32 v107, v96, v107
	v_lshlrev_b32_e32 v96, 16, v103
	v_mul_f32_e32 v96, 0xbfb8aa3b, v96
	v_mul_f32_e32 v97, 0xbfb8aa3b, v97
	v_exp_f32_e32 v96, v96
	v_exp_f32_e32 v97, v97
	v_div_scale_f32 v106, vcc, 1.0, v92, 1.0
	v_mul_f32_e32 v108, v106, v107
	v_fma_f32 v103, -v102, v108, v106
	v_pk_add_f32 v[96:97], v[96:97], 1.0 op_sel_hi:[1,0]
	v_fmac_f32_e32 v108, v103, v107
	v_div_scale_f32 v103, s[8:9], v97, v97, 1.0
	v_fma_f32 v102, -v102, v108, v106
	v_rcp_f32_e32 v106, v103
	v_div_fmas_f32 v102, v102, v107, v108
	v_div_fixup_f32 v92, v102, v92, 1.0
	v_pk_mul_f32 v[78:79], v[78:79], v[92:93]
	v_fma_f32 v92, -v103, v106, 1.0
	v_fmac_f32_e32 v106, v92, v106
	v_div_scale_f32 v92, vcc, 1.0, v97, 1.0
	v_mul_f32_e32 v93, v92, v106
	v_fma_f32 v102, -v103, v93, v92
	v_div_scale_f32 v107, s[8:9], v96, v96, 1.0
	v_fmac_f32_e32 v93, v102, v106
	v_rcp_f32_e32 v108, v107
	v_fma_f32 v92, -v103, v93, v92
	v_lshlrev_b32_e32 v102, 16, v104
	v_and_b32_e32 v103, 0xffff0000, v104
	v_mul_f32_e32 v102, 0xbfb8aa3b, v102
	v_mul_f32_e32 v103, 0xbfb8aa3b, v103
	v_div_fmas_f32 v92, v92, v106, v93
	v_exp_f32_e32 v102, v102
	v_exp_f32_e32 v103, v103
	v_div_fixup_f32 v93, v92, v97, 1.0
	v_fma_f32 v92, -v107, v108, 1.0
	v_fmac_f32_e32 v108, v92, v108
	v_div_scale_f32 v92, vcc, 1.0, v96, 1.0
	v_mul_f32_e32 v97, v92, v108
	v_fma_f32 v104, -v107, v97, v92
	v_pk_add_f32 v[102:103], v[102:103], 1.0 op_sel_hi:[1,0]
	v_fmac_f32_e32 v97, v104, v108
	v_div_scale_f32 v104, s[8:9], v103, v103, 1.0
	v_rcp_f32_e32 v106, v104
	v_fma_f32 v92, -v107, v97, v92
	v_div_fmas_f32 v92, v92, v108, v97
	v_div_fixup_f32 v92, v92, v96, 1.0
	v_pk_mul_f32 v[80:81], v[80:81], v[92:93]
	v_fma_f32 v92, -v104, v106, 1.0
	v_fmac_f32_e32 v106, v92, v106
	v_div_scale_f32 v92, vcc, 1.0, v103, 1.0
	v_mul_f32_e32 v93, v92, v106
	v_fma_f32 v96, -v104, v93, v92
	v_fmac_f32_e32 v93, v96, v106
	v_fma_f32 v92, -v104, v93, v92
	v_div_scale_f32 v104, s[8:9], v102, v102, 1.0
	v_rcp_f32_e32 v107, v104
	v_lshlrev_b32_e32 v96, 16, v105
	v_and_b32_e32 v97, 0xffff0000, v105
	v_div_fmas_f32 v92, v92, v106, v93
	v_mul_f32_e32 v96, 0xbfb8aa3b, v96
	v_mul_f32_e32 v97, 0xbfb8aa3b, v97
	v_div_fixup_f32 v93, v92, v103, 1.0
	v_fma_f32 v92, -v104, v107, 1.0
	v_exp_f32_e32 v96, v96
	v_exp_f32_e32 v97, v97
	v_fmac_f32_e32 v107, v92, v107
	v_div_scale_f32 v92, vcc, 1.0, v102, 1.0
	v_mul_f32_e32 v103, v92, v107
	v_fma_f32 v105, -v104, v103, v92
	v_fmac_f32_e32 v103, v105, v107
	v_pk_add_f32 v[96:97], v[96:97], 1.0 op_sel_hi:[1,0]
	v_fma_f32 v92, -v104, v103, v92
	v_div_scale_f32 v104, s[8:9], v97, v97, 1.0
	v_rcp_f32_e32 v105, v104
	v_div_fmas_f32 v92, v92, v107, v103
	v_div_fixup_f32 v92, v92, v102, 1.0
	v_pk_mul_f32 v[92:93], v[74:75], v[92:93]
	v_fma_f32 v74, -v104, v105, 1.0
	v_fmac_f32_e32 v105, v74, v105
	v_div_scale_f32 v74, vcc, 1.0, v97, 1.0
	v_mul_f32_e32 v75, v74, v105
	v_fma_f32 v102, -v104, v75, v74
	v_fmac_f32_e32 v75, v102, v105
	v_div_scale_f32 v102, s[8:9], v96, v96, 1.0
	v_rcp_f32_e32 v103, v102
	v_fma_f32 v74, -v104, v75, v74
	v_div_fmas_f32 v74, v74, v105, v75
	v_div_fixup_f32 v75, v74, v97, 1.0
	v_fma_f32 v74, -v102, v103, 1.0
	v_fmac_f32_e32 v103, v74, v103
	v_div_scale_f32 v74, vcc, 1.0, v96, 1.0
	v_mul_f32_e32 v97, v74, v103
	v_fma_f32 v104, -v102, v97, v74
	v_fmac_f32_e32 v97, v104, v103
	v_fma_f32 v74, -v102, v97, v74
	v_div_fmas_f32 v74, v74, v103, v97
	v_div_fixup_f32 v74, v74, v96, 1.0
	v_pk_mul_f32 v[96:97], v[76:77], v[74:75]
	s_waitcnt vmcnt(4)
	v_lshlrev_b32_e32 v75, 16, v98
	v_mul_f32_e32 v75, 0xbfb8aa3b, v75
	v_cvt_pk_bf16_f32 v74, v78, v79
	v_exp_f32_e32 v78, v75
	v_and_b32_e32 v75, 0xffff0000, v98
	v_mul_f32_e32 v75, 0xbfb8aa3b, v75
	v_exp_f32_e32 v79, v75
	v_cvt_pk_bf16_f32 v76, v92, v93
	v_cvt_pk_bf16_f32 v75, v80, v81
	v_lshl_add_u64 v[80:81], s[18:19], 0, v[94:95]
	v_pk_add_f32 v[78:79], v[78:79], 1.0 op_sel_hi:[1,0]
	v_cvt_pk_bf16_f32 v77, v96, v97
	v_div_scale_f32 v92, s[8:9], v79, v79, 1.0
	v_rcp_f32_e32 v93, v92
	v_lshl_add_u64 v[80:81], v[80:81], 0, v[150:151]
	global_store_dwordx4 v[80:81], v[74:77], off sc1
	s_nop 1
	v_fma_f32 v74, -v92, v93, 1.0
	v_fmac_f32_e32 v93, v74, v93
	v_div_scale_f32 v74, vcc, 1.0, v79, 1.0
	v_mul_f32_e32 v75, v74, v93
	v_fma_f32 v76, -v92, v75, v74
	v_fmac_f32_e32 v75, v76, v93
	v_fma_f32 v74, -v92, v75, v74
	v_div_scale_f32 v92, s[8:9], v78, v78, 1.0
	v_rcp_f32_e32 v94, v92
	v_lshlrev_b32_e32 v76, 16, v99
	v_and_b32_e32 v77, 0xffff0000, v99
	v_div_fmas_f32 v74, v74, v93, v75
	v_mul_f32_e32 v76, 0xbfb8aa3b, v76
	v_mul_f32_e32 v77, 0xbfb8aa3b, v77
	v_div_fixup_f32 v75, v74, v79, 1.0
	v_fma_f32 v74, -v92, v94, 1.0
	v_exp_f32_e32 v76, v76
	v_exp_f32_e32 v77, v77
	v_fmac_f32_e32 v94, v74, v94
	v_div_scale_f32 v74, vcc, 1.0, v78, 1.0
	v_mul_f32_e32 v79, v74, v94
	v_fma_f32 v93, -v92, v79, v74
	v_fmac_f32_e32 v79, v93, v94
	v_pk_add_f32 v[76:77], v[76:77], 1.0 op_sel_hi:[1,0]
	v_fma_f32 v74, -v92, v79, v74
	v_div_scale_f32 v92, s[8:9], v77, v77, 1.0
	v_rcp_f32_e32 v93, v92
	v_div_fmas_f32 v74, v74, v94, v79
	v_div_fixup_f32 v74, v74, v78, 1.0
	v_pk_mul_f32 v[70:71], v[70:71], v[74:75]
	v_fma_f32 v74, -v92, v93, 1.0
	v_fmac_f32_e32 v93, v74, v93
	v_div_scale_f32 v74, vcc, 1.0, v77, 1.0
	v_mul_f32_e32 v75, v74, v93
	v_fma_f32 v78, -v92, v75, v74
	v_fmac_f32_e32 v75, v78, v93
	v_fma_f32 v74, -v92, v75, v74
	v_div_scale_f32 v92, s[8:9], v76, v76, 1.0
	v_rcp_f32_e32 v94, v92
	v_lshlrev_b32_e32 v78, 16, v100
	v_and_b32_e32 v79, 0xffff0000, v100
	v_div_fmas_f32 v74, v74, v93, v75
	v_mul_f32_e32 v78, 0xbfb8aa3b, v78
	v_mul_f32_e32 v79, 0xbfb8aa3b, v79
	v_div_fixup_f32 v75, v74, v77, 1.0
	v_fma_f32 v74, -v92, v94, 1.0
	v_exp_f32_e32 v78, v78
	v_exp_f32_e32 v79, v79
	v_fmac_f32_e32 v94, v74, v94
	v_div_scale_f32 v74, vcc, 1.0, v76, 1.0
	v_mul_f32_e32 v77, v74, v94
	v_fma_f32 v93, -v92, v77, v74
	v_fmac_f32_e32 v77, v93, v94
	v_pk_add_f32 v[78:79], v[78:79], 1.0 op_sel_hi:[1,0]
	v_fma_f32 v74, -v92, v77, v74
	v_div_scale_f32 v92, s[8:9], v79, v79, 1.0
	v_rcp_f32_e32 v93, v92
	v_div_fmas_f32 v74, v74, v94, v77
	v_div_fixup_f32 v74, v74, v76, 1.0
	v_pk_mul_f32 v[72:73], v[72:73], v[74:75]
	v_fma_f32 v74, -v92, v93, 1.0
	v_fmac_f32_e32 v93, v74, v93
	v_div_scale_f32 v74, vcc, 1.0, v79, 1.0
	v_mul_f32_e32 v75, v74, v93
	v_fma_f32 v76, -v92, v75, v74
	v_fmac_f32_e32 v75, v76, v93
	v_fma_f32 v74, -v92, v75, v74
	v_div_scale_f32 v92, s[8:9], v78, v78, 1.0
	v_rcp_f32_e32 v94, v92
	v_lshlrev_b32_e32 v76, 16, v101
	v_and_b32_e32 v77, 0xffff0000, v101
	v_div_fmas_f32 v74, v74, v93, v75
	v_mul_f32_e32 v76, 0xbfb8aa3b, v76
	v_mul_f32_e32 v77, 0xbfb8aa3b, v77
	v_div_fixup_f32 v75, v74, v79, 1.0
	v_fma_f32 v74, -v92, v94, 1.0
	v_exp_f32_e32 v76, v76
	v_exp_f32_e32 v77, v77
	v_fmac_f32_e32 v94, v74, v94
	v_div_scale_f32 v74, vcc, 1.0, v78, 1.0
	v_mul_f32_e32 v79, v74, v94
	v_fma_f32 v93, -v92, v79, v74
	v_fmac_f32_e32 v79, v93, v94
	v_pk_add_f32 v[76:77], v[76:77], 1.0 op_sel_hi:[1,0]
	v_fma_f32 v74, -v92, v79, v74
	v_div_scale_f32 v92, s[8:9], v77, v77, 1.0
	v_rcp_f32_e32 v93, v92
	v_div_fmas_f32 v74, v74, v94, v79
	v_div_fixup_f32 v74, v74, v78, 1.0
	v_pk_mul_f32 v[74:75], v[66:67], v[74:75]
	v_fma_f32 v66, -v92, v93, 1.0
	v_fmac_f32_e32 v93, v66, v93
	v_div_scale_f32 v66, vcc, 1.0, v77, 1.0
	v_mul_f32_e32 v67, v66, v93
	v_fma_f32 v78, -v92, v67, v66
	v_fmac_f32_e32 v67, v78, v93
	v_div_scale_f32 v78, s[8:9], v76, v76, 1.0
	v_rcp_f32_e32 v79, v78
	v_fma_f32 v66, -v92, v67, v66
	v_div_fmas_f32 v66, v66, v93, v67
	v_div_fixup_f32 v67, v66, v77, 1.0
	v_fma_f32 v66, -v78, v79, 1.0
	v_fmac_f32_e32 v79, v66, v79
	v_div_scale_f32 v66, vcc, 1.0, v76, 1.0
	v_mul_f32_e32 v77, v66, v79
	v_fma_f32 v92, -v78, v77, v66
	v_fmac_f32_e32 v77, v92, v79
	v_fma_f32 v66, -v78, v77, v66
	v_div_fmas_f32 v66, v66, v79, v77
	v_div_fixup_f32 v66, v66, v76, 1.0
	v_pk_mul_f32 v[76:77], v[68:69], v[66:67]
	v_cvt_pk_bf16_f32 v66, v70, v71
	v_cvt_pk_bf16_f32 v67, v72, v73
	v_cvt_pk_bf16_f32 v68, v74, v75
	v_cvt_pk_bf16_f32 v69, v76, v77
	global_store_dwordx4 v[80:81], v[66:69], off offset:256 sc1
	v_lshlrev_b64 v[78:79], 12, v[90:91]
	v_add_u32_e32 v74, 0x90, v152
	s_waitcnt vmcnt(3)
	v_lshlrev_b32_e32 v66, 16, v86
	v_and_b32_e32 v67, 0xffff0000, v86
	v_mul_f32_e32 v66, 0xbfb8aa3b, v66
	v_mul_f32_e32 v67, 0xbfb8aa3b, v67
	v_exp_f32_e32 v66, v66
	v_exp_f32_e32 v67, v67
	v_ashrrev_i32_e32 v75, 31, v74
	v_lshlrev_b64 v[68:69], 13, v[74:75]
	v_lshl_add_u64 v[68:69], s[20:21], 0, v[68:69]
	v_pk_add_f32 v[76:77], v[66:67], 1.0 op_sel_hi:[1,0]
	v_lshl_add_u64 v[68:69], v[68:69], 0, v[150:151]
	v_div_scale_f32 v80, s[8:9], v77, v77, 1.0
	v_rcp_f32_e32 v81, v80
	global_load_dwordx4 v[70:73], v[68:69], off
	s_nop 0
	global_load_dwordx4 v[66:69], v[68:69], off offset:256
	v_fma_f32 v86, -v80, v81, 1.0
	v_fmac_f32_e32 v81, v86, v81
	v_div_scale_f32 v86, vcc, 1.0, v77, 1.0
	v_mul_f32_e32 v90, v86, v81
	v_fma_f32 v91, -v80, v90, v86
	v_fmac_f32_e32 v90, v91, v81
	v_fma_f32 v80, -v80, v90, v86
	v_div_scale_f32 v86, s[8:9], v76, v76, 1.0
	v_rcp_f32_e32 v91, v86
	v_div_fmas_f32 v80, v80, v81, v90
	v_div_fixup_f32 v77, v80, v77, 1.0
	v_and_b32_e32 v81, 0xffff0000, v87
	v_fma_f32 v80, -v86, v91, 1.0
	v_fmac_f32_e32 v91, v80, v91
	v_lshlrev_b32_e32 v80, 16, v87
	v_mul_f32_e32 v80, 0xbfb8aa3b, v80
	v_mul_f32_e32 v81, 0xbfb8aa3b, v81
	v_exp_f32_e32 v80, v80
	v_exp_f32_e32 v81, v81
	v_div_scale_f32 v90, vcc, 1.0, v76, 1.0
	v_mul_f32_e32 v92, v90, v91
	v_fma_f32 v87, -v86, v92, v90
	v_pk_add_f32 v[80:81], v[80:81], 1.0 op_sel_hi:[1,0]
	v_fmac_f32_e32 v92, v87, v91
	v_div_scale_f32 v87, s[8:9], v81, v81, 1.0
	v_fma_f32 v86, -v86, v92, v90
	v_rcp_f32_e32 v90, v87
	v_div_fmas_f32 v86, v86, v91, v92
	v_div_fixup_f32 v76, v86, v76, 1.0
	v_pk_mul_f32 v[62:63], v[62:63], v[76:77]
	v_fma_f32 v76, -v87, v90, 1.0
	v_fmac_f32_e32 v90, v76, v90
	v_div_scale_f32 v76, vcc, 1.0, v81, 1.0
	v_mul_f32_e32 v77, v76, v90
	v_fma_f32 v86, -v87, v77, v76
	v_div_scale_f32 v91, s[8:9], v80, v80, 1.0
	v_fmac_f32_e32 v77, v86, v90
	v_rcp_f32_e32 v92, v91
	v_fma_f32 v76, -v87, v77, v76
	v_lshlrev_b32_e32 v86, 16, v88
	v_and_b32_e32 v87, 0xffff0000, v88
	v_mul_f32_e32 v86, 0xbfb8aa3b, v86
	v_mul_f32_e32 v87, 0xbfb8aa3b, v87
	v_div_fmas_f32 v76, v76, v90, v77
	v_exp_f32_e32 v86, v86
	v_exp_f32_e32 v87, v87
	v_div_fixup_f32 v77, v76, v81, 1.0
	v_fma_f32 v76, -v91, v92, 1.0
	v_fmac_f32_e32 v92, v76, v92
	v_div_scale_f32 v76, vcc, 1.0, v80, 1.0
	v_mul_f32_e32 v81, v76, v92
	v_fma_f32 v88, -v91, v81, v76
	v_pk_add_f32 v[86:87], v[86:87], 1.0 op_sel_hi:[1,0]
	v_fmac_f32_e32 v81, v88, v92
	v_div_scale_f32 v88, s[8:9], v87, v87, 1.0
	v_rcp_f32_e32 v90, v88
	v_fma_f32 v76, -v91, v81, v76
	v_div_fmas_f32 v76, v76, v92, v81
	v_div_fixup_f32 v76, v76, v80, 1.0
	v_pk_mul_f32 v[64:65], v[64:65], v[76:77]
	v_fma_f32 v76, -v88, v90, 1.0
	v_fmac_f32_e32 v90, v76, v90
	v_div_scale_f32 v76, vcc, 1.0, v87, 1.0
	v_mul_f32_e32 v77, v76, v90
	v_fma_f32 v80, -v88, v77, v76
	v_fmac_f32_e32 v77, v80, v90
	v_fma_f32 v76, -v88, v77, v76
	v_div_scale_f32 v88, s[8:9], v86, v86, 1.0
	v_rcp_f32_e32 v91, v88
	v_lshlrev_b32_e32 v80, 16, v89
	v_and_b32_e32 v81, 0xffff0000, v89
	v_div_fmas_f32 v76, v76, v90, v77
	v_mul_f32_e32 v80, 0xbfb8aa3b, v80
	v_mul_f32_e32 v81, 0xbfb8aa3b, v81
	v_div_fixup_f32 v77, v76, v87, 1.0
	v_fma_f32 v76, -v88, v91, 1.0
	v_exp_f32_e32 v80, v80
	v_exp_f32_e32 v81, v81
	v_fmac_f32_e32 v91, v76, v91
	v_div_scale_f32 v76, vcc, 1.0, v86, 1.0
	v_mul_f32_e32 v87, v76, v91
	v_fma_f32 v89, -v88, v87, v76
	v_fmac_f32_e32 v87, v89, v91
	v_pk_add_f32 v[80:81], v[80:81], 1.0 op_sel_hi:[1,0]
	v_fma_f32 v76, -v88, v87, v76
	v_div_scale_f32 v88, s[8:9], v81, v81, 1.0
	v_rcp_f32_e32 v89, v88
	v_div_fmas_f32 v76, v76, v91, v87
	v_div_fixup_f32 v76, v76, v86, 1.0
	v_pk_mul_f32 v[76:77], v[58:59], v[76:77]
	v_fma_f32 v58, -v88, v89, 1.0
	v_fmac_f32_e32 v89, v58, v89
	v_div_scale_f32 v58, vcc, 1.0, v81, 1.0
	v_mul_f32_e32 v59, v58, v89
	v_fma_f32 v86, -v88, v59, v58
	v_fmac_f32_e32 v59, v86, v89
	v_div_scale_f32 v86, s[8:9], v80, v80, 1.0
	v_rcp_f32_e32 v87, v86
	v_fma_f32 v58, -v88, v59, v58
	v_div_fmas_f32 v58, v58, v89, v59
	v_div_fixup_f32 v59, v58, v81, 1.0
	v_fma_f32 v58, -v86, v87, 1.0
	v_fmac_f32_e32 v87, v58, v87
	v_div_scale_f32 v58, vcc, 1.0, v80, 1.0
	v_mul_f32_e32 v81, v58, v87
	v_fma_f32 v88, -v86, v81, v58
	v_fmac_f32_e32 v81, v88, v87
	v_fma_f32 v58, -v86, v81, v58
	v_div_fmas_f32 v58, v58, v87, v81
	v_div_fixup_f32 v58, v58, v80, 1.0
	v_pk_mul_f32 v[80:81], v[60:61], v[58:59]
	s_waitcnt vmcnt(4)
	v_lshlrev_b32_e32 v59, 16, v82
	v_mul_f32_e32 v59, 0xbfb8aa3b, v59
	v_cvt_pk_bf16_f32 v58, v62, v63
	v_exp_f32_e32 v62, v59
	v_and_b32_e32 v59, 0xffff0000, v82
	v_mul_f32_e32 v59, 0xbfb8aa3b, v59
	v_exp_f32_e32 v63, v59
	v_cvt_pk_bf16_f32 v60, v76, v77
	v_cvt_pk_bf16_f32 v59, v64, v65
	v_lshl_add_u64 v[64:65], s[18:19], 0, v[78:79]
	v_pk_add_f32 v[62:63], v[62:63], 1.0 op_sel_hi:[1,0]
	v_cvt_pk_bf16_f32 v61, v80, v81
	v_div_scale_f32 v76, s[8:9], v63, v63, 1.0
	v_rcp_f32_e32 v77, v76
	v_lshl_add_u64 v[64:65], v[64:65], 0, v[150:151]
	global_store_dwordx4 v[64:65], v[58:61], off sc1
	s_nop 1
	v_fma_f32 v58, -v76, v77, 1.0
	v_fmac_f32_e32 v77, v58, v77
	v_div_scale_f32 v58, vcc, 1.0, v63, 1.0
	v_mul_f32_e32 v59, v58, v77
	v_fma_f32 v60, -v76, v59, v58
	v_fmac_f32_e32 v59, v60, v77
	v_fma_f32 v58, -v76, v59, v58
	v_div_scale_f32 v76, s[8:9], v62, v62, 1.0
	v_rcp_f32_e32 v78, v76
	v_lshlrev_b32_e32 v60, 16, v83
	v_and_b32_e32 v61, 0xffff0000, v83
	v_div_fmas_f32 v58, v58, v77, v59
	v_mul_f32_e32 v60, 0xbfb8aa3b, v60
	v_mul_f32_e32 v61, 0xbfb8aa3b, v61
	v_div_fixup_f32 v59, v58, v63, 1.0
	v_fma_f32 v58, -v76, v78, 1.0
	v_exp_f32_e32 v60, v60
	v_exp_f32_e32 v61, v61
	v_fmac_f32_e32 v78, v58, v78
	v_div_scale_f32 v58, vcc, 1.0, v62, 1.0
	v_mul_f32_e32 v63, v58, v78
	v_fma_f32 v77, -v76, v63, v58
	v_fmac_f32_e32 v63, v77, v78
	v_pk_add_f32 v[60:61], v[60:61], 1.0 op_sel_hi:[1,0]
	v_fma_f32 v58, -v76, v63, v58
	v_div_scale_f32 v76, s[8:9], v61, v61, 1.0
	v_rcp_f32_e32 v77, v76
	v_div_fmas_f32 v58, v58, v78, v63
	v_div_fixup_f32 v58, v58, v62, 1.0
	v_pk_mul_f32 v[54:55], v[54:55], v[58:59]
	v_fma_f32 v58, -v76, v77, 1.0
	v_fmac_f32_e32 v77, v58, v77
	v_div_scale_f32 v58, vcc, 1.0, v61, 1.0
	v_mul_f32_e32 v59, v58, v77
	v_fma_f32 v62, -v76, v59, v58
	v_fmac_f32_e32 v59, v62, v77
	v_fma_f32 v58, -v76, v59, v58
	v_div_scale_f32 v76, s[8:9], v60, v60, 1.0
	v_rcp_f32_e32 v78, v76
	v_lshlrev_b32_e32 v62, 16, v84
	v_and_b32_e32 v63, 0xffff0000, v84
	v_div_fmas_f32 v58, v58, v77, v59
	v_mul_f32_e32 v62, 0xbfb8aa3b, v62
	v_mul_f32_e32 v63, 0xbfb8aa3b, v63
	v_div_fixup_f32 v59, v58, v61, 1.0
	v_fma_f32 v58, -v76, v78, 1.0
	v_exp_f32_e32 v62, v62
	v_exp_f32_e32 v63, v63
	v_fmac_f32_e32 v78, v58, v78
	v_div_scale_f32 v58, vcc, 1.0, v60, 1.0
	v_mul_f32_e32 v61, v58, v78
	v_fma_f32 v77, -v76, v61, v58
	v_fmac_f32_e32 v61, v77, v78
	v_pk_add_f32 v[62:63], v[62:63], 1.0 op_sel_hi:[1,0]
	v_fma_f32 v58, -v76, v61, v58
	v_div_scale_f32 v76, s[8:9], v63, v63, 1.0
	v_rcp_f32_e32 v77, v76
	v_div_fmas_f32 v58, v58, v78, v61
	v_div_fixup_f32 v58, v58, v60, 1.0
	v_pk_mul_f32 v[56:57], v[56:57], v[58:59]
	v_fma_f32 v58, -v76, v77, 1.0
	v_fmac_f32_e32 v77, v58, v77
	v_div_scale_f32 v58, vcc, 1.0, v63, 1.0
	v_mul_f32_e32 v59, v58, v77
	v_fma_f32 v60, -v76, v59, v58
	v_fmac_f32_e32 v59, v60, v77
	v_fma_f32 v58, -v76, v59, v58
	v_div_scale_f32 v76, s[8:9], v62, v62, 1.0
	v_rcp_f32_e32 v78, v76
	v_lshlrev_b32_e32 v60, 16, v85
	v_and_b32_e32 v61, 0xffff0000, v85
	v_div_fmas_f32 v58, v58, v77, v59
	v_mul_f32_e32 v60, 0xbfb8aa3b, v60
	v_mul_f32_e32 v61, 0xbfb8aa3b, v61
	v_div_fixup_f32 v59, v58, v63, 1.0
	v_fma_f32 v58, -v76, v78, 1.0
	v_exp_f32_e32 v60, v60
	v_exp_f32_e32 v61, v61
	v_fmac_f32_e32 v78, v58, v78
	v_div_scale_f32 v58, vcc, 1.0, v62, 1.0
	v_mul_f32_e32 v63, v58, v78
	v_fma_f32 v77, -v76, v63, v58
	v_fmac_f32_e32 v63, v77, v78
	v_pk_add_f32 v[60:61], v[60:61], 1.0 op_sel_hi:[1,0]
	v_fma_f32 v58, -v76, v63, v58
	v_div_scale_f32 v76, s[8:9], v61, v61, 1.0
	v_rcp_f32_e32 v77, v76
	v_div_fmas_f32 v58, v58, v78, v63
	v_div_fixup_f32 v58, v58, v62, 1.0
	v_pk_mul_f32 v[58:59], v[50:51], v[58:59]
	v_fma_f32 v50, -v76, v77, 1.0
	v_fmac_f32_e32 v77, v50, v77
	v_div_scale_f32 v50, vcc, 1.0, v61, 1.0
	v_mul_f32_e32 v51, v50, v77
	v_fma_f32 v62, -v76, v51, v50
	v_fmac_f32_e32 v51, v62, v77
	v_div_scale_f32 v62, s[8:9], v60, v60, 1.0
	v_rcp_f32_e32 v63, v62
	v_fma_f32 v50, -v76, v51, v50
	v_div_fmas_f32 v50, v50, v77, v51
	v_div_fixup_f32 v51, v50, v61, 1.0
	v_fma_f32 v50, -v62, v63, 1.0
	v_fmac_f32_e32 v63, v50, v63
	v_div_scale_f32 v50, vcc, 1.0, v60, 1.0
	v_mul_f32_e32 v61, v50, v63
	v_fma_f32 v76, -v62, v61, v50
	v_fmac_f32_e32 v61, v76, v63
	v_fma_f32 v50, -v62, v61, v50
	v_div_fmas_f32 v50, v50, v63, v61
	v_div_fixup_f32 v50, v50, v60, 1.0
	v_pk_mul_f32 v[60:61], v[52:53], v[50:51]
	v_cvt_pk_bf16_f32 v50, v54, v55
	v_cvt_pk_bf16_f32 v51, v56, v57
	v_cvt_pk_bf16_f32 v52, v58, v59
	v_cvt_pk_bf16_f32 v53, v60, v61
	global_store_dwordx4 v[64:65], v[50:53], off offset:256 sc1
	v_lshlrev_b64 v[62:63], 12, v[74:75]
	v_add_u32_e32 v58, 0xa0, v152
	s_waitcnt vmcnt(3)
	v_lshlrev_b32_e32 v50, 16, v70
	v_and_b32_e32 v51, 0xffff0000, v70
	v_mul_f32_e32 v50, 0xbfb8aa3b, v50
	v_mul_f32_e32 v51, 0xbfb8aa3b, v51
	v_exp_f32_e32 v50, v50
	v_exp_f32_e32 v51, v51
	v_ashrrev_i32_e32 v59, 31, v58
	v_lshlrev_b64 v[52:53], 13, v[58:59]
	v_lshl_add_u64 v[52:53], s[20:21], 0, v[52:53]
	v_pk_add_f32 v[60:61], v[50:51], 1.0 op_sel_hi:[1,0]
	v_lshl_add_u64 v[52:53], v[52:53], 0, v[150:151]
	v_div_scale_f32 v64, s[8:9], v61, v61, 1.0
	v_rcp_f32_e32 v65, v64
	global_load_dwordx4 v[54:57], v[52:53], off
	s_nop 0
	global_load_dwordx4 v[50:53], v[52:53], off offset:256
	v_fma_f32 v70, -v64, v65, 1.0
	v_fmac_f32_e32 v65, v70, v65
	v_div_scale_f32 v70, vcc, 1.0, v61, 1.0
	v_mul_f32_e32 v74, v70, v65
	v_fma_f32 v75, -v64, v74, v70
	v_fmac_f32_e32 v74, v75, v65
	v_fma_f32 v64, -v64, v74, v70
	v_div_scale_f32 v70, s[8:9], v60, v60, 1.0
	v_rcp_f32_e32 v75, v70
	v_div_fmas_f32 v64, v64, v65, v74
	v_div_fixup_f32 v61, v64, v61, 1.0
	v_and_b32_e32 v65, 0xffff0000, v71
	v_fma_f32 v64, -v70, v75, 1.0
	v_fmac_f32_e32 v75, v64, v75
	v_lshlrev_b32_e32 v64, 16, v71
	v_mul_f32_e32 v64, 0xbfb8aa3b, v64
	v_mul_f32_e32 v65, 0xbfb8aa3b, v65
	v_exp_f32_e32 v64, v64
	v_exp_f32_e32 v65, v65
	v_div_scale_f32 v74, vcc, 1.0, v60, 1.0
	v_mul_f32_e32 v76, v74, v75
	v_fma_f32 v71, -v70, v76, v74
	v_pk_add_f32 v[64:65], v[64:65], 1.0 op_sel_hi:[1,0]
	v_fmac_f32_e32 v76, v71, v75
	v_div_scale_f32 v71, s[8:9], v65, v65, 1.0
	v_fma_f32 v70, -v70, v76, v74
	v_rcp_f32_e32 v74, v71
	v_div_fmas_f32 v70, v70, v75, v76
	v_div_fixup_f32 v60, v70, v60, 1.0
	v_pk_mul_f32 v[46:47], v[46:47], v[60:61]
	v_fma_f32 v60, -v71, v74, 1.0
	v_fmac_f32_e32 v74, v60, v74
	v_div_scale_f32 v60, vcc, 1.0, v65, 1.0
	v_mul_f32_e32 v61, v60, v74
	v_fma_f32 v70, -v71, v61, v60
	v_div_scale_f32 v75, s[8:9], v64, v64, 1.0
	v_fmac_f32_e32 v61, v70, v74
	v_rcp_f32_e32 v76, v75
	v_fma_f32 v60, -v71, v61, v60
	v_lshlrev_b32_e32 v70, 16, v72
	v_and_b32_e32 v71, 0xffff0000, v72
	v_mul_f32_e32 v70, 0xbfb8aa3b, v70
	v_mul_f32_e32 v71, 0xbfb8aa3b, v71
	v_div_fmas_f32 v60, v60, v74, v61
	v_exp_f32_e32 v70, v70
	v_exp_f32_e32 v71, v71
	v_div_fixup_f32 v61, v60, v65, 1.0
	v_fma_f32 v60, -v75, v76, 1.0
	v_fmac_f32_e32 v76, v60, v76
	v_div_scale_f32 v60, vcc, 1.0, v64, 1.0
	v_mul_f32_e32 v65, v60, v76
	v_fma_f32 v72, -v75, v65, v60
	v_pk_add_f32 v[70:71], v[70:71], 1.0 op_sel_hi:[1,0]
	v_fmac_f32_e32 v65, v72, v76
	v_div_scale_f32 v72, s[8:9], v71, v71, 1.0
	v_rcp_f32_e32 v74, v72
	v_fma_f32 v60, -v75, v65, v60
	v_div_fmas_f32 v60, v60, v76, v65
	v_div_fixup_f32 v60, v60, v64, 1.0
	v_pk_mul_f32 v[48:49], v[48:49], v[60:61]
	v_fma_f32 v60, -v72, v74, 1.0
	v_fmac_f32_e32 v74, v60, v74
	v_div_scale_f32 v60, vcc, 1.0, v71, 1.0
	v_mul_f32_e32 v61, v60, v74
	v_fma_f32 v64, -v72, v61, v60
	v_fmac_f32_e32 v61, v64, v74
	v_fma_f32 v60, -v72, v61, v60
	v_div_scale_f32 v72, s[8:9], v70, v70, 1.0
	v_rcp_f32_e32 v75, v72
	v_lshlrev_b32_e32 v64, 16, v73
	v_and_b32_e32 v65, 0xffff0000, v73
	v_div_fmas_f32 v60, v60, v74, v61
	v_mul_f32_e32 v64, 0xbfb8aa3b, v64
	v_mul_f32_e32 v65, 0xbfb8aa3b, v65
	v_div_fixup_f32 v61, v60, v71, 1.0
	v_fma_f32 v60, -v72, v75, 1.0
	v_exp_f32_e32 v64, v64
	v_exp_f32_e32 v65, v65
	v_fmac_f32_e32 v75, v60, v75
	v_div_scale_f32 v60, vcc, 1.0, v70, 1.0
	v_mul_f32_e32 v71, v60, v75
	v_fma_f32 v73, -v72, v71, v60
	v_fmac_f32_e32 v71, v73, v75
	v_pk_add_f32 v[64:65], v[64:65], 1.0 op_sel_hi:[1,0]
	v_fma_f32 v60, -v72, v71, v60
	v_div_scale_f32 v72, s[8:9], v65, v65, 1.0
	v_rcp_f32_e32 v73, v72
	v_div_fmas_f32 v60, v60, v75, v71
	v_div_fixup_f32 v60, v60, v70, 1.0
	v_pk_mul_f32 v[60:61], v[42:43], v[60:61]
	v_fma_f32 v42, -v72, v73, 1.0
	v_fmac_f32_e32 v73, v42, v73
	v_div_scale_f32 v42, vcc, 1.0, v65, 1.0
	v_mul_f32_e32 v43, v42, v73
	v_fma_f32 v70, -v72, v43, v42
	v_fmac_f32_e32 v43, v70, v73
	v_div_scale_f32 v70, s[8:9], v64, v64, 1.0
	v_rcp_f32_e32 v71, v70
	v_fma_f32 v42, -v72, v43, v42
	v_div_fmas_f32 v42, v42, v73, v43
	v_div_fixup_f32 v43, v42, v65, 1.0
	v_fma_f32 v42, -v70, v71, 1.0
	v_fmac_f32_e32 v71, v42, v71
	v_div_scale_f32 v42, vcc, 1.0, v64, 1.0
	v_mul_f32_e32 v65, v42, v71
	v_fma_f32 v72, -v70, v65, v42
	v_fmac_f32_e32 v65, v72, v71
	v_fma_f32 v42, -v70, v65, v42
	v_div_fmas_f32 v42, v42, v71, v65
	v_div_fixup_f32 v42, v42, v64, 1.0
	v_pk_mul_f32 v[64:65], v[44:45], v[42:43]
	s_waitcnt vmcnt(4)
	v_lshlrev_b32_e32 v43, 16, v66
	v_mul_f32_e32 v43, 0xbfb8aa3b, v43
	v_cvt_pk_bf16_f32 v42, v46, v47
	v_exp_f32_e32 v46, v43
	v_and_b32_e32 v43, 0xffff0000, v66
	v_mul_f32_e32 v43, 0xbfb8aa3b, v43
	v_exp_f32_e32 v47, v43
	v_cvt_pk_bf16_f32 v44, v60, v61
	v_cvt_pk_bf16_f32 v43, v48, v49
	v_lshl_add_u64 v[48:49], s[18:19], 0, v[62:63]
	v_pk_add_f32 v[46:47], v[46:47], 1.0 op_sel_hi:[1,0]
	v_cvt_pk_bf16_f32 v45, v64, v65
	v_div_scale_f32 v60, s[8:9], v47, v47, 1.0
	v_rcp_f32_e32 v61, v60
	v_lshl_add_u64 v[48:49], v[48:49], 0, v[150:151]
	global_store_dwordx4 v[48:49], v[42:45], off sc1
	s_nop 1
	v_fma_f32 v42, -v60, v61, 1.0
	v_fmac_f32_e32 v61, v42, v61
	v_div_scale_f32 v42, vcc, 1.0, v47, 1.0
	v_mul_f32_e32 v43, v42, v61
	v_fma_f32 v44, -v60, v43, v42
	v_fmac_f32_e32 v43, v44, v61
	v_fma_f32 v42, -v60, v43, v42
	v_div_scale_f32 v60, s[8:9], v46, v46, 1.0
	v_rcp_f32_e32 v62, v60
	v_lshlrev_b32_e32 v44, 16, v67
	v_and_b32_e32 v45, 0xffff0000, v67
	v_div_fmas_f32 v42, v42, v61, v43
	v_mul_f32_e32 v44, 0xbfb8aa3b, v44
	v_mul_f32_e32 v45, 0xbfb8aa3b, v45
	v_div_fixup_f32 v43, v42, v47, 1.0
	v_fma_f32 v42, -v60, v62, 1.0
	v_exp_f32_e32 v44, v44
	v_exp_f32_e32 v45, v45
	v_fmac_f32_e32 v62, v42, v62
	v_div_scale_f32 v42, vcc, 1.0, v46, 1.0
	v_mul_f32_e32 v47, v42, v62
	v_fma_f32 v61, -v60, v47, v42
	v_fmac_f32_e32 v47, v61, v62
	v_pk_add_f32 v[44:45], v[44:45], 1.0 op_sel_hi:[1,0]
	v_fma_f32 v42, -v60, v47, v42
	v_div_scale_f32 v60, s[8:9], v45, v45, 1.0
	v_rcp_f32_e32 v61, v60
	v_div_fmas_f32 v42, v42, v62, v47
	v_div_fixup_f32 v42, v42, v46, 1.0
	v_pk_mul_f32 v[38:39], v[38:39], v[42:43]
	v_fma_f32 v42, -v60, v61, 1.0
	v_fmac_f32_e32 v61, v42, v61
	v_div_scale_f32 v42, vcc, 1.0, v45, 1.0
	v_mul_f32_e32 v43, v42, v61
	v_fma_f32 v46, -v60, v43, v42
	v_fmac_f32_e32 v43, v46, v61
	v_fma_f32 v42, -v60, v43, v42
	v_div_scale_f32 v60, s[8:9], v44, v44, 1.0
	v_rcp_f32_e32 v62, v60
	v_lshlrev_b32_e32 v46, 16, v68
	v_and_b32_e32 v47, 0xffff0000, v68
	v_div_fmas_f32 v42, v42, v61, v43
	v_mul_f32_e32 v46, 0xbfb8aa3b, v46
	v_mul_f32_e32 v47, 0xbfb8aa3b, v47
	v_div_fixup_f32 v43, v42, v45, 1.0
	v_fma_f32 v42, -v60, v62, 1.0
	v_exp_f32_e32 v46, v46
	v_exp_f32_e32 v47, v47
	v_fmac_f32_e32 v62, v42, v62
	v_div_scale_f32 v42, vcc, 1.0, v44, 1.0
	v_mul_f32_e32 v45, v42, v62
	v_fma_f32 v61, -v60, v45, v42
	v_fmac_f32_e32 v45, v61, v62
	v_pk_add_f32 v[46:47], v[46:47], 1.0 op_sel_hi:[1,0]
	v_fma_f32 v42, -v60, v45, v42
	v_div_scale_f32 v60, s[8:9], v47, v47, 1.0
	v_rcp_f32_e32 v61, v60
	v_div_fmas_f32 v42, v42, v62, v45
	v_div_fixup_f32 v42, v42, v44, 1.0
	v_pk_mul_f32 v[40:41], v[40:41], v[42:43]
	v_fma_f32 v42, -v60, v61, 1.0
	v_fmac_f32_e32 v61, v42, v61
	v_div_scale_f32 v42, vcc, 1.0, v47, 1.0
	v_mul_f32_e32 v43, v42, v61
	v_fma_f32 v44, -v60, v43, v42
	v_fmac_f32_e32 v43, v44, v61
	v_fma_f32 v42, -v60, v43, v42
	v_div_scale_f32 v60, s[8:9], v46, v46, 1.0
	v_rcp_f32_e32 v62, v60
	v_lshlrev_b32_e32 v44, 16, v69
	v_and_b32_e32 v45, 0xffff0000, v69
	v_div_fmas_f32 v42, v42, v61, v43
	v_mul_f32_e32 v44, 0xbfb8aa3b, v44
	v_mul_f32_e32 v45, 0xbfb8aa3b, v45
	v_div_fixup_f32 v43, v42, v47, 1.0
	v_fma_f32 v42, -v60, v62, 1.0
	v_exp_f32_e32 v44, v44
	v_exp_f32_e32 v45, v45
	v_fmac_f32_e32 v62, v42, v62
	v_div_scale_f32 v42, vcc, 1.0, v46, 1.0
	v_mul_f32_e32 v47, v42, v62
	v_fma_f32 v61, -v60, v47, v42
	v_fmac_f32_e32 v47, v61, v62
	v_pk_add_f32 v[44:45], v[44:45], 1.0 op_sel_hi:[1,0]
	v_fma_f32 v42, -v60, v47, v42
	v_div_scale_f32 v60, s[8:9], v45, v45, 1.0
	v_rcp_f32_e32 v61, v60
	v_div_fmas_f32 v42, v42, v62, v47
	v_div_fixup_f32 v42, v42, v46, 1.0
	v_pk_mul_f32 v[42:43], v[34:35], v[42:43]
	v_fma_f32 v34, -v60, v61, 1.0
	v_fmac_f32_e32 v61, v34, v61
	v_div_scale_f32 v34, vcc, 1.0, v45, 1.0
	v_mul_f32_e32 v35, v34, v61
	v_fma_f32 v46, -v60, v35, v34
	v_fmac_f32_e32 v35, v46, v61
	v_div_scale_f32 v46, s[8:9], v44, v44, 1.0
	v_rcp_f32_e32 v47, v46
	v_fma_f32 v34, -v60, v35, v34
	v_div_fmas_f32 v34, v34, v61, v35
	v_div_fixup_f32 v35, v34, v45, 1.0
	v_fma_f32 v34, -v46, v47, 1.0
	v_fmac_f32_e32 v47, v34, v47
	v_div_scale_f32 v34, vcc, 1.0, v44, 1.0
	v_mul_f32_e32 v45, v34, v47
	v_fma_f32 v60, -v46, v45, v34
	v_fmac_f32_e32 v45, v60, v47
	v_fma_f32 v34, -v46, v45, v34
	v_div_fmas_f32 v34, v34, v47, v45
	v_div_fixup_f32 v34, v34, v44, 1.0
	v_pk_mul_f32 v[44:45], v[36:37], v[34:35]
	v_cvt_pk_bf16_f32 v34, v38, v39
	v_cvt_pk_bf16_f32 v35, v40, v41
	v_cvt_pk_bf16_f32 v36, v42, v43
	v_cvt_pk_bf16_f32 v37, v44, v45
	global_store_dwordx4 v[48:49], v[34:37], off offset:256 sc1
	v_lshlrev_b64 v[46:47], 12, v[58:59]
	v_add_u32_e32 v42, 0xb0, v152
	s_waitcnt vmcnt(3)
	v_lshlrev_b32_e32 v34, 16, v54
	v_and_b32_e32 v35, 0xffff0000, v54
	v_mul_f32_e32 v34, 0xbfb8aa3b, v34
	v_mul_f32_e32 v35, 0xbfb8aa3b, v35
	v_exp_f32_e32 v34, v34
	v_exp_f32_e32 v35, v35
	v_ashrrev_i32_e32 v43, 31, v42
	v_lshlrev_b64 v[36:37], 13, v[42:43]
	v_lshl_add_u64 v[36:37], s[20:21], 0, v[36:37]
	v_pk_add_f32 v[44:45], v[34:35], 1.0 op_sel_hi:[1,0]
	v_lshl_add_u64 v[36:37], v[36:37], 0, v[150:151]
	v_div_scale_f32 v48, s[8:9], v45, v45, 1.0
	v_rcp_f32_e32 v49, v48
	global_load_dwordx4 v[38:41], v[36:37], off
	s_nop 0
	global_load_dwordx4 v[34:37], v[36:37], off offset:256
	v_fma_f32 v54, -v48, v49, 1.0
	v_fmac_f32_e32 v49, v54, v49
	v_div_scale_f32 v54, vcc, 1.0, v45, 1.0
	v_mul_f32_e32 v58, v54, v49
	v_fma_f32 v59, -v48, v58, v54
	v_fmac_f32_e32 v58, v59, v49
	v_fma_f32 v48, -v48, v58, v54
	v_div_scale_f32 v54, s[8:9], v44, v44, 1.0
	v_rcp_f32_e32 v59, v54
	v_div_fmas_f32 v48, v48, v49, v58
	v_div_fixup_f32 v45, v48, v45, 1.0
	v_and_b32_e32 v49, 0xffff0000, v55
	v_fma_f32 v48, -v54, v59, 1.0
	v_fmac_f32_e32 v59, v48, v59
	v_lshlrev_b32_e32 v48, 16, v55
	v_mul_f32_e32 v48, 0xbfb8aa3b, v48
	v_mul_f32_e32 v49, 0xbfb8aa3b, v49
	v_exp_f32_e32 v48, v48
	v_exp_f32_e32 v49, v49
	v_div_scale_f32 v58, vcc, 1.0, v44, 1.0
	v_mul_f32_e32 v60, v58, v59
	v_fma_f32 v55, -v54, v60, v58
	v_pk_add_f32 v[48:49], v[48:49], 1.0 op_sel_hi:[1,0]
	v_fmac_f32_e32 v60, v55, v59
	v_div_scale_f32 v55, s[8:9], v49, v49, 1.0
	v_fma_f32 v54, -v54, v60, v58
	v_rcp_f32_e32 v58, v55
	v_div_fmas_f32 v54, v54, v59, v60
	v_div_fixup_f32 v44, v54, v44, 1.0
	v_pk_mul_f32 v[30:31], v[30:31], v[44:45]
	v_fma_f32 v44, -v55, v58, 1.0
	v_fmac_f32_e32 v58, v44, v58
	v_div_scale_f32 v44, vcc, 1.0, v49, 1.0
	v_mul_f32_e32 v45, v44, v58
	v_fma_f32 v54, -v55, v45, v44
	v_div_scale_f32 v59, s[8:9], v48, v48, 1.0
	v_fmac_f32_e32 v45, v54, v58
	v_rcp_f32_e32 v60, v59
	v_fma_f32 v44, -v55, v45, v44
	v_lshlrev_b32_e32 v54, 16, v56
	v_and_b32_e32 v55, 0xffff0000, v56
	v_mul_f32_e32 v54, 0xbfb8aa3b, v54
	v_mul_f32_e32 v55, 0xbfb8aa3b, v55
	v_div_fmas_f32 v44, v44, v58, v45
	v_exp_f32_e32 v54, v54
	v_exp_f32_e32 v55, v55
	v_div_fixup_f32 v45, v44, v49, 1.0
	v_fma_f32 v44, -v59, v60, 1.0
	v_fmac_f32_e32 v60, v44, v60
	v_div_scale_f32 v44, vcc, 1.0, v48, 1.0
	v_mul_f32_e32 v49, v44, v60
	v_fma_f32 v56, -v59, v49, v44
	v_pk_add_f32 v[54:55], v[54:55], 1.0 op_sel_hi:[1,0]
	v_fmac_f32_e32 v49, v56, v60
	v_div_scale_f32 v56, s[8:9], v55, v55, 1.0
	v_rcp_f32_e32 v58, v56
	v_fma_f32 v44, -v59, v49, v44
	v_div_fmas_f32 v44, v44, v60, v49
	v_div_fixup_f32 v44, v44, v48, 1.0
	v_pk_mul_f32 v[32:33], v[32:33], v[44:45]
	v_fma_f32 v44, -v56, v58, 1.0
	v_fmac_f32_e32 v58, v44, v58
	v_div_scale_f32 v44, vcc, 1.0, v55, 1.0
	v_mul_f32_e32 v45, v44, v58
	v_fma_f32 v48, -v56, v45, v44
	v_fmac_f32_e32 v45, v48, v58
	v_fma_f32 v44, -v56, v45, v44
	v_div_scale_f32 v56, s[8:9], v54, v54, 1.0
	v_rcp_f32_e32 v59, v56
	v_lshlrev_b32_e32 v48, 16, v57
	v_and_b32_e32 v49, 0xffff0000, v57
	v_div_fmas_f32 v44, v44, v58, v45
	v_mul_f32_e32 v48, 0xbfb8aa3b, v48
	v_mul_f32_e32 v49, 0xbfb8aa3b, v49
	v_div_fixup_f32 v45, v44, v55, 1.0
	v_fma_f32 v44, -v56, v59, 1.0
	v_exp_f32_e32 v48, v48
	v_exp_f32_e32 v49, v49
	v_fmac_f32_e32 v59, v44, v59
	v_div_scale_f32 v44, vcc, 1.0, v54, 1.0
	v_mul_f32_e32 v55, v44, v59
	v_fma_f32 v57, -v56, v55, v44
	v_fmac_f32_e32 v55, v57, v59
	v_pk_add_f32 v[48:49], v[48:49], 1.0 op_sel_hi:[1,0]
	v_fma_f32 v44, -v56, v55, v44
	v_div_scale_f32 v56, s[8:9], v49, v49, 1.0
	v_rcp_f32_e32 v57, v56
	v_div_fmas_f32 v44, v44, v59, v55
	v_div_fixup_f32 v44, v44, v54, 1.0
	v_pk_mul_f32 v[44:45], v[26:27], v[44:45]
	v_fma_f32 v26, -v56, v57, 1.0
	v_fmac_f32_e32 v57, v26, v57
	v_div_scale_f32 v26, vcc, 1.0, v49, 1.0
	v_mul_f32_e32 v27, v26, v57
	v_fma_f32 v54, -v56, v27, v26
	v_fmac_f32_e32 v27, v54, v57
	v_div_scale_f32 v54, s[8:9], v48, v48, 1.0
	v_rcp_f32_e32 v55, v54
	v_fma_f32 v26, -v56, v27, v26
	v_div_fmas_f32 v26, v26, v57, v27
	v_div_fixup_f32 v27, v26, v49, 1.0
	v_fma_f32 v26, -v54, v55, 1.0
	v_fmac_f32_e32 v55, v26, v55
	v_div_scale_f32 v26, vcc, 1.0, v48, 1.0
	v_mul_f32_e32 v49, v26, v55
	v_fma_f32 v56, -v54, v49, v26
	v_fmac_f32_e32 v49, v56, v55
	v_fma_f32 v26, -v54, v49, v26
	v_div_fmas_f32 v26, v26, v55, v49
	v_div_fixup_f32 v26, v26, v48, 1.0
	v_pk_mul_f32 v[48:49], v[28:29], v[26:27]
	s_waitcnt vmcnt(4)
	v_lshlrev_b32_e32 v27, 16, v50
	v_mul_f32_e32 v27, 0xbfb8aa3b, v27
	v_cvt_pk_bf16_f32 v26, v30, v31
	v_exp_f32_e32 v30, v27
	v_and_b32_e32 v27, 0xffff0000, v50
	v_mul_f32_e32 v27, 0xbfb8aa3b, v27
	v_exp_f32_e32 v31, v27
	v_cvt_pk_bf16_f32 v28, v44, v45
	v_cvt_pk_bf16_f32 v27, v32, v33
	v_lshl_add_u64 v[32:33], s[18:19], 0, v[46:47]
	v_pk_add_f32 v[30:31], v[30:31], 1.0 op_sel_hi:[1,0]
	v_cvt_pk_bf16_f32 v29, v48, v49
	v_div_scale_f32 v44, s[8:9], v31, v31, 1.0
	v_rcp_f32_e32 v45, v44
	v_lshl_add_u64 v[32:33], v[32:33], 0, v[150:151]
	global_store_dwordx4 v[32:33], v[26:29], off sc1
	s_nop 1
	v_fma_f32 v26, -v44, v45, 1.0
	v_fmac_f32_e32 v45, v26, v45
	v_div_scale_f32 v26, vcc, 1.0, v31, 1.0
	v_mul_f32_e32 v27, v26, v45
	v_fma_f32 v28, -v44, v27, v26
	v_fmac_f32_e32 v27, v28, v45
	v_fma_f32 v26, -v44, v27, v26
	v_div_scale_f32 v44, s[8:9], v30, v30, 1.0
	v_rcp_f32_e32 v46, v44
	v_lshlrev_b32_e32 v28, 16, v51
	v_and_b32_e32 v29, 0xffff0000, v51
	v_div_fmas_f32 v26, v26, v45, v27
	v_mul_f32_e32 v28, 0xbfb8aa3b, v28
	v_mul_f32_e32 v29, 0xbfb8aa3b, v29
	v_div_fixup_f32 v27, v26, v31, 1.0
	v_fma_f32 v26, -v44, v46, 1.0
	v_exp_f32_e32 v28, v28
	v_exp_f32_e32 v29, v29
	v_fmac_f32_e32 v46, v26, v46
	v_div_scale_f32 v26, vcc, 1.0, v30, 1.0
	v_mul_f32_e32 v31, v26, v46
	v_fma_f32 v45, -v44, v31, v26
	v_fmac_f32_e32 v31, v45, v46
	v_pk_add_f32 v[28:29], v[28:29], 1.0 op_sel_hi:[1,0]
	v_fma_f32 v26, -v44, v31, v26
	v_div_scale_f32 v44, s[8:9], v29, v29, 1.0
	v_rcp_f32_e32 v45, v44
	v_div_fmas_f32 v26, v26, v46, v31
	v_div_fixup_f32 v26, v26, v30, 1.0
	v_pk_mul_f32 v[22:23], v[22:23], v[26:27]
	v_fma_f32 v26, -v44, v45, 1.0
	v_fmac_f32_e32 v45, v26, v45
	v_div_scale_f32 v26, vcc, 1.0, v29, 1.0
	v_mul_f32_e32 v27, v26, v45
	v_fma_f32 v30, -v44, v27, v26
	v_fmac_f32_e32 v27, v30, v45
	v_fma_f32 v26, -v44, v27, v26
	v_div_scale_f32 v44, s[8:9], v28, v28, 1.0
	v_rcp_f32_e32 v46, v44
	v_lshlrev_b32_e32 v30, 16, v52
	v_and_b32_e32 v31, 0xffff0000, v52
	v_div_fmas_f32 v26, v26, v45, v27
	v_mul_f32_e32 v30, 0xbfb8aa3b, v30
	v_mul_f32_e32 v31, 0xbfb8aa3b, v31
	v_div_fixup_f32 v27, v26, v29, 1.0
	v_fma_f32 v26, -v44, v46, 1.0
	v_exp_f32_e32 v30, v30
	v_exp_f32_e32 v31, v31
	v_fmac_f32_e32 v46, v26, v46
	v_div_scale_f32 v26, vcc, 1.0, v28, 1.0
	v_mul_f32_e32 v29, v26, v46
	v_fma_f32 v45, -v44, v29, v26
	v_fmac_f32_e32 v29, v45, v46
	v_pk_add_f32 v[30:31], v[30:31], 1.0 op_sel_hi:[1,0]
	v_fma_f32 v26, -v44, v29, v26
	v_div_scale_f32 v44, s[8:9], v31, v31, 1.0
	v_rcp_f32_e32 v45, v44
	v_div_fmas_f32 v26, v26, v46, v29
	v_div_fixup_f32 v26, v26, v28, 1.0
	v_pk_mul_f32 v[24:25], v[24:25], v[26:27]
	v_fma_f32 v26, -v44, v45, 1.0
	v_fmac_f32_e32 v45, v26, v45
	v_div_scale_f32 v26, vcc, 1.0, v31, 1.0
	v_mul_f32_e32 v27, v26, v45
	v_fma_f32 v28, -v44, v27, v26
	v_fmac_f32_e32 v27, v28, v45
	v_fma_f32 v26, -v44, v27, v26
	v_div_scale_f32 v44, s[8:9], v30, v30, 1.0
	v_rcp_f32_e32 v46, v44
	v_lshlrev_b32_e32 v28, 16, v53
	v_and_b32_e32 v29, 0xffff0000, v53
	v_div_fmas_f32 v26, v26, v45, v27
	v_mul_f32_e32 v28, 0xbfb8aa3b, v28
	v_mul_f32_e32 v29, 0xbfb8aa3b, v29
	v_div_fixup_f32 v27, v26, v31, 1.0
	v_fma_f32 v26, -v44, v46, 1.0
	v_exp_f32_e32 v28, v28
	v_exp_f32_e32 v29, v29
	v_fmac_f32_e32 v46, v26, v46
	v_div_scale_f32 v26, vcc, 1.0, v30, 1.0
	v_mul_f32_e32 v31, v26, v46
	v_fma_f32 v45, -v44, v31, v26
	v_fmac_f32_e32 v31, v45, v46
	v_pk_add_f32 v[28:29], v[28:29], 1.0 op_sel_hi:[1,0]
	v_fma_f32 v26, -v44, v31, v26
	v_div_scale_f32 v44, s[8:9], v29, v29, 1.0
	v_rcp_f32_e32 v45, v44
	v_div_fmas_f32 v26, v26, v46, v31
	v_div_fixup_f32 v26, v26, v30, 1.0
	v_pk_mul_f32 v[26:27], v[18:19], v[26:27]
	v_fma_f32 v18, -v44, v45, 1.0
	v_fmac_f32_e32 v45, v18, v45
	v_div_scale_f32 v18, vcc, 1.0, v29, 1.0
	v_mul_f32_e32 v19, v18, v45
	v_fma_f32 v30, -v44, v19, v18
	v_fmac_f32_e32 v19, v30, v45
	v_div_scale_f32 v30, s[8:9], v28, v28, 1.0
	v_rcp_f32_e32 v31, v30
	v_fma_f32 v18, -v44, v19, v18
	v_div_fmas_f32 v18, v18, v45, v19
	v_div_fixup_f32 v19, v18, v29, 1.0
	v_fma_f32 v18, -v30, v31, 1.0
	v_fmac_f32_e32 v31, v18, v31
	v_div_scale_f32 v18, vcc, 1.0, v28, 1.0
	v_mul_f32_e32 v29, v18, v31
	v_fma_f32 v44, -v30, v29, v18
	v_fmac_f32_e32 v29, v44, v31
	v_fma_f32 v18, -v30, v29, v18
	v_div_fmas_f32 v18, v18, v31, v29
	v_div_fixup_f32 v18, v18, v28, 1.0
	v_pk_mul_f32 v[28:29], v[20:21], v[18:19]
	s_waitcnt vmcnt(2)
	v_lshlrev_b32_e32 v18, 16, v38
	v_mul_f32_e32 v18, 0xbfb8aa3b, v18
	v_exp_f32_e32 v30, v18
	v_and_b32_e32 v18, 0xffff0000, v38
	v_mul_f32_e32 v18, 0xbfb8aa3b, v18
	v_exp_f32_e32 v31, v18
	v_cvt_pk_bf16_f32 v18, v22, v23
	v_cvt_pk_bf16_f32 v19, v24, v25
	v_cvt_pk_bf16_f32 v20, v26, v27
	v_pk_add_f32 v[22:23], v[30:31], 1.0 op_sel_hi:[1,0]
	v_cvt_pk_bf16_f32 v21, v28, v29
	v_div_scale_f32 v24, s[8:9], v23, v23, 1.0
	v_rcp_f32_e32 v25, v24
	global_store_dwordx4 v[32:33], v[18:21], off offset:256 sc1
	s_nop 1
	v_fma_f32 v20, -v24, v25, 1.0
	v_fmac_f32_e32 v25, v20, v25
	v_div_scale_f32 v20, vcc, 1.0, v23, 1.0
	v_mul_f32_e32 v21, v20, v25
	v_fma_f32 v26, -v24, v21, v20
	v_fmac_f32_e32 v21, v26, v25
	v_div_scale_f32 v26, s[8:9], v22, v22, 1.0
	v_rcp_f32_e32 v27, v26
	v_fma_f32 v20, -v24, v21, v20
	v_div_fmas_f32 v20, v20, v25, v21
	v_lshlrev_b32_e32 v24, 16, v39
	v_and_b32_e32 v25, 0xffff0000, v39
	v_mul_f32_e32 v24, 0xbfb8aa3b, v24
	v_mul_f32_e32 v25, 0xbfb8aa3b, v25
	v_div_fixup_f32 v21, v20, v23, 1.0
	v_fma_f32 v20, -v26, v27, 1.0
	v_exp_f32_e32 v24, v24
	v_exp_f32_e32 v25, v25
	v_fmac_f32_e32 v27, v20, v27
	v_div_scale_f32 v20, vcc, 1.0, v22, 1.0
	v_mul_f32_e32 v23, v20, v27
	v_fma_f32 v28, -v26, v23, v20
	v_fmac_f32_e32 v23, v28, v27
	v_pk_add_f32 v[24:25], v[24:25], 1.0 op_sel_hi:[1,0]
	v_fma_f32 v20, -v26, v23, v20
	v_div_scale_f32 v26, s[8:9], v25, v25, 1.0
	v_rcp_f32_e32 v28, v26
	v_div_fmas_f32 v20, v20, v27, v23
	v_div_fixup_f32 v20, v20, v22, 1.0
	v_pk_mul_f32 v[14:15], v[14:15], v[20:21]
	v_fma_f32 v20, -v26, v28, 1.0
	v_fmac_f32_e32 v28, v20, v28
	v_div_scale_f32 v20, vcc, 1.0, v25, 1.0
	v_mul_f32_e32 v21, v20, v28
	v_fma_f32 v22, -v26, v21, v20
	v_fmac_f32_e32 v21, v22, v28
	v_fma_f32 v20, -v26, v21, v20
	v_div_scale_f32 v26, s[8:9], v24, v24, 1.0
	v_rcp_f32_e32 v27, v26
	v_lshlrev_b32_e32 v22, 16, v40
	v_and_b32_e32 v23, 0xffff0000, v40
	v_div_fmas_f32 v20, v20, v28, v21
	v_mul_f32_e32 v22, 0xbfb8aa3b, v22
	v_mul_f32_e32 v23, 0xbfb8aa3b, v23
	v_div_fixup_f32 v21, v20, v25, 1.0
	v_fma_f32 v20, -v26, v27, 1.0
	v_exp_f32_e32 v22, v22
	v_exp_f32_e32 v23, v23
	v_fmac_f32_e32 v27, v20, v27
	v_div_scale_f32 v20, vcc, 1.0, v24, 1.0
	v_mul_f32_e32 v25, v20, v27
	v_fma_f32 v28, -v26, v25, v20
	v_fmac_f32_e32 v25, v28, v27
	v_pk_add_f32 v[22:23], v[22:23], 1.0 op_sel_hi:[1,0]
	v_fma_f32 v20, -v26, v25, v20
	v_div_scale_f32 v26, s[8:9], v23, v23, 1.0
	v_rcp_f32_e32 v28, v26
	v_div_fmas_f32 v20, v20, v27, v25
	v_div_fixup_f32 v20, v20, v24, 1.0
	v_pk_mul_f32 v[16:17], v[16:17], v[20:21]
	v_fma_f32 v20, -v26, v28, 1.0
	v_fmac_f32_e32 v28, v20, v28
	v_div_scale_f32 v20, vcc, 1.0, v23, 1.0
	v_mul_f32_e32 v21, v20, v28
	v_fma_f32 v24, -v26, v21, v20
	v_fmac_f32_e32 v21, v24, v28
	v_fma_f32 v20, -v26, v21, v20
	v_div_scale_f32 v26, s[8:9], v22, v22, 1.0
	v_rcp_f32_e32 v27, v26
	v_lshlrev_b32_e32 v24, 16, v41
	v_and_b32_e32 v25, 0xffff0000, v41
	v_div_fmas_f32 v20, v20, v28, v21
	v_mul_f32_e32 v24, 0xbfb8aa3b, v24
	v_mul_f32_e32 v25, 0xbfb8aa3b, v25
	v_div_fixup_f32 v21, v20, v23, 1.0
	v_fma_f32 v20, -v26, v27, 1.0
	v_exp_f32_e32 v24, v24
	v_exp_f32_e32 v25, v25
	v_fmac_f32_e32 v27, v20, v27
	v_div_scale_f32 v20, vcc, 1.0, v22, 1.0
	v_mul_f32_e32 v23, v20, v27
	v_fma_f32 v28, -v26, v23, v20
	v_fmac_f32_e32 v23, v28, v27
	v_pk_add_f32 v[24:25], v[24:25], 1.0 op_sel_hi:[1,0]
	v_fma_f32 v20, -v26, v23, v20
	v_div_scale_f32 v26, s[8:9], v25, v25, 1.0
	v_rcp_f32_e32 v28, v26
	v_div_fmas_f32 v20, v20, v27, v23
	v_div_fixup_f32 v20, v20, v22, 1.0
	v_pk_mul_f32 v[20:21], v[10:11], v[20:21]
	v_fma_f32 v10, -v26, v28, 1.0
	v_fmac_f32_e32 v28, v10, v28
	v_div_scale_f32 v10, vcc, 1.0, v25, 1.0
	v_mul_f32_e32 v11, v10, v28
	v_fma_f32 v22, -v26, v11, v10
	v_fmac_f32_e32 v11, v22, v28
	v_div_scale_f32 v22, s[8:9], v24, v24, 1.0
	v_rcp_f32_e32 v23, v22
	v_fma_f32 v10, -v26, v11, v10
	v_div_fmas_f32 v10, v10, v28, v11
	v_div_fixup_f32 v11, v10, v25, 1.0
	v_fma_f32 v10, -v22, v23, 1.0
	v_fmac_f32_e32 v23, v10, v23
	v_div_scale_f32 v10, vcc, 1.0, v24, 1.0
	v_mul_f32_e32 v25, v10, v23
	v_fma_f32 v26, -v22, v25, v10
	v_fmac_f32_e32 v25, v26, v23
	v_fma_f32 v10, -v22, v25, v10
	v_div_fmas_f32 v10, v10, v23, v25
	v_div_fixup_f32 v10, v10, v24, 1.0
	v_pk_mul_f32 v[22:23], v[12:13], v[10:11]
	s_waitcnt vmcnt(2)
	v_lshlrev_b32_e32 v11, 16, v34
	v_mul_f32_e32 v11, 0xbfb8aa3b, v11
	v_cvt_pk_bf16_f32 v10, v14, v15
	v_exp_f32_e32 v14, v11
	v_and_b32_e32 v11, 0xffff0000, v34
	v_mul_f32_e32 v11, 0xbfb8aa3b, v11
	v_exp_f32_e32 v15, v11
	v_cvt_pk_bf16_f32 v12, v20, v21
	v_lshlrev_b64 v[18:19], 12, v[42:43]
	v_cvt_pk_bf16_f32 v11, v16, v17
	v_pk_add_f32 v[14:15], v[14:15], 1.0 op_sel_hi:[1,0]
	v_lshl_add_u64 v[16:17], s[18:19], 0, v[18:19]
	v_div_scale_f32 v20, s[8:9], v15, v15, 1.0
	v_rcp_f32_e32 v21, v20
	v_cvt_pk_bf16_f32 v13, v22, v23
	v_lshl_add_u64 v[16:17], v[16:17], 0, v[150:151]
	global_store_dwordx4 v[16:17], v[10:13], off sc1
	v_div_scale_f32 v18, s[8:9], v14, v14, 1.0
	s_nop 0
	v_fma_f32 v10, -v20, v21, 1.0
	v_fmac_f32_e32 v21, v10, v21
	v_div_scale_f32 v10, vcc, 1.0, v15, 1.0
	v_mul_f32_e32 v11, v10, v21
	v_fma_f32 v12, -v20, v11, v10
	v_rcp_f32_e32 v19, v18
	v_fmac_f32_e32 v11, v12, v21
	v_fma_f32 v10, -v20, v11, v10
	v_lshlrev_b32_e32 v12, 16, v35
	v_and_b32_e32 v13, 0xffff0000, v35
	v_div_fmas_f32 v10, v10, v21, v11
	v_mul_f32_e32 v12, 0xbfb8aa3b, v12
	v_mul_f32_e32 v13, 0xbfb8aa3b, v13
	v_div_fixup_f32 v11, v10, v15, 1.0
	v_fma_f32 v10, -v18, v19, 1.0
	v_exp_f32_e32 v12, v12
	v_exp_f32_e32 v13, v13
	v_fmac_f32_e32 v19, v10, v19
	v_div_scale_f32 v10, vcc, 1.0, v14, 1.0
	v_mul_f32_e32 v15, v10, v19
	v_fma_f32 v20, -v18, v15, v10
	v_fmac_f32_e32 v15, v20, v19
	v_pk_add_f32 v[12:13], v[12:13], 1.0 op_sel_hi:[1,0]
	v_fma_f32 v10, -v18, v15, v10
	v_div_scale_f32 v18, s[8:9], v13, v13, 1.0
	v_rcp_f32_e32 v20, v18
	v_div_fmas_f32 v10, v10, v19, v15
	v_div_fixup_f32 v10, v10, v14, 1.0
	v_pk_mul_f32 v[6:7], v[6:7], v[10:11]
	v_fma_f32 v10, -v18, v20, 1.0
	v_fmac_f32_e32 v20, v10, v20
	v_div_scale_f32 v10, vcc, 1.0, v13, 1.0
	v_mul_f32_e32 v11, v10, v20
	v_fma_f32 v14, -v18, v11, v10
	v_fmac_f32_e32 v11, v14, v20
	v_fma_f32 v10, -v18, v11, v10
	v_div_scale_f32 v18, s[8:9], v12, v12, 1.0
	v_rcp_f32_e32 v19, v18
	v_lshlrev_b32_e32 v14, 16, v36
	v_and_b32_e32 v15, 0xffff0000, v36
	v_div_fmas_f32 v10, v10, v20, v11
	v_mul_f32_e32 v14, 0xbfb8aa3b, v14
	v_mul_f32_e32 v15, 0xbfb8aa3b, v15
	v_div_fixup_f32 v11, v10, v13, 1.0
	v_fma_f32 v10, -v18, v19, 1.0
	v_exp_f32_e32 v14, v14
	v_exp_f32_e32 v15, v15
	v_fmac_f32_e32 v19, v10, v19
	v_div_scale_f32 v10, vcc, 1.0, v12, 1.0
	v_mul_f32_e32 v13, v10, v19
	v_fma_f32 v20, -v18, v13, v10
	v_fmac_f32_e32 v13, v20, v19
	v_pk_add_f32 v[14:15], v[14:15], 1.0 op_sel_hi:[1,0]
	v_fma_f32 v10, -v18, v13, v10
	v_div_scale_f32 v18, s[8:9], v15, v15, 1.0
	v_rcp_f32_e32 v20, v18
	v_div_fmas_f32 v10, v10, v19, v13
	v_div_fixup_f32 v10, v10, v12, 1.0
	v_pk_mul_f32 v[8:9], v[8:9], v[10:11]
	v_fma_f32 v10, -v18, v20, 1.0
	v_fmac_f32_e32 v20, v10, v20
	v_div_scale_f32 v10, vcc, 1.0, v15, 1.0
	v_mul_f32_e32 v11, v10, v20
	v_fma_f32 v12, -v18, v11, v10
	v_fmac_f32_e32 v11, v12, v20
	v_fma_f32 v10, -v18, v11, v10
	v_div_scale_f32 v18, s[8:9], v14, v14, 1.0
	v_rcp_f32_e32 v19, v18
	v_lshlrev_b32_e32 v12, 16, v37
	v_and_b32_e32 v13, 0xffff0000, v37
	v_div_fmas_f32 v10, v10, v20, v11
	v_mul_f32_e32 v12, 0xbfb8aa3b, v12
	v_mul_f32_e32 v13, 0xbfb8aa3b, v13
	v_div_fixup_f32 v11, v10, v15, 1.0
	v_fma_f32 v10, -v18, v19, 1.0
	v_exp_f32_e32 v12, v12
	v_exp_f32_e32 v13, v13
	v_fmac_f32_e32 v19, v10, v19
	v_div_scale_f32 v10, vcc, 1.0, v14, 1.0
	v_mul_f32_e32 v15, v10, v19
	v_fma_f32 v20, -v18, v15, v10
	v_fmac_f32_e32 v15, v20, v19
	v_pk_add_f32 v[12:13], v[12:13], 1.0 op_sel_hi:[1,0]
	v_fma_f32 v10, -v18, v15, v10
	v_div_scale_f32 v18, s[8:9], v13, v13, 1.0
	v_rcp_f32_e32 v20, v18
	v_div_fmas_f32 v10, v10, v19, v15
	v_div_fixup_f32 v10, v10, v14, 1.0
	v_pk_mul_f32 v[10:11], v[2:3], v[10:11]
	v_fma_f32 v2, -v18, v20, 1.0
	v_fmac_f32_e32 v20, v2, v20
	v_div_scale_f32 v2, vcc, 1.0, v13, 1.0
	v_mul_f32_e32 v3, v2, v20
	v_fma_f32 v14, -v18, v3, v2
	v_fmac_f32_e32 v3, v14, v20
	v_div_scale_f32 v14, s[8:9], v12, v12, 1.0
	v_rcp_f32_e32 v15, v14
	v_fma_f32 v2, -v18, v3, v2
	v_div_fmas_f32 v2, v2, v20, v3
	v_div_fixup_f32 v3, v2, v13, 1.0
	v_fma_f32 v2, -v14, v15, 1.0
	v_fmac_f32_e32 v15, v2, v15
	v_div_scale_f32 v2, vcc, 1.0, v12, 1.0
	v_mul_f32_e32 v13, v2, v15
	v_fma_f32 v18, -v14, v13, v2
	v_fmac_f32_e32 v13, v18, v15
	v_fma_f32 v2, -v14, v13, v2
	v_div_fmas_f32 v2, v2, v15, v13
	v_div_fixup_f32 v2, v2, v12, 1.0
	v_pk_mul_f32 v[12:13], v[4:5], v[2:3]
	v_cvt_pk_bf16_f32 v2, v6, v7
	v_cvt_pk_bf16_f32 v3, v8, v9
	v_cvt_pk_bf16_f32 v4, v10, v11
	v_cvt_pk_bf16_f32 v5, v12, v13
	s_andn2_b64 vcc, exec, s[6:7]
	s_mov_b64 s[6:7], -1
	global_store_dwordx4 v[16:17], v[2:5], off offset:256 sc1
	s_cbranch_vccnz .LBB0_694
	s_andn2_b64 vcc, exec, s[24:25]
	s_cbranch_vccnz .LBB0_693
	s_barrier
	s_branch .LBB0_693

.LBB0_729:
	v_lshl_add_u32 v170, s8, 8, v178
	v_lshl_or_b32 v130, s9, 8, v180
	v_ashrrev_i32_e32 v171, 31, v170
	v_lshlrev_b64 v[132:133], 13, v[170:171]
	v_ashrrev_i32_e32 v131, 31, v130
	v_lshl_add_u64 v[132:133], s[20:21], 0, v[132:133]
	v_lshlrev_b64 v[172:173], 1, v[130:131]
	v_lshl_add_u64 v[130:131], v[132:133], 0, v[172:173]
	v_lshlrev_b64 v[132:133], 12, v[170:171]
	v_lshl_add_u64 v[132:133], s[18:19], 0, v[132:133]
	v_lshl_add_u64 v[176:177], v[132:133], 0, v[172:173]
	v_add_co_u32_e32 v132, vcc, 0x1000, v130
	global_load_dwordx4 v[184:187], v[176:177], off
	s_nop 0
	v_addc_co_u32_e32 v133, vcc, 0, v131, vcc
	global_load_dwordx4 v[188:191], v[132:133], off
	v_lshl_add_u64 v[130:131], v[130:131], 0, s[24:25]
	global_load_dwordx4 v[150:153], v[130:131], off offset:256
	v_or_b32_e32 v132, 16, v170
	v_ashrrev_i32_e32 v133, 31, v132
	v_lshlrev_b64 v[134:135], 13, v[132:133]
	v_lshlrev_b64 v[132:133], 12, v[132:133]
	v_lshl_add_u64 v[134:135], s[20:21], 0, v[134:135]
	v_lshl_add_u64 v[132:133], s[18:19], 0, v[132:133]
	v_lshl_add_u64 v[134:135], v[134:135], 0, v[172:173]
	v_lshl_add_u64 v[174:175], v[132:133], 0, v[172:173]
	v_add_co_u32_e32 v132, vcc, s80, v134
	v_lshl_add_u64 v[130:131], v[134:135], 0, s[24:25]
	s_nop 0
	v_addc_co_u32_e32 v133, vcc, 0, v135, vcc
	global_load_dwordx4 v[146:149], v[176:177], off offset:256
	global_load_dwordx4 v[138:141], v[174:175], off
	global_load_dwordx4 v[134:137], v[130:131], off offset:256
	global_load_dwordx4 v[142:145], v[132:133], off
	s_nop 0
	global_load_dwordx4 v[130:133], v[174:175], off offset:256
	s_waitcnt vmcnt(0)
	v_lshlrev_b32_e32 v192, 16, v184
	v_and_b32_e32 v193, 0xffff0000, v184
	v_lshlrev_b32_e32 v184, 16, v185
	v_lshlrev_b32_e32 v171, 16, v188
	v_and_b32_e32 v183, 0xffff0000, v188
	v_lshlrev_b32_e32 v188, 16, v189
	v_and_b32_e32 v189, 0xffff0000, v189
	v_mul_f32_e32 v171, 0xbfb8aa3b, v171
	v_mul_f32_e32 v183, 0xbfb8aa3b, v183
	v_mul_f32_e32 v196, 0xbfb8aa3b, v188
	v_mul_f32_e32 v197, 0xbfb8aa3b, v189
	v_exp_f32_e32 v188, v171
	v_exp_f32_e32 v189, v183
	v_lshlrev_b32_e32 v194, 16, v190
	v_and_b32_e32 v190, 0xffff0000, v190
	v_lshlrev_b32_e32 v195, 16, v191
	v_pk_add_f32 v[188:189], v[188:189], 1.0 op_sel_hi:[1,0]
	v_and_b32_e32 v191, 0xffff0000, v191
	v_mul_f32_e32 v198, 0xbfb8aa3b, v190
	v_div_scale_f32 v171, s[8:9], v189, v189, 1.0
	v_mul_f32_e32 v199, 0xbfb8aa3b, v195
	v_mul_f32_e32 v200, 0xbfb8aa3b, v191
	v_exp_f32_e32 v190, v196
	v_exp_f32_e32 v191, v197
	v_exp_f32_e32 v195, v198
	v_div_scale_f32 v198, s[8:9], v188, v188, 1.0
	v_rcp_f32_e32 v201, v171
	v_rcp_f32_e32 v202, v198
	v_pk_add_f32 v[190:191], v[190:191], 1.0 op_sel_hi:[1,0]
	v_exp_f32_e32 v197, v200
	v_fma_f32 v205, -v171, v201, 1.0
	v_div_scale_f32 v183, vcc, 1.0, v189, 1.0
	v_div_scale_f32 v200, s[10:11], v191, v191, 1.0
	v_fma_f32 v206, -v198, v202, 1.0
	v_fmac_f32_e32 v201, v205, v201
	v_exp_f32_e32 v196, v199
	v_div_scale_f32 v199, s[8:9], 1.0, v188, 1.0
	v_rcp_f32_e32 v203, v200
	v_fmac_f32_e32 v202, v206, v202
	v_mul_f32_e32 v205, v183, v201
	v_mul_f32_e32 v206, v199, v202
	v_fma_f32 v208, -v171, v205, v183
	v_fma_f32 v209, -v198, v206, v199
	v_fmac_f32_e32 v205, v208, v201
	v_fmac_f32_e32 v206, v209, v202
	v_fma_f32 v171, -v171, v205, v183
	v_fma_f32 v207, -v200, v203, 1.0
	v_fma_f32 v183, -v198, v206, v199
	v_div_fmas_f32 v171, v171, v201, v205
	s_mov_b64 vcc, s[8:9]
	v_div_scale_f32 v204, s[10:11], 1.0, v191, 1.0
	v_fmac_f32_e32 v203, v207, v203
	v_div_fixup_f32 v189, v171, v189, 1.0
	v_div_fmas_f32 v171, v183, v202, v206
	v_mul_f32_e32 v207, v204, v203
	v_div_fixup_f32 v188, v171, v188, 1.0
	v_div_scale_f32 v171, s[8:9], v190, v190, 1.0
	v_fma_f32 v210, -v200, v207, v204
	v_rcp_f32_e32 v183, v171
	v_fmac_f32_e32 v207, v210, v203
	v_fma_f32 v198, -v200, v207, v204
	s_mov_b64 vcc, s[10:11]
	v_pk_fma_f32 v[126:127], v[126:127], v[188:189], v[192:193]
	v_div_fmas_f32 v188, v198, v203, v207
	v_div_fixup_f32 v189, v188, v191, 1.0
	v_fma_f32 v188, -v171, v183, 1.0
	v_fmac_f32_e32 v183, v188, v183
	v_div_scale_f32 v188, vcc, 1.0, v190, 1.0
	v_mul_f32_e32 v194, 0xbfb8aa3b, v194
	v_mul_f32_e32 v191, v188, v183
	v_exp_f32_e32 v194, v194
	v_fma_f32 v192, -v171, v191, v188
	v_fmac_f32_e32 v191, v192, v183
	v_fma_f32 v171, -v171, v191, v188
	v_div_fmas_f32 v171, v171, v183, v191
	v_div_fixup_f32 v188, v171, v190, 1.0
	v_pk_add_f32 v[190:191], v[194:195], 1.0 op_sel_hi:[1,0]
	v_and_b32_e32 v185, 0xffff0000, v185
	v_div_scale_f32 v171, s[8:9], v191, v191, 1.0
	v_rcp_f32_e32 v183, v171
	v_pk_fma_f32 v[128:129], v[128:129], v[188:189], v[184:185]
	v_lshlrev_b32_e32 v184, 16, v186
	v_and_b32_e32 v185, 0xffff0000, v186
	v_fma_f32 v186, -v171, v183, 1.0
	v_fmac_f32_e32 v183, v186, v183
	v_div_scale_f32 v186, vcc, 1.0, v191, 1.0
	v_mul_f32_e32 v188, v186, v183
	v_fma_f32 v189, -v171, v188, v186
	v_fmac_f32_e32 v188, v189, v183
	v_fma_f32 v171, -v171, v188, v186
	v_div_scale_f32 v186, s[8:9], v190, v190, 1.0
	v_rcp_f32_e32 v192, v186
	v_div_fmas_f32 v171, v171, v183, v188
	v_div_fixup_f32 v189, v171, v191, 1.0
	v_fma_f32 v171, -v186, v192, 1.0
	v_fmac_f32_e32 v192, v171, v192
	v_div_scale_f32 v171, vcc, 1.0, v190, 1.0
	v_mul_f32_e32 v183, v171, v192
	v_fma_f32 v188, -v186, v183, v171
	v_fmac_f32_e32 v183, v188, v192
	v_fma_f32 v171, -v186, v183, v171
	v_div_fmas_f32 v171, v171, v192, v183
	v_div_fixup_f32 v188, v171, v190, 1.0
	v_pk_add_f32 v[190:191], v[196:197], 1.0 op_sel_hi:[1,0]
	v_pk_fma_f32 v[184:185], v[122:123], v[188:189], v[184:185]
	v_div_scale_f32 v171, s[8:9], v191, v191, 1.0
	v_rcp_f32_e32 v183, v171
	v_lshlrev_b32_e32 v122, 16, v187
	v_and_b32_e32 v123, 0xffff0000, v187
	v_fma_f32 v186, -v171, v183, 1.0
	v_fmac_f32_e32 v183, v186, v183
	v_div_scale_f32 v186, vcc, 1.0, v191, 1.0
	v_mul_f32_e32 v187, v186, v183
	v_fma_f32 v188, -v171, v187, v186
	v_fmac_f32_e32 v187, v188, v183
	v_fma_f32 v171, -v171, v187, v186
	v_div_scale_f32 v186, s[8:9], v190, v190, 1.0
	v_rcp_f32_e32 v188, v186
	v_div_fmas_f32 v171, v171, v183, v187
	v_div_fixup_f32 v187, v171, v191, 1.0
	v_fma_f32 v171, -v186, v188, 1.0
	v_fmac_f32_e32 v188, v171, v188
	v_div_scale_f32 v171, vcc, 1.0, v190, 1.0
	v_mul_f32_e32 v183, v171, v188
	v_fma_f32 v189, -v186, v183, v171
	v_fmac_f32_e32 v183, v189, v188
	v_fma_f32 v171, -v186, v183, v171
	v_div_fmas_f32 v171, v171, v188, v183
	v_div_fixup_f32 v186, v171, v190, 1.0
	v_pk_fma_f32 v[186:187], v[124:125], v[186:187], v[122:123]
	v_cvt_pk_bf16_f32 v122, v126, v127
	v_cvt_pk_bf16_f32 v123, v128, v129
	v_cvt_pk_bf16_f32 v124, v184, v185
	v_cvt_pk_bf16_f32 v125, v186, v187
	global_store_dwordx4 v[176:177], v[122:125], off sc1
	v_lshlrev_b32_e32 v126, 16, v152
	v_and_b32_e32 v127, 0xffff0000, v152
	v_lshlrev_b32_e32 v122, 16, v150
	v_and_b32_e32 v123, 0xffff0000, v150
	v_mul_f32_e32 v122, 0xbfb8aa3b, v122
	v_mul_f32_e32 v123, 0xbfb8aa3b, v123
	v_exp_f32_e32 v122, v122
	v_exp_f32_e32 v123, v123
	v_lshlrev_b32_e32 v128, 16, v153
	v_and_b32_e32 v129, 0xffff0000, v153
	v_lshlrev_b32_e32 v124, 16, v151
	v_pk_add_f32 v[122:123], v[122:123], 1.0 op_sel_hi:[1,0]
	v_and_b32_e32 v125, 0xffff0000, v151
	v_div_scale_f32 v152, s[8:9], v123, v123, 1.0
	v_rcp_f32_e32 v153, v152
	v_lshlrev_b32_e32 v150, 16, v146
	v_and_b32_e32 v151, 0xffff0000, v146
	v_mul_f32_e32 v124, 0xbfb8aa3b, v124
	v_fma_f32 v146, -v152, v153, 1.0
	v_fmac_f32_e32 v153, v146, v153
	v_div_scale_f32 v146, vcc, 1.0, v123, 1.0
	v_mul_f32_e32 v171, v146, v153
	v_fma_f32 v183, -v152, v171, v146
	v_fmac_f32_e32 v171, v183, v153
	v_fma_f32 v146, -v152, v171, v146
	v_div_scale_f32 v152, s[8:9], v122, v122, 1.0
	v_rcp_f32_e32 v183, v152
	v_div_fmas_f32 v146, v146, v153, v171
	v_div_fixup_f32 v123, v146, v123, 1.0
	v_mul_f32_e32 v125, 0xbfb8aa3b, v125
	v_fma_f32 v146, -v152, v183, 1.0
	v_fmac_f32_e32 v183, v146, v183
	v_div_scale_f32 v146, vcc, 1.0, v122, 1.0
	v_exp_f32_e32 v124, v124
	v_exp_f32_e32 v125, v125
	v_mul_f32_e32 v153, v146, v183
	v_fma_f32 v171, -v152, v153, v146
	v_fmac_f32_e32 v153, v171, v183
	v_fma_f32 v146, -v152, v153, v146
	v_div_fmas_f32 v146, v146, v183, v153
	v_pk_add_f32 v[124:125], v[124:125], 1.0 op_sel_hi:[1,0]
	v_div_fixup_f32 v122, v146, v122, 1.0
	v_div_scale_f32 v146, s[8:9], v125, v125, 1.0
	v_rcp_f32_e32 v152, v146
	v_pk_fma_f32 v[118:119], v[118:119], v[122:123], v[150:151]
	v_lshlrev_b32_e32 v122, 16, v147
	v_and_b32_e32 v123, 0xffff0000, v147
	v_fma_f32 v147, -v146, v152, 1.0
	v_fmac_f32_e32 v152, v147, v152
	v_div_scale_f32 v147, vcc, 1.0, v125, 1.0
	v_mul_f32_e32 v150, v147, v152
	v_fma_f32 v151, -v146, v150, v147
	v_fmac_f32_e32 v150, v151, v152
	v_fma_f32 v146, -v146, v150, v147
	v_div_scale_f32 v147, s[8:9], v124, v124, 1.0
	v_rcp_f32_e32 v151, v147
	v_div_fmas_f32 v146, v146, v152, v150
	v_div_fixup_f32 v125, v146, v125, 1.0
	v_mul_f32_e32 v126, 0xbfb8aa3b, v126
	v_fma_f32 v146, -v147, v151, 1.0
	v_mul_f32_e32 v127, 0xbfb8aa3b, v127
	v_fmac_f32_e32 v151, v146, v151
	v_div_scale_f32 v146, vcc, 1.0, v124, 1.0
	v_exp_f32_e32 v126, v126
	v_exp_f32_e32 v127, v127
	v_mul_f32_e32 v150, v146, v151
	v_fma_f32 v152, -v147, v150, v146
	v_fmac_f32_e32 v150, v152, v151
	v_fma_f32 v146, -v147, v150, v146
	v_div_fmas_f32 v146, v146, v151, v150
	v_pk_add_f32 v[126:127], v[126:127], 1.0 op_sel_hi:[1,0]
	v_div_fixup_f32 v124, v146, v124, 1.0
	v_div_scale_f32 v146, s[8:9], v127, v127, 1.0
	v_rcp_f32_e32 v147, v146
	v_pk_fma_f32 v[120:121], v[120:121], v[124:125], v[122:123]
	v_lshlrev_b32_e32 v122, 16, v148
	v_and_b32_e32 v123, 0xffff0000, v148
	v_fma_f32 v124, -v146, v147, 1.0
	v_fmac_f32_e32 v147, v124, v147
	v_div_scale_f32 v124, vcc, 1.0, v127, 1.0
	v_mul_f32_e32 v125, v124, v147
	v_fma_f32 v148, -v146, v125, v124
	v_fmac_f32_e32 v125, v148, v147
	v_fma_f32 v124, -v146, v125, v124
	v_div_scale_f32 v146, s[8:9], v126, v126, 1.0
	v_rcp_f32_e32 v148, v146
	v_div_fmas_f32 v124, v124, v147, v125
	v_div_fixup_f32 v125, v124, v127, 1.0
	v_mul_f32_e32 v128, 0xbfb8aa3b, v128
	v_fma_f32 v124, -v146, v148, 1.0
	v_fmac_f32_e32 v148, v124, v148
	v_div_scale_f32 v124, vcc, 1.0, v126, 1.0
	v_mul_f32_e32 v129, 0xbfb8aa3b, v129
	v_mul_f32_e32 v127, v124, v148
	v_exp_f32_e32 v128, v128
	v_exp_f32_e32 v129, v129
	v_fma_f32 v147, -v146, v127, v124
	v_fmac_f32_e32 v127, v147, v148
	v_fma_f32 v124, -v146, v127, v124
	v_div_fmas_f32 v124, v124, v148, v127
	v_div_fixup_f32 v124, v124, v126, 1.0
	v_pk_add_f32 v[126:127], v[128:129], 1.0 op_sel_hi:[1,0]
	v_pk_fma_f32 v[122:123], v[114:115], v[124:125], v[122:123]
	v_div_scale_f32 v128, s[8:9], v127, v127, 1.0
	v_rcp_f32_e32 v129, v128
	v_lshlrev_b32_e32 v148, 16, v142
	v_and_b32_e32 v142, 0xffff0000, v142
	v_mul_f32_e32 v148, 0xbfb8aa3b, v148
	v_fma_f32 v124, -v128, v129, 1.0
	v_fmac_f32_e32 v129, v124, v129
	v_div_scale_f32 v124, vcc, 1.0, v127, 1.0
	v_mul_f32_e32 v125, v124, v129
	v_fma_f32 v146, -v128, v125, v124
	v_fmac_f32_e32 v125, v146, v129
	v_fma_f32 v124, -v128, v125, v124
	v_div_scale_f32 v128, s[8:9], v126, v126, 1.0
	v_rcp_f32_e32 v146, v128
	v_div_fmas_f32 v124, v124, v129, v125
	v_div_fixup_f32 v125, v124, v127, 1.0
	v_mul_f32_e32 v142, 0xbfb8aa3b, v142
	v_fma_f32 v124, -v128, v146, 1.0
	v_fmac_f32_e32 v146, v124, v146
	v_div_scale_f32 v124, vcc, 1.0, v126, 1.0
	v_mul_f32_e32 v127, v124, v146
	v_fma_f32 v129, -v128, v127, v124
	v_fmac_f32_e32 v127, v129, v146
	v_fma_f32 v124, -v128, v127, v124
	v_lshlrev_b32_e32 v114, 16, v149
	v_and_b32_e32 v115, 0xffff0000, v149
	v_div_fmas_f32 v124, v124, v146, v127
	v_exp_f32_e32 v148, v148
	v_exp_f32_e32 v149, v142
	v_div_fixup_f32 v124, v124, v126, 1.0
	v_pk_fma_f32 v[124:125], v[116:117], v[124:125], v[114:115]
	v_cvt_pk_bf16_f32 v114, v118, v119
	v_cvt_pk_bf16_f32 v115, v120, v121
	v_cvt_pk_bf16_f32 v116, v122, v123
	v_cvt_pk_bf16_f32 v117, v124, v125
	global_store_dwordx4 v[176:177], v[114:117], off offset:256 sc1
	v_pk_add_f32 v[148:149], v[148:149], 1.0 op_sel_hi:[1,0]
	v_lshlrev_b32_e32 v152, 16, v138
	v_or_b32_e32 v114, 32, v170
	v_ashrrev_i32_e32 v115, 31, v114
	v_div_scale_f32 v171, s[8:9], v149, v149, 1.0
	v_lshlrev_b64 v[116:117], 13, v[114:115]
	v_rcp_f32_e32 v176, v171
	v_lshl_add_u64 v[116:117], s[20:21], 0, v[116:117]
	v_lshlrev_b64 v[114:115], 12, v[114:115]
	v_lshl_add_u64 v[116:117], v[116:117], 0, v[172:173]
	v_lshl_add_u64 v[114:115], s[18:19], 0, v[114:115]
	v_lshl_add_u64 v[146:147], v[114:115], 0, v[172:173]
	v_add_co_u32_e32 v114, vcc, s80, v116
	v_and_b32_e32 v153, 0xffff0000, v138
	s_nop 0
	v_addc_co_u32_e32 v115, vcc, 0, v117, vcc
	v_fma_f32 v138, -v171, v176, 1.0
	v_fmac_f32_e32 v176, v138, v176
	v_div_scale_f32 v138, vcc, 1.0, v149, 1.0
	v_mul_f32_e32 v177, v138, v176
	v_fma_f32 v183, -v171, v177, v138
	v_fmac_f32_e32 v177, v183, v176
	v_fma_f32 v138, -v171, v177, v138
	v_div_scale_f32 v171, s[8:9], v148, v148, 1.0
	v_rcp_f32_e32 v183, v171
	v_lshlrev_b32_e32 v142, 16, v143
	v_and_b32_e32 v143, 0xffff0000, v143
	v_mul_f32_e32 v142, 0xbfb8aa3b, v142
	v_mul_f32_e32 v143, 0xbfb8aa3b, v143
	v_div_fmas_f32 v138, v138, v176, v177
	v_exp_f32_e32 v142, v142
	v_exp_f32_e32 v143, v143
	v_div_fixup_f32 v149, v138, v149, 1.0
	v_fma_f32 v138, -v171, v183, 1.0
	v_fmac_f32_e32 v183, v138, v183
	v_div_scale_f32 v138, vcc, 1.0, v148, 1.0
	v_mul_f32_e32 v176, v138, v183
	v_fma_f32 v177, -v171, v176, v138
	v_fmac_f32_e32 v176, v177, v183
	v_pk_add_f32 v[142:143], v[142:143], 1.0 op_sel_hi:[1,0]
	v_fma_f32 v138, -v171, v176, v138
	v_div_scale_f32 v171, s[8:9], v143, v143, 1.0
	v_div_fmas_f32 v138, v138, v183, v176
	v_rcp_f32_e32 v176, v171
	v_div_fixup_f32 v148, v138, v148, 1.0
	v_pk_fma_f32 v[110:111], v[110:111], v[148:149], v[152:153]
	v_lshlrev_b32_e32 v150, 16, v144
	v_fma_f32 v148, -v171, v176, 1.0
	v_fmac_f32_e32 v176, v148, v176
	v_div_scale_f32 v148, vcc, 1.0, v143, 1.0
	v_mul_f32_e32 v149, v148, v176
	v_fma_f32 v152, -v171, v149, v148
	v_fmac_f32_e32 v149, v152, v176
	v_div_scale_f32 v152, s[8:9], v142, v142, 1.0
	v_rcp_f32_e32 v153, v152
	v_fma_f32 v148, -v171, v149, v148
	v_div_fmas_f32 v148, v148, v176, v149
	v_div_fixup_f32 v143, v148, v143, 1.0
	v_fma_f32 v148, -v152, v153, 1.0
	v_and_b32_e32 v144, 0xffff0000, v144
	v_fmac_f32_e32 v153, v148, v153
	v_div_scale_f32 v148, vcc, 1.0, v142, 1.0
	v_mul_f32_e32 v150, 0xbfb8aa3b, v150
	v_mul_f32_e32 v144, 0xbfb8aa3b, v144
	v_mul_f32_e32 v149, v148, v153
	v_exp_f32_e32 v150, v150
	v_exp_f32_e32 v151, v144
	v_fma_f32 v171, -v152, v149, v148
	v_fmac_f32_e32 v149, v171, v153
	v_fma_f32 v148, -v152, v149, v148
	v_div_fmas_f32 v148, v148, v153, v149
	v_div_fixup_f32 v142, v148, v142, 1.0
	v_pk_add_f32 v[148:149], v[150:151], 1.0 op_sel_hi:[1,0]
	v_lshlrev_b32_e32 v138, 16, v139
	v_div_scale_f32 v150, s[8:9], v149, v149, 1.0
	v_rcp_f32_e32 v151, v150
	v_and_b32_e32 v139, 0xffff0000, v139
	v_pk_fma_f32 v[112:113], v[112:113], v[142:143], v[138:139]
	v_lshlrev_b32_e32 v138, 16, v140
	v_and_b32_e32 v139, 0xffff0000, v140
	v_fma_f32 v140, -v150, v151, 1.0
	v_fmac_f32_e32 v151, v140, v151
	v_div_scale_f32 v140, vcc, 1.0, v149, 1.0
	v_mul_f32_e32 v142, v140, v151
	v_fma_f32 v143, -v150, v142, v140
	v_fmac_f32_e32 v142, v143, v151
	v_fma_f32 v140, -v150, v142, v140
	v_div_scale_f32 v150, s[8:9], v148, v148, 1.0
	v_rcp_f32_e32 v152, v150
	v_div_fmas_f32 v140, v140, v151, v142
	v_lshlrev_b32_e32 v144, 16, v145
	v_and_b32_e32 v145, 0xffff0000, v145
	v_div_fixup_f32 v143, v140, v149, 1.0
	v_fma_f32 v140, -v150, v152, 1.0
	v_mul_f32_e32 v144, 0xbfb8aa3b, v144
	v_mul_f32_e32 v145, 0xbfb8aa3b, v145
	v_fmac_f32_e32 v152, v140, v152
	v_div_scale_f32 v140, vcc, 1.0, v148, 1.0
	v_exp_f32_e32 v144, v144
	v_exp_f32_e32 v145, v145
	v_mul_f32_e32 v142, v140, v152
	v_fma_f32 v149, -v150, v142, v140
	v_fmac_f32_e32 v142, v149, v152
	v_fma_f32 v140, -v150, v142, v140
	v_div_fmas_f32 v140, v140, v152, v142
	v_pk_add_f32 v[144:145], v[144:145], 1.0 op_sel_hi:[1,0]
	v_div_fixup_f32 v142, v140, v148, 1.0
	v_div_scale_f32 v140, s[8:9], v145, v145, 1.0
	v_rcp_f32_e32 v148, v140
	v_pk_fma_f32 v[138:139], v[106:107], v[142:143], v[138:139]
	v_lshlrev_b32_e32 v106, 16, v141
	v_and_b32_e32 v107, 0xffff0000, v141
	v_fma_f32 v141, -v140, v148, 1.0
	v_fmac_f32_e32 v148, v141, v148
	v_div_scale_f32 v141, vcc, 1.0, v145, 1.0
	v_mul_f32_e32 v142, v141, v148
	v_fma_f32 v143, -v140, v142, v141
	v_fmac_f32_e32 v142, v143, v148
	v_div_scale_f32 v143, s[8:9], v144, v144, 1.0
	v_rcp_f32_e32 v149, v143
	v_fma_f32 v140, -v140, v142, v141
	v_div_fmas_f32 v140, v140, v148, v142
	v_div_fixup_f32 v141, v140, v145, 1.0
	v_fma_f32 v140, -v143, v149, 1.0
	v_fmac_f32_e32 v149, v140, v149
	v_div_scale_f32 v140, vcc, 1.0, v144, 1.0
	v_mul_f32_e32 v142, v140, v149
	v_fma_f32 v145, -v143, v142, v140
	v_fmac_f32_e32 v142, v145, v149
	v_fma_f32 v140, -v143, v142, v140
	v_div_fmas_f32 v140, v140, v149, v142
	v_div_fixup_f32 v140, v140, v144, 1.0
	v_pk_fma_f32 v[140:141], v[108:109], v[140:141], v[106:107]
	v_lshl_add_u64 v[118:119], v[116:117], 0, s[24:25]
	v_cvt_pk_bf16_f32 v106, v110, v111
	v_cvt_pk_bf16_f32 v107, v112, v113
	v_cvt_pk_bf16_f32 v108, v138, v139
	v_cvt_pk_bf16_f32 v109, v140, v141
	global_load_dwordx4 v[122:125], v[146:147], off
	s_nop 0
	global_load_dwordx4 v[118:121], v[118:119], off offset:256
	s_nop 0
	global_load_dwordx4 v[126:129], v[114:115], off
	s_nop 0
	global_load_dwordx4 v[114:117], v[146:147], off offset:256
	v_lshlrev_b32_e32 v110, 16, v136
	global_store_dwordx4 v[174:175], v[106:109], off sc1
	v_and_b32_e32 v111, 0xffff0000, v136
	v_lshlrev_b32_e32 v112, 16, v137
	v_lshlrev_b32_e32 v106, 16, v134
	v_and_b32_e32 v107, 0xffff0000, v134
	v_mul_f32_e32 v106, 0xbfb8aa3b, v106
	v_mul_f32_e32 v107, 0xbfb8aa3b, v107
	v_exp_f32_e32 v106, v106
	v_exp_f32_e32 v107, v107
	v_and_b32_e32 v113, 0xffff0000, v137
	v_lshlrev_b32_e32 v108, 16, v135
	v_and_b32_e32 v109, 0xffff0000, v135
	v_pk_add_f32 v[106:107], v[106:107], 1.0 op_sel_hi:[1,0]
	v_lshlrev_b32_e32 v134, 16, v130
	v_div_scale_f32 v136, s[8:9], v107, v107, 1.0
	v_rcp_f32_e32 v137, v136
	v_and_b32_e32 v135, 0xffff0000, v130
	v_mul_f32_e32 v108, 0xbfb8aa3b, v108
	v_mul_f32_e32 v109, 0xbfb8aa3b, v109
	v_fma_f32 v130, -v136, v137, 1.0
	v_fmac_f32_e32 v137, v130, v137
	v_div_scale_f32 v130, vcc, 1.0, v107, 1.0
	v_mul_f32_e32 v138, v130, v137
	v_fma_f32 v139, -v136, v138, v130
	v_fmac_f32_e32 v138, v139, v137
	v_fma_f32 v130, -v136, v138, v130
	v_div_scale_f32 v136, s[8:9], v106, v106, 1.0
	v_rcp_f32_e32 v139, v136
	v_div_fmas_f32 v130, v130, v137, v138
	v_div_fixup_f32 v107, v130, v107, 1.0
	v_exp_f32_e32 v108, v108
	v_fma_f32 v130, -v136, v139, 1.0
	v_fmac_f32_e32 v139, v130, v139
	v_div_scale_f32 v130, vcc, 1.0, v106, 1.0
	v_exp_f32_e32 v109, v109
	v_mul_f32_e32 v137, v130, v139
	v_fma_f32 v138, -v136, v137, v130
	v_fmac_f32_e32 v137, v138, v139
	v_fma_f32 v130, -v136, v137, v130
	v_div_fmas_f32 v130, v130, v139, v137
	v_pk_add_f32 v[108:109], v[108:109], 1.0 op_sel_hi:[1,0]
	v_div_fixup_f32 v106, v130, v106, 1.0
	v_div_scale_f32 v130, s[8:9], v109, v109, 1.0
	v_rcp_f32_e32 v136, v130
	v_pk_fma_f32 v[102:103], v[102:103], v[106:107], v[134:135]
	v_lshlrev_b32_e32 v106, 16, v131
	v_and_b32_e32 v107, 0xffff0000, v131
	v_fma_f32 v131, -v130, v136, 1.0
	v_fmac_f32_e32 v136, v131, v136
	v_div_scale_f32 v131, vcc, 1.0, v109, 1.0
	v_mul_f32_e32 v134, v131, v136
	v_fma_f32 v135, -v130, v134, v131
	v_fmac_f32_e32 v134, v135, v136
	v_fma_f32 v130, -v130, v134, v131
	v_div_scale_f32 v131, s[8:9], v108, v108, 1.0
	v_rcp_f32_e32 v135, v131
	v_div_fmas_f32 v130, v130, v136, v134
	v_div_fixup_f32 v109, v130, v109, 1.0
	v_mul_f32_e32 v110, 0xbfb8aa3b, v110
	v_fma_f32 v130, -v131, v135, 1.0
	v_mul_f32_e32 v111, 0xbfb8aa3b, v111
	v_fmac_f32_e32 v135, v130, v135
	v_div_scale_f32 v130, vcc, 1.0, v108, 1.0
	v_exp_f32_e32 v110, v110
	v_exp_f32_e32 v111, v111
	v_mul_f32_e32 v134, v130, v135
	v_fma_f32 v136, -v131, v134, v130
	v_fmac_f32_e32 v134, v136, v135
	v_fma_f32 v130, -v131, v134, v130
	v_div_fmas_f32 v130, v130, v135, v134
	v_pk_add_f32 v[110:111], v[110:111], 1.0 op_sel_hi:[1,0]
	v_div_fixup_f32 v108, v130, v108, 1.0
	v_div_scale_f32 v130, s[8:9], v111, v111, 1.0
	v_rcp_f32_e32 v131, v130
	v_pk_fma_f32 v[104:105], v[104:105], v[108:109], v[106:107]
	v_lshlrev_b32_e32 v106, 16, v132
	v_and_b32_e32 v107, 0xffff0000, v132
	v_fma_f32 v108, -v130, v131, 1.0
	v_fmac_f32_e32 v131, v108, v131
	v_div_scale_f32 v108, vcc, 1.0, v111, 1.0
	v_mul_f32_e32 v109, v108, v131
	v_fma_f32 v132, -v130, v109, v108
	v_fmac_f32_e32 v109, v132, v131
	v_fma_f32 v108, -v130, v109, v108
	v_div_scale_f32 v130, s[8:9], v110, v110, 1.0
	v_rcp_f32_e32 v132, v130
	v_div_fmas_f32 v108, v108, v131, v109
	v_div_fixup_f32 v109, v108, v111, 1.0
	v_mul_f32_e32 v112, 0xbfb8aa3b, v112
	v_fma_f32 v108, -v130, v132, 1.0
	v_fmac_f32_e32 v132, v108, v132
	v_div_scale_f32 v108, vcc, 1.0, v110, 1.0
	v_mul_f32_e32 v113, 0xbfb8aa3b, v113
	v_mul_f32_e32 v111, v108, v132
	v_exp_f32_e32 v112, v112
	v_exp_f32_e32 v113, v113
	v_fma_f32 v131, -v130, v111, v108
	v_fmac_f32_e32 v111, v131, v132
	v_fma_f32 v108, -v130, v111, v108
	v_div_fmas_f32 v108, v108, v132, v111
	v_div_fixup_f32 v108, v108, v110, 1.0
	v_pk_add_f32 v[110:111], v[112:113], 1.0 op_sel_hi:[1,0]
	v_pk_fma_f32 v[106:107], v[98:99], v[108:109], v[106:107]
	v_div_scale_f32 v112, s[8:9], v111, v111, 1.0
	v_rcp_f32_e32 v113, v112
	s_waitcnt vmcnt(2)
	v_lshlrev_b32_e32 v132, 16, v126
	v_and_b32_e32 v126, 0xffff0000, v126
	v_mul_f32_e32 v132, 0xbfb8aa3b, v132
	v_fma_f32 v108, -v112, v113, 1.0
	v_fmac_f32_e32 v113, v108, v113
	v_div_scale_f32 v108, vcc, 1.0, v111, 1.0
	v_mul_f32_e32 v109, v108, v113
	v_fma_f32 v130, -v112, v109, v108
	v_fmac_f32_e32 v109, v130, v113
	v_fma_f32 v108, -v112, v109, v108
	v_div_scale_f32 v112, s[8:9], v110, v110, 1.0
	v_rcp_f32_e32 v130, v112
	v_div_fmas_f32 v108, v108, v113, v109
	v_div_fixup_f32 v109, v108, v111, 1.0
	v_mul_f32_e32 v126, 0xbfb8aa3b, v126
	v_fma_f32 v108, -v112, v130, 1.0
	v_fmac_f32_e32 v130, v108, v130
	v_div_scale_f32 v108, vcc, 1.0, v110, 1.0
	v_mul_f32_e32 v111, v108, v130
	v_fma_f32 v113, -v112, v111, v108
	v_fmac_f32_e32 v111, v113, v130
	v_fma_f32 v108, -v112, v111, v108
	v_lshlrev_b32_e32 v98, 16, v133
	v_and_b32_e32 v99, 0xffff0000, v133
	v_div_fmas_f32 v108, v108, v130, v111
	v_exp_f32_e32 v132, v132
	v_exp_f32_e32 v133, v126
	v_div_fixup_f32 v108, v108, v110, 1.0
	v_pk_fma_f32 v[108:109], v[100:101], v[108:109], v[98:99]
	v_cvt_pk_bf16_f32 v98, v102, v103
	v_cvt_pk_bf16_f32 v99, v104, v105
	v_cvt_pk_bf16_f32 v100, v106, v107
	v_cvt_pk_bf16_f32 v101, v108, v109
	global_store_dwordx4 v[174:175], v[98:101], off offset:256 sc1
	v_pk_add_f32 v[132:133], v[132:133], 1.0 op_sel_hi:[1,0]
	v_lshlrev_b32_e32 v136, 16, v122
	v_or_b32_e32 v98, 48, v170
	v_ashrrev_i32_e32 v99, 31, v98
	v_div_scale_f32 v138, s[8:9], v133, v133, 1.0
	v_lshlrev_b64 v[100:101], 13, v[98:99]
	v_rcp_f32_e32 v139, v138
	v_lshl_add_u64 v[100:101], s[20:21], 0, v[100:101]
	v_lshlrev_b64 v[98:99], 12, v[98:99]
	v_lshl_add_u64 v[100:101], v[100:101], 0, v[172:173]
	v_lshl_add_u64 v[98:99], s[18:19], 0, v[98:99]
	v_lshl_add_u64 v[130:131], v[98:99], 0, v[172:173]
	v_add_co_u32_e32 v98, vcc, s80, v100
	v_and_b32_e32 v137, 0xffff0000, v122
	s_nop 0
	v_addc_co_u32_e32 v99, vcc, 0, v101, vcc
	v_fma_f32 v122, -v138, v139, 1.0
	v_fmac_f32_e32 v139, v122, v139
	v_div_scale_f32 v122, vcc, 1.0, v133, 1.0
	v_mul_f32_e32 v140, v122, v139
	v_fma_f32 v141, -v138, v140, v122
	v_fmac_f32_e32 v140, v141, v139
	v_fma_f32 v122, -v138, v140, v122
	v_div_scale_f32 v138, s[8:9], v132, v132, 1.0
	v_rcp_f32_e32 v141, v138
	v_lshlrev_b32_e32 v126, 16, v127
	v_and_b32_e32 v127, 0xffff0000, v127
	v_mul_f32_e32 v126, 0xbfb8aa3b, v126
	v_mul_f32_e32 v127, 0xbfb8aa3b, v127
	v_div_fmas_f32 v122, v122, v139, v140
	v_exp_f32_e32 v126, v126
	v_exp_f32_e32 v127, v127
	v_div_fixup_f32 v133, v122, v133, 1.0
	v_fma_f32 v122, -v138, v141, 1.0
	v_fmac_f32_e32 v141, v122, v141
	v_div_scale_f32 v122, vcc, 1.0, v132, 1.0
	v_mul_f32_e32 v139, v122, v141
	v_fma_f32 v140, -v138, v139, v122
	v_fmac_f32_e32 v139, v140, v141
	v_pk_add_f32 v[126:127], v[126:127], 1.0 op_sel_hi:[1,0]
	v_fma_f32 v122, -v138, v139, v122
	v_div_scale_f32 v138, s[8:9], v127, v127, 1.0
	v_div_fmas_f32 v122, v122, v141, v139
	v_rcp_f32_e32 v139, v138
	v_div_fixup_f32 v132, v122, v132, 1.0
	v_pk_fma_f32 v[94:95], v[94:95], v[132:133], v[136:137]
	v_lshlrev_b32_e32 v134, 16, v128
	v_fma_f32 v132, -v138, v139, 1.0
	v_fmac_f32_e32 v139, v132, v139
	v_div_scale_f32 v132, vcc, 1.0, v127, 1.0
	v_mul_f32_e32 v133, v132, v139
	v_fma_f32 v136, -v138, v133, v132
	v_fmac_f32_e32 v133, v136, v139
	v_div_scale_f32 v136, s[8:9], v126, v126, 1.0
	v_rcp_f32_e32 v137, v136
	v_fma_f32 v132, -v138, v133, v132
	v_div_fmas_f32 v132, v132, v139, v133
	v_div_fixup_f32 v127, v132, v127, 1.0
	v_fma_f32 v132, -v136, v137, 1.0
	v_and_b32_e32 v128, 0xffff0000, v128
	v_fmac_f32_e32 v137, v132, v137
	v_div_scale_f32 v132, vcc, 1.0, v126, 1.0
	v_mul_f32_e32 v134, 0xbfb8aa3b, v134
	v_mul_f32_e32 v128, 0xbfb8aa3b, v128
	v_mul_f32_e32 v133, v132, v137
	v_exp_f32_e32 v134, v134
	v_exp_f32_e32 v135, v128
	v_fma_f32 v138, -v136, v133, v132
	v_fmac_f32_e32 v133, v138, v137
	v_fma_f32 v132, -v136, v133, v132
	v_div_fmas_f32 v132, v132, v137, v133
	v_div_fixup_f32 v126, v132, v126, 1.0
	v_pk_add_f32 v[132:133], v[134:135], 1.0 op_sel_hi:[1,0]
	v_lshlrev_b32_e32 v122, 16, v123
	v_div_scale_f32 v134, s[8:9], v133, v133, 1.0
	v_rcp_f32_e32 v135, v134
	v_and_b32_e32 v123, 0xffff0000, v123
	v_pk_fma_f32 v[96:97], v[96:97], v[126:127], v[122:123]
	v_lshlrev_b32_e32 v122, 16, v124
	v_and_b32_e32 v123, 0xffff0000, v124
	v_fma_f32 v124, -v134, v135, 1.0
	v_fmac_f32_e32 v135, v124, v135
	v_div_scale_f32 v124, vcc, 1.0, v133, 1.0
	v_mul_f32_e32 v126, v124, v135
	v_fma_f32 v127, -v134, v126, v124
	v_fmac_f32_e32 v126, v127, v135
	v_fma_f32 v124, -v134, v126, v124
	v_div_scale_f32 v134, s[8:9], v132, v132, 1.0
	v_rcp_f32_e32 v136, v134
	v_div_fmas_f32 v124, v124, v135, v126
	v_lshlrev_b32_e32 v128, 16, v129
	v_and_b32_e32 v129, 0xffff0000, v129
	v_div_fixup_f32 v127, v124, v133, 1.0
	v_fma_f32 v124, -v134, v136, 1.0
	v_mul_f32_e32 v128, 0xbfb8aa3b, v128
	v_mul_f32_e32 v129, 0xbfb8aa3b, v129
	v_fmac_f32_e32 v136, v124, v136
	v_div_scale_f32 v124, vcc, 1.0, v132, 1.0
	v_exp_f32_e32 v128, v128
	v_exp_f32_e32 v129, v129
	v_mul_f32_e32 v126, v124, v136
	v_fma_f32 v133, -v134, v126, v124
	v_fmac_f32_e32 v126, v133, v136
	v_fma_f32 v124, -v134, v126, v124
	v_div_fmas_f32 v124, v124, v136, v126
	v_pk_add_f32 v[128:129], v[128:129], 1.0 op_sel_hi:[1,0]
	v_div_fixup_f32 v126, v124, v132, 1.0
	v_div_scale_f32 v124, s[8:9], v129, v129, 1.0
	v_rcp_f32_e32 v132, v124
	v_pk_fma_f32 v[122:123], v[90:91], v[126:127], v[122:123]
	v_lshlrev_b32_e32 v90, 16, v125
	v_and_b32_e32 v91, 0xffff0000, v125
	v_fma_f32 v125, -v124, v132, 1.0
	v_fmac_f32_e32 v132, v125, v132
	v_div_scale_f32 v125, vcc, 1.0, v129, 1.0
	v_mul_f32_e32 v126, v125, v132
	v_fma_f32 v127, -v124, v126, v125
	v_fmac_f32_e32 v126, v127, v132
	v_div_scale_f32 v127, s[8:9], v128, v128, 1.0
	v_rcp_f32_e32 v133, v127
	v_fma_f32 v124, -v124, v126, v125
	v_div_fmas_f32 v124, v124, v132, v126
	v_div_fixup_f32 v125, v124, v129, 1.0
	v_fma_f32 v124, -v127, v133, 1.0
	v_fmac_f32_e32 v133, v124, v133
	v_div_scale_f32 v124, vcc, 1.0, v128, 1.0
	v_mul_f32_e32 v126, v124, v133
	v_fma_f32 v129, -v127, v126, v124
	v_fmac_f32_e32 v126, v129, v133
	v_fma_f32 v124, -v127, v126, v124
	v_div_fmas_f32 v124, v124, v133, v126
	v_div_fixup_f32 v124, v124, v128, 1.0
	v_pk_fma_f32 v[124:125], v[92:93], v[124:125], v[90:91]
	v_lshl_add_u64 v[102:103], v[100:101], 0, s[24:25]
	v_cvt_pk_bf16_f32 v90, v94, v95
	v_cvt_pk_bf16_f32 v91, v96, v97
	v_cvt_pk_bf16_f32 v92, v122, v123
	v_cvt_pk_bf16_f32 v93, v124, v125
	global_load_dwordx4 v[106:109], v[130:131], off
	s_nop 0
	global_load_dwordx4 v[102:105], v[102:103], off offset:256
	s_nop 0
	global_load_dwordx4 v[110:113], v[98:99], off
	s_nop 0
	global_load_dwordx4 v[98:101], v[130:131], off offset:256
	v_lshlrev_b32_e32 v94, 16, v120
	global_store_dwordx4 v[146:147], v[90:93], off sc1
	v_and_b32_e32 v95, 0xffff0000, v120
	v_lshlrev_b32_e32 v96, 16, v121
	v_lshlrev_b32_e32 v90, 16, v118
	v_and_b32_e32 v91, 0xffff0000, v118
	v_mul_f32_e32 v90, 0xbfb8aa3b, v90
	v_mul_f32_e32 v91, 0xbfb8aa3b, v91
	v_exp_f32_e32 v90, v90
	v_exp_f32_e32 v91, v91
	v_and_b32_e32 v97, 0xffff0000, v121
	v_lshlrev_b32_e32 v92, 16, v119
	v_and_b32_e32 v93, 0xffff0000, v119
	v_pk_add_f32 v[90:91], v[90:91], 1.0 op_sel_hi:[1,0]
	s_waitcnt vmcnt(7)
	v_lshlrev_b32_e32 v118, 16, v114
	v_div_scale_f32 v120, s[8:9], v91, v91, 1.0
	v_rcp_f32_e32 v121, v120
	v_and_b32_e32 v119, 0xffff0000, v114
	v_mul_f32_e32 v92, 0xbfb8aa3b, v92
	v_mul_f32_e32 v93, 0xbfb8aa3b, v93
	v_fma_f32 v114, -v120, v121, 1.0
	v_fmac_f32_e32 v121, v114, v121
	v_div_scale_f32 v114, vcc, 1.0, v91, 1.0
	v_mul_f32_e32 v122, v114, v121
	v_fma_f32 v123, -v120, v122, v114
	v_fmac_f32_e32 v122, v123, v121
	v_fma_f32 v114, -v120, v122, v114
	v_div_scale_f32 v120, s[8:9], v90, v90, 1.0
	v_rcp_f32_e32 v123, v120
	v_div_fmas_f32 v114, v114, v121, v122
	v_div_fixup_f32 v91, v114, v91, 1.0
	v_exp_f32_e32 v92, v92
	v_fma_f32 v114, -v120, v123, 1.0
	v_fmac_f32_e32 v123, v114, v123
	v_div_scale_f32 v114, vcc, 1.0, v90, 1.0
	v_exp_f32_e32 v93, v93
	v_mul_f32_e32 v121, v114, v123
	v_fma_f32 v122, -v120, v121, v114
	v_fmac_f32_e32 v121, v122, v123
	v_fma_f32 v114, -v120, v121, v114
	v_div_fmas_f32 v114, v114, v123, v121
	v_pk_add_f32 v[92:93], v[92:93], 1.0 op_sel_hi:[1,0]
	v_div_fixup_f32 v90, v114, v90, 1.0
	v_div_scale_f32 v114, s[8:9], v93, v93, 1.0
	v_rcp_f32_e32 v120, v114
	v_pk_fma_f32 v[86:87], v[86:87], v[90:91], v[118:119]
	v_lshlrev_b32_e32 v90, 16, v115
	v_and_b32_e32 v91, 0xffff0000, v115
	v_fma_f32 v115, -v114, v120, 1.0
	v_fmac_f32_e32 v120, v115, v120
	v_div_scale_f32 v115, vcc, 1.0, v93, 1.0
	v_mul_f32_e32 v118, v115, v120
	v_fma_f32 v119, -v114, v118, v115
	v_fmac_f32_e32 v118, v119, v120
	v_fma_f32 v114, -v114, v118, v115
	v_div_scale_f32 v115, s[8:9], v92, v92, 1.0
	v_rcp_f32_e32 v119, v115
	v_div_fmas_f32 v114, v114, v120, v118
	v_div_fixup_f32 v93, v114, v93, 1.0
	v_mul_f32_e32 v94, 0xbfb8aa3b, v94
	v_fma_f32 v114, -v115, v119, 1.0
	v_mul_f32_e32 v95, 0xbfb8aa3b, v95
	v_fmac_f32_e32 v119, v114, v119
	v_div_scale_f32 v114, vcc, 1.0, v92, 1.0
	v_exp_f32_e32 v94, v94
	v_exp_f32_e32 v95, v95
	v_mul_f32_e32 v118, v114, v119
	v_fma_f32 v120, -v115, v118, v114
	v_fmac_f32_e32 v118, v120, v119
	v_fma_f32 v114, -v115, v118, v114
	v_div_fmas_f32 v114, v114, v119, v118
	v_pk_add_f32 v[94:95], v[94:95], 1.0 op_sel_hi:[1,0]
	v_div_fixup_f32 v92, v114, v92, 1.0
	v_div_scale_f32 v114, s[8:9], v95, v95, 1.0
	v_rcp_f32_e32 v115, v114
	v_pk_fma_f32 v[88:89], v[88:89], v[92:93], v[90:91]
	v_lshlrev_b32_e32 v90, 16, v116
	v_and_b32_e32 v91, 0xffff0000, v116
	v_fma_f32 v92, -v114, v115, 1.0
	v_fmac_f32_e32 v115, v92, v115
	v_div_scale_f32 v92, vcc, 1.0, v95, 1.0
	v_mul_f32_e32 v93, v92, v115
	v_fma_f32 v116, -v114, v93, v92
	v_fmac_f32_e32 v93, v116, v115
	v_fma_f32 v92, -v114, v93, v92
	v_div_scale_f32 v114, s[8:9], v94, v94, 1.0
	v_rcp_f32_e32 v116, v114
	v_div_fmas_f32 v92, v92, v115, v93
	v_div_fixup_f32 v93, v92, v95, 1.0
	v_mul_f32_e32 v96, 0xbfb8aa3b, v96
	v_fma_f32 v92, -v114, v116, 1.0
	v_fmac_f32_e32 v116, v92, v116
	v_div_scale_f32 v92, vcc, 1.0, v94, 1.0
	v_mul_f32_e32 v97, 0xbfb8aa3b, v97
	v_mul_f32_e32 v95, v92, v116
	v_exp_f32_e32 v96, v96
	v_exp_f32_e32 v97, v97
	v_fma_f32 v115, -v114, v95, v92
	v_fmac_f32_e32 v95, v115, v116
	v_fma_f32 v92, -v114, v95, v92
	v_div_fmas_f32 v92, v92, v116, v95
	v_div_fixup_f32 v92, v92, v94, 1.0
	v_pk_add_f32 v[94:95], v[96:97], 1.0 op_sel_hi:[1,0]
	v_pk_fma_f32 v[90:91], v[82:83], v[92:93], v[90:91]
	v_div_scale_f32 v96, s[8:9], v95, v95, 1.0
	v_rcp_f32_e32 v97, v96
	s_waitcnt vmcnt(2)
	v_lshlrev_b32_e32 v116, 16, v110
	v_and_b32_e32 v110, 0xffff0000, v110
	v_mul_f32_e32 v116, 0xbfb8aa3b, v116
	v_fma_f32 v92, -v96, v97, 1.0
	v_fmac_f32_e32 v97, v92, v97
	v_div_scale_f32 v92, vcc, 1.0, v95, 1.0
	v_mul_f32_e32 v93, v92, v97
	v_fma_f32 v114, -v96, v93, v92
	v_fmac_f32_e32 v93, v114, v97
	v_fma_f32 v92, -v96, v93, v92
	v_div_scale_f32 v96, s[8:9], v94, v94, 1.0
	v_rcp_f32_e32 v114, v96
	v_div_fmas_f32 v92, v92, v97, v93
	v_div_fixup_f32 v93, v92, v95, 1.0
	v_mul_f32_e32 v110, 0xbfb8aa3b, v110
	v_fma_f32 v92, -v96, v114, 1.0
	v_fmac_f32_e32 v114, v92, v114
	v_div_scale_f32 v92, vcc, 1.0, v94, 1.0
	v_mul_f32_e32 v95, v92, v114
	v_fma_f32 v97, -v96, v95, v92
	v_fmac_f32_e32 v95, v97, v114
	v_fma_f32 v92, -v96, v95, v92
	v_lshlrev_b32_e32 v82, 16, v117
	v_and_b32_e32 v83, 0xffff0000, v117
	v_div_fmas_f32 v92, v92, v114, v95
	v_exp_f32_e32 v116, v116
	v_exp_f32_e32 v117, v110
	v_div_fixup_f32 v92, v92, v94, 1.0
	v_pk_fma_f32 v[92:93], v[84:85], v[92:93], v[82:83]
	v_cvt_pk_bf16_f32 v82, v86, v87
	v_cvt_pk_bf16_f32 v83, v88, v89
	v_cvt_pk_bf16_f32 v84, v90, v91
	v_cvt_pk_bf16_f32 v85, v92, v93
	global_store_dwordx4 v[146:147], v[82:85], off offset:256 sc1
	v_pk_add_f32 v[116:117], v[116:117], 1.0 op_sel_hi:[1,0]
	v_lshlrev_b32_e32 v120, 16, v106
	v_add_u32_e32 v82, 0x80, v170
	v_ashrrev_i32_e32 v83, 31, v82
	v_div_scale_f32 v122, s[8:9], v117, v117, 1.0
	v_lshlrev_b64 v[84:85], 13, v[82:83]
	v_rcp_f32_e32 v123, v122
	v_lshl_add_u64 v[84:85], s[20:21], 0, v[84:85]
	v_lshlrev_b64 v[82:83], 12, v[82:83]
	v_lshl_add_u64 v[84:85], v[84:85], 0, v[172:173]
	v_lshl_add_u64 v[82:83], s[18:19], 0, v[82:83]
	v_lshl_add_u64 v[114:115], v[82:83], 0, v[172:173]
	v_add_co_u32_e32 v82, vcc, s80, v84
	v_and_b32_e32 v121, 0xffff0000, v106
	s_nop 0
	v_addc_co_u32_e32 v83, vcc, 0, v85, vcc
	v_fma_f32 v106, -v122, v123, 1.0
	v_fmac_f32_e32 v123, v106, v123
	v_div_scale_f32 v106, vcc, 1.0, v117, 1.0
	v_mul_f32_e32 v124, v106, v123
	v_fma_f32 v125, -v122, v124, v106
	v_fmac_f32_e32 v124, v125, v123
	v_fma_f32 v106, -v122, v124, v106
	v_div_scale_f32 v122, s[8:9], v116, v116, 1.0
	v_rcp_f32_e32 v125, v122
	v_lshlrev_b32_e32 v110, 16, v111
	v_and_b32_e32 v111, 0xffff0000, v111
	v_mul_f32_e32 v110, 0xbfb8aa3b, v110
	v_mul_f32_e32 v111, 0xbfb8aa3b, v111
	v_div_fmas_f32 v106, v106, v123, v124
	v_exp_f32_e32 v110, v110
	v_exp_f32_e32 v111, v111
	v_div_fixup_f32 v117, v106, v117, 1.0
	v_fma_f32 v106, -v122, v125, 1.0
	v_fmac_f32_e32 v125, v106, v125
	v_div_scale_f32 v106, vcc, 1.0, v116, 1.0
	v_mul_f32_e32 v123, v106, v125
	v_fma_f32 v124, -v122, v123, v106
	v_fmac_f32_e32 v123, v124, v125
	v_pk_add_f32 v[110:111], v[110:111], 1.0 op_sel_hi:[1,0]
	v_fma_f32 v106, -v122, v123, v106
	v_div_scale_f32 v122, s[8:9], v111, v111, 1.0
	v_div_fmas_f32 v106, v106, v125, v123
	v_rcp_f32_e32 v123, v122
	v_div_fixup_f32 v116, v106, v116, 1.0
	v_pk_fma_f32 v[78:79], v[78:79], v[116:117], v[120:121]
	v_lshlrev_b32_e32 v118, 16, v112
	v_fma_f32 v116, -v122, v123, 1.0
	v_fmac_f32_e32 v123, v116, v123
	v_div_scale_f32 v116, vcc, 1.0, v111, 1.0
	v_mul_f32_e32 v117, v116, v123
	v_fma_f32 v120, -v122, v117, v116
	v_fmac_f32_e32 v117, v120, v123
	v_div_scale_f32 v120, s[8:9], v110, v110, 1.0
	v_rcp_f32_e32 v121, v120
	v_fma_f32 v116, -v122, v117, v116
	v_div_fmas_f32 v116, v116, v123, v117
	v_div_fixup_f32 v111, v116, v111, 1.0
	v_fma_f32 v116, -v120, v121, 1.0
	v_and_b32_e32 v112, 0xffff0000, v112
	v_fmac_f32_e32 v121, v116, v121
	v_div_scale_f32 v116, vcc, 1.0, v110, 1.0
	v_mul_f32_e32 v118, 0xbfb8aa3b, v118
	v_mul_f32_e32 v112, 0xbfb8aa3b, v112
	v_mul_f32_e32 v117, v116, v121
	v_exp_f32_e32 v118, v118
	v_exp_f32_e32 v119, v112
	v_fma_f32 v122, -v120, v117, v116
	v_fmac_f32_e32 v117, v122, v121
	v_fma_f32 v116, -v120, v117, v116
	v_div_fmas_f32 v116, v116, v121, v117
	v_div_fixup_f32 v110, v116, v110, 1.0
	v_pk_add_f32 v[116:117], v[118:119], 1.0 op_sel_hi:[1,0]
	v_lshlrev_b32_e32 v106, 16, v107
	v_div_scale_f32 v118, s[8:9], v117, v117, 1.0
	v_rcp_f32_e32 v119, v118
	v_and_b32_e32 v107, 0xffff0000, v107
	v_pk_fma_f32 v[80:81], v[80:81], v[110:111], v[106:107]
	v_lshlrev_b32_e32 v106, 16, v108
	v_and_b32_e32 v107, 0xffff0000, v108
	v_fma_f32 v108, -v118, v119, 1.0
	v_fmac_f32_e32 v119, v108, v119
	v_div_scale_f32 v108, vcc, 1.0, v117, 1.0
	v_mul_f32_e32 v110, v108, v119
	v_fma_f32 v111, -v118, v110, v108
	v_fmac_f32_e32 v110, v111, v119
	v_fma_f32 v108, -v118, v110, v108
	v_div_scale_f32 v118, s[8:9], v116, v116, 1.0
	v_rcp_f32_e32 v120, v118
	v_div_fmas_f32 v108, v108, v119, v110
	v_lshlrev_b32_e32 v112, 16, v113
	v_and_b32_e32 v113, 0xffff0000, v113
	v_div_fixup_f32 v111, v108, v117, 1.0
	v_fma_f32 v108, -v118, v120, 1.0
	v_mul_f32_e32 v112, 0xbfb8aa3b, v112
	v_mul_f32_e32 v113, 0xbfb8aa3b, v113
	v_fmac_f32_e32 v120, v108, v120
	v_div_scale_f32 v108, vcc, 1.0, v116, 1.0
	v_exp_f32_e32 v112, v112
	v_exp_f32_e32 v113, v113
	v_mul_f32_e32 v110, v108, v120
	v_fma_f32 v117, -v118, v110, v108
	v_fmac_f32_e32 v110, v117, v120
	v_fma_f32 v108, -v118, v110, v108
	v_div_fmas_f32 v108, v108, v120, v110
	v_pk_add_f32 v[112:113], v[112:113], 1.0 op_sel_hi:[1,0]
	v_div_fixup_f32 v110, v108, v116, 1.0
	v_div_scale_f32 v108, s[8:9], v113, v113, 1.0
	v_rcp_f32_e32 v116, v108
	v_pk_fma_f32 v[106:107], v[74:75], v[110:111], v[106:107]
	v_lshlrev_b32_e32 v74, 16, v109
	v_and_b32_e32 v75, 0xffff0000, v109
	v_fma_f32 v109, -v108, v116, 1.0
	v_fmac_f32_e32 v116, v109, v116
	v_div_scale_f32 v109, vcc, 1.0, v113, 1.0
	v_mul_f32_e32 v110, v109, v116
	v_fma_f32 v111, -v108, v110, v109
	v_fmac_f32_e32 v110, v111, v116
	v_div_scale_f32 v111, s[8:9], v112, v112, 1.0
	v_rcp_f32_e32 v117, v111
	v_fma_f32 v108, -v108, v110, v109
	v_div_fmas_f32 v108, v108, v116, v110
	v_div_fixup_f32 v109, v108, v113, 1.0
	v_fma_f32 v108, -v111, v117, 1.0
	v_fmac_f32_e32 v117, v108, v117
	v_div_scale_f32 v108, vcc, 1.0, v112, 1.0
	v_mul_f32_e32 v110, v108, v117
	v_fma_f32 v113, -v111, v110, v108
	v_fmac_f32_e32 v110, v113, v117
	v_fma_f32 v108, -v111, v110, v108
	v_div_fmas_f32 v108, v108, v117, v110
	v_div_fixup_f32 v108, v108, v112, 1.0
	v_pk_fma_f32 v[108:109], v[76:77], v[108:109], v[74:75]
	v_lshl_add_u64 v[86:87], v[84:85], 0, s[24:25]
	v_cvt_pk_bf16_f32 v74, v78, v79
	v_cvt_pk_bf16_f32 v75, v80, v81
	v_cvt_pk_bf16_f32 v76, v106, v107
	v_cvt_pk_bf16_f32 v77, v108, v109
	global_load_dwordx4 v[90:93], v[114:115], off
	s_nop 0
	global_load_dwordx4 v[86:89], v[86:87], off offset:256
	s_nop 0
	global_load_dwordx4 v[94:97], v[82:83], off
	s_nop 0
	global_load_dwordx4 v[82:85], v[114:115], off offset:256
	v_lshlrev_b32_e32 v78, 16, v104
	global_store_dwordx4 v[130:131], v[74:77], off sc1
	v_and_b32_e32 v79, 0xffff0000, v104
	v_lshlrev_b32_e32 v80, 16, v105
	v_lshlrev_b32_e32 v74, 16, v102
	v_and_b32_e32 v75, 0xffff0000, v102
	v_mul_f32_e32 v74, 0xbfb8aa3b, v74
	v_mul_f32_e32 v75, 0xbfb8aa3b, v75
	v_exp_f32_e32 v74, v74
	v_exp_f32_e32 v75, v75
	v_and_b32_e32 v81, 0xffff0000, v105
	v_lshlrev_b32_e32 v76, 16, v103
	v_and_b32_e32 v77, 0xffff0000, v103
	v_pk_add_f32 v[74:75], v[74:75], 1.0 op_sel_hi:[1,0]
	s_waitcnt vmcnt(7)
	v_lshlrev_b32_e32 v102, 16, v98
	v_div_scale_f32 v104, s[8:9], v75, v75, 1.0
	v_rcp_f32_e32 v105, v104
	v_and_b32_e32 v103, 0xffff0000, v98
	v_mul_f32_e32 v76, 0xbfb8aa3b, v76
	v_mul_f32_e32 v77, 0xbfb8aa3b, v77
	v_fma_f32 v98, -v104, v105, 1.0
	v_fmac_f32_e32 v105, v98, v105
	v_div_scale_f32 v98, vcc, 1.0, v75, 1.0
	v_mul_f32_e32 v106, v98, v105
	v_fma_f32 v107, -v104, v106, v98
	v_fmac_f32_e32 v106, v107, v105
	v_fma_f32 v98, -v104, v106, v98
	v_div_scale_f32 v104, s[8:9], v74, v74, 1.0
	v_rcp_f32_e32 v107, v104
	v_div_fmas_f32 v98, v98, v105, v106
	v_div_fixup_f32 v75, v98, v75, 1.0
	v_exp_f32_e32 v76, v76
	v_fma_f32 v98, -v104, v107, 1.0
	v_fmac_f32_e32 v107, v98, v107
	v_div_scale_f32 v98, vcc, 1.0, v74, 1.0
	v_exp_f32_e32 v77, v77
	v_mul_f32_e32 v105, v98, v107
	v_fma_f32 v106, -v104, v105, v98
	v_fmac_f32_e32 v105, v106, v107
	v_fma_f32 v98, -v104, v105, v98
	v_div_fmas_f32 v98, v98, v107, v105
	v_pk_add_f32 v[76:77], v[76:77], 1.0 op_sel_hi:[1,0]
	v_div_fixup_f32 v74, v98, v74, 1.0
	v_div_scale_f32 v98, s[8:9], v77, v77, 1.0
	v_rcp_f32_e32 v104, v98
	v_pk_fma_f32 v[70:71], v[70:71], v[74:75], v[102:103]
	v_lshlrev_b32_e32 v74, 16, v99
	v_and_b32_e32 v75, 0xffff0000, v99
	v_fma_f32 v99, -v98, v104, 1.0
	v_fmac_f32_e32 v104, v99, v104
	v_div_scale_f32 v99, vcc, 1.0, v77, 1.0
	v_mul_f32_e32 v102, v99, v104
	v_fma_f32 v103, -v98, v102, v99
	v_fmac_f32_e32 v102, v103, v104
	v_fma_f32 v98, -v98, v102, v99
	v_div_scale_f32 v99, s[8:9], v76, v76, 1.0
	v_rcp_f32_e32 v103, v99
	v_div_fmas_f32 v98, v98, v104, v102
	v_div_fixup_f32 v77, v98, v77, 1.0
	v_mul_f32_e32 v78, 0xbfb8aa3b, v78
	v_fma_f32 v98, -v99, v103, 1.0
	v_mul_f32_e32 v79, 0xbfb8aa3b, v79
	v_fmac_f32_e32 v103, v98, v103
	v_div_scale_f32 v98, vcc, 1.0, v76, 1.0
	v_exp_f32_e32 v78, v78
	v_exp_f32_e32 v79, v79
	v_mul_f32_e32 v102, v98, v103
	v_fma_f32 v104, -v99, v102, v98
	v_fmac_f32_e32 v102, v104, v103
	v_fma_f32 v98, -v99, v102, v98
	v_div_fmas_f32 v98, v98, v103, v102
	v_pk_add_f32 v[78:79], v[78:79], 1.0 op_sel_hi:[1,0]
	v_div_fixup_f32 v76, v98, v76, 1.0
	v_div_scale_f32 v98, s[8:9], v79, v79, 1.0
	v_rcp_f32_e32 v99, v98
	v_pk_fma_f32 v[72:73], v[72:73], v[76:77], v[74:75]
	v_lshlrev_b32_e32 v74, 16, v100
	v_and_b32_e32 v75, 0xffff0000, v100
	v_fma_f32 v76, -v98, v99, 1.0
	v_fmac_f32_e32 v99, v76, v99
	v_div_scale_f32 v76, vcc, 1.0, v79, 1.0
	v_mul_f32_e32 v77, v76, v99
	v_fma_f32 v100, -v98, v77, v76
	v_fmac_f32_e32 v77, v100, v99
	v_fma_f32 v76, -v98, v77, v76
	v_div_scale_f32 v98, s[8:9], v78, v78, 1.0
	v_rcp_f32_e32 v100, v98
	v_div_fmas_f32 v76, v76, v99, v77
	v_div_fixup_f32 v77, v76, v79, 1.0
	v_mul_f32_e32 v80, 0xbfb8aa3b, v80
	v_fma_f32 v76, -v98, v100, 1.0
	v_fmac_f32_e32 v100, v76, v100
	v_div_scale_f32 v76, vcc, 1.0, v78, 1.0
	v_mul_f32_e32 v81, 0xbfb8aa3b, v81
	v_mul_f32_e32 v79, v76, v100
	v_exp_f32_e32 v80, v80
	v_exp_f32_e32 v81, v81
	v_fma_f32 v99, -v98, v79, v76
	v_fmac_f32_e32 v79, v99, v100
	v_fma_f32 v76, -v98, v79, v76
	v_div_fmas_f32 v76, v76, v100, v79
	v_div_fixup_f32 v76, v76, v78, 1.0
	v_pk_add_f32 v[78:79], v[80:81], 1.0 op_sel_hi:[1,0]
	v_pk_fma_f32 v[74:75], v[66:67], v[76:77], v[74:75]
	v_div_scale_f32 v80, s[8:9], v79, v79, 1.0
	v_rcp_f32_e32 v81, v80
	s_waitcnt vmcnt(2)
	v_lshlrev_b32_e32 v100, 16, v94
	v_and_b32_e32 v94, 0xffff0000, v94
	v_mul_f32_e32 v100, 0xbfb8aa3b, v100
	v_fma_f32 v76, -v80, v81, 1.0
	v_fmac_f32_e32 v81, v76, v81
	v_div_scale_f32 v76, vcc, 1.0, v79, 1.0
	v_mul_f32_e32 v77, v76, v81
	v_fma_f32 v98, -v80, v77, v76
	v_fmac_f32_e32 v77, v98, v81
	v_fma_f32 v76, -v80, v77, v76
	v_div_scale_f32 v80, s[8:9], v78, v78, 1.0
	v_rcp_f32_e32 v98, v80
	v_div_fmas_f32 v76, v76, v81, v77
	v_div_fixup_f32 v77, v76, v79, 1.0
	v_mul_f32_e32 v94, 0xbfb8aa3b, v94
	v_fma_f32 v76, -v80, v98, 1.0
	v_fmac_f32_e32 v98, v76, v98
	v_div_scale_f32 v76, vcc, 1.0, v78, 1.0
	v_mul_f32_e32 v79, v76, v98
	v_fma_f32 v81, -v80, v79, v76
	v_fmac_f32_e32 v79, v81, v98
	v_fma_f32 v76, -v80, v79, v76
	v_lshlrev_b32_e32 v66, 16, v101
	v_and_b32_e32 v67, 0xffff0000, v101
	v_div_fmas_f32 v76, v76, v98, v79
	v_exp_f32_e32 v100, v100
	v_exp_f32_e32 v101, v94
	v_div_fixup_f32 v76, v76, v78, 1.0
	v_pk_fma_f32 v[76:77], v[68:69], v[76:77], v[66:67]
	v_cvt_pk_bf16_f32 v66, v70, v71
	v_cvt_pk_bf16_f32 v67, v72, v73
	v_cvt_pk_bf16_f32 v68, v74, v75
	v_cvt_pk_bf16_f32 v69, v76, v77
	global_store_dwordx4 v[130:131], v[66:69], off offset:256 sc1
	v_pk_add_f32 v[100:101], v[100:101], 1.0 op_sel_hi:[1,0]
	v_lshlrev_b32_e32 v104, 16, v90
	v_add_u32_e32 v66, 0x90, v170
	v_ashrrev_i32_e32 v67, 31, v66
	v_div_scale_f32 v106, s[8:9], v101, v101, 1.0
	v_lshlrev_b64 v[68:69], 13, v[66:67]
	v_rcp_f32_e32 v107, v106
	v_lshl_add_u64 v[68:69], s[20:21], 0, v[68:69]
	v_lshlrev_b64 v[66:67], 12, v[66:67]
	v_lshl_add_u64 v[68:69], v[68:69], 0, v[172:173]
	v_lshl_add_u64 v[66:67], s[18:19], 0, v[66:67]
	v_lshl_add_u64 v[98:99], v[66:67], 0, v[172:173]
	v_add_co_u32_e32 v66, vcc, s80, v68
	v_and_b32_e32 v105, 0xffff0000, v90
	s_nop 0
	v_addc_co_u32_e32 v67, vcc, 0, v69, vcc
	v_fma_f32 v90, -v106, v107, 1.0
	v_fmac_f32_e32 v107, v90, v107
	v_div_scale_f32 v90, vcc, 1.0, v101, 1.0
	v_mul_f32_e32 v108, v90, v107
	v_fma_f32 v109, -v106, v108, v90
	v_fmac_f32_e32 v108, v109, v107
	v_fma_f32 v90, -v106, v108, v90
	v_div_scale_f32 v106, s[8:9], v100, v100, 1.0
	v_rcp_f32_e32 v109, v106
	v_lshlrev_b32_e32 v94, 16, v95
	v_and_b32_e32 v95, 0xffff0000, v95
	v_mul_f32_e32 v94, 0xbfb8aa3b, v94
	v_mul_f32_e32 v95, 0xbfb8aa3b, v95
	v_div_fmas_f32 v90, v90, v107, v108
	v_exp_f32_e32 v94, v94
	v_exp_f32_e32 v95, v95
	v_div_fixup_f32 v101, v90, v101, 1.0
	v_fma_f32 v90, -v106, v109, 1.0
	v_fmac_f32_e32 v109, v90, v109
	v_div_scale_f32 v90, vcc, 1.0, v100, 1.0
	v_mul_f32_e32 v107, v90, v109
	v_fma_f32 v108, -v106, v107, v90
	v_fmac_f32_e32 v107, v108, v109
	v_pk_add_f32 v[94:95], v[94:95], 1.0 op_sel_hi:[1,0]
	v_fma_f32 v90, -v106, v107, v90
	v_div_scale_f32 v106, s[8:9], v95, v95, 1.0
	v_div_fmas_f32 v90, v90, v109, v107
	v_rcp_f32_e32 v107, v106
	v_div_fixup_f32 v100, v90, v100, 1.0
	v_pk_fma_f32 v[62:63], v[62:63], v[100:101], v[104:105]
	v_lshlrev_b32_e32 v102, 16, v96
	v_fma_f32 v100, -v106, v107, 1.0
	v_fmac_f32_e32 v107, v100, v107
	v_div_scale_f32 v100, vcc, 1.0, v95, 1.0
	v_mul_f32_e32 v101, v100, v107
	v_fma_f32 v104, -v106, v101, v100
	v_fmac_f32_e32 v101, v104, v107
	v_div_scale_f32 v104, s[8:9], v94, v94, 1.0
	v_rcp_f32_e32 v105, v104
	v_fma_f32 v100, -v106, v101, v100
	v_div_fmas_f32 v100, v100, v107, v101
	v_div_fixup_f32 v95, v100, v95, 1.0
	v_fma_f32 v100, -v104, v105, 1.0
	v_and_b32_e32 v96, 0xffff0000, v96
	v_fmac_f32_e32 v105, v100, v105
	v_div_scale_f32 v100, vcc, 1.0, v94, 1.0
	v_mul_f32_e32 v102, 0xbfb8aa3b, v102
	v_mul_f32_e32 v96, 0xbfb8aa3b, v96
	v_mul_f32_e32 v101, v100, v105
	v_exp_f32_e32 v102, v102
	v_exp_f32_e32 v103, v96
	v_fma_f32 v106, -v104, v101, v100
	v_fmac_f32_e32 v101, v106, v105
	v_fma_f32 v100, -v104, v101, v100
	v_div_fmas_f32 v100, v100, v105, v101
	v_div_fixup_f32 v94, v100, v94, 1.0
	v_pk_add_f32 v[100:101], v[102:103], 1.0 op_sel_hi:[1,0]
	v_lshlrev_b32_e32 v90, 16, v91
	v_div_scale_f32 v102, s[8:9], v101, v101, 1.0
	v_rcp_f32_e32 v103, v102
	v_and_b32_e32 v91, 0xffff0000, v91
	v_pk_fma_f32 v[64:65], v[64:65], v[94:95], v[90:91]
	v_lshlrev_b32_e32 v90, 16, v92
	v_and_b32_e32 v91, 0xffff0000, v92
	v_fma_f32 v92, -v102, v103, 1.0
	v_fmac_f32_e32 v103, v92, v103
	v_div_scale_f32 v92, vcc, 1.0, v101, 1.0
	v_mul_f32_e32 v94, v92, v103
	v_fma_f32 v95, -v102, v94, v92
	v_fmac_f32_e32 v94, v95, v103
	v_fma_f32 v92, -v102, v94, v92
	v_div_scale_f32 v102, s[8:9], v100, v100, 1.0
	v_rcp_f32_e32 v104, v102
	v_div_fmas_f32 v92, v92, v103, v94
	v_lshlrev_b32_e32 v96, 16, v97
	v_and_b32_e32 v97, 0xffff0000, v97
	v_div_fixup_f32 v95, v92, v101, 1.0
	v_fma_f32 v92, -v102, v104, 1.0
	v_mul_f32_e32 v96, 0xbfb8aa3b, v96
	v_mul_f32_e32 v97, 0xbfb8aa3b, v97
	v_fmac_f32_e32 v104, v92, v104
	v_div_scale_f32 v92, vcc, 1.0, v100, 1.0
	v_exp_f32_e32 v96, v96
	v_exp_f32_e32 v97, v97
	v_mul_f32_e32 v94, v92, v104
	v_fma_f32 v101, -v102, v94, v92
	v_fmac_f32_e32 v94, v101, v104
	v_fma_f32 v92, -v102, v94, v92
	v_div_fmas_f32 v92, v92, v104, v94
	v_pk_add_f32 v[96:97], v[96:97], 1.0 op_sel_hi:[1,0]
	v_div_fixup_f32 v94, v92, v100, 1.0
	v_div_scale_f32 v92, s[8:9], v97, v97, 1.0
	v_rcp_f32_e32 v100, v92
	v_pk_fma_f32 v[90:91], v[58:59], v[94:95], v[90:91]
	v_lshlrev_b32_e32 v58, 16, v93
	v_and_b32_e32 v59, 0xffff0000, v93
	v_fma_f32 v93, -v92, v100, 1.0
	v_fmac_f32_e32 v100, v93, v100
	v_div_scale_f32 v93, vcc, 1.0, v97, 1.0
	v_mul_f32_e32 v94, v93, v100
	v_fma_f32 v95, -v92, v94, v93
	v_fmac_f32_e32 v94, v95, v100
	v_div_scale_f32 v95, s[8:9], v96, v96, 1.0
	v_rcp_f32_e32 v101, v95
	v_fma_f32 v92, -v92, v94, v93
	v_div_fmas_f32 v92, v92, v100, v94
	v_div_fixup_f32 v93, v92, v97, 1.0
	v_fma_f32 v92, -v95, v101, 1.0
	v_fmac_f32_e32 v101, v92, v101
	v_div_scale_f32 v92, vcc, 1.0, v96, 1.0
	v_mul_f32_e32 v94, v92, v101
	v_fma_f32 v97, -v95, v94, v92
	v_fmac_f32_e32 v94, v97, v101
	v_fma_f32 v92, -v95, v94, v92
	v_div_fmas_f32 v92, v92, v101, v94
	v_div_fixup_f32 v92, v92, v96, 1.0
	v_pk_fma_f32 v[92:93], v[60:61], v[92:93], v[58:59]
	v_lshl_add_u64 v[70:71], v[68:69], 0, s[24:25]
	v_cvt_pk_bf16_f32 v58, v62, v63
	v_cvt_pk_bf16_f32 v59, v64, v65
	v_cvt_pk_bf16_f32 v60, v90, v91
	v_cvt_pk_bf16_f32 v61, v92, v93
	global_load_dwordx4 v[74:77], v[98:99], off
	s_nop 0
	global_load_dwordx4 v[70:73], v[70:71], off offset:256
	s_nop 0
	global_load_dwordx4 v[78:81], v[66:67], off
	s_nop 0
	global_load_dwordx4 v[66:69], v[98:99], off offset:256
	v_lshlrev_b32_e32 v62, 16, v88
	global_store_dwordx4 v[114:115], v[58:61], off sc1
	v_and_b32_e32 v63, 0xffff0000, v88
	v_lshlrev_b32_e32 v64, 16, v89
	v_lshlrev_b32_e32 v58, 16, v86
	v_and_b32_e32 v59, 0xffff0000, v86
	v_mul_f32_e32 v58, 0xbfb8aa3b, v58
	v_mul_f32_e32 v59, 0xbfb8aa3b, v59
	v_exp_f32_e32 v58, v58
	v_exp_f32_e32 v59, v59
	v_and_b32_e32 v65, 0xffff0000, v89
	v_lshlrev_b32_e32 v60, 16, v87
	v_and_b32_e32 v61, 0xffff0000, v87
	v_pk_add_f32 v[58:59], v[58:59], 1.0 op_sel_hi:[1,0]
	s_waitcnt vmcnt(7)
	v_lshlrev_b32_e32 v86, 16, v82
	v_div_scale_f32 v88, s[8:9], v59, v59, 1.0
	v_rcp_f32_e32 v89, v88
	v_and_b32_e32 v87, 0xffff0000, v82
	v_mul_f32_e32 v60, 0xbfb8aa3b, v60
	v_mul_f32_e32 v61, 0xbfb8aa3b, v61
	v_fma_f32 v82, -v88, v89, 1.0
	v_fmac_f32_e32 v89, v82, v89
	v_div_scale_f32 v82, vcc, 1.0, v59, 1.0
	v_mul_f32_e32 v90, v82, v89
	v_fma_f32 v91, -v88, v90, v82
	v_fmac_f32_e32 v90, v91, v89
	v_fma_f32 v82, -v88, v90, v82
	v_div_scale_f32 v88, s[8:9], v58, v58, 1.0
	v_rcp_f32_e32 v91, v88
	v_div_fmas_f32 v82, v82, v89, v90
	v_div_fixup_f32 v59, v82, v59, 1.0
	v_exp_f32_e32 v60, v60
	v_fma_f32 v82, -v88, v91, 1.0
	v_fmac_f32_e32 v91, v82, v91
	v_div_scale_f32 v82, vcc, 1.0, v58, 1.0
	v_exp_f32_e32 v61, v61
	v_mul_f32_e32 v89, v82, v91
	v_fma_f32 v90, -v88, v89, v82
	v_fmac_f32_e32 v89, v90, v91
	v_fma_f32 v82, -v88, v89, v82
	v_div_fmas_f32 v82, v82, v91, v89
	v_pk_add_f32 v[60:61], v[60:61], 1.0 op_sel_hi:[1,0]
	v_div_fixup_f32 v58, v82, v58, 1.0
	v_div_scale_f32 v82, s[8:9], v61, v61, 1.0
	v_rcp_f32_e32 v88, v82
	v_pk_fma_f32 v[54:55], v[54:55], v[58:59], v[86:87]
	v_lshlrev_b32_e32 v58, 16, v83
	v_and_b32_e32 v59, 0xffff0000, v83
	v_fma_f32 v83, -v82, v88, 1.0
	v_fmac_f32_e32 v88, v83, v88
	v_div_scale_f32 v83, vcc, 1.0, v61, 1.0
	v_mul_f32_e32 v86, v83, v88
	v_fma_f32 v87, -v82, v86, v83
	v_fmac_f32_e32 v86, v87, v88
	v_fma_f32 v82, -v82, v86, v83
	v_div_scale_f32 v83, s[8:9], v60, v60, 1.0
	v_rcp_f32_e32 v87, v83
	v_div_fmas_f32 v82, v82, v88, v86
	v_div_fixup_f32 v61, v82, v61, 1.0
	v_mul_f32_e32 v62, 0xbfb8aa3b, v62
	v_fma_f32 v82, -v83, v87, 1.0
	v_mul_f32_e32 v63, 0xbfb8aa3b, v63
	v_fmac_f32_e32 v87, v82, v87
	v_div_scale_f32 v82, vcc, 1.0, v60, 1.0
	v_exp_f32_e32 v62, v62
	v_exp_f32_e32 v63, v63
	v_mul_f32_e32 v86, v82, v87
	v_fma_f32 v88, -v83, v86, v82
	v_fmac_f32_e32 v86, v88, v87
	v_fma_f32 v82, -v83, v86, v82
	v_div_fmas_f32 v82, v82, v87, v86
	v_pk_add_f32 v[62:63], v[62:63], 1.0 op_sel_hi:[1,0]
	v_div_fixup_f32 v60, v82, v60, 1.0
	v_div_scale_f32 v82, s[8:9], v63, v63, 1.0
	v_rcp_f32_e32 v83, v82
	v_pk_fma_f32 v[56:57], v[56:57], v[60:61], v[58:59]
	v_lshlrev_b32_e32 v58, 16, v84
	v_and_b32_e32 v59, 0xffff0000, v84
	v_fma_f32 v60, -v82, v83, 1.0
	v_fmac_f32_e32 v83, v60, v83
	v_div_scale_f32 v60, vcc, 1.0, v63, 1.0
	v_mul_f32_e32 v61, v60, v83
	v_fma_f32 v84, -v82, v61, v60
	v_fmac_f32_e32 v61, v84, v83
	v_fma_f32 v60, -v82, v61, v60
	v_div_scale_f32 v82, s[8:9], v62, v62, 1.0
	v_rcp_f32_e32 v84, v82
	v_div_fmas_f32 v60, v60, v83, v61
	v_div_fixup_f32 v61, v60, v63, 1.0
	v_mul_f32_e32 v64, 0xbfb8aa3b, v64
	v_fma_f32 v60, -v82, v84, 1.0
	v_fmac_f32_e32 v84, v60, v84
	v_div_scale_f32 v60, vcc, 1.0, v62, 1.0
	v_mul_f32_e32 v65, 0xbfb8aa3b, v65
	v_mul_f32_e32 v63, v60, v84
	v_exp_f32_e32 v64, v64
	v_exp_f32_e32 v65, v65
	v_fma_f32 v83, -v82, v63, v60
	v_fmac_f32_e32 v63, v83, v84
	v_fma_f32 v60, -v82, v63, v60
	v_div_fmas_f32 v60, v60, v84, v63
	v_div_fixup_f32 v60, v60, v62, 1.0
	v_pk_add_f32 v[62:63], v[64:65], 1.0 op_sel_hi:[1,0]
	v_pk_fma_f32 v[58:59], v[50:51], v[60:61], v[58:59]
	v_div_scale_f32 v64, s[8:9], v63, v63, 1.0
	v_rcp_f32_e32 v65, v64
	s_waitcnt vmcnt(2)
	v_lshlrev_b32_e32 v84, 16, v78
	v_and_b32_e32 v78, 0xffff0000, v78
	v_mul_f32_e32 v84, 0xbfb8aa3b, v84
	v_fma_f32 v60, -v64, v65, 1.0
	v_fmac_f32_e32 v65, v60, v65
	v_div_scale_f32 v60, vcc, 1.0, v63, 1.0
	v_mul_f32_e32 v61, v60, v65
	v_fma_f32 v82, -v64, v61, v60
	v_fmac_f32_e32 v61, v82, v65
	v_fma_f32 v60, -v64, v61, v60
	v_div_scale_f32 v64, s[8:9], v62, v62, 1.0
	v_rcp_f32_e32 v82, v64
	v_div_fmas_f32 v60, v60, v65, v61
	v_div_fixup_f32 v61, v60, v63, 1.0
	v_mul_f32_e32 v78, 0xbfb8aa3b, v78
	v_fma_f32 v60, -v64, v82, 1.0
	v_fmac_f32_e32 v82, v60, v82
	v_div_scale_f32 v60, vcc, 1.0, v62, 1.0
	v_mul_f32_e32 v63, v60, v82
	v_fma_f32 v65, -v64, v63, v60
	v_fmac_f32_e32 v63, v65, v82
	v_fma_f32 v60, -v64, v63, v60
	v_lshlrev_b32_e32 v50, 16, v85
	v_and_b32_e32 v51, 0xffff0000, v85
	v_div_fmas_f32 v60, v60, v82, v63
	v_exp_f32_e32 v84, v84
	v_exp_f32_e32 v85, v78
	v_div_fixup_f32 v60, v60, v62, 1.0
	v_pk_fma_f32 v[60:61], v[52:53], v[60:61], v[50:51]
	v_cvt_pk_bf16_f32 v50, v54, v55
	v_cvt_pk_bf16_f32 v51, v56, v57
	v_cvt_pk_bf16_f32 v52, v58, v59
	v_cvt_pk_bf16_f32 v53, v60, v61
	global_store_dwordx4 v[114:115], v[50:53], off offset:256 sc1
	v_pk_add_f32 v[84:85], v[84:85], 1.0 op_sel_hi:[1,0]
	v_lshlrev_b32_e32 v88, 16, v74
	v_add_u32_e32 v50, 0xa0, v170
	v_ashrrev_i32_e32 v51, 31, v50
	v_div_scale_f32 v90, s[8:9], v85, v85, 1.0
	v_lshlrev_b64 v[52:53], 13, v[50:51]
	v_rcp_f32_e32 v91, v90
	v_lshl_add_u64 v[52:53], s[20:21], 0, v[52:53]
	v_lshlrev_b64 v[50:51], 12, v[50:51]
	v_lshl_add_u64 v[52:53], v[52:53], 0, v[172:173]
	v_lshl_add_u64 v[50:51], s[18:19], 0, v[50:51]
	v_lshl_add_u64 v[82:83], v[50:51], 0, v[172:173]
	v_add_co_u32_e32 v50, vcc, s80, v52
	v_and_b32_e32 v89, 0xffff0000, v74
	s_nop 0
	v_addc_co_u32_e32 v51, vcc, 0, v53, vcc
	v_fma_f32 v74, -v90, v91, 1.0
	v_fmac_f32_e32 v91, v74, v91
	v_div_scale_f32 v74, vcc, 1.0, v85, 1.0
	v_mul_f32_e32 v92, v74, v91
	v_fma_f32 v93, -v90, v92, v74
	v_fmac_f32_e32 v92, v93, v91
	v_fma_f32 v74, -v90, v92, v74
	v_div_scale_f32 v90, s[8:9], v84, v84, 1.0
	v_rcp_f32_e32 v93, v90
	v_lshlrev_b32_e32 v78, 16, v79
	v_and_b32_e32 v79, 0xffff0000, v79
	v_mul_f32_e32 v78, 0xbfb8aa3b, v78
	v_mul_f32_e32 v79, 0xbfb8aa3b, v79
	v_div_fmas_f32 v74, v74, v91, v92
	v_exp_f32_e32 v78, v78
	v_exp_f32_e32 v79, v79
	v_div_fixup_f32 v85, v74, v85, 1.0
	v_fma_f32 v74, -v90, v93, 1.0
	v_fmac_f32_e32 v93, v74, v93
	v_div_scale_f32 v74, vcc, 1.0, v84, 1.0
	v_mul_f32_e32 v91, v74, v93
	v_fma_f32 v92, -v90, v91, v74
	v_fmac_f32_e32 v91, v92, v93
	v_pk_add_f32 v[78:79], v[78:79], 1.0 op_sel_hi:[1,0]
	v_fma_f32 v74, -v90, v91, v74
	v_div_scale_f32 v90, s[8:9], v79, v79, 1.0
	v_div_fmas_f32 v74, v74, v93, v91
	v_rcp_f32_e32 v91, v90
	v_div_fixup_f32 v84, v74, v84, 1.0
	v_pk_fma_f32 v[46:47], v[46:47], v[84:85], v[88:89]
	v_lshlrev_b32_e32 v86, 16, v80
	v_fma_f32 v84, -v90, v91, 1.0
	v_fmac_f32_e32 v91, v84, v91
	v_div_scale_f32 v84, vcc, 1.0, v79, 1.0
	v_mul_f32_e32 v85, v84, v91
	v_fma_f32 v88, -v90, v85, v84
	v_fmac_f32_e32 v85, v88, v91
	v_div_scale_f32 v88, s[8:9], v78, v78, 1.0
	v_rcp_f32_e32 v89, v88
	v_fma_f32 v84, -v90, v85, v84
	v_div_fmas_f32 v84, v84, v91, v85
	v_div_fixup_f32 v79, v84, v79, 1.0
	v_fma_f32 v84, -v88, v89, 1.0
	v_and_b32_e32 v80, 0xffff0000, v80
	v_fmac_f32_e32 v89, v84, v89
	v_div_scale_f32 v84, vcc, 1.0, v78, 1.0
	v_mul_f32_e32 v86, 0xbfb8aa3b, v86
	v_mul_f32_e32 v80, 0xbfb8aa3b, v80
	v_mul_f32_e32 v85, v84, v89
	v_exp_f32_e32 v86, v86
	v_exp_f32_e32 v87, v80
	v_fma_f32 v90, -v88, v85, v84
	v_fmac_f32_e32 v85, v90, v89
	v_fma_f32 v84, -v88, v85, v84
	v_div_fmas_f32 v84, v84, v89, v85
	v_div_fixup_f32 v78, v84, v78, 1.0
	v_pk_add_f32 v[84:85], v[86:87], 1.0 op_sel_hi:[1,0]
	v_lshlrev_b32_e32 v74, 16, v75
	v_div_scale_f32 v86, s[8:9], v85, v85, 1.0
	v_rcp_f32_e32 v87, v86
	v_and_b32_e32 v75, 0xffff0000, v75
	v_pk_fma_f32 v[48:49], v[48:49], v[78:79], v[74:75]
	v_lshlrev_b32_e32 v74, 16, v76
	v_and_b32_e32 v75, 0xffff0000, v76
	v_fma_f32 v76, -v86, v87, 1.0
	v_fmac_f32_e32 v87, v76, v87
	v_div_scale_f32 v76, vcc, 1.0, v85, 1.0
	v_mul_f32_e32 v78, v76, v87
	v_fma_f32 v79, -v86, v78, v76
	v_fmac_f32_e32 v78, v79, v87
	v_fma_f32 v76, -v86, v78, v76
	v_div_scale_f32 v86, s[8:9], v84, v84, 1.0
	v_rcp_f32_e32 v88, v86
	v_div_fmas_f32 v76, v76, v87, v78
	v_lshlrev_b32_e32 v80, 16, v81
	v_and_b32_e32 v81, 0xffff0000, v81
	v_div_fixup_f32 v79, v76, v85, 1.0
	v_fma_f32 v76, -v86, v88, 1.0
	v_mul_f32_e32 v80, 0xbfb8aa3b, v80
	v_mul_f32_e32 v81, 0xbfb8aa3b, v81
	v_fmac_f32_e32 v88, v76, v88
	v_div_scale_f32 v76, vcc, 1.0, v84, 1.0
	v_exp_f32_e32 v80, v80
	v_exp_f32_e32 v81, v81
	v_mul_f32_e32 v78, v76, v88
	v_fma_f32 v85, -v86, v78, v76
	v_fmac_f32_e32 v78, v85, v88
	v_fma_f32 v76, -v86, v78, v76
	v_div_fmas_f32 v76, v76, v88, v78
	v_pk_add_f32 v[80:81], v[80:81], 1.0 op_sel_hi:[1,0]
	v_div_fixup_f32 v78, v76, v84, 1.0
	v_div_scale_f32 v76, s[8:9], v81, v81, 1.0
	v_rcp_f32_e32 v84, v76
	v_pk_fma_f32 v[74:75], v[42:43], v[78:79], v[74:75]
	v_lshlrev_b32_e32 v42, 16, v77
	v_and_b32_e32 v43, 0xffff0000, v77
	v_fma_f32 v77, -v76, v84, 1.0
	v_fmac_f32_e32 v84, v77, v84
	v_div_scale_f32 v77, vcc, 1.0, v81, 1.0
	v_mul_f32_e32 v78, v77, v84
	v_fma_f32 v79, -v76, v78, v77
	v_fmac_f32_e32 v78, v79, v84
	v_div_scale_f32 v79, s[8:9], v80, v80, 1.0
	v_rcp_f32_e32 v85, v79
	v_fma_f32 v76, -v76, v78, v77
	v_div_fmas_f32 v76, v76, v84, v78
	v_div_fixup_f32 v77, v76, v81, 1.0
	v_fma_f32 v76, -v79, v85, 1.0
	v_fmac_f32_e32 v85, v76, v85
	v_div_scale_f32 v76, vcc, 1.0, v80, 1.0
	v_mul_f32_e32 v78, v76, v85
	v_fma_f32 v81, -v79, v78, v76
	v_fmac_f32_e32 v78, v81, v85
	v_fma_f32 v76, -v79, v78, v76
	v_div_fmas_f32 v76, v76, v85, v78
	v_div_fixup_f32 v76, v76, v80, 1.0
	v_pk_fma_f32 v[76:77], v[44:45], v[76:77], v[42:43]
	v_lshl_add_u64 v[54:55], v[52:53], 0, s[24:25]
	v_cvt_pk_bf16_f32 v42, v46, v47
	v_cvt_pk_bf16_f32 v43, v48, v49
	v_cvt_pk_bf16_f32 v44, v74, v75
	v_cvt_pk_bf16_f32 v45, v76, v77
	global_load_dwordx4 v[58:61], v[82:83], off
	s_nop 0
	global_load_dwordx4 v[54:57], v[54:55], off offset:256
	s_nop 0
	global_load_dwordx4 v[62:65], v[50:51], off
	s_nop 0
	global_load_dwordx4 v[50:53], v[82:83], off offset:256
	v_lshlrev_b32_e32 v46, 16, v72
	global_store_dwordx4 v[98:99], v[42:45], off sc1
	v_and_b32_e32 v47, 0xffff0000, v72
	v_lshlrev_b32_e32 v48, 16, v73
	v_lshlrev_b32_e32 v42, 16, v70
	v_and_b32_e32 v43, 0xffff0000, v70
	v_mul_f32_e32 v42, 0xbfb8aa3b, v42
	v_mul_f32_e32 v43, 0xbfb8aa3b, v43
	v_exp_f32_e32 v42, v42
	v_exp_f32_e32 v43, v43
	v_and_b32_e32 v49, 0xffff0000, v73
	v_lshlrev_b32_e32 v44, 16, v71
	v_and_b32_e32 v45, 0xffff0000, v71
	v_pk_add_f32 v[42:43], v[42:43], 1.0 op_sel_hi:[1,0]
	s_waitcnt vmcnt(7)
	v_lshlrev_b32_e32 v70, 16, v66
	v_div_scale_f32 v72, s[8:9], v43, v43, 1.0
	v_rcp_f32_e32 v73, v72
	v_and_b32_e32 v71, 0xffff0000, v66
	v_mul_f32_e32 v44, 0xbfb8aa3b, v44
	v_mul_f32_e32 v45, 0xbfb8aa3b, v45
	v_fma_f32 v66, -v72, v73, 1.0
	v_fmac_f32_e32 v73, v66, v73
	v_div_scale_f32 v66, vcc, 1.0, v43, 1.0
	v_mul_f32_e32 v74, v66, v73
	v_fma_f32 v75, -v72, v74, v66
	v_fmac_f32_e32 v74, v75, v73
	v_fma_f32 v66, -v72, v74, v66
	v_div_scale_f32 v72, s[8:9], v42, v42, 1.0
	v_rcp_f32_e32 v75, v72
	v_div_fmas_f32 v66, v66, v73, v74
	v_div_fixup_f32 v43, v66, v43, 1.0
	v_exp_f32_e32 v44, v44
	v_fma_f32 v66, -v72, v75, 1.0
	v_fmac_f32_e32 v75, v66, v75
	v_div_scale_f32 v66, vcc, 1.0, v42, 1.0
	v_exp_f32_e32 v45, v45
	v_mul_f32_e32 v73, v66, v75
	v_fma_f32 v74, -v72, v73, v66
	v_fmac_f32_e32 v73, v74, v75
	v_fma_f32 v66, -v72, v73, v66
	v_div_fmas_f32 v66, v66, v75, v73
	v_pk_add_f32 v[44:45], v[44:45], 1.0 op_sel_hi:[1,0]
	v_div_fixup_f32 v42, v66, v42, 1.0
	v_div_scale_f32 v66, s[8:9], v45, v45, 1.0
	v_rcp_f32_e32 v72, v66
	v_pk_fma_f32 v[38:39], v[38:39], v[42:43], v[70:71]
	v_lshlrev_b32_e32 v42, 16, v67
	v_and_b32_e32 v43, 0xffff0000, v67
	v_fma_f32 v67, -v66, v72, 1.0
	v_fmac_f32_e32 v72, v67, v72
	v_div_scale_f32 v67, vcc, 1.0, v45, 1.0
	v_mul_f32_e32 v70, v67, v72
	v_fma_f32 v71, -v66, v70, v67
	v_fmac_f32_e32 v70, v71, v72
	v_fma_f32 v66, -v66, v70, v67
	v_div_scale_f32 v67, s[8:9], v44, v44, 1.0
	v_rcp_f32_e32 v71, v67
	v_div_fmas_f32 v66, v66, v72, v70
	v_div_fixup_f32 v45, v66, v45, 1.0
	v_mul_f32_e32 v46, 0xbfb8aa3b, v46
	v_fma_f32 v66, -v67, v71, 1.0
	v_mul_f32_e32 v47, 0xbfb8aa3b, v47
	v_fmac_f32_e32 v71, v66, v71
	v_div_scale_f32 v66, vcc, 1.0, v44, 1.0
	v_exp_f32_e32 v46, v46
	v_exp_f32_e32 v47, v47
	v_mul_f32_e32 v70, v66, v71
	v_fma_f32 v72, -v67, v70, v66
	v_fmac_f32_e32 v70, v72, v71
	v_fma_f32 v66, -v67, v70, v66
	v_div_fmas_f32 v66, v66, v71, v70
	v_pk_add_f32 v[46:47], v[46:47], 1.0 op_sel_hi:[1,0]
	v_div_fixup_f32 v44, v66, v44, 1.0
	v_div_scale_f32 v66, s[8:9], v47, v47, 1.0
	v_rcp_f32_e32 v67, v66
	v_pk_fma_f32 v[40:41], v[40:41], v[44:45], v[42:43]
	v_lshlrev_b32_e32 v42, 16, v68
	v_and_b32_e32 v43, 0xffff0000, v68
	v_fma_f32 v44, -v66, v67, 1.0
	v_fmac_f32_e32 v67, v44, v67
	v_div_scale_f32 v44, vcc, 1.0, v47, 1.0
	v_mul_f32_e32 v45, v44, v67
	v_fma_f32 v68, -v66, v45, v44
	v_fmac_f32_e32 v45, v68, v67
	v_fma_f32 v44, -v66, v45, v44
	v_div_scale_f32 v66, s[8:9], v46, v46, 1.0
	v_rcp_f32_e32 v68, v66
	v_div_fmas_f32 v44, v44, v67, v45
	v_div_fixup_f32 v45, v44, v47, 1.0
	v_mul_f32_e32 v48, 0xbfb8aa3b, v48
	v_fma_f32 v44, -v66, v68, 1.0
	v_fmac_f32_e32 v68, v44, v68
	v_div_scale_f32 v44, vcc, 1.0, v46, 1.0
	v_mul_f32_e32 v49, 0xbfb8aa3b, v49
	v_mul_f32_e32 v47, v44, v68
	v_exp_f32_e32 v48, v48
	v_exp_f32_e32 v49, v49
	v_fma_f32 v67, -v66, v47, v44
	v_fmac_f32_e32 v47, v67, v68
	v_fma_f32 v44, -v66, v47, v44
	v_div_fmas_f32 v44, v44, v68, v47
	v_div_fixup_f32 v44, v44, v46, 1.0
	v_pk_add_f32 v[46:47], v[48:49], 1.0 op_sel_hi:[1,0]
	v_pk_fma_f32 v[42:43], v[34:35], v[44:45], v[42:43]
	v_div_scale_f32 v48, s[8:9], v47, v47, 1.0
	v_rcp_f32_e32 v49, v48
	s_waitcnt vmcnt(2)
	v_lshlrev_b32_e32 v68, 16, v62
	v_and_b32_e32 v62, 0xffff0000, v62
	v_mul_f32_e32 v68, 0xbfb8aa3b, v68
	v_fma_f32 v44, -v48, v49, 1.0
	v_fmac_f32_e32 v49, v44, v49
	v_div_scale_f32 v44, vcc, 1.0, v47, 1.0
	v_mul_f32_e32 v45, v44, v49
	v_fma_f32 v66, -v48, v45, v44
	v_fmac_f32_e32 v45, v66, v49
	v_fma_f32 v44, -v48, v45, v44
	v_div_scale_f32 v48, s[8:9], v46, v46, 1.0
	v_rcp_f32_e32 v66, v48
	v_div_fmas_f32 v44, v44, v49, v45
	v_div_fixup_f32 v45, v44, v47, 1.0
	v_mul_f32_e32 v62, 0xbfb8aa3b, v62
	v_fma_f32 v44, -v48, v66, 1.0
	v_fmac_f32_e32 v66, v44, v66
	v_div_scale_f32 v44, vcc, 1.0, v46, 1.0
	v_mul_f32_e32 v47, v44, v66
	v_fma_f32 v49, -v48, v47, v44
	v_fmac_f32_e32 v47, v49, v66
	v_fma_f32 v44, -v48, v47, v44
	v_lshlrev_b32_e32 v34, 16, v69
	v_and_b32_e32 v35, 0xffff0000, v69
	v_div_fmas_f32 v44, v44, v66, v47
	v_exp_f32_e32 v68, v68
	v_exp_f32_e32 v69, v62
	v_div_fixup_f32 v44, v44, v46, 1.0
	v_pk_fma_f32 v[44:45], v[36:37], v[44:45], v[34:35]
	v_cvt_pk_bf16_f32 v34, v38, v39
	v_cvt_pk_bf16_f32 v35, v40, v41
	v_cvt_pk_bf16_f32 v36, v42, v43
	v_cvt_pk_bf16_f32 v37, v44, v45
	global_store_dwordx4 v[98:99], v[34:37], off offset:256 sc1
	v_pk_add_f32 v[68:69], v[68:69], 1.0 op_sel_hi:[1,0]
	v_lshlrev_b32_e32 v72, 16, v58
	v_add_u32_e32 v34, 0xb0, v170
	v_ashrrev_i32_e32 v35, 31, v34
	v_div_scale_f32 v74, s[8:9], v69, v69, 1.0
	v_lshlrev_b64 v[36:37], 13, v[34:35]
	v_rcp_f32_e32 v75, v74
	v_lshl_add_u64 v[36:37], s[20:21], 0, v[36:37]
	v_lshlrev_b64 v[34:35], 12, v[34:35]
	v_lshl_add_u64 v[36:37], v[36:37], 0, v[172:173]
	v_lshl_add_u64 v[34:35], s[18:19], 0, v[34:35]
	v_lshl_add_u64 v[66:67], v[34:35], 0, v[172:173]
	v_add_co_u32_e32 v34, vcc, s80, v36
	v_and_b32_e32 v73, 0xffff0000, v58
	s_nop 0
	v_addc_co_u32_e32 v35, vcc, 0, v37, vcc
	v_fma_f32 v58, -v74, v75, 1.0
	v_fmac_f32_e32 v75, v58, v75
	v_div_scale_f32 v58, vcc, 1.0, v69, 1.0
	v_mul_f32_e32 v76, v58, v75
	v_fma_f32 v77, -v74, v76, v58
	v_fmac_f32_e32 v76, v77, v75
	v_fma_f32 v58, -v74, v76, v58
	v_div_scale_f32 v74, s[8:9], v68, v68, 1.0
	v_rcp_f32_e32 v77, v74
	v_lshlrev_b32_e32 v62, 16, v63
	v_and_b32_e32 v63, 0xffff0000, v63
	v_mul_f32_e32 v62, 0xbfb8aa3b, v62
	v_mul_f32_e32 v63, 0xbfb8aa3b, v63
	v_div_fmas_f32 v58, v58, v75, v76
	v_exp_f32_e32 v62, v62
	v_exp_f32_e32 v63, v63
	v_div_fixup_f32 v69, v58, v69, 1.0
	v_fma_f32 v58, -v74, v77, 1.0
	v_fmac_f32_e32 v77, v58, v77
	v_div_scale_f32 v58, vcc, 1.0, v68, 1.0
	v_mul_f32_e32 v75, v58, v77
	v_fma_f32 v76, -v74, v75, v58
	v_fmac_f32_e32 v75, v76, v77
	v_pk_add_f32 v[62:63], v[62:63], 1.0 op_sel_hi:[1,0]
	v_fma_f32 v58, -v74, v75, v58
	v_div_scale_f32 v74, s[8:9], v63, v63, 1.0
	v_div_fmas_f32 v58, v58, v77, v75
	v_rcp_f32_e32 v75, v74
	v_div_fixup_f32 v68, v58, v68, 1.0
	v_pk_fma_f32 v[30:31], v[30:31], v[68:69], v[72:73]
	v_lshlrev_b32_e32 v70, 16, v64
	v_fma_f32 v68, -v74, v75, 1.0
	v_fmac_f32_e32 v75, v68, v75
	v_div_scale_f32 v68, vcc, 1.0, v63, 1.0
	v_mul_f32_e32 v69, v68, v75
	v_fma_f32 v72, -v74, v69, v68
	v_fmac_f32_e32 v69, v72, v75
	v_div_scale_f32 v72, s[8:9], v62, v62, 1.0
	v_rcp_f32_e32 v73, v72
	v_fma_f32 v68, -v74, v69, v68
	v_div_fmas_f32 v68, v68, v75, v69
	v_div_fixup_f32 v63, v68, v63, 1.0
	v_fma_f32 v68, -v72, v73, 1.0
	v_and_b32_e32 v64, 0xffff0000, v64
	v_fmac_f32_e32 v73, v68, v73
	v_div_scale_f32 v68, vcc, 1.0, v62, 1.0
	v_mul_f32_e32 v70, 0xbfb8aa3b, v70
	v_mul_f32_e32 v64, 0xbfb8aa3b, v64
	v_mul_f32_e32 v69, v68, v73
	v_exp_f32_e32 v70, v70
	v_exp_f32_e32 v71, v64
	v_fma_f32 v74, -v72, v69, v68
	v_fmac_f32_e32 v69, v74, v73
	v_fma_f32 v68, -v72, v69, v68
	v_div_fmas_f32 v68, v68, v73, v69
	v_div_fixup_f32 v62, v68, v62, 1.0
	v_pk_add_f32 v[68:69], v[70:71], 1.0 op_sel_hi:[1,0]
	v_lshlrev_b32_e32 v58, 16, v59
	v_div_scale_f32 v70, s[8:9], v69, v69, 1.0
	v_rcp_f32_e32 v71, v70
	v_and_b32_e32 v59, 0xffff0000, v59
	v_pk_fma_f32 v[32:33], v[32:33], v[62:63], v[58:59]
	v_lshlrev_b32_e32 v58, 16, v60
	v_and_b32_e32 v59, 0xffff0000, v60
	v_fma_f32 v60, -v70, v71, 1.0
	v_fmac_f32_e32 v71, v60, v71
	v_div_scale_f32 v60, vcc, 1.0, v69, 1.0
	v_mul_f32_e32 v62, v60, v71
	v_fma_f32 v63, -v70, v62, v60
	v_fmac_f32_e32 v62, v63, v71
	v_fma_f32 v60, -v70, v62, v60
	v_div_scale_f32 v70, s[8:9], v68, v68, 1.0
	v_rcp_f32_e32 v72, v70
	v_div_fmas_f32 v60, v60, v71, v62
	v_lshlrev_b32_e32 v64, 16, v65
	v_and_b32_e32 v65, 0xffff0000, v65
	v_div_fixup_f32 v63, v60, v69, 1.0
	v_fma_f32 v60, -v70, v72, 1.0
	v_mul_f32_e32 v64, 0xbfb8aa3b, v64
	v_mul_f32_e32 v65, 0xbfb8aa3b, v65
	v_fmac_f32_e32 v72, v60, v72
	v_div_scale_f32 v60, vcc, 1.0, v68, 1.0
	v_exp_f32_e32 v64, v64
	v_exp_f32_e32 v65, v65
	v_mul_f32_e32 v62, v60, v72
	v_fma_f32 v69, -v70, v62, v60
	v_fmac_f32_e32 v62, v69, v72
	v_fma_f32 v60, -v70, v62, v60
	v_div_fmas_f32 v60, v60, v72, v62
	v_pk_add_f32 v[64:65], v[64:65], 1.0 op_sel_hi:[1,0]
	v_div_fixup_f32 v62, v60, v68, 1.0
	v_div_scale_f32 v60, s[8:9], v65, v65, 1.0
	v_rcp_f32_e32 v68, v60
	v_pk_fma_f32 v[58:59], v[26:27], v[62:63], v[58:59]
	v_lshlrev_b32_e32 v26, 16, v61
	v_and_b32_e32 v27, 0xffff0000, v61
	v_fma_f32 v61, -v60, v68, 1.0
	v_fmac_f32_e32 v68, v61, v68
	v_div_scale_f32 v61, vcc, 1.0, v65, 1.0
	v_mul_f32_e32 v62, v61, v68
	v_fma_f32 v63, -v60, v62, v61
	v_fmac_f32_e32 v62, v63, v68
	v_div_scale_f32 v63, s[8:9], v64, v64, 1.0
	v_rcp_f32_e32 v69, v63
	v_fma_f32 v60, -v60, v62, v61
	v_div_fmas_f32 v60, v60, v68, v62
	v_div_fixup_f32 v61, v60, v65, 1.0
	v_fma_f32 v60, -v63, v69, 1.0
	v_fmac_f32_e32 v69, v60, v69
	v_div_scale_f32 v60, vcc, 1.0, v64, 1.0
	v_mul_f32_e32 v62, v60, v69
	v_fma_f32 v65, -v63, v62, v60
	v_fmac_f32_e32 v62, v65, v69
	v_fma_f32 v60, -v63, v62, v60
	v_div_fmas_f32 v60, v60, v69, v62
	v_div_fixup_f32 v60, v60, v64, 1.0
	v_pk_fma_f32 v[60:61], v[28:29], v[60:61], v[26:27]
	v_lshl_add_u64 v[38:39], v[36:37], 0, s[24:25]
	v_cvt_pk_bf16_f32 v26, v30, v31
	v_cvt_pk_bf16_f32 v27, v32, v33
	v_cvt_pk_bf16_f32 v28, v58, v59
	v_cvt_pk_bf16_f32 v29, v60, v61
	global_load_dwordx4 v[42:45], v[66:67], off
	s_nop 0
	global_load_dwordx4 v[38:41], v[38:39], off offset:256
	s_nop 0
	global_load_dwordx4 v[46:49], v[34:35], off
	s_nop 0
	global_load_dwordx4 v[34:37], v[66:67], off offset:256
	v_lshlrev_b32_e32 v30, 16, v56
	global_store_dwordx4 v[82:83], v[26:29], off sc1
	v_and_b32_e32 v31, 0xffff0000, v56
	v_lshlrev_b32_e32 v32, 16, v57
	v_lshlrev_b32_e32 v26, 16, v54
	v_and_b32_e32 v27, 0xffff0000, v54
	v_mul_f32_e32 v26, 0xbfb8aa3b, v26
	v_mul_f32_e32 v27, 0xbfb8aa3b, v27
	v_exp_f32_e32 v26, v26
	v_exp_f32_e32 v27, v27
	v_and_b32_e32 v33, 0xffff0000, v57
	v_lshlrev_b32_e32 v28, 16, v55
	v_and_b32_e32 v29, 0xffff0000, v55
	v_pk_add_f32 v[26:27], v[26:27], 1.0 op_sel_hi:[1,0]
	s_waitcnt vmcnt(7)
	v_lshlrev_b32_e32 v54, 16, v50
	v_div_scale_f32 v56, s[8:9], v27, v27, 1.0
	v_rcp_f32_e32 v57, v56
	v_and_b32_e32 v55, 0xffff0000, v50
	v_mul_f32_e32 v28, 0xbfb8aa3b, v28
	v_mul_f32_e32 v29, 0xbfb8aa3b, v29
	v_fma_f32 v50, -v56, v57, 1.0
	v_fmac_f32_e32 v57, v50, v57
	v_div_scale_f32 v50, vcc, 1.0, v27, 1.0
	v_mul_f32_e32 v58, v50, v57
	v_fma_f32 v59, -v56, v58, v50
	v_fmac_f32_e32 v58, v59, v57
	v_fma_f32 v50, -v56, v58, v50
	v_div_scale_f32 v56, s[8:9], v26, v26, 1.0
	v_rcp_f32_e32 v59, v56
	v_div_fmas_f32 v50, v50, v57, v58
	v_div_fixup_f32 v27, v50, v27, 1.0
	v_exp_f32_e32 v28, v28
	v_fma_f32 v50, -v56, v59, 1.0
	v_fmac_f32_e32 v59, v50, v59
	v_div_scale_f32 v50, vcc, 1.0, v26, 1.0
	v_exp_f32_e32 v29, v29
	v_mul_f32_e32 v57, v50, v59
	v_fma_f32 v58, -v56, v57, v50
	v_fmac_f32_e32 v57, v58, v59
	v_fma_f32 v50, -v56, v57, v50
	v_div_fmas_f32 v50, v50, v59, v57
	v_pk_add_f32 v[28:29], v[28:29], 1.0 op_sel_hi:[1,0]
	v_div_fixup_f32 v26, v50, v26, 1.0
	v_div_scale_f32 v50, s[8:9], v29, v29, 1.0
	v_rcp_f32_e32 v56, v50
	v_pk_fma_f32 v[22:23], v[22:23], v[26:27], v[54:55]
	v_lshlrev_b32_e32 v26, 16, v51
	v_and_b32_e32 v27, 0xffff0000, v51
	v_fma_f32 v51, -v50, v56, 1.0
	v_fmac_f32_e32 v56, v51, v56
	v_div_scale_f32 v51, vcc, 1.0, v29, 1.0
	v_mul_f32_e32 v54, v51, v56
	v_fma_f32 v55, -v50, v54, v51
	v_fmac_f32_e32 v54, v55, v56
	v_fma_f32 v50, -v50, v54, v51
	v_div_scale_f32 v51, s[8:9], v28, v28, 1.0
	v_rcp_f32_e32 v55, v51
	v_div_fmas_f32 v50, v50, v56, v54
	v_div_fixup_f32 v29, v50, v29, 1.0
	v_mul_f32_e32 v30, 0xbfb8aa3b, v30
	v_fma_f32 v50, -v51, v55, 1.0
	v_mul_f32_e32 v31, 0xbfb8aa3b, v31
	v_fmac_f32_e32 v55, v50, v55
	v_div_scale_f32 v50, vcc, 1.0, v28, 1.0
	v_exp_f32_e32 v30, v30
	v_exp_f32_e32 v31, v31
	v_mul_f32_e32 v54, v50, v55
	v_fma_f32 v56, -v51, v54, v50
	v_fmac_f32_e32 v54, v56, v55
	v_fma_f32 v50, -v51, v54, v50
	v_div_fmas_f32 v50, v50, v55, v54
	v_pk_add_f32 v[30:31], v[30:31], 1.0 op_sel_hi:[1,0]
	v_div_fixup_f32 v28, v50, v28, 1.0
	v_div_scale_f32 v50, s[8:9], v31, v31, 1.0
	v_rcp_f32_e32 v51, v50
	v_pk_fma_f32 v[24:25], v[24:25], v[28:29], v[26:27]
	v_lshlrev_b32_e32 v26, 16, v52
	v_and_b32_e32 v27, 0xffff0000, v52
	v_fma_f32 v28, -v50, v51, 1.0
	v_fmac_f32_e32 v51, v28, v51
	v_div_scale_f32 v28, vcc, 1.0, v31, 1.0
	v_mul_f32_e32 v29, v28, v51
	v_fma_f32 v52, -v50, v29, v28
	v_fmac_f32_e32 v29, v52, v51
	v_fma_f32 v28, -v50, v29, v28
	v_div_scale_f32 v50, s[8:9], v30, v30, 1.0
	v_rcp_f32_e32 v52, v50
	v_div_fmas_f32 v28, v28, v51, v29
	v_div_fixup_f32 v29, v28, v31, 1.0
	v_mul_f32_e32 v32, 0xbfb8aa3b, v32
	v_fma_f32 v28, -v50, v52, 1.0
	v_fmac_f32_e32 v52, v28, v52
	v_div_scale_f32 v28, vcc, 1.0, v30, 1.0
	v_mul_f32_e32 v33, 0xbfb8aa3b, v33
	v_mul_f32_e32 v31, v28, v52
	v_exp_f32_e32 v32, v32
	v_exp_f32_e32 v33, v33
	v_fma_f32 v51, -v50, v31, v28
	v_fmac_f32_e32 v31, v51, v52
	v_fma_f32 v28, -v50, v31, v28
	v_div_fmas_f32 v28, v28, v52, v31
	v_div_fixup_f32 v28, v28, v30, 1.0
	v_pk_add_f32 v[30:31], v[32:33], 1.0 op_sel_hi:[1,0]
	v_pk_fma_f32 v[26:27], v[18:19], v[28:29], v[26:27]
	v_div_scale_f32 v32, s[8:9], v31, v31, 1.0
	v_rcp_f32_e32 v33, v32
	v_lshlrev_b32_e32 v18, 16, v53
	v_and_b32_e32 v19, 0xffff0000, v53
	v_fma_f32 v28, -v32, v33, 1.0
	v_fmac_f32_e32 v33, v28, v33
	v_div_scale_f32 v28, vcc, 1.0, v31, 1.0
	v_mul_f32_e32 v29, v28, v33
	v_fma_f32 v50, -v32, v29, v28
	v_fmac_f32_e32 v29, v50, v33
	v_fma_f32 v28, -v32, v29, v28
	v_div_scale_f32 v32, s[8:9], v30, v30, 1.0
	v_rcp_f32_e32 v50, v32
	v_div_fmas_f32 v28, v28, v33, v29
	v_div_fixup_f32 v29, v28, v31, 1.0
	v_fma_f32 v28, -v32, v50, 1.0
	v_fmac_f32_e32 v50, v28, v50
	v_div_scale_f32 v28, vcc, 1.0, v30, 1.0
	v_mul_f32_e32 v31, v28, v50
	v_fma_f32 v33, -v32, v31, v28
	v_fmac_f32_e32 v31, v33, v50
	v_fma_f32 v28, -v32, v31, v28
	v_div_fmas_f32 v28, v28, v50, v31
	v_div_fixup_f32 v28, v28, v30, 1.0
	v_pk_fma_f32 v[28:29], v[20:21], v[28:29], v[18:19]
	v_cvt_pk_bf16_f32 v18, v22, v23
	v_cvt_pk_bf16_f32 v19, v24, v25
	v_cvt_pk_bf16_f32 v20, v26, v27
	v_cvt_pk_bf16_f32 v21, v28, v29
	global_store_dwordx4 v[82:83], v[18:21], off offset:256 sc1
	s_waitcnt vmcnt(5)
	v_lshlrev_b32_e32 v26, 16, v42
	v_and_b32_e32 v27, 0xffff0000, v42
	s_waitcnt vmcnt(3)
	v_lshlrev_b32_e32 v18, 16, v46
	v_and_b32_e32 v19, 0xffff0000, v46
	v_mul_f32_e32 v18, 0xbfb8aa3b, v18
	v_mul_f32_e32 v19, 0xbfb8aa3b, v19
	v_exp_f32_e32 v18, v18
	v_exp_f32_e32 v19, v19
	v_lshlrev_b32_e32 v20, 16, v47
	v_and_b32_e32 v21, 0xffff0000, v47
	v_mul_f32_e32 v20, 0xbfb8aa3b, v20
	v_pk_add_f32 v[18:19], v[18:19], 1.0 op_sel_hi:[1,0]
	v_mul_f32_e32 v21, 0xbfb8aa3b, v21
	v_div_scale_f32 v28, s[8:9], v19, v19, 1.0
	v_rcp_f32_e32 v29, v28
	v_exp_f32_e32 v20, v20
	v_exp_f32_e32 v21, v21
	v_lshlrev_b32_e32 v22, 16, v48
	v_fma_f32 v30, -v28, v29, 1.0
	v_fmac_f32_e32 v29, v30, v29
	v_div_scale_f32 v30, vcc, 1.0, v19, 1.0
	v_mul_f32_e32 v31, v30, v29
	v_fma_f32 v32, -v28, v31, v30
	v_fmac_f32_e32 v31, v32, v29
	v_fma_f32 v28, -v28, v31, v30
	v_div_scale_f32 v30, s[8:9], v18, v18, 1.0
	v_rcp_f32_e32 v32, v30
	v_div_fmas_f32 v28, v28, v29, v31
	v_div_fixup_f32 v19, v28, v19, 1.0
	v_pk_add_f32 v[20:21], v[20:21], 1.0 op_sel_hi:[1,0]
	v_fma_f32 v28, -v30, v32, 1.0
	v_fmac_f32_e32 v32, v28, v32
	v_div_scale_f32 v28, vcc, 1.0, v18, 1.0
	v_mul_f32_e32 v29, v28, v32
	v_fma_f32 v31, -v30, v29, v28
	v_fmac_f32_e32 v29, v31, v32
	v_fma_f32 v28, -v30, v29, v28
	v_div_fmas_f32 v28, v28, v32, v29
	v_div_fixup_f32 v18, v28, v18, 1.0
	v_div_scale_f32 v28, s[8:9], v21, v21, 1.0
	v_rcp_f32_e32 v29, v28
	v_pk_fma_f32 v[14:15], v[14:15], v[18:19], v[26:27]
	v_and_b32_e32 v23, 0xffff0000, v48
	v_mul_f32_e32 v22, 0xbfb8aa3b, v22
	v_fma_f32 v26, -v28, v29, 1.0
	v_fmac_f32_e32 v29, v26, v29
	v_div_scale_f32 v26, vcc, 1.0, v21, 1.0
	v_mul_f32_e32 v27, v26, v29
	v_fma_f32 v30, -v28, v27, v26
	v_fmac_f32_e32 v27, v30, v29
	v_fma_f32 v26, -v28, v27, v26
	v_div_scale_f32 v28, s[8:9], v20, v20, 1.0
	v_rcp_f32_e32 v30, v28
	v_div_fmas_f32 v26, v26, v29, v27
	v_div_fixup_f32 v21, v26, v21, 1.0
	v_mul_f32_e32 v23, 0xbfb8aa3b, v23
	v_fma_f32 v26, -v28, v30, 1.0
	v_fmac_f32_e32 v30, v26, v30
	v_div_scale_f32 v26, vcc, 1.0, v20, 1.0
	v_exp_f32_e32 v22, v22
	v_exp_f32_e32 v23, v23
	v_mul_f32_e32 v27, v26, v30
	v_fma_f32 v29, -v28, v27, v26
	v_fmac_f32_e32 v27, v29, v30
	v_fma_f32 v26, -v28, v27, v26
	v_div_fmas_f32 v26, v26, v30, v27
	v_pk_add_f32 v[22:23], v[22:23], 1.0 op_sel_hi:[1,0]
	v_div_fixup_f32 v20, v26, v20, 1.0
	v_div_scale_f32 v26, s[8:9], v23, v23, 1.0
	v_rcp_f32_e32 v27, v26
	v_lshlrev_b32_e32 v18, 16, v43
	v_and_b32_e32 v19, 0xffff0000, v43
	v_pk_fma_f32 v[16:17], v[16:17], v[20:21], v[18:19]
	v_fma_f32 v20, -v26, v27, 1.0
	v_fmac_f32_e32 v27, v20, v27
	v_div_scale_f32 v20, vcc, 1.0, v23, 1.0
	v_mul_f32_e32 v21, v20, v27
	v_fma_f32 v28, -v26, v21, v20
	v_fmac_f32_e32 v21, v28, v27
	v_fma_f32 v20, -v26, v21, v20
	v_div_scale_f32 v26, s[8:9], v22, v22, 1.0
	v_rcp_f32_e32 v28, v26
	v_div_fmas_f32 v20, v20, v27, v21
	v_div_fixup_f32 v21, v20, v23, 1.0
	v_lshlrev_b32_e32 v24, 16, v49
	v_fma_f32 v20, -v26, v28, 1.0
	v_and_b32_e32 v25, 0xffff0000, v49
	v_fmac_f32_e32 v28, v20, v28
	v_div_scale_f32 v20, vcc, 1.0, v22, 1.0
	v_mul_f32_e32 v24, 0xbfb8aa3b, v24
	v_mul_f32_e32 v25, 0xbfb8aa3b, v25
	v_mul_f32_e32 v23, v20, v28
	v_exp_f32_e32 v24, v24
	v_exp_f32_e32 v25, v25
	v_fma_f32 v27, -v26, v23, v20
	v_fmac_f32_e32 v23, v27, v28
	v_fma_f32 v20, -v26, v23, v20
	v_div_fmas_f32 v20, v20, v28, v23
	v_div_fixup_f32 v20, v20, v22, 1.0
	v_pk_add_f32 v[22:23], v[24:25], 1.0 op_sel_hi:[1,0]
	v_lshlrev_b32_e32 v18, 16, v44
	v_div_scale_f32 v24, s[8:9], v23, v23, 1.0
	v_rcp_f32_e32 v25, v24
	v_and_b32_e32 v19, 0xffff0000, v44
	v_pk_fma_f32 v[18:19], v[10:11], v[20:21], v[18:19]
	v_lshlrev_b32_e32 v10, 16, v45
	v_fma_f32 v20, -v24, v25, 1.0
	v_fmac_f32_e32 v25, v20, v25
	v_div_scale_f32 v20, vcc, 1.0, v23, 1.0
	v_mul_f32_e32 v21, v20, v25
	v_fma_f32 v26, -v24, v21, v20
	v_fmac_f32_e32 v21, v26, v25
	v_fma_f32 v20, -v24, v21, v20
	v_div_scale_f32 v24, s[8:9], v22, v22, 1.0
	v_rcp_f32_e32 v26, v24
	v_div_fmas_f32 v20, v20, v25, v21
	v_div_fixup_f32 v21, v20, v23, 1.0
	v_and_b32_e32 v11, 0xffff0000, v45
	v_fma_f32 v20, -v24, v26, 1.0
	v_fmac_f32_e32 v26, v20, v26
	v_div_scale_f32 v20, vcc, 1.0, v22, 1.0
	v_mul_f32_e32 v23, v20, v26
	v_fma_f32 v25, -v24, v23, v20
	v_fmac_f32_e32 v23, v25, v26
	v_fma_f32 v20, -v24, v23, v20
	v_div_fmas_f32 v20, v20, v26, v23
	v_div_fixup_f32 v20, v20, v22, 1.0
	v_pk_fma_f32 v[20:21], v[12:13], v[20:21], v[10:11]
	v_cvt_pk_bf16_f32 v10, v14, v15
	v_cvt_pk_bf16_f32 v11, v16, v17
	v_cvt_pk_bf16_f32 v12, v18, v19
	v_cvt_pk_bf16_f32 v13, v20, v21
	global_store_dwordx4 v[66:67], v[10:13], off sc1
	s_waitcnt vmcnt(3)
	v_lshlrev_b32_e32 v18, 16, v34
	v_and_b32_e32 v19, 0xffff0000, v34
	v_lshlrev_b32_e32 v10, 16, v38
	v_and_b32_e32 v11, 0xffff0000, v38
	v_mul_f32_e32 v10, 0xbfb8aa3b, v10
	v_mul_f32_e32 v11, 0xbfb8aa3b, v11
	v_exp_f32_e32 v10, v10
	v_exp_f32_e32 v11, v11
	v_lshlrev_b32_e32 v12, 16, v39
	v_and_b32_e32 v13, 0xffff0000, v39
	v_mul_f32_e32 v12, 0xbfb8aa3b, v12
	v_pk_add_f32 v[10:11], v[10:11], 1.0 op_sel_hi:[1,0]
	v_mul_f32_e32 v13, 0xbfb8aa3b, v13
	v_div_scale_f32 v20, s[8:9], v11, v11, 1.0
	v_rcp_f32_e32 v21, v20
	v_exp_f32_e32 v12, v12
	v_exp_f32_e32 v13, v13
	v_lshlrev_b32_e32 v14, 16, v40
	v_fma_f32 v22, -v20, v21, 1.0
	v_fmac_f32_e32 v21, v22, v21
	v_div_scale_f32 v22, vcc, 1.0, v11, 1.0
	v_mul_f32_e32 v23, v22, v21
	v_fma_f32 v24, -v20, v23, v22
	v_fmac_f32_e32 v23, v24, v21
	v_fma_f32 v20, -v20, v23, v22
	v_div_scale_f32 v22, s[8:9], v10, v10, 1.0
	v_rcp_f32_e32 v24, v22
	v_div_fmas_f32 v20, v20, v21, v23
	v_div_fixup_f32 v11, v20, v11, 1.0
	v_pk_add_f32 v[12:13], v[12:13], 1.0 op_sel_hi:[1,0]
	v_fma_f32 v20, -v22, v24, 1.0
	v_fmac_f32_e32 v24, v20, v24
	v_div_scale_f32 v20, vcc, 1.0, v10, 1.0
	v_mul_f32_e32 v21, v20, v24
	v_fma_f32 v23, -v22, v21, v20
	v_fmac_f32_e32 v21, v23, v24
	v_fma_f32 v20, -v22, v21, v20
	v_div_fmas_f32 v20, v20, v24, v21
	v_div_fixup_f32 v10, v20, v10, 1.0
	v_div_scale_f32 v20, s[8:9], v13, v13, 1.0
	v_rcp_f32_e32 v21, v20
	v_pk_fma_f32 v[6:7], v[6:7], v[10:11], v[18:19]
	v_and_b32_e32 v15, 0xffff0000, v40
	v_mul_f32_e32 v14, 0xbfb8aa3b, v14
	v_fma_f32 v18, -v20, v21, 1.0
	v_fmac_f32_e32 v21, v18, v21
	v_div_scale_f32 v18, vcc, 1.0, v13, 1.0
	v_mul_f32_e32 v19, v18, v21
	v_fma_f32 v22, -v20, v19, v18
	v_fmac_f32_e32 v19, v22, v21
	v_fma_f32 v18, -v20, v19, v18
	v_div_scale_f32 v20, s[8:9], v12, v12, 1.0
	v_rcp_f32_e32 v22, v20
	v_div_fmas_f32 v18, v18, v21, v19
	v_div_fixup_f32 v13, v18, v13, 1.0
	v_mul_f32_e32 v15, 0xbfb8aa3b, v15
	v_fma_f32 v18, -v20, v22, 1.0
	v_fmac_f32_e32 v22, v18, v22
	v_div_scale_f32 v18, vcc, 1.0, v12, 1.0
	v_exp_f32_e32 v14, v14
	v_exp_f32_e32 v15, v15
	v_mul_f32_e32 v19, v18, v22
	v_fma_f32 v21, -v20, v19, v18
	v_fmac_f32_e32 v19, v21, v22
	v_fma_f32 v18, -v20, v19, v18
	v_div_fmas_f32 v18, v18, v22, v19
	v_pk_add_f32 v[14:15], v[14:15], 1.0 op_sel_hi:[1,0]
	v_div_fixup_f32 v12, v18, v12, 1.0
	v_div_scale_f32 v18, s[8:9], v15, v15, 1.0
	v_rcp_f32_e32 v19, v18
	v_lshlrev_b32_e32 v10, 16, v35
	v_and_b32_e32 v11, 0xffff0000, v35
	v_pk_fma_f32 v[8:9], v[8:9], v[12:13], v[10:11]
	v_fma_f32 v12, -v18, v19, 1.0
	v_fmac_f32_e32 v19, v12, v19
	v_div_scale_f32 v12, vcc, 1.0, v15, 1.0
	v_mul_f32_e32 v13, v12, v19
	v_fma_f32 v20, -v18, v13, v12
	v_fmac_f32_e32 v13, v20, v19
	v_fma_f32 v12, -v18, v13, v12
	v_div_scale_f32 v18, s[8:9], v14, v14, 1.0
	v_rcp_f32_e32 v20, v18
	v_div_fmas_f32 v12, v12, v19, v13
	v_div_fixup_f32 v13, v12, v15, 1.0
	v_lshlrev_b32_e32 v16, 16, v41
	v_fma_f32 v12, -v18, v20, 1.0
	v_and_b32_e32 v17, 0xffff0000, v41
	v_fmac_f32_e32 v20, v12, v20
	v_div_scale_f32 v12, vcc, 1.0, v14, 1.0
	v_mul_f32_e32 v16, 0xbfb8aa3b, v16
	v_mul_f32_e32 v17, 0xbfb8aa3b, v17
	v_mul_f32_e32 v15, v12, v20
	v_exp_f32_e32 v16, v16
	v_exp_f32_e32 v17, v17
	v_fma_f32 v19, -v18, v15, v12
	v_fmac_f32_e32 v15, v19, v20
	v_fma_f32 v12, -v18, v15, v12
	v_div_fmas_f32 v12, v12, v20, v15
	v_div_fixup_f32 v12, v12, v14, 1.0
	v_pk_add_f32 v[14:15], v[16:17], 1.0 op_sel_hi:[1,0]
	v_lshlrev_b32_e32 v10, 16, v36
	v_div_scale_f32 v16, s[8:9], v15, v15, 1.0
	v_rcp_f32_e32 v17, v16
	v_and_b32_e32 v11, 0xffff0000, v36
	v_pk_fma_f32 v[10:11], v[2:3], v[12:13], v[10:11]
	v_lshlrev_b32_e32 v2, 16, v37
	v_fma_f32 v12, -v16, v17, 1.0
	v_fmac_f32_e32 v17, v12, v17
	v_div_scale_f32 v12, vcc, 1.0, v15, 1.0
	v_mul_f32_e32 v13, v12, v17
	v_fma_f32 v18, -v16, v13, v12
	v_fmac_f32_e32 v13, v18, v17
	v_fma_f32 v12, -v16, v13, v12
	v_div_scale_f32 v16, s[8:9], v14, v14, 1.0
	v_rcp_f32_e32 v18, v16
	v_div_fmas_f32 v12, v12, v17, v13
	v_div_fixup_f32 v13, v12, v15, 1.0
	v_and_b32_e32 v3, 0xffff0000, v37
	v_fma_f32 v12, -v16, v18, 1.0
	v_fmac_f32_e32 v18, v12, v18
	v_div_scale_f32 v12, vcc, 1.0, v14, 1.0
	v_mul_f32_e32 v15, v12, v18
	v_fma_f32 v17, -v16, v15, v12
	v_fmac_f32_e32 v15, v17, v18
	v_fma_f32 v12, -v16, v15, v12
	v_div_fmas_f32 v12, v12, v18, v15
	v_div_fixup_f32 v12, v12, v14, 1.0
	v_pk_fma_f32 v[12:13], v[4:5], v[12:13], v[2:3]
	v_cvt_pk_bf16_f32 v2, v6, v7
	v_cvt_pk_bf16_f32 v3, v8, v9
	v_cvt_pk_bf16_f32 v4, v10, v11
	v_cvt_pk_bf16_f32 v5, v12, v13
	s_andn2_b64 vcc, exec, s[6:7]
	s_mov_b64 s[6:7], -1
	global_store_dwordx4 v[66:67], v[2:5], off offset:256 sc1
	s_cbranch_vccnz .LBB0_718
	s_andn2_b64 vcc, exec, s[12:13]
	s_cbranch_vccnz .LBB0_717
	s_barrier
	s_branch .LBB0_717

.LBB0_810:
	v_lshl_add_u32 v164, s42, 8, v1
	v_lshl_or_b32 v162, s12, 8, v171
	v_ashrrev_i32_e32 v165, 31, v164
	v_ashrrev_i32_e32 v163, 31, v162
	v_lshlrev_b64 v[130:131], 13, v[164:165]
	v_lshl_add_u64 v[130:131], s[36:37], 0, v[130:131]
	v_lshlrev_b64 v[132:133], 2, v[162:163]
	v_lshl_add_u64 v[130:131], v[130:131], 0, v[132:133]
	global_load_dwordx4 v[178:181], v[130:131], off
	global_load_dwordx4 v[182:185], v[130:131], off offset:16
	global_load_dwordx4 v[186:189], v[130:131], off offset:512
	global_load_dwordx4 v[190:193], v[130:131], off offset:528
	v_or_b32_e32 v166, 16, v164
	v_ashrrev_i32_e32 v167, 31, v166
	v_lshlrev_b64 v[130:131], 13, v[166:167]
	v_lshl_add_u64 v[130:131], s[36:37], 0, v[130:131]
	v_lshl_add_u64 v[134:135], v[130:131], 0, v[132:133]
	global_load_dwordx4 v[138:141], v[134:135], off offset:16
	global_load_dwordx4 v[142:145], v[134:135], off
	global_load_dwordx4 v[130:133], v[134:135], off offset:528
	s_nop 0
	global_load_dwordx4 v[134:137], v[134:135], off offset:512
	v_and_b32_e32 v169, 64, v175
	v_xor_b32_e32 v168, 16, v175
	v_add_u32_e32 v169, 64, v169
	v_cmp_lt_i32_e32 vcc, v168, v169
	v_xor_b32_e32 v176, 32, v175
	s_lshl_b32 s42, s12, 2
	v_cndmask_b32_e32 v177, v175, v168, vcc
	v_lshlrev_b32_e32 v177, 2, v177
	v_cmp_lt_i32_e32 vcc, v176, v169
	v_lshlrev_b64 v[168:169], 12, v[164:165]
	s_ashr_i32 s43, s42, 31
	v_cndmask_b32_e32 v176, v175, v176, vcc
	v_lshlrev_b32_e32 v176, 2, v176
	s_waitcnt vmcnt(0)
	v_pk_add_f32 v[128:129], v[128:129], v[180:181]
	v_pk_add_f32 v[126:127], v[126:127], v[178:179]
	v_pk_add_f32 v[122:123], v[122:123], v[182:183]
	v_pk_add_f32 v[118:119], v[118:119], v[186:187]
	v_pk_add_f32 v[180:181], v[114:115], v[190:191]
	v_pk_add_f32 v[178:179], v[116:117], v[192:193]
	v_mul_f32_e32 v182, v127, v127
	v_mul_f32_e32 v183, v123, v123
	v_cvt_pk_bf16_f32 v114, v126, v127
	v_cvt_pk_bf16_f32 v116, v122, v123
	v_mul_f32_e32 v123, v119, v119
	v_mul_f32_e32 v127, v181, v181
	v_pk_add_f32 v[124:125], v[124:125], v[184:185]
	v_pk_add_f32 v[120:121], v[120:121], v[188:189]
	v_fmac_f32_e32 v182, v126, v126
	v_fmac_f32_e32 v183, v122, v122
	v_fmac_f32_e32 v123, v118, v118
	v_fmac_f32_e32 v127, v180, v180
	v_fmac_f32_e32 v182, v128, v128
	v_fmac_f32_e32 v183, v124, v124
	v_fmac_f32_e32 v123, v120, v120
	v_fmac_f32_e32 v127, v178, v178
	v_fmac_f32_e32 v182, v129, v129
	v_fmac_f32_e32 v183, v125, v125
	v_fmac_f32_e32 v123, v121, v121
	v_fmac_f32_e32 v127, v179, v179
	v_add_f32_e32 v122, v182, v183
	v_add_f32_e32 v123, v123, v127
	v_cvt_pk_bf16_f32 v117, v124, v125
	v_add_f32_e32 v124, v122, v123
	ds_bpermute_b32 v125, v177, v124
	v_lshl_add_u64 v[122:123], s[16:17], 0, v[168:169]
	v_cvt_pk_bf16_f32 v115, v128, v129
	v_lshl_add_u64 v[122:123], v[162:163], 1, v[122:123]
	global_store_dwordx4 v[122:123], v[114:117], off sc1
	s_waitcnt lgkmcnt(0)
	s_nop 0
	v_add_f32_e32 v114, v124, v125
	ds_bpermute_b32 v115, v176, v114
	v_cvt_pk_bf16_f32 v116, v118, v119
	v_cvt_pk_bf16_f32 v117, v120, v121
	v_cvt_pk_bf16_f32 v118, v180, v181
	v_cvt_pk_bf16_f32 v119, v178, v179
	global_store_dwordx4 v[122:123], v[116:119], off offset:256 sc1
	s_and_saveexec_b64 s[44:45], s[6:7]
	s_cbranch_execz .LBB0_812
	v_lshlrev_b64 v[116:117], 7, v[164:165]
	v_lshl_add_u64 v[116:117], s[18:19], 0, v[116:117]
	v_lshl_add_u64 v[116:117], s[42:43], 2, v[116:117]
	s_lshl_b32 s12, s75, 2
	v_lshl_add_u64 v[116:117], v[116:117], 0, s[12:13]
	s_waitcnt lgkmcnt(0)
	v_add_f32_e32 v114, v114, v115
	global_store_dword v[116:117], v114, off
.LBB0_812:
	s_or_b64 exec, exec, s[44:45]
	v_or_b32_e32 v168, 32, v164
	v_ashrrev_i32_e32 v169, 31, v168
	s_waitcnt lgkmcnt(0)
	v_lshlrev_b64 v[114:115], 13, v[168:169]
	v_lshl_add_u64 v[114:115], s[36:37], 0, v[114:115]
	v_lshl_add_u64 v[118:119], v[162:163], 2, v[114:115]
	global_load_dwordx4 v[122:125], v[118:119], off offset:16
	global_load_dwordx4 v[126:129], v[118:119], off
	global_load_dwordx4 v[114:117], v[118:119], off offset:528
	s_nop 0
	global_load_dwordx4 v[118:121], v[118:119], off offset:512
	v_pk_add_f32 v[110:111], v[110:111], v[142:143]
	v_pk_add_f32 v[140:141], v[108:109], v[140:141]
	v_pk_add_f32 v[108:109], v[106:107], v[138:139]
	v_mul_f32_e32 v106, v111, v111
	v_mul_f32_e32 v107, v109, v109
	v_pk_add_f32 v[112:113], v[112:113], v[144:145]
	v_fmac_f32_e32 v106, v110, v110
	v_fmac_f32_e32 v107, v108, v108
	v_fmac_f32_e32 v106, v112, v112
	v_fmac_f32_e32 v107, v140, v140
	v_fmac_f32_e32 v106, v113, v113
	v_fmac_f32_e32 v107, v141, v141
	v_add_f32_e32 v138, v106, v107
	v_cvt_pk_bf16_f32 v107, v112, v113
	v_pk_add_f32 v[102:103], v[102:103], v[134:135]
	v_pk_add_f32 v[112:113], v[98:99], v[130:131]
	v_mul_f32_e32 v98, v103, v103
	v_mul_f32_e32 v99, v113, v113
	v_cvt_pk_bf16_f32 v106, v110, v111
	v_pk_add_f32 v[104:105], v[104:105], v[136:137]
	v_pk_add_f32 v[110:111], v[100:101], v[132:133]
	v_fmac_f32_e32 v98, v102, v102
	v_fmac_f32_e32 v99, v112, v112
	v_fmac_f32_e32 v98, v104, v104
	v_fmac_f32_e32 v99, v110, v110
	v_fmac_f32_e32 v98, v105, v105
	v_fmac_f32_e32 v99, v111, v111
	v_add_f32_e32 v98, v98, v99
	v_add_f32_e32 v101, v138, v98
	ds_bpermute_b32 v132, v177, v101
	v_lshlrev_b64 v[178:179], 12, v[166:167]
	v_lshl_add_u64 v[98:99], s[16:17], 0, v[178:179]
	v_lshl_add_u64 v[130:131], v[162:163], 1, v[98:99]
	v_cvt_pk_bf16_f32 v108, v108, v109
	s_waitcnt lgkmcnt(0)
	v_add_f32_e32 v98, v101, v132
	ds_bpermute_b32 v99, v176, v98
	v_cvt_pk_bf16_f32 v109, v140, v141
	v_cvt_pk_bf16_f32 v100, v102, v103
	v_cvt_pk_bf16_f32 v101, v104, v105
	v_cvt_pk_bf16_f32 v102, v112, v113
	v_cvt_pk_bf16_f32 v103, v110, v111
	global_store_dwordx4 v[130:131], v[106:109], off sc1
	global_store_dwordx4 v[130:131], v[100:103], off offset:256 sc1
	s_and_saveexec_b64 s[44:45], s[6:7]
	s_cbranch_execz .LBB0_814
	v_lshlrev_b64 v[100:101], 7, v[166:167]
	v_lshl_add_u64 v[100:101], s[18:19], 0, v[100:101]
	v_lshl_add_u64 v[100:101], s[42:43], 2, v[100:101]
	s_lshl_b32 s12, s75, 2
	v_lshl_add_u64 v[100:101], v[100:101], 0, s[12:13]
	s_waitcnt lgkmcnt(0)
	v_add_f32_e32 v98, v98, v99
	global_store_dword v[100:101], v98, off
.LBB0_814:
	s_or_b64 exec, exec, s[44:45]
	v_or_b32_e32 v130, 48, v164
	v_ashrrev_i32_e32 v131, 31, v130
	s_waitcnt lgkmcnt(0)
	v_lshlrev_b64 v[98:99], 13, v[130:131]
	v_lshl_add_u64 v[98:99], s[36:37], 0, v[98:99]
	v_lshl_add_u64 v[102:103], v[162:163], 2, v[98:99]
	global_load_dwordx4 v[106:109], v[102:103], off offset:16
	global_load_dwordx4 v[110:113], v[102:103], off
	global_load_dwordx4 v[98:101], v[102:103], off offset:528
	s_nop 0
	global_load_dwordx4 v[102:105], v[102:103], off offset:512
	s_waitcnt vmcnt(8)
	v_pk_add_f32 v[94:95], v[94:95], v[126:127]
	v_pk_add_f32 v[124:125], v[92:93], v[124:125]
	v_pk_add_f32 v[92:93], v[90:91], v[122:123]
	v_mul_f32_e32 v90, v95, v95
	v_mul_f32_e32 v91, v93, v93
	v_pk_add_f32 v[96:97], v[96:97], v[128:129]
	v_fmac_f32_e32 v90, v94, v94
	v_fmac_f32_e32 v91, v92, v92
	v_fmac_f32_e32 v90, v96, v96
	v_fmac_f32_e32 v91, v124, v124
	v_fmac_f32_e32 v90, v97, v97
	v_fmac_f32_e32 v91, v125, v125
	v_add_f32_e32 v122, v90, v91
	v_cvt_pk_bf16_f32 v91, v96, v97
	s_waitcnt vmcnt(6)
	v_pk_add_f32 v[86:87], v[86:87], v[118:119]
	v_pk_add_f32 v[96:97], v[82:83], v[114:115]
	v_mul_f32_e32 v82, v87, v87
	v_mul_f32_e32 v83, v97, v97
	v_cvt_pk_bf16_f32 v90, v94, v95
	v_pk_add_f32 v[88:89], v[88:89], v[120:121]
	v_pk_add_f32 v[94:95], v[84:85], v[116:117]
	v_fmac_f32_e32 v82, v86, v86
	v_fmac_f32_e32 v83, v96, v96
	v_fmac_f32_e32 v82, v88, v88
	v_fmac_f32_e32 v83, v94, v94
	v_fmac_f32_e32 v82, v89, v89
	v_fmac_f32_e32 v83, v95, v95
	v_add_f32_e32 v82, v82, v83
	v_add_f32_e32 v85, v122, v82
	ds_bpermute_b32 v116, v177, v85
	v_lshlrev_b64 v[132:133], 12, v[168:169]
	v_lshl_add_u64 v[82:83], s[16:17], 0, v[132:133]
	v_lshl_add_u64 v[114:115], v[162:163], 1, v[82:83]
	v_cvt_pk_bf16_f32 v92, v92, v93
	s_waitcnt lgkmcnt(0)
	v_add_f32_e32 v82, v85, v116
	ds_bpermute_b32 v83, v176, v82
	v_cvt_pk_bf16_f32 v93, v124, v125
	v_cvt_pk_bf16_f32 v84, v86, v87
	v_cvt_pk_bf16_f32 v85, v88, v89
	v_cvt_pk_bf16_f32 v86, v96, v97
	v_cvt_pk_bf16_f32 v87, v94, v95
	global_store_dwordx4 v[114:115], v[90:93], off sc1
	global_store_dwordx4 v[114:115], v[84:87], off offset:256 sc1
	s_and_saveexec_b64 s[44:45], s[6:7]
	s_cbranch_execz .LBB0_816
	v_lshlrev_b64 v[84:85], 7, v[168:169]
	v_lshl_add_u64 v[84:85], s[18:19], 0, v[84:85]
	v_lshl_add_u64 v[84:85], s[42:43], 2, v[84:85]
	s_lshl_b32 s12, s75, 2
	v_lshl_add_u64 v[84:85], v[84:85], 0, s[12:13]
	s_waitcnt lgkmcnt(0)
	v_add_f32_e32 v82, v82, v83
	global_store_dword v[84:85], v82, off
.LBB0_816:
	s_or_b64 exec, exec, s[44:45]
	v_add_u32_e32 v114, 0x80, v164
	v_ashrrev_i32_e32 v115, 31, v114
	s_waitcnt lgkmcnt(0)
	v_lshlrev_b64 v[82:83], 13, v[114:115]
	v_lshl_add_u64 v[82:83], s[36:37], 0, v[82:83]
	v_lshl_add_u64 v[86:87], v[162:163], 2, v[82:83]
	global_load_dwordx4 v[90:93], v[86:87], off offset:16
	global_load_dwordx4 v[94:97], v[86:87], off
	global_load_dwordx4 v[82:85], v[86:87], off offset:528
	s_nop 0
	global_load_dwordx4 v[86:89], v[86:87], off offset:512
	s_waitcnt vmcnt(8)
	v_pk_add_f32 v[78:79], v[78:79], v[110:111]
	v_pk_add_f32 v[108:109], v[76:77], v[108:109]
	v_pk_add_f32 v[76:77], v[74:75], v[106:107]
	v_mul_f32_e32 v74, v79, v79
	v_mul_f32_e32 v75, v77, v77
	v_pk_add_f32 v[80:81], v[80:81], v[112:113]
	v_fmac_f32_e32 v74, v78, v78
	v_fmac_f32_e32 v75, v76, v76
	v_fmac_f32_e32 v74, v80, v80
	v_fmac_f32_e32 v75, v108, v108
	v_fmac_f32_e32 v74, v81, v81
	v_fmac_f32_e32 v75, v109, v109
	v_add_f32_e32 v106, v74, v75
	v_cvt_pk_bf16_f32 v75, v80, v81
	s_waitcnt vmcnt(6)
	v_pk_add_f32 v[70:71], v[70:71], v[102:103]
	v_pk_add_f32 v[80:81], v[66:67], v[98:99]
	v_mul_f32_e32 v66, v71, v71
	v_mul_f32_e32 v67, v81, v81
	v_cvt_pk_bf16_f32 v74, v78, v79
	v_pk_add_f32 v[72:73], v[72:73], v[104:105]
	v_pk_add_f32 v[78:79], v[68:69], v[100:101]
	v_fmac_f32_e32 v66, v70, v70
	v_fmac_f32_e32 v67, v80, v80
	v_fmac_f32_e32 v66, v72, v72
	v_fmac_f32_e32 v67, v78, v78
	v_fmac_f32_e32 v66, v73, v73
	v_fmac_f32_e32 v67, v79, v79
	v_add_f32_e32 v66, v66, v67
	v_add_f32_e32 v69, v106, v66
	ds_bpermute_b32 v100, v177, v69
	v_lshlrev_b64 v[116:117], 12, v[130:131]
	v_lshl_add_u64 v[66:67], s[16:17], 0, v[116:117]
	v_lshl_add_u64 v[98:99], v[162:163], 1, v[66:67]
	v_cvt_pk_bf16_f32 v76, v76, v77
	s_waitcnt lgkmcnt(0)
	v_add_f32_e32 v66, v69, v100
	ds_bpermute_b32 v67, v176, v66
	v_cvt_pk_bf16_f32 v77, v108, v109
	v_cvt_pk_bf16_f32 v68, v70, v71
	v_cvt_pk_bf16_f32 v69, v72, v73
	v_cvt_pk_bf16_f32 v70, v80, v81
	v_cvt_pk_bf16_f32 v71, v78, v79
	global_store_dwordx4 v[98:99], v[74:77], off sc1
	global_store_dwordx4 v[98:99], v[68:71], off offset:256 sc1
	s_and_saveexec_b64 s[44:45], s[6:7]
	s_cbranch_execz .LBB0_818
	v_lshlrev_b64 v[68:69], 7, v[130:131]
	v_lshl_add_u64 v[68:69], s[18:19], 0, v[68:69]
	v_lshl_add_u64 v[68:69], s[42:43], 2, v[68:69]
	s_lshl_b32 s12, s75, 2
	v_lshl_add_u64 v[68:69], v[68:69], 0, s[12:13]
	s_waitcnt lgkmcnt(0)
	v_add_f32_e32 v66, v66, v67
	global_store_dword v[68:69], v66, off
.LBB0_818:
	s_or_b64 exec, exec, s[44:45]
	v_or_b32_e32 v98, 16, v114
	v_ashrrev_i32_e32 v99, 31, v98
	s_waitcnt lgkmcnt(0)
	v_lshlrev_b64 v[66:67], 13, v[98:99]
	v_lshl_add_u64 v[66:67], s[36:37], 0, v[66:67]
	v_lshl_add_u64 v[70:71], v[162:163], 2, v[66:67]
	global_load_dwordx4 v[74:77], v[70:71], off offset:16
	global_load_dwordx4 v[78:81], v[70:71], off
	global_load_dwordx4 v[66:69], v[70:71], off offset:528
	s_nop 0
	global_load_dwordx4 v[70:73], v[70:71], off offset:512
	s_waitcnt vmcnt(8)
	v_pk_add_f32 v[62:63], v[62:63], v[94:95]
	v_pk_add_f32 v[92:93], v[60:61], v[92:93]
	v_pk_add_f32 v[60:61], v[58:59], v[90:91]
	v_mul_f32_e32 v58, v63, v63
	v_mul_f32_e32 v59, v61, v61
	v_pk_add_f32 v[64:65], v[64:65], v[96:97]
	v_fmac_f32_e32 v58, v62, v62
	v_fmac_f32_e32 v59, v60, v60
	v_fmac_f32_e32 v58, v64, v64
	v_fmac_f32_e32 v59, v92, v92
	v_fmac_f32_e32 v58, v65, v65
	v_fmac_f32_e32 v59, v93, v93
	v_add_f32_e32 v90, v58, v59
	v_cvt_pk_bf16_f32 v59, v64, v65
	s_waitcnt vmcnt(6)
	v_pk_add_f32 v[54:55], v[54:55], v[86:87]
	v_pk_add_f32 v[64:65], v[50:51], v[82:83]
	v_mul_f32_e32 v50, v55, v55
	v_mul_f32_e32 v51, v65, v65
	v_cvt_pk_bf16_f32 v58, v62, v63
	v_pk_add_f32 v[56:57], v[56:57], v[88:89]
	v_pk_add_f32 v[62:63], v[52:53], v[84:85]
	v_fmac_f32_e32 v50, v54, v54
	v_fmac_f32_e32 v51, v64, v64
	v_fmac_f32_e32 v50, v56, v56
	v_fmac_f32_e32 v51, v62, v62
	v_fmac_f32_e32 v50, v57, v57
	v_fmac_f32_e32 v51, v63, v63
	v_add_f32_e32 v50, v50, v51
	v_add_f32_e32 v53, v90, v50
	ds_bpermute_b32 v84, v177, v53
	v_lshlrev_b64 v[100:101], 12, v[114:115]
	v_lshl_add_u64 v[50:51], s[16:17], 0, v[100:101]
	v_lshl_add_u64 v[82:83], v[162:163], 1, v[50:51]
	v_cvt_pk_bf16_f32 v60, v60, v61
	s_waitcnt lgkmcnt(0)
	v_add_f32_e32 v50, v53, v84
	ds_bpermute_b32 v51, v176, v50
	v_cvt_pk_bf16_f32 v61, v92, v93
	v_cvt_pk_bf16_f32 v52, v54, v55
	v_cvt_pk_bf16_f32 v53, v56, v57
	v_cvt_pk_bf16_f32 v54, v64, v65
	v_cvt_pk_bf16_f32 v55, v62, v63
	global_store_dwordx4 v[82:83], v[58:61], off sc1
	global_store_dwordx4 v[82:83], v[52:55], off offset:256 sc1
	s_and_saveexec_b64 s[44:45], s[6:7]
	s_cbranch_execz .LBB0_820
	v_lshlrev_b64 v[52:53], 7, v[114:115]
	v_lshl_add_u64 v[52:53], s[18:19], 0, v[52:53]
	v_lshl_add_u64 v[52:53], s[42:43], 2, v[52:53]
	s_lshl_b32 s12, s75, 2
	v_lshl_add_u64 v[52:53], v[52:53], 0, s[12:13]
	s_waitcnt lgkmcnt(0)
	v_add_f32_e32 v50, v50, v51
	global_store_dword v[52:53], v50, off
.LBB0_820:
	s_or_b64 exec, exec, s[44:45]
	v_or_b32_e32 v82, 32, v114
	v_ashrrev_i32_e32 v83, 31, v82
	s_waitcnt lgkmcnt(0)
	v_lshlrev_b64 v[50:51], 13, v[82:83]
	v_lshl_add_u64 v[50:51], s[36:37], 0, v[50:51]
	v_lshl_add_u64 v[54:55], v[162:163], 2, v[50:51]
	global_load_dwordx4 v[58:61], v[54:55], off offset:16
	global_load_dwordx4 v[62:65], v[54:55], off
	global_load_dwordx4 v[50:53], v[54:55], off offset:528
	s_nop 0
	global_load_dwordx4 v[54:57], v[54:55], off offset:512
	s_waitcnt vmcnt(8)
	v_pk_add_f32 v[46:47], v[46:47], v[78:79]
	v_pk_add_f32 v[76:77], v[44:45], v[76:77]
	v_pk_add_f32 v[44:45], v[42:43], v[74:75]
	v_mul_f32_e32 v42, v47, v47
	v_mul_f32_e32 v43, v45, v45
	v_pk_add_f32 v[48:49], v[48:49], v[80:81]
	v_fmac_f32_e32 v42, v46, v46
	v_fmac_f32_e32 v43, v44, v44
	v_fmac_f32_e32 v42, v48, v48
	v_fmac_f32_e32 v43, v76, v76
	v_fmac_f32_e32 v42, v49, v49
	v_fmac_f32_e32 v43, v77, v77
	v_add_f32_e32 v74, v42, v43
	v_cvt_pk_bf16_f32 v43, v48, v49
	s_waitcnt vmcnt(6)
	v_pk_add_f32 v[38:39], v[38:39], v[70:71]
	v_pk_add_f32 v[48:49], v[34:35], v[66:67]
	v_mul_f32_e32 v34, v39, v39
	v_mul_f32_e32 v35, v49, v49
	v_cvt_pk_bf16_f32 v42, v46, v47
	v_pk_add_f32 v[40:41], v[40:41], v[72:73]
	v_pk_add_f32 v[46:47], v[36:37], v[68:69]
	v_fmac_f32_e32 v34, v38, v38
	v_fmac_f32_e32 v35, v48, v48
	v_fmac_f32_e32 v34, v40, v40
	v_fmac_f32_e32 v35, v46, v46
	v_fmac_f32_e32 v34, v41, v41
	v_fmac_f32_e32 v35, v47, v47
	v_add_f32_e32 v34, v34, v35
	v_add_f32_e32 v37, v74, v34
	ds_bpermute_b32 v68, v177, v37
	v_lshlrev_b64 v[84:85], 12, v[98:99]
	v_lshl_add_u64 v[34:35], s[16:17], 0, v[84:85]
	v_lshl_add_u64 v[66:67], v[162:163], 1, v[34:35]
	v_cvt_pk_bf16_f32 v44, v44, v45
	s_waitcnt lgkmcnt(0)
	v_add_f32_e32 v34, v37, v68
	ds_bpermute_b32 v35, v176, v34
	v_cvt_pk_bf16_f32 v45, v76, v77
	v_cvt_pk_bf16_f32 v36, v38, v39
	v_cvt_pk_bf16_f32 v37, v40, v41
	v_cvt_pk_bf16_f32 v38, v48, v49
	v_cvt_pk_bf16_f32 v39, v46, v47
	global_store_dwordx4 v[66:67], v[42:45], off sc1
	global_store_dwordx4 v[66:67], v[36:39], off offset:256 sc1
	s_and_saveexec_b64 s[44:45], s[6:7]
	s_cbranch_execz .LBB0_822
	v_lshlrev_b64 v[36:37], 7, v[98:99]
	v_lshl_add_u64 v[36:37], s[18:19], 0, v[36:37]
	v_lshl_add_u64 v[36:37], s[42:43], 2, v[36:37]
	s_lshl_b32 s12, s75, 2
	v_lshl_add_u64 v[36:37], v[36:37], 0, s[12:13]
	s_waitcnt lgkmcnt(0)
	v_add_f32_e32 v34, v34, v35
	global_store_dword v[36:37], v34, off
.LBB0_822:
	s_or_b64 exec, exec, s[44:45]
	v_or_b32_e32 v66, 48, v114
	v_ashrrev_i32_e32 v67, 31, v66
	s_waitcnt lgkmcnt(0)
	v_lshlrev_b64 v[34:35], 13, v[66:67]
	v_lshl_add_u64 v[34:35], s[36:37], 0, v[34:35]
	v_lshl_add_u64 v[38:39], v[162:163], 2, v[34:35]
	global_load_dwordx4 v[42:45], v[38:39], off offset:16
	global_load_dwordx4 v[46:49], v[38:39], off
	global_load_dwordx4 v[34:37], v[38:39], off offset:528
	s_nop 0
	global_load_dwordx4 v[38:41], v[38:39], off offset:512
	s_waitcnt vmcnt(8)
	v_pk_add_f32 v[30:31], v[30:31], v[62:63]
	v_pk_add_f32 v[60:61], v[28:29], v[60:61]
	v_pk_add_f32 v[28:29], v[26:27], v[58:59]
	v_mul_f32_e32 v26, v31, v31
	v_mul_f32_e32 v27, v29, v29
	v_pk_add_f32 v[32:33], v[32:33], v[64:65]
	v_fmac_f32_e32 v26, v30, v30
	v_fmac_f32_e32 v27, v28, v28
	v_fmac_f32_e32 v26, v32, v32
	v_fmac_f32_e32 v27, v60, v60
	v_fmac_f32_e32 v26, v33, v33
	v_fmac_f32_e32 v27, v61, v61
	v_add_f32_e32 v58, v26, v27
	v_cvt_pk_bf16_f32 v27, v32, v33
	s_waitcnt vmcnt(6)
	v_pk_add_f32 v[22:23], v[22:23], v[54:55]
	v_pk_add_f32 v[32:33], v[18:19], v[50:51]
	v_mul_f32_e32 v18, v23, v23
	v_mul_f32_e32 v19, v33, v33
	v_cvt_pk_bf16_f32 v26, v30, v31
	v_pk_add_f32 v[24:25], v[24:25], v[56:57]
	v_pk_add_f32 v[30:31], v[20:21], v[52:53]
	v_fmac_f32_e32 v18, v22, v22
	v_fmac_f32_e32 v19, v32, v32
	v_fmac_f32_e32 v18, v24, v24
	v_fmac_f32_e32 v19, v30, v30
	v_fmac_f32_e32 v18, v25, v25
	v_fmac_f32_e32 v19, v31, v31
	v_add_f32_e32 v18, v18, v19
	v_add_f32_e32 v21, v58, v18
	ds_bpermute_b32 v52, v177, v21
	v_lshlrev_b64 v[68:69], 12, v[82:83]
	v_lshl_add_u64 v[18:19], s[16:17], 0, v[68:69]
	v_lshl_add_u64 v[50:51], v[162:163], 1, v[18:19]
	v_cvt_pk_bf16_f32 v28, v28, v29
	s_waitcnt lgkmcnt(0)
	v_add_f32_e32 v18, v21, v52
	ds_bpermute_b32 v19, v176, v18
	v_cvt_pk_bf16_f32 v29, v60, v61
	v_cvt_pk_bf16_f32 v20, v22, v23
	v_cvt_pk_bf16_f32 v21, v24, v25
	v_cvt_pk_bf16_f32 v22, v32, v33
	v_cvt_pk_bf16_f32 v23, v30, v31
	global_store_dwordx4 v[50:51], v[26:29], off sc1
	global_store_dwordx4 v[50:51], v[20:23], off offset:256 sc1
	s_and_saveexec_b64 s[44:45], s[6:7]
	s_cbranch_execz .LBB0_824
	v_lshlrev_b64 v[20:21], 7, v[82:83]
	v_lshl_add_u64 v[20:21], s[18:19], 0, v[20:21]
	v_lshl_add_u64 v[20:21], s[42:43], 2, v[20:21]
	s_lshl_b32 s12, s75, 2
	v_lshl_add_u64 v[20:21], v[20:21], 0, s[12:13]
	s_waitcnt lgkmcnt(0)
	v_add_f32_e32 v18, v18, v19
	global_store_dword v[20:21], v18, off
.LBB0_824:
	s_or_b64 exec, exec, s[44:45]
	s_waitcnt vmcnt(4)
	v_pk_add_f32 v[14:15], v[14:15], v[46:47]
	v_pk_add_f32 v[20:21], v[12:13], v[44:45]
	v_pk_add_f32 v[12:13], v[10:11], v[42:43]
	v_mul_f32_e32 v10, v15, v15
	v_mul_f32_e32 v11, v13, v13
	v_pk_add_f32 v[16:17], v[16:17], v[48:49]
	v_fmac_f32_e32 v10, v14, v14
	v_fmac_f32_e32 v11, v12, v12
	v_fmac_f32_e32 v10, v16, v16
	v_fmac_f32_e32 v11, v20, v20
	v_fmac_f32_e32 v10, v17, v17
	v_fmac_f32_e32 v11, v21, v21
	v_add_f32_e32 v22, v10, v11
	v_cvt_pk_bf16_f32 v11, v16, v17
	s_waitcnt vmcnt(2)
	v_pk_add_f32 v[6:7], v[6:7], v[38:39]
	v_pk_add_f32 v[16:17], v[2:3], v[34:35]
	v_mul_f32_e32 v2, v7, v7
	v_mul_f32_e32 v3, v17, v17
	v_cvt_pk_bf16_f32 v10, v14, v15
	v_pk_add_f32 v[8:9], v[8:9], v[40:41]
	v_pk_add_f32 v[14:15], v[4:5], v[36:37]
	v_fmac_f32_e32 v2, v6, v6
	v_fmac_f32_e32 v3, v16, v16
	v_fmac_f32_e32 v2, v8, v8
	v_fmac_f32_e32 v3, v14, v14
	v_fmac_f32_e32 v2, v9, v9
	v_fmac_f32_e32 v3, v15, v15
	v_add_f32_e32 v2, v2, v3
	v_add_f32_e32 v5, v22, v2
	v_cvt_pk_bf16_f32 v12, v12, v13
	v_cvt_pk_bf16_f32 v13, v20, v21
	ds_bpermute_b32 v20, v177, v5
	s_waitcnt lgkmcnt(1)
	v_lshlrev_b64 v[18:19], 12, v[66:67]
	v_lshl_add_u64 v[2:3], s[16:17], 0, v[18:19]
	v_lshl_add_u64 v[18:19], v[162:163], 1, v[2:3]
	v_cvt_pk_bf16_f32 v4, v6, v7
	s_waitcnt lgkmcnt(0)
	v_add_f32_e32 v2, v5, v20
	ds_bpermute_b32 v3, v176, v2
	v_cvt_pk_bf16_f32 v5, v8, v9
	v_cvt_pk_bf16_f32 v6, v16, v17
	v_cvt_pk_bf16_f32 v7, v14, v15
	global_store_dwordx4 v[18:19], v[10:13], off sc1
	global_store_dwordx4 v[18:19], v[4:7], off offset:256 sc1
	s_and_saveexec_b64 s[44:45], s[6:7]
	s_cbranch_execz .LBB0_826
	v_lshlrev_b64 v[4:5], 7, v[66:67]
	v_lshl_add_u64 v[4:5], s[18:19], 0, v[4:5]
	v_lshl_add_u64 v[4:5], s[42:43], 2, v[4:5]
	s_lshl_b32 s12, s75, 2
	v_lshl_add_u64 v[4:5], v[4:5], 0, s[12:13]
	s_waitcnt lgkmcnt(0)
	v_add_f32_e32 v2, v2, v3
	global_store_dword v[4:5], v2, off

.LBB0_897:
	v_lshl_add_u32 v168, s8, 8, v182
	v_ashrrev_i32_e32 v169, 31, v168
	v_or_b32_e32 v164, 16, v168
	v_lshlrev_b64 v[130:131], 7, v[168:169]
	v_ashrrev_i32_e32 v165, 31, v164
	v_lshl_add_u64 v[130:131], v[154:155], 0, v[130:131]
	v_lshlrev_b64 v[138:139], 7, v[164:165]
	global_load_dwordx4 v[134:137], v[130:131], off
	s_nop 0
	global_load_dwordx4 v[130:133], v[130:131], off offset:16
	v_lshl_add_u64 v[138:139], v[154:155], 0, v[138:139]
	global_load_dwordx4 v[142:145], v[138:139], off
	s_nop 0
	global_load_dwordx4 v[138:141], v[138:139], off offset:16
	v_or_b32_e32 v174, 32, v168
	v_ashrrev_i32_e32 v175, 31, v174
	v_lshlrev_b64 v[166:167], 7, v[174:175]
	v_lshl_add_u64 v[166:167], v[154:155], 0, v[166:167]
	global_load_dwordx4 v[190:193], v[166:167], off
	global_load_dwordx4 v[194:197], v[166:167], off offset:16
	v_or_b32_e32 v166, 48, v168
	v_ashrrev_i32_e32 v167, 31, v166
	v_lshlrev_b64 v[170:171], 7, v[166:167]
	v_lshl_add_u64 v[170:171], v[154:155], 0, v[170:171]
	global_load_dwordx4 v[198:201], v[170:171], off
	global_load_dwordx4 v[202:205], v[170:171], off offset:16
	v_add_u32_e32 v176, 0x80, v168
	v_add_u32_e32 v170, 0x90, v168
	v_add_u32_e32 v178, 0xa0, v168
	v_add_u32_e32 v172, 0xb0, v168
	v_ashrrev_i32_e32 v177, 31, v176
	v_ashrrev_i32_e32 v171, 31, v170
	v_ashrrev_i32_e32 v179, 31, v178
	v_ashrrev_i32_e32 v173, 31, v172
	v_lshlrev_b64 v[206:207], 7, v[176:177]
	v_lshlrev_b64 v[208:209], 7, v[170:171]
	v_lshlrev_b64 v[210:211], 7, v[178:179]
	v_lshlrev_b64 v[212:213], 7, v[172:173]
	v_lshl_add_u64 v[214:215], v[154:155], 0, v[206:207]
	v_lshl_add_u64 v[218:219], v[154:155], 0, v[208:209]
	v_lshl_add_u64 v[226:227], v[154:155], 0, v[210:211]
	v_lshl_add_u64 v[234:235], v[154:155], 0, v[212:213]
	global_load_dwordx4 v[206:209], v[214:215], off
	global_load_dwordx4 v[210:213], v[214:215], off offset:16
	s_nop 0
	global_load_dwordx4 v[214:217], v[218:219], off
	s_nop 0
	global_load_dwordx4 v[218:221], v[218:219], off offset:16
	s_nop 0
	global_load_dwordx4 v[222:225], v[226:227], off
	s_nop 0
	global_load_dwordx4 v[226:229], v[226:227], off offset:16
	s_nop 0
	global_load_dwordx4 v[230:233], v[234:235], off
	s_nop 0
	global_load_dwordx4 v[234:237], v[234:235], off offset:16
	v_and_b32_e32 v167, 64, v188
	v_xor_b32_e32 v165, 16, v188
	v_add_u32_e32 v167, 64, v167
	v_cmp_lt_i32_e32 vcc, v165, v167
	v_xor_b32_e32 v169, 32, v188
	v_mov_b64_e32 v[180:181], s[26:27]
	v_cndmask_b32_e32 v165, v188, v165, vcc
	v_lshlrev_b32_e32 v165, 2, v165
	v_cmp_lt_i32_e32 vcc, v169, v167
	s_waitcnt vmcnt(0)
	v_mov_b32_e32 v238, v134
	v_mov_b32_e32 v239, v130
	v_mov_b32_e32 v130, v135
	v_mov_b32_e32 v134, v136
	v_mov_b32_e32 v135, v132
	v_mov_b32_e32 v132, v137
	v_pk_add_f32 v[130:131], v[238:239], v[130:131]
	v_pk_add_f32 v[132:133], v[134:135], v[132:133]
	v_mov_b32_e32 v134, v142
	v_mov_b32_e32 v135, v138
	v_mov_b32_e32 v138, v143
	v_mov_b32_e32 v136, v144
	v_mov_b32_e32 v137, v140
	v_mov_b32_e32 v140, v145
	v_pk_add_f32 v[130:131], v[130:131], v[132:133]
	v_pk_add_f32 v[132:133], v[134:135], v[138:139]
	v_pk_add_f32 v[134:135], v[136:137], v[140:141]
	v_cndmask_b32_e32 v167, v188, v169, vcc
	v_pk_add_f32 v[132:133], v[132:133], v[134:135]
	v_mov_b32_e32 v135, v130
	v_mov_b32_e32 v134, v132
	v_mov_b32_e32 v130, v133
	v_pk_add_f32 v[130:131], v[134:135], v[130:131]
	ds_bpermute_b32 v133, v165, v131
	ds_bpermute_b32 v132, v165, v130
	v_lshlrev_b32_e32 v167, 2, v167
	v_mov_b32_e32 v142, v190
	v_mov_b32_e32 v143, v194
	v_mov_b32_e32 v194, v191
	s_waitcnt lgkmcnt(0)
	v_pk_add_f32 v[130:131], v[130:131], v[132:133]
	ds_bpermute_b32 v133, v167, v131
	ds_bpermute_b32 v132, v167, v130
	v_mov_b32_e32 v144, v192
	v_mov_b32_e32 v145, v196
	v_mov_b32_e32 v196, v193
	v_mov_b32_e32 v134, v198
	s_waitcnt lgkmcnt(0)
	v_pk_add_f32 v[130:131], v[130:131], v[132:133]
	v_mov_b32_e32 v135, v202
	v_pk_fma_f32 v[130:131], v[130:131], s[24:25], v[180:181] op_sel_hi:[1,0,0]
	v_mov_b32_e32 v202, v199
	v_mov_b32_e32 v136, v200
	v_mul_f32_e32 v132, 0x4b800000, v131
	v_cmp_gt_f32_e32 vcc, s77, v131
	v_mov_b32_e32 v137, v204
	v_mov_b32_e32 v204, v201
	v_pk_add_f32 v[138:139], v[142:143], v[194:195]
	v_pk_add_f32 v[140:141], v[144:145], v[196:197]
	v_pk_add_f32 v[134:135], v[134:135], v[202:203]
	v_cndmask_b32_e32 v131, v131, v132, vcc
	v_pk_add_f32 v[132:133], v[136:137], v[204:205]
	v_pk_add_f32 v[138:139], v[138:139], v[140:141]
	v_pk_add_f32 v[132:133], v[134:135], v[132:133]
	v_mov_b32_e32 v135, v138
	v_mov_b32_e32 v134, v132
	v_mov_b32_e32 v138, v133
	v_pk_add_f32 v[132:133], v[134:135], v[138:139]
	ds_bpermute_b32 v135, v165, v133
	ds_bpermute_b32 v134, v165, v132
	v_rsq_f32_e32 v140, v131
	v_mul_f32_e32 v131, 0x4b800000, v130
	v_cmp_gt_f32_e64 s[8:9], s77, v130
	v_mov_b32_e32 v136, v216
	v_mov_b32_e32 v137, v220
	v_cndmask_b32_e64 v130, v130, v131, s[8:9]
	v_rsq_f32_e32 v139, v130
	s_waitcnt lgkmcnt(0)
	v_pk_add_f32 v[130:131], v[132:133], v[134:135]
	ds_bpermute_b32 v133, v167, v131
	ds_bpermute_b32 v132, v167, v130
	v_mul_f32_e32 v134, 0x45800000, v140
	v_cndmask_b32_e32 v138, v140, v134, vcc
	v_mov_b32_e32 v134, v208
	v_mov_b32_e32 v135, v212
	s_waitcnt lgkmcnt(0)
	v_pk_add_f32 v[130:131], v[130:131], v[132:133]
	v_mov_b32_e32 v133, v210
	v_pk_fma_f32 v[130:131], v[130:131], s[24:25], v[180:181] op_sel_hi:[1,0,0]
	v_mov_b32_e32 v210, v207
	v_mul_f32_e32 v132, 0x4b800000, v131
	v_cmp_gt_f32_e32 vcc, s77, v131
	v_mov_b32_e32 v212, v209
	v_pk_add_f32 v[134:135], v[134:135], v[212:213]
	v_cndmask_b32_e32 v131, v131, v132, vcc
	v_mov_b32_e32 v132, v206
	v_pk_add_f32 v[132:133], v[132:133], v[210:211]
	v_mov_b32_e32 v220, v217
	v_pk_add_f32 v[132:133], v[132:133], v[134:135]
	v_mov_b32_e32 v134, v214
	v_mov_b32_e32 v135, v218
	v_mov_b32_e32 v218, v215
	v_pk_add_f32 v[134:135], v[134:135], v[218:219]
	v_pk_add_f32 v[136:137], v[136:137], v[220:221]
	v_rsq_f32_e32 v141, v131
	v_pk_add_f32 v[134:135], v[134:135], v[136:137]
	v_mov_b32_e32 v137, v132
	v_mov_b32_e32 v136, v134
	v_mov_b32_e32 v132, v135
	v_pk_add_f32 v[132:133], v[136:137], v[132:133]
	ds_bpermute_b32 v135, v165, v133
	ds_bpermute_b32 v134, v165, v132
	v_mul_f32_e32 v131, 0x4b800000, v130
	v_cmp_gt_f32_e64 s[10:11], s77, v130
	v_mov_b32_e32 v136, v232
	v_mov_b32_e32 v137, v236
	v_cndmask_b32_e64 v130, v130, v131, s[10:11]
	v_rsq_f32_e32 v143, v130
	s_waitcnt lgkmcnt(0)
	v_pk_add_f32 v[130:131], v[132:133], v[134:135]
	ds_bpermute_b32 v133, v167, v131
	ds_bpermute_b32 v132, v167, v130
	v_mul_f32_e32 v134, 0x45800000, v141
	v_cndmask_b32_e32 v142, v141, v134, vcc
	v_mov_b32_e32 v134, v224
	v_mov_b32_e32 v135, v228
	s_waitcnt lgkmcnt(0)
	v_pk_add_f32 v[130:131], v[130:131], v[132:133]
	v_mov_b32_e32 v133, v226
	v_pk_fma_f32 v[130:131], v[130:131], s[24:25], v[180:181] op_sel_hi:[1,0,0]
	v_mov_b32_e32 v226, v223
	v_mul_f32_e32 v132, 0x4b800000, v131
	v_cmp_gt_f32_e32 vcc, s77, v131
	v_mov_b32_e32 v228, v225
	v_pk_add_f32 v[134:135], v[134:135], v[228:229]
	v_cndmask_b32_e32 v131, v131, v132, vcc
	v_mov_b32_e32 v132, v222
	v_pk_add_f32 v[132:133], v[132:133], v[226:227]
	v_mov_b32_e32 v236, v233
	v_pk_add_f32 v[132:133], v[132:133], v[134:135]
	v_mov_b32_e32 v134, v230
	v_mov_b32_e32 v135, v234
	v_mov_b32_e32 v234, v231
	v_pk_add_f32 v[134:135], v[134:135], v[234:235]
	v_pk_add_f32 v[136:137], v[136:137], v[236:237]
	v_mul_f32_e32 v140, 0x45800000, v139
	v_pk_add_f32 v[134:135], v[134:135], v[136:137]
	v_mov_b32_e32 v137, v132
	v_mov_b32_e32 v136, v134
	v_mov_b32_e32 v132, v135
	v_pk_add_f32 v[132:133], v[136:137], v[132:133]
	ds_bpermute_b32 v135, v165, v133
	ds_bpermute_b32 v134, v165, v132
	v_cndmask_b32_e64 v140, v139, v140, s[8:9]
	v_rsq_f32_e32 v141, v131
	v_mul_f32_e32 v131, 0x4b800000, v130
	v_cmp_gt_f32_e64 s[8:9], s77, v130
	v_mul_f32_e32 v139, 0x45800000, v143
	v_cndmask_b32_e64 v144, v143, v139, s[10:11]
	v_cndmask_b32_e64 v130, v130, v131, s[8:9]
	v_rsq_f32_e32 v136, v130
	s_waitcnt lgkmcnt(0)
	v_pk_add_f32 v[130:131], v[132:133], v[134:135]
	ds_bpermute_b32 v133, v167, v131
	ds_bpermute_b32 v132, v167, v130
	v_mul_f32_e32 v134, 0x45800000, v141
	v_cndmask_b32_e32 v190, v141, v134, vcc
	v_mul_f32_e32 v134, 0x45800000, v136
	v_pk_mul_f32 v[128:129], v[128:129], v[138:139] op_sel_hi:[1,0]
	s_waitcnt lgkmcnt(0)
	v_pk_add_f32 v[130:131], v[130:131], v[132:133]
	v_pk_mul_f32 v[126:127], v[126:127], v[138:139] op_sel_hi:[1,0]
	v_pk_fma_f32 v[130:131], v[130:131], s[24:25], v[180:181] op_sel_hi:[1,0,0]
	v_cndmask_b32_e64 v180, v136, v134, s[8:9]
	v_mul_f32_e32 v132, 0x4b800000, v131
	v_cmp_gt_f32_e32 vcc, s77, v131
	v_cmp_gt_f32_e64 s[10:11], s77, v130
	v_lshl_or_b32 v134, s79, 8, v184
	v_cndmask_b32_e32 v131, v131, v132, vcc
	v_rsq_f32_e32 v131, v131
	v_mul_f32_e32 v132, 0x4b800000, v130
	v_cndmask_b32_e64 v130, v130, v132, s[10:11]
	v_ashrrev_i32_e32 v135, 31, v134
	v_mul_f32_e32 v132, 0x45800000, v131
	v_cndmask_b32_e32 v136, v131, v132, vcc
	v_mov_b64_e32 v[132:133], s[18:19]
	v_mad_i64_i32 v[168:169], s[8:9], v168, s78, v[132:133]
	v_lshlrev_b64 v[134:135], 1, v[134:135]
	v_pk_mul_f32 v[192:193], v[124:125], v[138:139] op_sel_hi:[1,0]
	v_pk_mul_f32 v[124:125], v[122:123], v[138:139] op_sel_hi:[1,0]
	v_lshl_add_u64 v[168:169], v[168:169], 0, v[134:135]
	v_cvt_pk_bf16_f32 v122, v126, v127
	v_cvt_pk_bf16_f32 v123, v128, v129
	v_cvt_pk_bf16_f32 v124, v124, v125
	v_cvt_pk_bf16_f32 v125, v192, v193
	global_store_dwordx4 v[168:169], v[122:125], off sc1
	v_pk_mul_f32 v[116:117], v[116:117], v[138:139] op_sel_hi:[1,0]
	v_pk_mul_f32 v[114:115], v[114:115], v[138:139] op_sel_hi:[1,0]
	v_pk_mul_f32 v[122:123], v[108:109], v[138:139] op_sel_hi:[1,0]
	v_pk_mul_f32 v[108:109], v[106:107], v[138:139] op_sel_hi:[1,0]
	v_cvt_pk_bf16_f32 v106, v114, v115
	v_cvt_pk_bf16_f32 v107, v116, v117
	v_cvt_pk_bf16_f32 v108, v108, v109
	v_cvt_pk_bf16_f32 v109, v122, v123
	global_store_dwordx4 v[168:169], v[106:109], off offset:256 sc1
	v_pk_mul_f32 v[112:113], v[112:113], v[140:141] op_sel_hi:[1,0]
	v_pk_mul_f32 v[110:111], v[110:111], v[140:141] op_sel_hi:[1,0]
	v_mad_i64_i32 v[106:107], s[8:9], v164, s78, v[132:133]
	v_lshl_add_u64 v[114:115], v[106:107], 0, v[134:135]
	v_pk_mul_f32 v[108:109], v[120:121], v[140:141] op_sel_hi:[1,0]
	v_pk_mul_f32 v[106:107], v[118:119], v[140:141] op_sel_hi:[1,0]
	v_pk_mul_f32 v[100:101], v[100:101], v[140:141] op_sel_hi:[1,0]
	v_cvt_pk_bf16_f32 v106, v106, v107
	v_cvt_pk_bf16_f32 v107, v108, v109
	v_cvt_pk_bf16_f32 v108, v110, v111
	v_cvt_pk_bf16_f32 v109, v112, v113
	global_store_dwordx4 v[114:115], v[106:109], off sc1
	v_pk_mul_f32 v[98:99], v[98:99], v[140:141] op_sel_hi:[1,0]
	v_pk_mul_f32 v[96:97], v[96:97], v[142:143] op_sel_hi:[1,0]
	v_pk_mul_f32 v[106:107], v[92:93], v[140:141] op_sel_hi:[1,0]
	v_pk_mul_f32 v[92:93], v[90:91], v[140:141] op_sel_hi:[1,0]
	v_cvt_pk_bf16_f32 v90, v98, v99
	v_cvt_pk_bf16_f32 v91, v100, v101
	v_cvt_pk_bf16_f32 v92, v92, v93
	v_cvt_pk_bf16_f32 v93, v106, v107
	global_store_dwordx4 v[114:115], v[90:93], off offset:256 sc1
	v_pk_mul_f32 v[94:95], v[94:95], v[142:143] op_sel_hi:[1,0]
	v_pk_mul_f32 v[84:85], v[84:85], v[142:143] op_sel_hi:[1,0]
	v_mad_i64_i32 v[90:91], s[8:9], v174, s78, v[132:133]
	v_lshl_add_u64 v[98:99], v[90:91], 0, v[134:135]
	v_pk_mul_f32 v[92:93], v[104:105], v[142:143] op_sel_hi:[1,0]
	v_pk_mul_f32 v[90:91], v[102:103], v[142:143] op_sel_hi:[1,0]
	v_pk_mul_f32 v[82:83], v[82:83], v[142:143] op_sel_hi:[1,0]
	v_cvt_pk_bf16_f32 v90, v90, v91
	v_cvt_pk_bf16_f32 v91, v92, v93
	v_cvt_pk_bf16_f32 v92, v94, v95
	v_cvt_pk_bf16_f32 v93, v96, v97
	global_store_dwordx4 v[98:99], v[90:93], off sc1
	v_pk_mul_f32 v[80:81], v[80:81], v[144:145] op_sel_hi:[1,0]
	v_pk_mul_f32 v[78:79], v[78:79], v[144:145] op_sel_hi:[1,0]
	v_pk_mul_f32 v[90:91], v[76:77], v[142:143] op_sel_hi:[1,0]
	v_pk_mul_f32 v[76:77], v[74:75], v[142:143] op_sel_hi:[1,0]
	v_cvt_pk_bf16_f32 v74, v82, v83
	v_cvt_pk_bf16_f32 v75, v84, v85
	v_cvt_pk_bf16_f32 v76, v76, v77
	v_cvt_pk_bf16_f32 v77, v90, v91
	global_store_dwordx4 v[98:99], v[74:77], off offset:256 sc1
	v_pk_mul_f32 v[72:73], v[72:73], v[144:145] op_sel_hi:[1,0]
	v_pk_mul_f32 v[70:71], v[70:71], v[144:145] op_sel_hi:[1,0]
	v_mad_i64_i32 v[74:75], s[8:9], v166, s78, v[132:133]
	v_lshl_add_u64 v[82:83], v[74:75], 0, v[134:135]
	v_pk_mul_f32 v[76:77], v[88:89], v[144:145] op_sel_hi:[1,0]
	v_pk_mul_f32 v[74:75], v[86:87], v[144:145] op_sel_hi:[1,0]
	v_pk_mul_f32 v[64:65], v[64:65], v[190:191] op_sel_hi:[1,0]
	v_cvt_pk_bf16_f32 v74, v74, v75
	v_cvt_pk_bf16_f32 v75, v76, v77
	v_cvt_pk_bf16_f32 v76, v78, v79
	v_cvt_pk_bf16_f32 v77, v80, v81
	global_store_dwordx4 v[82:83], v[74:77], off sc1
	v_pk_mul_f32 v[62:63], v[62:63], v[190:191] op_sel_hi:[1,0]
	v_pk_mul_f32 v[52:53], v[52:53], v[190:191] op_sel_hi:[1,0]
	v_pk_mul_f32 v[74:75], v[68:69], v[144:145] op_sel_hi:[1,0]
	v_pk_mul_f32 v[68:69], v[66:67], v[144:145] op_sel_hi:[1,0]
	v_cvt_pk_bf16_f32 v66, v70, v71
	v_cvt_pk_bf16_f32 v67, v72, v73
	v_cvt_pk_bf16_f32 v68, v68, v69
	v_cvt_pk_bf16_f32 v69, v74, v75
	global_store_dwordx4 v[82:83], v[66:69], off offset:256 sc1
	v_pk_mul_f32 v[50:51], v[50:51], v[190:191] op_sel_hi:[1,0]
	v_pk_mul_f32 v[48:49], v[48:49], v[180:181] op_sel_hi:[1,0]
	v_mad_i64_i32 v[66:67], s[8:9], v176, s78, v[132:133]
	v_pk_mul_f32 v[68:69], v[60:61], v[190:191] op_sel_hi:[1,0]
	v_pk_mul_f32 v[60:61], v[58:59], v[190:191] op_sel_hi:[1,0]
	v_lshl_add_u64 v[66:67], v[66:67], 0, v[134:135]
	v_cvt_pk_bf16_f32 v58, v62, v63
	v_cvt_pk_bf16_f32 v59, v64, v65
	v_cvt_pk_bf16_f32 v60, v60, v61
	v_cvt_pk_bf16_f32 v61, v68, v69
	global_store_dwordx4 v[66:67], v[58:61], off sc1
	v_pk_mul_f32 v[46:47], v[46:47], v[180:181] op_sel_hi:[1,0]
	v_pk_mul_f32 v[36:37], v[36:37], v[180:181] op_sel_hi:[1,0]
	v_pk_mul_f32 v[58:59], v[44:45], v[190:191] op_sel_hi:[1,0]
	v_pk_mul_f32 v[44:45], v[42:43], v[190:191] op_sel_hi:[1,0]
	v_cvt_pk_bf16_f32 v42, v50, v51
	v_cvt_pk_bf16_f32 v43, v52, v53
	v_cvt_pk_bf16_f32 v44, v44, v45
	v_cvt_pk_bf16_f32 v45, v58, v59
	global_store_dwordx4 v[66:67], v[42:45], off offset:256 sc1
	v_pk_mul_f32 v[34:35], v[34:35], v[180:181] op_sel_hi:[1,0]
	v_rsq_f32_e32 v130, v130
	v_mad_i64_i32 v[42:43], s[8:9], v170, s78, v[132:133]
	v_lshl_add_u64 v[50:51], v[42:43], 0, v[134:135]
	v_pk_mul_f32 v[44:45], v[56:57], v[180:181] op_sel_hi:[1,0]
	v_pk_mul_f32 v[42:43], v[54:55], v[180:181] op_sel_hi:[1,0]
	v_pk_mul_f32 v[32:33], v[32:33], v[136:137] op_sel_hi:[1,0]
	v_cvt_pk_bf16_f32 v42, v42, v43
	v_cvt_pk_bf16_f32 v43, v44, v45
	v_cvt_pk_bf16_f32 v44, v46, v47
	v_cvt_pk_bf16_f32 v45, v48, v49
	global_store_dwordx4 v[50:51], v[42:45], off sc1
	v_pk_mul_f32 v[30:31], v[30:31], v[136:137] op_sel_hi:[1,0]
	v_pk_mul_f32 v[20:21], v[20:21], v[136:137] op_sel_hi:[1,0]
	v_pk_mul_f32 v[42:43], v[28:29], v[180:181] op_sel_hi:[1,0]
	v_pk_mul_f32 v[28:29], v[26:27], v[180:181] op_sel_hi:[1,0]
	v_cvt_pk_bf16_f32 v26, v34, v35
	v_cvt_pk_bf16_f32 v27, v36, v37
	v_cvt_pk_bf16_f32 v28, v28, v29
	v_cvt_pk_bf16_f32 v29, v42, v43
	global_store_dwordx4 v[50:51], v[26:29], off offset:256 sc1
	v_pk_mul_f32 v[18:19], v[18:19], v[136:137] op_sel_hi:[1,0]
	v_mul_f32_e32 v131, 0x45800000, v130
	v_mad_i64_i32 v[26:27], s[8:9], v178, s78, v[132:133]
	v_lshl_add_u64 v[34:35], v[26:27], 0, v[134:135]
	v_pk_mul_f32 v[28:29], v[40:41], v[136:137] op_sel_hi:[1,0]
	v_pk_mul_f32 v[26:27], v[38:39], v[136:137] op_sel_hi:[1,0]
	v_cndmask_b32_e64 v130, v130, v131, s[10:11]
	v_cvt_pk_bf16_f32 v26, v26, v27
	v_cvt_pk_bf16_f32 v27, v28, v29
	v_cvt_pk_bf16_f32 v28, v30, v31
	v_cvt_pk_bf16_f32 v29, v32, v33
	global_store_dwordx4 v[34:35], v[26:29], off sc1
	v_pk_mul_f32 v[16:17], v[16:17], v[130:131] op_sel_hi:[1,0]
	v_pk_mul_f32 v[14:15], v[14:15], v[130:131] op_sel_hi:[1,0]
	v_pk_mul_f32 v[26:27], v[12:13], v[136:137] op_sel_hi:[1,0]
	v_pk_mul_f32 v[12:13], v[10:11], v[136:137] op_sel_hi:[1,0]
	v_cvt_pk_bf16_f32 v10, v18, v19
	v_cvt_pk_bf16_f32 v11, v20, v21
	v_cvt_pk_bf16_f32 v12, v12, v13
	v_cvt_pk_bf16_f32 v13, v26, v27
	global_store_dwordx4 v[34:35], v[10:13], off offset:256 sc1
	v_pk_mul_f32 v[8:9], v[8:9], v[130:131] op_sel_hi:[1,0]
	v_pk_mul_f32 v[6:7], v[6:7], v[130:131] op_sel_hi:[1,0]
	v_mad_i64_i32 v[10:11], s[8:9], v172, s78, v[132:133]
	v_lshl_add_u64 v[18:19], v[10:11], 0, v[134:135]
	v_pk_mul_f32 v[12:13], v[24:25], v[130:131] op_sel_hi:[1,0]
	v_pk_mul_f32 v[10:11], v[22:23], v[130:131] op_sel_hi:[1,0]
	s_andn2_b64 vcc, exec, s[6:7]
	v_cvt_pk_bf16_f32 v10, v10, v11
	v_cvt_pk_bf16_f32 v11, v12, v13
	v_cvt_pk_bf16_f32 v12, v14, v15
	v_cvt_pk_bf16_f32 v13, v16, v17
	global_store_dwordx4 v[18:19], v[10:13], off sc1
	s_mov_b64 s[6:7], -1
	s_nop 0
	v_pk_mul_f32 v[10:11], v[4:5], v[130:131] op_sel_hi:[1,0]
	v_pk_mul_f32 v[4:5], v[2:3], v[130:131] op_sel_hi:[1,0]
	v_cvt_pk_bf16_f32 v2, v6, v7
	v_cvt_pk_bf16_f32 v3, v8, v9
	v_cvt_pk_bf16_f32 v4, v4, v5
	v_cvt_pk_bf16_f32 v5, v10, v11
	global_store_dwordx4 v[18:19], v[2:5], off offset:256 sc1
	s_cbranch_vccnz .LBB0_890
	s_andn2_b64 vcc, exec, s[16:17]
	s_cbranch_vccnz .LBB0_889
	s_barrier
	s_branch .LBB0_889

.LBB0_904:
	v_add_u32_e32 v2, 0xa280, v80
	ds_write2_b32 v2, v10, v11 offset1:1
	v_add_u32_e32 v2, 0xa288, v80
	ds_write2_b32 v2, v8, v9 offset1:1
	s_waitcnt vmcnt(0)
	v_pk_mul_f32 v[2:3], v[22:23], v[6:7] op_sel_hi:[1,0]
	v_add_u32_e32 v4, 0xc300, v80
	ds_write2_b32 v4, v2, v3 offset1:1
	v_pk_mul_f32 v[2:3], v[24:25], v[6:7] op_sel_hi:[1,0]
	v_add_u32_e32 v4, 0xc308, v80
	s_add_i32 s40, s40, s25
	ds_write2_b32 v4, v2, v3 offset1:1
	v_add_u32_e32 v2, s40, v50
	v_ashrrev_i32_e32 v3, 31, v2
	v_lshlrev_b64 v[2:3], 12, v[2:3]
	s_waitcnt lgkmcnt(0)
	s_barrier
	v_lshl_add_u64 v[2:3], s[16:17], 0, v[2:3]
	v_lshl_add_u64 v[6:7], s[20:21], 1, v[2:3]
	ds_read2_b32 v[2:3], v52 offset0:65 offset1:130
	ds_read2_b32 v[4:5], v72 offset0:67 offset1:132
	ds_read2_b32 v[8:9], v73 offset0:69 offset1:134
	ds_read_b32 v10, v51
	ds_read_b32 v11, v52 offset:1820
	ds_read_b32 v14, v52 offset:16640
	ds_read_b32 v16, v53 offset:1820
	ds_read_b32 v17, v53 offset:16640
	ds_read_b32 v18, v54 offset:1820
	ds_read_b32 v19, v54 offset:16640
	ds_read_b32 v20, v55 offset:1820
	s_waitcnt lgkmcnt(7)
	v_cvt_pk_bf16_f32 v2, v10, v2
	v_cvt_pk_bf16_f32 v3, v3, v4
	v_cvt_pk_bf16_f32 v4, v5, v8
	s_waitcnt lgkmcnt(6)
	v_cvt_pk_bf16_f32 v5, v9, v11
	ds_read2_b32 v[8:9], v53 offset0:65 offset1:130
	ds_read2_b32 v[10:11], v74 offset0:67 offset1:132
	ds_read2_b32 v[12:13], v75 offset0:69 offset1:134
	v_lshl_add_u64 v[6:7], v[6:7], 0, v[36:37]
	global_store_dwordx4 v[6:7], v[2:5], off sc1
	s_waitcnt lgkmcnt(2)
	s_nop 0
	v_cvt_pk_bf16_f32 v2, v14, v8
	s_waitcnt lgkmcnt(1)
	v_cvt_pk_bf16_f32 v3, v9, v10
	s_waitcnt lgkmcnt(0)
	v_cvt_pk_bf16_f32 v4, v11, v12
	ds_read2_b32 v[8:9], v54 offset0:65 offset1:130
	ds_read2_b32 v[10:11], v76 offset0:67 offset1:132
	ds_read2_b32 v[14:15], v77 offset0:69 offset1:134
	v_cvt_pk_bf16_f32 v5, v13, v16
	global_store_dwordx4 v[6:7], v[2:5], off offset:128 sc1
	s_waitcnt lgkmcnt(2)
	s_nop 0
	v_cvt_pk_bf16_f32 v2, v17, v8
	s_waitcnt lgkmcnt(1)
	v_cvt_pk_bf16_f32 v3, v9, v10
	s_waitcnt lgkmcnt(0)
	v_cvt_pk_bf16_f32 v4, v11, v14
	ds_read2_b32 v[8:9], v55 offset0:65 offset1:130
	ds_read2_b32 v[10:11], v78 offset0:67 offset1:132
	ds_read2_b32 v[12:13], v79 offset0:69 offset1:134
	v_cvt_pk_bf16_f32 v5, v15, v18
	global_store_dwordx4 v[6:7], v[2:5], off offset:256 sc1
	s_waitcnt lgkmcnt(2)
	s_nop 0
	v_cvt_pk_bf16_f32 v2, v19, v8
	s_waitcnt lgkmcnt(1)
	v_cvt_pk_bf16_f32 v3, v9, v10
	s_waitcnt lgkmcnt(0)
	v_cvt_pk_bf16_f32 v4, v11, v12
	v_cvt_pk_bf16_f32 v5, v13, v20
	global_store_dwordx4 v[6:7], v[2:5], off offset:384 sc1
	s_waitcnt lgkmcnt(0)
	s_barrier

.LBB0_906:
	s_cmpk_gt_i32 s24, 0x47f
	s_mov_b64 s[6:7], -1
	s_cbranch_scc0 .LBB0_918
	s_cmpk_gt_u32 s24, 0x9ff
	s_cbranch_scc0 .LBB0_909
	s_and_b32 s6, s27, 0x7f00
	s_addk_i32 s6, 0xb000
	s_and_b32 s20, s25, 0x7c0
	v_or_b32_e32 v18, s6, v34
	s_lshl_b32 s8, s20, 2
	v_or_b32_e32 v4, 32, v18
	v_mov_b32_e32 v5, v37
	v_lshl_add_u64 v[30:31], v[38:39], 0, s[8:9]
	v_lshlrev_b64 v[4:5], 13, v[4:5]
	v_lshl_add_u64 v[6:7], v[30:31], 0, v[4:5]
	v_or_b32_e32 v4, 64, v18
	v_mov_b32_e32 v5, v37
	v_lshlrev_b64 v[4:5], 13, v[4:5]
	v_lshl_add_u64 v[10:11], v[30:31], 0, v[4:5]
	v_or_b32_e32 v4, 0x60, v18
	v_mov_b32_e32 v5, v37
	v_lshlrev_b64 v[4:5], 13, v[4:5]
	v_lshl_add_u64 v[14:15], v[30:31], 0, v[4:5]
	v_or_b32_e32 v4, 0x80, v18
	v_mov_b32_e32 v5, v37
	v_mov_b32_e32 v19, v37
	v_lshlrev_b64 v[4:5], 13, v[4:5]
	v_lshlrev_b64 v[2:3], 13, v[18:19]
	v_lshl_add_u64 v[20:21], v[30:31], 0, v[4:5]
	v_or_b32_e32 v4, 0xa0, v18
	v_mov_b32_e32 v5, v37
	v_lshl_add_u64 v[2:3], v[30:31], 0, v[2:3]
	v_lshlrev_b64 v[4:5], 13, v[4:5]
	s_waitcnt vmcnt(0)
	v_lshl_add_u64 v[22:23], v[30:31], 0, v[4:5]
	global_load_dwordx4 v[2:5], v[2:3], off
	v_or_b32_e32 v12, 0xc0, v18
	global_load_dwordx4 v[6:9], v[6:7], off
	v_mov_b32_e32 v13, v37
	v_lshlrev_b64 v[16:17], 13, v[12:13]
	global_load_dwordx4 v[10:13], v[10:11], off
	v_lshl_add_u64 v[26:27], v[30:31], 0, v[16:17]
	global_load_dwordx4 v[14:17], v[14:15], off
	v_or_b32_e32 v28, 0xe0, v18
	global_load_dwordx4 v[18:21], v[20:21], off
	v_mov_b32_e32 v29, v37
	global_load_dwordx4 v[22:25], v[22:23], off
	v_lshlrev_b64 v[32:33], 13, v[28:29]
	global_load_dwordx4 v[26:29], v[26:27], off
	v_lshl_add_u64 v[30:31], v[30:31], 0, v[32:33]
	global_load_dwordx4 v[30:33], v[30:31], off
	v_or_b32_e32 v44, s20, v50
	v_mul_u32_u24_e32 v44, 0x1600, v44
	v_mov_b32_e32 v45, v37
	v_lshlrev_b32_e32 v44, 1, v44
	s_mov_b32 s7, s9
	v_lshl_add_u64 v[44:45], s[70:71], 0, v[44:45]
	v_lshl_add_u64 v[44:45], s[6:7], 1, v[44:45]
	v_lshl_add_u64 v[44:45], v[44:45], 0, v[36:37]
	s_mov_b64 s[6:7], 0
	s_waitcnt vmcnt(7)
	ds_write2_b32 v57, v2, v3 offset1:1
	ds_write2_b32 v57, v4, v5 offset0:2 offset1:3
	s_waitcnt vmcnt(6)
	ds_write2_b32 v58, v6, v7 offset1:1
	ds_write2_b32 v59, v8, v9 offset1:1
	s_waitcnt vmcnt(5)
	ds_write2_b32 v60, v10, v11 offset1:1
	ds_write2_b32 v61, v12, v13 offset1:1
	s_waitcnt vmcnt(4)
	ds_write2_b32 v62, v14, v15 offset1:1
	ds_write2_b32 v63, v16, v17 offset1:1
	s_waitcnt vmcnt(3)
	ds_write2_b32 v64, v18, v19 offset1:1
	ds_write2_b32 v65, v20, v21 offset1:1
	s_waitcnt vmcnt(2)
	ds_write2_b32 v66, v22, v23 offset1:1
	ds_write2_b32 v67, v24, v25 offset1:1
	s_waitcnt vmcnt(1)
	ds_write2_b32 v68, v26, v27 offset1:1
	ds_write2_b32 v69, v28, v29 offset1:1
	s_waitcnt vmcnt(0)
	ds_write2_b32 v70, v30, v31 offset1:1
	ds_write2_b32 v71, v32, v33 offset1:1
	s_waitcnt lgkmcnt(0)
	s_barrier
	ds_read2_b32 v[2:3], v52 offset0:65 offset1:130
	ds_read2_b32 v[4:5], v72 offset0:67 offset1:132
	ds_read2_b32 v[6:7], v73 offset0:69 offset1:134
	ds_read2_b32 v[8:9], v53 offset0:65 offset1:130
	ds_read2_b32 v[10:11], v74 offset0:67 offset1:132
	ds_read2_b32 v[12:13], v75 offset0:69 offset1:134
	ds_read2_b32 v[14:15], v54 offset0:65 offset1:130
	ds_read_b32 v16, v51
	ds_read_b32 v17, v52 offset:1820
	ds_read_b32 v18, v52 offset:16640
	ds_read_b32 v19, v53 offset:1820
	ds_read_b32 v20, v53 offset:16640
	ds_read_b32 v21, v54 offset:1820
	ds_read_b32 v22, v54 offset:16640
	ds_read_b32 v23, v55 offset:1820
	s_waitcnt lgkmcnt(7)
	v_cvt_pk_bf16_f32 v2, v16, v2
	v_cvt_pk_bf16_f32 v3, v3, v4
	v_cvt_pk_bf16_f32 v4, v5, v6
	s_waitcnt lgkmcnt(6)
	v_cvt_pk_bf16_f32 v5, v7, v17
	s_waitcnt lgkmcnt(5)
	v_cvt_pk_bf16_f32 v6, v18, v8
	v_cvt_pk_bf16_f32 v7, v9, v10
	v_cvt_pk_bf16_f32 v8, v11, v12
	global_store_dwordx4 v[44:45], v[2:5], off sc1
	s_waitcnt lgkmcnt(4)
	v_cvt_pk_bf16_f32 v9, v13, v19
	ds_read2_b32 v[4:5], v76 offset0:67 offset1:132
	ds_read2_b32 v[10:11], v77 offset0:69 offset1:134
	global_store_dwordx4 v[44:45], v[6:9], off offset:128 sc1
	ds_read2_b32 v[6:7], v55 offset0:65 offset1:130
	ds_read2_b32 v[8:9], v78 offset0:67 offset1:132
	ds_read2_b32 v[12:13], v79 offset0:69 offset1:134
	s_waitcnt lgkmcnt(8)
	v_cvt_pk_bf16_f32 v2, v20, v14
	s_waitcnt lgkmcnt(4)
	v_cvt_pk_bf16_f32 v3, v15, v4
	s_waitcnt lgkmcnt(3)
	v_cvt_pk_bf16_f32 v4, v5, v10
	v_cvt_pk_bf16_f32 v5, v11, v21
	global_store_dwordx4 v[44:45], v[2:5], off offset:256 sc1
	s_waitcnt lgkmcnt(2)
	s_nop 0
	v_cvt_pk_bf16_f32 v2, v22, v6
	s_waitcnt lgkmcnt(1)
	v_cvt_pk_bf16_f32 v3, v7, v8
	s_waitcnt lgkmcnt(0)
	v_cvt_pk_bf16_f32 v4, v9, v12
	v_cvt_pk_bf16_f32 v5, v13, v23
	global_store_dwordx4 v[44:45], v[2:5], off offset:384 sc1
	s_waitcnt lgkmcnt(0)
	s_barrier

.LBB0_916:
	v_add_u32_e32 v6, 0xa280, v24
	ds_write2_b32 v6, v22, v23 offset1:1
	v_add_u32_e32 v6, 0xa288, v24
	s_lshl_b32 s6, s23, 6
	ds_write2_b32 v6, v20, v21 offset1:1
	s_waitcnt vmcnt(0)
	v_pk_mul_f32 v[2:3], v[2:3], v[18:19] op_sel_hi:[1,0]
	v_add_u32_e32 v6, 0xc300, v24
	s_and_b32 s6, 0xffff, s6
	ds_write2_b32 v6, v2, v3 offset1:1
	v_pk_mul_f32 v[2:3], v[4:5], v[18:19] op_sel_hi:[1,0]
	v_add_u32_e32 v4, 0xc308, v24
	ds_write2_b32 v4, v2, v3 offset1:1
	v_add_lshl_u32 v2, v50, s6, 12
	v_mov_b32_e32 v3, v37
	s_waitcnt lgkmcnt(0)
	s_barrier
	v_lshl_add_u64 v[2:3], s[14:15], 0, v[2:3]
	s_lshl_b32 s8, s22, 1
	v_lshl_add_u64 v[6:7], v[2:3], 0, s[8:9]
	ds_read2_b32 v[2:3], v52 offset0:65 offset1:130
	ds_read2_b32 v[4:5], v72 offset0:67 offset1:132
	ds_read2_b32 v[8:9], v73 offset0:69 offset1:134
	ds_read_b32 v10, v51
	ds_read_b32 v11, v52 offset:1820
	ds_read_b32 v14, v52 offset:16640
	ds_read_b32 v16, v53 offset:1820
	ds_read_b32 v17, v53 offset:16640
	ds_read_b32 v18, v54 offset:1820
	ds_read_b32 v19, v54 offset:16640
	ds_read_b32 v20, v55 offset:1820
	s_waitcnt lgkmcnt(7)
	v_cvt_pk_bf16_f32 v2, v10, v2
	v_cvt_pk_bf16_f32 v3, v3, v4
	v_cvt_pk_bf16_f32 v4, v5, v8
	s_waitcnt lgkmcnt(6)
	v_cvt_pk_bf16_f32 v5, v9, v11
	ds_read2_b32 v[8:9], v53 offset0:65 offset1:130
	ds_read2_b32 v[10:11], v74 offset0:67 offset1:132
	ds_read2_b32 v[12:13], v75 offset0:69 offset1:134
	v_lshl_add_u64 v[6:7], v[6:7], 0, v[36:37]
	global_store_dwordx4 v[6:7], v[2:5], off sc1
	s_waitcnt lgkmcnt(2)
	s_nop 0
	v_cvt_pk_bf16_f32 v2, v14, v8
	s_waitcnt lgkmcnt(1)
	v_cvt_pk_bf16_f32 v3, v9, v10
	s_waitcnt lgkmcnt(0)
	v_cvt_pk_bf16_f32 v4, v11, v12
	ds_read2_b32 v[8:9], v54 offset0:65 offset1:130
	ds_read2_b32 v[10:11], v76 offset0:67 offset1:132
	ds_read2_b32 v[14:15], v77 offset0:69 offset1:134
	v_cvt_pk_bf16_f32 v5, v13, v16
	global_store_dwordx4 v[6:7], v[2:5], off offset:128 sc1
	s_waitcnt lgkmcnt(2)
	s_nop 0
	v_cvt_pk_bf16_f32 v2, v17, v8
	s_waitcnt lgkmcnt(1)
	v_cvt_pk_bf16_f32 v3, v9, v10
	s_waitcnt lgkmcnt(0)
	v_cvt_pk_bf16_f32 v4, v11, v14
	ds_read2_b32 v[8:9], v55 offset0:65 offset1:130
	ds_read2_b32 v[10:11], v78 offset0:67 offset1:132
	ds_read2_b32 v[12:13], v79 offset0:69 offset1:134
	v_cvt_pk_bf16_f32 v5, v15, v18
	global_store_dwordx4 v[6:7], v[2:5], off offset:256 sc1
	s_waitcnt lgkmcnt(2)
	s_nop 0
	v_cvt_pk_bf16_f32 v2, v19, v8
	s_waitcnt lgkmcnt(1)
	v_cvt_pk_bf16_f32 v3, v9, v10
	s_waitcnt lgkmcnt(0)
	v_cvt_pk_bf16_f32 v4, v11, v12
	v_cvt_pk_bf16_f32 v5, v13, v20
	global_store_dwordx4 v[6:7], v[2:5], off offset:384 sc1
	s_waitcnt lgkmcnt(0)
	s_barrier

.LBB0_1008:
	s_or_b64 exec, exec, s[6:7]
	v_lshlrev_b64 v[14:15], 2, v[36:37]
	v_lshl_add_u64 v[6:7], s[16:17], 0, v[14:15]
	v_lshl_add_u64 v[8:9], s[22:23], 0, v[14:15]
	global_load_dwordx4 v[2:5], v[6:7], off
	global_load_dwordx4 v[18:21], v[8:9], off
	v_lshl_add_u64 v[6:7], s[54:55], 0, v[14:15]
	v_lshl_add_u64 v[10:11], s[20:21], 0, v[14:15]
	global_load_dwordx4 v[6:9], v[6:7], off
	v_lshl_add_u64 v[16:17], s[18:19], 0, v[14:15]
	global_load_dwordx4 v[22:25], v[10:11], off
	v_lshl_add_u64 v[30:31], s[24:25], 0, v[14:15]
	global_load_dwordx4 v[10:13], v[16:17], off
	global_load_dwordx4 v[26:29], v[30:31], off
	v_lshl_add_u64 v[16:17], s[26:27], 0, v[14:15]
	global_load_dwordx4 v[30:33], v[16:17], off
	v_lshl_add_u64 v[14:15], s[56:57], 0, v[14:15]
	global_load_dwordx4 v[14:17], v[14:15], off
	s_waitcnt vmcnt(24)
	v_lshlrev_b32_e32 v98, 16, v76
	v_and_b32_e32 v99, 0xffff0000, v76
	v_lshlrev_b32_e32 v92, 16, v62
	v_lshlrev_b32_e32 v94, 16, v72
	s_waitcnt vmcnt(23)
	v_lshlrev_b32_e32 v70, 16, v80
	v_and_b32_e32 v93, 0xffff0000, v62
	v_and_b32_e32 v95, 0xffff0000, v72
	v_and_b32_e32 v71, 0xffff0000, v80
	v_lshlrev_b32_e32 v96, 16, v63
	v_lshlrev_b32_e32 v74, 16, v73
	v_lshlrev_b32_e32 v62, 16, v81
	v_and_b32_e32 v97, 0xffff0000, v63
	v_and_b32_e32 v75, 0xffff0000, v73
	v_and_b32_e32 v63, 0xffff0000, v81
	v_lshlrev_b32_e32 v80, 16, v66
	s_waitcnt vmcnt(22)
	v_lshlrev_b32_e32 v72, 16, v78
	v_and_b32_e32 v81, 0xffff0000, v66
	v_and_b32_e32 v73, 0xffff0000, v78
	v_lshlrev_b32_e32 v100, 16, v67
	v_lshlrev_b32_e32 v66, 16, v79
	v_and_b32_e32 v101, 0xffff0000, v67
	v_and_b32_e32 v67, 0xffff0000, v79
	v_lshlrev_b32_e32 v102, 16, v77
	v_and_b32_e32 v103, 0xffff0000, v77
	v_lshl_add_u64 v[36:37], v[36:37], 1, s[14:15]
	v_add_u32_e32 v1, s3, v1
	v_add_u32_e32 v82, s30, v82
	s_waitcnt vmcnt(7)
	v_pk_mul_f32 v[104:105], v[4:5], v[74:75]
	s_waitcnt vmcnt(6)
	v_pk_mul_f32 v[78:79], v[18:19], v[98:99]
	v_pk_mul_f32 v[76:77], v[2:3], v[94:95]
	v_pk_mul_f32 v[106:107], v[20:21], v[102:103]
	s_waitcnt vmcnt(5)
	v_pk_fma_f32 v[76:77], v[6:7], v[92:93], v[76:77]
	s_waitcnt vmcnt(4)
	v_pk_fma_f32 v[78:79], v[22:23], v[80:81], v[78:79]
	v_pk_fma_f32 v[80:81], v[8:9], v[96:97], v[104:105]
	s_waitcnt vmcnt(2)
	v_pk_fma_f32 v[78:79], v[26:27], v[72:73], v[78:79]
	v_pk_fma_f32 v[92:93], v[24:25], v[100:101], v[106:107]
	s_waitcnt vmcnt(1)
	v_pk_add_f32 v[78:79], v[78:79], v[30:31]
	v_pk_fma_f32 v[92:93], v[28:29], v[66:67], v[92:93]
	v_mul_f32_e32 v91, 0xbfb8aa3b, v78
	v_mul_f32_e32 v97, 0xbfb8aa3b, v79
	v_exp_f32_e32 v96, v91
	v_exp_f32_e32 v97, v97
	v_pk_add_f32 v[92:93], v[92:93], v[32:33]
	v_pk_fma_f32 v[76:77], v[10:11], v[70:71], v[76:77]
	v_mul_f32_e32 v100, 0xbfb8aa3b, v92
	v_pk_add_f32 v[96:97], v[96:97], 1.0 op_sel_hi:[1,0]
	v_mul_f32_e32 v101, 0xbfb8aa3b, v93
	v_div_scale_f32 v91, s[6:7], v97, v97, 1.0
	v_div_scale_f32 v105, s[6:7], v96, v96, 1.0
	v_rcp_f32_e32 v108, v91
	v_rcp_f32_e32 v109, v105
	v_exp_f32_e32 v100, v100
	v_exp_f32_e32 v101, v101
	v_fma_f32 v112, -v91, v108, 1.0
	v_div_scale_f32 v104, vcc, 1.0, v97, 1.0
	v_fma_f32 v113, -v105, v109, 1.0
	v_fmac_f32_e32 v108, v112, v108
	v_pk_add_f32 v[100:101], v[100:101], 1.0 op_sel_hi:[1,0]
	v_div_scale_f32 v106, s[6:7], 1.0, v96, 1.0
	v_fmac_f32_e32 v109, v113, v109
	v_mul_f32_e32 v112, v104, v108
	v_div_scale_f32 v107, s[8:9], v101, v101, 1.0
	v_mul_f32_e32 v113, v106, v109
	v_fma_f32 v115, -v91, v112, v104
	v_rcp_f32_e32 v110, v107
	v_fma_f32 v116, -v105, v113, v106
	v_fmac_f32_e32 v112, v115, v108
	v_fmac_f32_e32 v113, v116, v109
	v_fma_f32 v91, -v91, v112, v104
	v_fma_f32 v104, -v105, v113, v106
	v_div_fmas_f32 v91, v91, v108, v112
	s_mov_b64 vcc, s[6:7]
	v_div_fixup_f32 v97, v91, v97, 1.0
	v_div_fmas_f32 v91, v104, v109, v113
	v_fma_f32 v114, -v107, v110, 1.0
	v_div_fixup_f32 v96, v91, v96, 1.0
	s_waitcnt vmcnt(0)
	v_pk_add_f32 v[76:77], v[76:77], v[14:15]
	v_div_scale_f32 v111, s[8:9], 1.0, v101, 1.0
	v_fmac_f32_e32 v110, v114, v110
	v_pk_mul_f32 v[78:79], v[78:79], v[96:97]
	v_mul_f32_e32 v114, v111, v110
	v_pk_mul_f32 v[76:77], v[76:77], v[78:79]
	v_div_scale_f32 v78, s[6:7], v100, v100, 1.0
	v_fma_f32 v117, -v107, v114, v111
	v_rcp_f32_e32 v91, v78
	v_fmac_f32_e32 v114, v117, v110
	v_cvt_pk_bf16_f32 v76, v76, v77
	v_fma_f32 v77, -v107, v114, v111
	s_mov_b64 vcc, s[8:9]
	v_div_fmas_f32 v77, v77, v110, v114
	v_div_fixup_f32 v79, v77, v101, 1.0
	v_fma_f32 v77, -v78, v91, 1.0
	v_fmac_f32_e32 v91, v77, v91
	v_div_scale_f32 v77, vcc, 1.0, v100, 1.0
	v_mul_f32_e32 v96, v77, v91
	v_fma_f32 v97, -v78, v96, v77
	v_fmac_f32_e32 v96, v97, v91
	v_fma_f32 v77, -v78, v96, v77
	v_div_fmas_f32 v77, v77, v91, v96
	v_pk_fma_f32 v[80:81], v[12:13], v[62:63], v[80:81]
	v_div_fixup_f32 v78, v77, v100, 1.0
	v_pk_add_f32 v[80:81], v[80:81], v[16:17]
	v_pk_mul_f32 v[78:79], v[92:93], v[78:79]
	v_pk_mul_f32 v[92:93], v[2:3], v[70:71]
	v_pk_mul_f32 v[78:79], v[80:81], v[78:79]
	v_lshlrev_b32_e32 v80, 16, v64
	v_cvt_pk_bf16_f32 v77, v78, v79
	v_mad_i64_i32 v[78:79], s[6:7], v90, s38, v[36:37]
	global_store_dwordx2 v[78:79], v[76:77], off sc1
	v_pk_mul_f32 v[78:79], v[18:19], v[72:73]
	v_and_b32_e32 v81, 0xffff0000, v64
	v_pk_fma_f32 v[78:79], v[22:23], v[98:99], v[78:79]
	v_pk_fma_f32 v[92:93], v[6:7], v[94:95], v[92:93]
	v_pk_fma_f32 v[78:79], v[26:27], v[80:81], v[78:79]
	v_lshlrev_b32_e32 v76, 16, v68
	v_pk_add_f32 v[78:79], v[78:79], v[30:31]
	v_and_b32_e32 v77, 0xffff0000, v68
	v_mul_f32_e32 v64, 0xbfb8aa3b, v78
	v_exp_f32_e32 v90, v64
	v_mul_f32_e32 v64, 0xbfb8aa3b, v79
	v_exp_f32_e32 v91, v64
	v_lshlrev_b32_e32 v64, 16, v65
	v_and_b32_e32 v65, 0xffff0000, v65
	v_pk_fma_f32 v[92:93], v[10:11], v[76:77], v[92:93]
	v_pk_add_f32 v[90:91], v[90:91], 1.0 op_sel_hi:[1,0]
	v_pk_add_f32 v[92:93], v[92:93], v[14:15]
	v_div_scale_f32 v96, s[6:7], v91, v91, 1.0
	v_rcp_f32_e32 v97, v96
	v_lshlrev_b32_e32 v68, 16, v69
	v_and_b32_e32 v69, 0xffff0000, v69
	v_fma_f32 v94, -v96, v97, 1.0
	v_fmac_f32_e32 v97, v94, v97
	v_div_scale_f32 v94, vcc, 1.0, v91, 1.0
	v_mul_f32_e32 v95, v94, v97
	v_fma_f32 v98, -v96, v95, v94
	v_fmac_f32_e32 v95, v98, v97
	v_fma_f32 v94, -v96, v95, v94
	v_div_scale_f32 v96, s[6:7], v90, v90, 1.0
	v_rcp_f32_e32 v98, v96
	v_div_fmas_f32 v94, v94, v97, v95
	v_div_fixup_f32 v91, v94, v91, 1.0
	v_fma_f32 v94, -v96, v98, 1.0
	v_fmac_f32_e32 v98, v94, v98
	v_div_scale_f32 v94, vcc, 1.0, v90, 1.0
	v_mul_f32_e32 v95, v94, v98
	v_fma_f32 v97, -v96, v95, v94
	v_fmac_f32_e32 v95, v97, v98
	v_fma_f32 v94, -v96, v95, v94
	v_div_fmas_f32 v94, v94, v98, v95
	v_div_fixup_f32 v90, v94, v90, 1.0
	v_pk_mul_f32 v[78:79], v[78:79], v[90:91]
	v_pk_mul_f32 v[90:91], v[20:21], v[66:67]
	v_pk_mul_f32 v[78:79], v[92:93], v[78:79]
	v_pk_fma_f32 v[90:91], v[24:25], v[102:103], v[90:91]
	v_cvt_pk_bf16_f32 v78, v78, v79
	v_pk_fma_f32 v[90:91], v[28:29], v[64:65], v[90:91]
	v_pk_mul_f32 v[92:93], v[4:5], v[62:63]
	v_pk_add_f32 v[90:91], v[90:91], v[32:33]
	v_pk_fma_f32 v[74:75], v[8:9], v[74:75], v[92:93]
	v_mul_f32_e32 v94, 0xbfb8aa3b, v90
	v_mul_f32_e32 v95, 0xbfb8aa3b, v91
	v_exp_f32_e32 v94, v94
	v_exp_f32_e32 v95, v95
	v_pk_fma_f32 v[74:75], v[12:13], v[68:69], v[74:75]
	v_pk_add_f32 v[94:95], v[94:95], 1.0 op_sel_hi:[1,0]
	s_nop 0
	v_div_scale_f32 v79, s[6:7], v95, v95, 1.0
	v_rcp_f32_e32 v96, v79
	v_pk_add_f32 v[74:75], v[74:75], v[16:17]
	v_fma_f32 v92, -v79, v96, 1.0
	v_fmac_f32_e32 v96, v92, v96
	v_div_scale_f32 v92, vcc, 1.0, v95, 1.0
	v_mul_f32_e32 v93, v92, v96
	v_fma_f32 v97, -v79, v93, v92
	v_fmac_f32_e32 v93, v97, v96
	v_fma_f32 v79, -v79, v93, v92
	v_div_scale_f32 v92, s[6:7], v94, v94, 1.0
	v_rcp_f32_e32 v97, v92
	v_div_fmas_f32 v79, v79, v96, v93
	v_div_fixup_f32 v93, v79, v95, 1.0
	v_fma_f32 v79, -v92, v97, 1.0
	v_fmac_f32_e32 v97, v79, v97
	v_div_scale_f32 v79, vcc, 1.0, v94, 1.0
	v_mul_f32_e32 v95, v79, v97
	v_fma_f32 v96, -v92, v95, v79
	v_fmac_f32_e32 v95, v96, v97
	v_fma_f32 v79, -v92, v95, v79
	v_div_fmas_f32 v79, v79, v97, v95
	v_div_fixup_f32 v92, v79, v94, 1.0
	v_pk_mul_f32 v[90:91], v[90:91], v[92:93]
	v_pk_mul_f32 v[92:93], v[2:3], v[76:77]
	v_pk_mul_f32 v[74:75], v[74:75], v[90:91]
	v_pk_mul_f32 v[90:91], v[18:19], v[80:81]
	v_cvt_pk_bf16_f32 v79, v74, v75
	v_mad_i64_i32 v[74:75], s[6:7], v89, s38, v[36:37]
	global_store_dwordx2 v[74:75], v[78:79], off sc1
	v_lshlrev_b32_e32 v78, 16, v58
	v_and_b32_e32 v79, 0xffff0000, v58
	v_pk_fma_f32 v[72:73], v[22:23], v[72:73], v[90:91]
	v_pk_fma_f32 v[70:71], v[6:7], v[70:71], v[92:93]
	v_pk_fma_f32 v[72:73], v[26:27], v[78:79], v[72:73]
	v_lshlrev_b32_e32 v74, 16, v60
	v_pk_add_f32 v[72:73], v[72:73], v[30:31]
	v_and_b32_e32 v75, 0xffff0000, v60
	v_mul_f32_e32 v58, 0xbfb8aa3b, v72
	v_exp_f32_e32 v90, v58
	v_mul_f32_e32 v58, 0xbfb8aa3b, v73
	v_exp_f32_e32 v91, v58
	v_lshlrev_b32_e32 v58, 16, v59
	v_and_b32_e32 v59, 0xffff0000, v59
	v_pk_fma_f32 v[70:71], v[10:11], v[74:75], v[70:71]
	v_pk_add_f32 v[90:91], v[90:91], 1.0 op_sel_hi:[1,0]
	v_pk_add_f32 v[70:71], v[70:71], v[14:15]
	v_div_scale_f32 v89, s[6:7], v91, v91, 1.0
	v_rcp_f32_e32 v94, v89
	v_lshlrev_b32_e32 v60, 16, v61
	v_and_b32_e32 v61, 0xffff0000, v61
	v_fma_f32 v92, -v89, v94, 1.0
	v_fmac_f32_e32 v94, v92, v94
	v_div_scale_f32 v92, vcc, 1.0, v91, 1.0
	v_mul_f32_e32 v93, v92, v94
	v_fma_f32 v95, -v89, v93, v92
	v_fmac_f32_e32 v93, v95, v94
	v_fma_f32 v89, -v89, v93, v92
	v_div_scale_f32 v92, s[6:7], v90, v90, 1.0
	v_rcp_f32_e32 v95, v92
	v_div_fmas_f32 v89, v89, v94, v93
	v_div_fixup_f32 v91, v89, v91, 1.0
	v_fma_f32 v89, -v92, v95, 1.0
	v_fmac_f32_e32 v95, v89, v95
	v_div_scale_f32 v89, vcc, 1.0, v90, 1.0
	v_mul_f32_e32 v93, v89, v95
	v_fma_f32 v94, -v92, v93, v89
	v_fmac_f32_e32 v93, v94, v95
	v_fma_f32 v89, -v92, v93, v89
	v_div_fmas_f32 v89, v89, v95, v93
	v_div_fixup_f32 v90, v89, v90, 1.0
	v_pk_mul_f32 v[72:73], v[72:73], v[90:91]
	v_pk_mul_f32 v[90:91], v[20:21], v[64:65]
	v_pk_mul_f32 v[70:71], v[70:71], v[72:73]
	v_pk_fma_f32 v[66:67], v[24:25], v[66:67], v[90:91]
	v_cvt_pk_bf16_f32 v70, v70, v71
	v_pk_fma_f32 v[66:67], v[28:29], v[58:59], v[66:67]
	v_pk_mul_f32 v[72:73], v[4:5], v[68:69]
	v_pk_add_f32 v[66:67], v[66:67], v[32:33]
	v_pk_fma_f32 v[62:63], v[8:9], v[62:63], v[72:73]
	v_mul_f32_e32 v89, 0xbfb8aa3b, v66
	v_exp_f32_e32 v90, v89
	v_mul_f32_e32 v89, 0xbfb8aa3b, v67
	v_exp_f32_e32 v91, v89
	v_pk_fma_f32 v[62:63], v[12:13], v[60:61], v[62:63]
	v_pk_add_f32 v[90:91], v[90:91], 1.0 op_sel_hi:[1,0]
	s_nop 0
	v_div_scale_f32 v71, s[6:7], v91, v91, 1.0
	v_rcp_f32_e32 v89, v71
	v_pk_add_f32 v[62:63], v[62:63], v[16:17]
	v_fma_f32 v72, -v71, v89, 1.0
	v_fmac_f32_e32 v89, v72, v89
	v_div_scale_f32 v72, vcc, 1.0, v91, 1.0
	v_mul_f32_e32 v73, v72, v89
	v_fma_f32 v92, -v71, v73, v72
	v_fmac_f32_e32 v73, v92, v89
	v_fma_f32 v71, -v71, v73, v72
	v_div_scale_f32 v72, s[6:7], v90, v90, 1.0
	v_rcp_f32_e32 v92, v72
	v_div_fmas_f32 v71, v71, v89, v73
	v_div_fixup_f32 v73, v71, v91, 1.0
	v_fma_f32 v71, -v72, v92, 1.0
	v_fmac_f32_e32 v92, v71, v92
	v_div_scale_f32 v71, vcc, 1.0, v90, 1.0
	v_mul_f32_e32 v89, v71, v92
	v_fma_f32 v91, -v72, v89, v71
	v_fmac_f32_e32 v89, v91, v92
	v_fma_f32 v71, -v72, v89, v71
	v_div_fmas_f32 v71, v71, v92, v89
	v_div_fixup_f32 v72, v71, v90, 1.0
	v_pk_mul_f32 v[66:67], v[66:67], v[72:73]
	s_nop 0
	v_pk_mul_f32 v[62:63], v[62:63], v[66:67]
	v_lshlrev_b32_e32 v66, 16, v56
	v_cvt_pk_bf16_f32 v71, v62, v63
	v_mad_i64_i32 v[62:63], s[6:7], v88, s38, v[36:37]
	global_store_dwordx2 v[62:63], v[70:71], off sc1
	v_pk_mul_f32 v[62:63], v[18:19], v[78:79]
	v_lshlrev_b32_e32 v70, 16, v54
	v_and_b32_e32 v71, 0xffff0000, v54
	v_pk_fma_f32 v[62:63], v[22:23], v[80:81], v[62:63]
	v_pk_mul_f32 v[80:81], v[2:3], v[74:75]
	v_pk_fma_f32 v[62:63], v[26:27], v[70:71], v[62:63]
	v_pk_fma_f32 v[76:77], v[6:7], v[76:77], v[80:81]
	v_pk_add_f32 v[62:63], v[62:63], v[30:31]
	v_and_b32_e32 v67, 0xffff0000, v56
	v_mul_f32_e32 v54, 0xbfb8aa3b, v62
	v_exp_f32_e32 v72, v54
	v_mul_f32_e32 v54, 0xbfb8aa3b, v63
	v_exp_f32_e32 v73, v54
	v_lshlrev_b32_e32 v54, 16, v55
	v_and_b32_e32 v55, 0xffff0000, v55
	v_pk_fma_f32 v[76:77], v[10:11], v[66:67], v[76:77]
	v_pk_add_f32 v[72:73], v[72:73], 1.0 op_sel_hi:[1,0]
	v_pk_add_f32 v[76:77], v[76:77], v[14:15]
	v_div_scale_f32 v88, s[6:7], v73, v73, 1.0
	v_rcp_f32_e32 v89, v88
	v_lshlrev_b32_e32 v56, 16, v57
	v_and_b32_e32 v57, 0xffff0000, v57
	v_fma_f32 v80, -v88, v89, 1.0
	v_fmac_f32_e32 v89, v80, v89
	v_div_scale_f32 v80, vcc, 1.0, v73, 1.0
	v_mul_f32_e32 v81, v80, v89
	v_fma_f32 v90, -v88, v81, v80
	v_fmac_f32_e32 v81, v90, v89
	v_fma_f32 v80, -v88, v81, v80
	v_div_scale_f32 v88, s[6:7], v72, v72, 1.0
	v_rcp_f32_e32 v90, v88
	v_div_fmas_f32 v80, v80, v89, v81
	v_div_fixup_f32 v73, v80, v73, 1.0
	v_fma_f32 v80, -v88, v90, 1.0
	v_fmac_f32_e32 v90, v80, v90
	v_div_scale_f32 v80, vcc, 1.0, v72, 1.0
	v_mul_f32_e32 v81, v80, v90
	v_fma_f32 v89, -v88, v81, v80
	v_fmac_f32_e32 v81, v89, v90
	v_fma_f32 v80, -v88, v81, v80
	v_div_fmas_f32 v80, v80, v90, v81
	v_div_fixup_f32 v72, v80, v72, 1.0
	v_pk_mul_f32 v[62:63], v[62:63], v[72:73]
	v_pk_mul_f32 v[72:73], v[20:21], v[58:59]
	v_pk_mul_f32 v[62:63], v[76:77], v[62:63]
	v_pk_fma_f32 v[64:65], v[24:25], v[64:65], v[72:73]
	v_cvt_pk_bf16_f32 v62, v62, v63
	v_pk_fma_f32 v[64:65], v[28:29], v[54:55], v[64:65]
	v_pk_mul_f32 v[76:77], v[4:5], v[60:61]
	v_pk_add_f32 v[64:65], v[64:65], v[32:33]
	v_pk_fma_f32 v[68:69], v[8:9], v[68:69], v[76:77]
	v_mul_f32_e32 v72, 0xbfb8aa3b, v64
	v_mul_f32_e32 v73, 0xbfb8aa3b, v65
	v_exp_f32_e32 v72, v72
	v_exp_f32_e32 v73, v73
	v_pk_fma_f32 v[68:69], v[12:13], v[56:57], v[68:69]
	v_pk_add_f32 v[72:73], v[72:73], 1.0 op_sel_hi:[1,0]
	s_nop 0
	v_div_scale_f32 v63, s[6:7], v73, v73, 1.0
	v_rcp_f32_e32 v80, v63
	v_pk_add_f32 v[68:69], v[68:69], v[16:17]
	v_fma_f32 v76, -v63, v80, 1.0
	v_fmac_f32_e32 v80, v76, v80
	v_div_scale_f32 v76, vcc, 1.0, v73, 1.0
	v_mul_f32_e32 v77, v76, v80
	v_fma_f32 v81, -v63, v77, v76
	v_fmac_f32_e32 v77, v81, v80
	v_fma_f32 v63, -v63, v77, v76
	v_div_scale_f32 v76, s[6:7], v72, v72, 1.0
	v_rcp_f32_e32 v81, v76
	v_div_fmas_f32 v63, v63, v80, v77
	v_div_fixup_f32 v73, v63, v73, 1.0
	v_fma_f32 v63, -v76, v81, 1.0
	v_fmac_f32_e32 v81, v63, v81
	v_div_scale_f32 v63, vcc, 1.0, v72, 1.0
	v_mul_f32_e32 v77, v63, v81
	v_fma_f32 v80, -v76, v77, v63
	v_fmac_f32_e32 v77, v80, v81
	v_fma_f32 v63, -v76, v77, v63
	v_div_fmas_f32 v63, v63, v81, v77
	v_div_fixup_f32 v72, v63, v72, 1.0
	v_pk_mul_f32 v[64:65], v[64:65], v[72:73]
	v_pk_mul_f32 v[76:77], v[2:3], v[66:67]
	v_pk_mul_f32 v[64:65], v[68:69], v[64:65]
	v_pk_mul_f32 v[68:69], v[18:19], v[70:71]
	v_cvt_pk_bf16_f32 v63, v64, v65
	v_mad_i64_i32 v[64:65], s[6:7], v87, s38, v[36:37]
	global_store_dwordx2 v[64:65], v[62:63], off sc1
	v_lshlrev_b32_e32 v64, 16, v50
	v_and_b32_e32 v65, 0xffff0000, v50
	v_pk_fma_f32 v[68:69], v[22:23], v[78:79], v[68:69]
	v_pk_fma_f32 v[74:75], v[6:7], v[74:75], v[76:77]
	v_pk_fma_f32 v[68:69], v[26:27], v[64:65], v[68:69]
	v_lshlrev_b32_e32 v62, 16, v52
	v_pk_add_f32 v[68:69], v[68:69], v[30:31]
	v_and_b32_e32 v63, 0xffff0000, v52
	v_mul_f32_e32 v50, 0xbfb8aa3b, v68
	v_exp_f32_e32 v72, v50
	v_mul_f32_e32 v50, 0xbfb8aa3b, v69
	v_exp_f32_e32 v73, v50
	v_lshlrev_b32_e32 v50, 16, v51
	v_and_b32_e32 v51, 0xffff0000, v51
	v_pk_fma_f32 v[74:75], v[10:11], v[62:63], v[74:75]
	v_pk_add_f32 v[72:73], v[72:73], 1.0 op_sel_hi:[1,0]
	v_pk_add_f32 v[74:75], v[74:75], v[14:15]
	v_div_scale_f32 v78, s[6:7], v73, v73, 1.0
	v_rcp_f32_e32 v79, v78
	v_lshlrev_b32_e32 v52, 16, v53
	v_and_b32_e32 v53, 0xffff0000, v53
	v_fma_f32 v76, -v78, v79, 1.0
	v_fmac_f32_e32 v79, v76, v79
	v_div_scale_f32 v76, vcc, 1.0, v73, 1.0
	v_mul_f32_e32 v77, v76, v79
	v_fma_f32 v80, -v78, v77, v76
	v_fmac_f32_e32 v77, v80, v79
	v_fma_f32 v76, -v78, v77, v76
	v_div_scale_f32 v78, s[6:7], v72, v72, 1.0
	v_rcp_f32_e32 v80, v78
	v_div_fmas_f32 v76, v76, v79, v77
	v_div_fixup_f32 v73, v76, v73, 1.0
	v_fma_f32 v76, -v78, v80, 1.0
	v_fmac_f32_e32 v80, v76, v80
	v_div_scale_f32 v76, vcc, 1.0, v72, 1.0
	v_mul_f32_e32 v77, v76, v80
	v_fma_f32 v79, -v78, v77, v76
	v_fmac_f32_e32 v77, v79, v80
	v_fma_f32 v76, -v78, v77, v76
	v_div_fmas_f32 v76, v76, v80, v77
	v_div_fixup_f32 v72, v76, v72, 1.0
	v_pk_mul_f32 v[68:69], v[68:69], v[72:73]
	v_pk_mul_f32 v[72:73], v[20:21], v[54:55]
	v_pk_mul_f32 v[68:69], v[74:75], v[68:69]
	v_pk_fma_f32 v[58:59], v[24:25], v[58:59], v[72:73]
	v_cvt_pk_bf16_f32 v68, v68, v69
	v_pk_fma_f32 v[58:59], v[28:29], v[50:51], v[58:59]
	v_pk_mul_f32 v[74:75], v[4:5], v[56:57]
	v_pk_add_f32 v[58:59], v[58:59], v[32:33]
	v_pk_fma_f32 v[60:61], v[8:9], v[60:61], v[74:75]
	v_mul_f32_e32 v72, 0xbfb8aa3b, v58
	v_mul_f32_e32 v73, 0xbfb8aa3b, v59
	v_exp_f32_e32 v72, v72
	v_exp_f32_e32 v73, v73
	v_pk_fma_f32 v[60:61], v[12:13], v[52:53], v[60:61]
	v_pk_add_f32 v[72:73], v[72:73], 1.0 op_sel_hi:[1,0]
	s_nop 0
	v_div_scale_f32 v69, s[6:7], v73, v73, 1.0
	v_rcp_f32_e32 v76, v69
	v_pk_add_f32 v[60:61], v[60:61], v[16:17]
	v_fma_f32 v74, -v69, v76, 1.0
	v_fmac_f32_e32 v76, v74, v76
	v_div_scale_f32 v74, vcc, 1.0, v73, 1.0
	v_mul_f32_e32 v75, v74, v76
	v_fma_f32 v77, -v69, v75, v74
	v_fmac_f32_e32 v75, v77, v76
	v_fma_f32 v69, -v69, v75, v74
	v_div_scale_f32 v74, s[6:7], v72, v72, 1.0
	v_rcp_f32_e32 v77, v74
	v_div_fmas_f32 v69, v69, v76, v75
	v_div_fixup_f32 v73, v69, v73, 1.0
	v_fma_f32 v69, -v74, v77, 1.0
	v_fmac_f32_e32 v77, v69, v77
	v_div_scale_f32 v69, vcc, 1.0, v72, 1.0
	v_mul_f32_e32 v75, v69, v77
	v_fma_f32 v76, -v74, v75, v69
	v_fmac_f32_e32 v75, v76, v77
	v_fma_f32 v69, -v74, v75, v69
	v_div_fmas_f32 v69, v69, v77, v75
	v_div_fixup_f32 v72, v69, v72, 1.0
	v_pk_mul_f32 v[58:59], v[58:59], v[72:73]
	v_pk_mul_f32 v[72:73], v[2:3], v[62:63]
	v_pk_mul_f32 v[58:59], v[60:61], v[58:59]
	v_lshlrev_b32_e32 v60, 16, v46
	v_cvt_pk_bf16_f32 v69, v58, v59
	v_mad_i64_i32 v[58:59], s[6:7], v86, s38, v[36:37]
	global_store_dwordx2 v[58:59], v[68:69], off sc1
	v_pk_mul_f32 v[68:69], v[18:19], v[64:65]
	v_and_b32_e32 v61, 0xffff0000, v46
	v_pk_fma_f32 v[68:69], v[22:23], v[70:71], v[68:69]
	v_pk_fma_f32 v[66:67], v[6:7], v[66:67], v[72:73]
	v_pk_fma_f32 v[68:69], v[26:27], v[60:61], v[68:69]
	v_lshlrev_b32_e32 v58, 16, v48
	v_pk_add_f32 v[68:69], v[68:69], v[30:31]
	v_and_b32_e32 v59, 0xffff0000, v48
	v_mul_f32_e32 v46, 0xbfb8aa3b, v68
	v_exp_f32_e32 v70, v46
	v_mul_f32_e32 v46, 0xbfb8aa3b, v69
	v_exp_f32_e32 v71, v46
	v_lshlrev_b32_e32 v46, 16, v47
	v_and_b32_e32 v47, 0xffff0000, v47
	v_pk_fma_f32 v[66:67], v[10:11], v[58:59], v[66:67]
	v_pk_add_f32 v[70:71], v[70:71], 1.0 op_sel_hi:[1,0]
	v_pk_add_f32 v[66:67], v[66:67], v[14:15]
	v_div_scale_f32 v74, s[6:7], v71, v71, 1.0
	v_rcp_f32_e32 v75, v74
	v_lshlrev_b32_e32 v48, 16, v49
	v_and_b32_e32 v49, 0xffff0000, v49
	v_fma_f32 v72, -v74, v75, 1.0
	v_fmac_f32_e32 v75, v72, v75
	v_div_scale_f32 v72, vcc, 1.0, v71, 1.0
	v_mul_f32_e32 v73, v72, v75
	v_fma_f32 v76, -v74, v73, v72
	v_fmac_f32_e32 v73, v76, v75
	v_fma_f32 v72, -v74, v73, v72
	v_div_scale_f32 v74, s[6:7], v70, v70, 1.0
	v_rcp_f32_e32 v76, v74
	v_div_fmas_f32 v72, v72, v75, v73
	v_div_fixup_f32 v71, v72, v71, 1.0
	v_fma_f32 v72, -v74, v76, 1.0
	v_fmac_f32_e32 v76, v72, v76
	v_div_scale_f32 v72, vcc, 1.0, v70, 1.0
	v_mul_f32_e32 v73, v72, v76
	v_fma_f32 v75, -v74, v73, v72
	v_fmac_f32_e32 v73, v75, v76
	v_fma_f32 v72, -v74, v73, v72
	v_div_fmas_f32 v72, v72, v76, v73
	v_div_fixup_f32 v70, v72, v70, 1.0
	v_pk_mul_f32 v[68:69], v[68:69], v[70:71]
	v_pk_mul_f32 v[70:71], v[20:21], v[50:51]
	v_pk_mul_f32 v[66:67], v[66:67], v[68:69]
	v_pk_fma_f32 v[54:55], v[24:25], v[54:55], v[70:71]
	v_cvt_pk_bf16_f32 v66, v66, v67
	v_pk_fma_f32 v[54:55], v[28:29], v[46:47], v[54:55]
	v_pk_mul_f32 v[68:69], v[4:5], v[52:53]
	v_pk_add_f32 v[54:55], v[54:55], v[32:33]
	v_pk_fma_f32 v[56:57], v[8:9], v[56:57], v[68:69]
	v_mul_f32_e32 v70, 0xbfb8aa3b, v54
	v_mul_f32_e32 v71, 0xbfb8aa3b, v55
	v_exp_f32_e32 v70, v70
	v_exp_f32_e32 v71, v71
	v_pk_fma_f32 v[56:57], v[12:13], v[48:49], v[56:57]
	v_pk_add_f32 v[70:71], v[70:71], 1.0 op_sel_hi:[1,0]
	s_nop 0
	v_div_scale_f32 v67, s[6:7], v71, v71, 1.0
	v_rcp_f32_e32 v72, v67
	v_pk_add_f32 v[56:57], v[56:57], v[16:17]
	v_fma_f32 v68, -v67, v72, 1.0
	v_fmac_f32_e32 v72, v68, v72
	v_div_scale_f32 v68, vcc, 1.0, v71, 1.0
	v_mul_f32_e32 v69, v68, v72
	v_fma_f32 v73, -v67, v69, v68
	v_fmac_f32_e32 v69, v73, v72
	v_fma_f32 v67, -v67, v69, v68
	v_div_scale_f32 v68, s[6:7], v70, v70, 1.0
	v_rcp_f32_e32 v73, v68
	v_div_fmas_f32 v67, v67, v72, v69
	v_div_fixup_f32 v69, v67, v71, 1.0
	v_fma_f32 v67, -v68, v73, 1.0
	v_fmac_f32_e32 v73, v67, v73
	v_div_scale_f32 v67, vcc, 1.0, v70, 1.0
	v_mul_f32_e32 v71, v67, v73
	v_fma_f32 v72, -v68, v71, v67
	v_fmac_f32_e32 v71, v72, v73
	v_fma_f32 v67, -v68, v71, v67
	v_div_fmas_f32 v67, v67, v73, v71
	v_div_fixup_f32 v68, v67, v70, 1.0
	v_pk_mul_f32 v[54:55], v[54:55], v[68:69]
	v_pk_mul_f32 v[68:69], v[2:3], v[58:59]
	v_pk_mul_f32 v[54:55], v[56:57], v[54:55]
	v_lshlrev_b32_e32 v56, 16, v42
	v_cvt_pk_bf16_f32 v67, v54, v55
	v_mad_i64_i32 v[54:55], s[6:7], v85, s38, v[36:37]
	global_store_dwordx2 v[54:55], v[66:67], off sc1
	v_pk_mul_f32 v[66:67], v[18:19], v[60:61]
	v_and_b32_e32 v57, 0xffff0000, v42
	v_pk_fma_f32 v[64:65], v[22:23], v[64:65], v[66:67]
	v_pk_fma_f32 v[62:63], v[6:7], v[62:63], v[68:69]
	v_pk_fma_f32 v[64:65], v[26:27], v[56:57], v[64:65]
	v_lshlrev_b32_e32 v54, 16, v44
	v_pk_add_f32 v[64:65], v[64:65], v[30:31]
	v_and_b32_e32 v55, 0xffff0000, v44
	v_mul_f32_e32 v42, 0xbfb8aa3b, v64
	v_exp_f32_e32 v66, v42
	v_mul_f32_e32 v42, 0xbfb8aa3b, v65
	v_exp_f32_e32 v67, v42
	v_lshlrev_b32_e32 v42, 16, v43
	v_and_b32_e32 v43, 0xffff0000, v43
	v_pk_fma_f32 v[62:63], v[10:11], v[54:55], v[62:63]
	v_pk_add_f32 v[66:67], v[66:67], 1.0 op_sel_hi:[1,0]
	v_pk_add_f32 v[62:63], v[62:63], v[14:15]
	v_div_scale_f32 v70, s[6:7], v67, v67, 1.0
	v_rcp_f32_e32 v71, v70
	v_lshlrev_b32_e32 v44, 16, v45
	v_and_b32_e32 v45, 0xffff0000, v45
	v_pk_mul_f32 v[18:19], v[18:19], v[56:57]
	v_fma_f32 v68, -v70, v71, 1.0
	v_fmac_f32_e32 v71, v68, v71
	v_div_scale_f32 v68, vcc, 1.0, v67, 1.0
	v_mul_f32_e32 v69, v68, v71
	v_fma_f32 v72, -v70, v69, v68
	v_fmac_f32_e32 v69, v72, v71
	v_fma_f32 v68, -v70, v69, v68
	v_div_scale_f32 v70, s[6:7], v66, v66, 1.0
	v_rcp_f32_e32 v72, v70
	v_div_fmas_f32 v68, v68, v71, v69
	v_div_fixup_f32 v67, v68, v67, 1.0
	v_pk_fma_f32 v[18:19], v[22:23], v[60:61], v[18:19]
	v_fma_f32 v68, -v70, v72, 1.0
	v_fmac_f32_e32 v72, v68, v72
	v_div_scale_f32 v68, vcc, 1.0, v66, 1.0
	v_mul_f32_e32 v69, v68, v72
	v_fma_f32 v71, -v70, v69, v68
	v_fmac_f32_e32 v69, v71, v72
	v_fma_f32 v68, -v70, v69, v68
	v_div_fmas_f32 v68, v68, v72, v69
	v_div_fixup_f32 v66, v68, v66, 1.0
	v_pk_mul_f32 v[64:65], v[64:65], v[66:67]
	v_pk_mul_f32 v[66:67], v[20:21], v[46:47]
	v_pk_mul_f32 v[62:63], v[62:63], v[64:65]
	v_pk_fma_f32 v[50:51], v[24:25], v[50:51], v[66:67]
	v_cvt_pk_bf16_f32 v62, v62, v63
	v_pk_fma_f32 v[50:51], v[28:29], v[42:43], v[50:51]
	v_pk_mul_f32 v[64:65], v[4:5], v[48:49]
	v_pk_add_f32 v[50:51], v[50:51], v[32:33]
	v_pk_fma_f32 v[52:53], v[8:9], v[52:53], v[64:65]
	v_mul_f32_e32 v66, 0xbfb8aa3b, v50
	v_mul_f32_e32 v67, 0xbfb8aa3b, v51
	v_exp_f32_e32 v66, v66
	v_exp_f32_e32 v67, v67
	v_pk_fma_f32 v[52:53], v[12:13], v[44:45], v[52:53]
	v_pk_mul_f32 v[2:3], v[2:3], v[54:55]
	v_pk_add_f32 v[52:53], v[52:53], v[16:17]
	v_pk_add_f32 v[66:67], v[66:67], 1.0 op_sel_hi:[1,0]
	v_pk_fma_f32 v[2:3], v[6:7], v[58:59], v[2:3]
	v_div_scale_f32 v63, s[6:7], v67, v67, 1.0
	v_rcp_f32_e32 v68, v63
	v_pk_mul_f32 v[4:5], v[4:5], v[44:45]
	v_fma_f32 v64, -v63, v68, 1.0
	v_fmac_f32_e32 v68, v64, v68
	v_div_scale_f32 v64, vcc, 1.0, v67, 1.0
	v_mul_f32_e32 v65, v64, v68
	v_fma_f32 v69, -v63, v65, v64
	v_fmac_f32_e32 v65, v69, v68
	v_fma_f32 v63, -v63, v65, v64
	v_div_scale_f32 v64, s[6:7], v66, v66, 1.0
	v_rcp_f32_e32 v69, v64
	v_div_fmas_f32 v63, v63, v68, v65
	v_div_fixup_f32 v65, v63, v67, 1.0
	v_pk_fma_f32 v[4:5], v[8:9], v[48:49], v[4:5]
	v_fma_f32 v63, -v64, v69, 1.0
	v_fmac_f32_e32 v69, v63, v69
	v_div_scale_f32 v63, vcc, 1.0, v66, 1.0
	v_mul_f32_e32 v67, v63, v69
	v_fma_f32 v68, -v64, v67, v63
	v_fmac_f32_e32 v67, v68, v69
	v_fma_f32 v63, -v64, v67, v63
	v_div_fmas_f32 v63, v63, v69, v67
	v_div_fixup_f32 v64, v63, v66, 1.0
	v_pk_mul_f32 v[50:51], v[50:51], v[64:65]
	s_nop 0
	v_pk_mul_f32 v[50:51], v[52:53], v[50:51]
	v_lshlrev_b32_e32 v52, 16, v38
	v_and_b32_e32 v53, 0xffff0000, v38
	v_pk_fma_f32 v[18:19], v[26:27], v[52:53], v[18:19]
	v_cvt_pk_bf16_f32 v63, v50, v51
	v_pk_add_f32 v[18:19], v[18:19], v[30:31]
	v_mad_i64_i32 v[50:51], s[6:7], v84, s38, v[36:37]
	v_mul_f32_e32 v22, 0xbfb8aa3b, v18
	v_mul_f32_e32 v23, 0xbfb8aa3b, v19
	v_exp_f32_e32 v22, v22
	v_exp_f32_e32 v23, v23
	global_store_dwordx2 v[50:51], v[62:63], off sc1
	v_lshlrev_b32_e32 v50, 16, v40
	v_and_b32_e32 v51, 0xffff0000, v40
	v_pk_add_f32 v[22:23], v[22:23], 1.0 op_sel_hi:[1,0]
	v_pk_fma_f32 v[2:3], v[10:11], v[50:51], v[2:3]
	v_div_scale_f32 v30, s[6:7], v23, v23, 1.0
	v_rcp_f32_e32 v31, v30
	v_pk_add_f32 v[2:3], v[2:3], v[14:15]
	v_lshlrev_b32_e32 v26, 16, v39
	v_and_b32_e32 v27, 0xffff0000, v39
	v_fma_f32 v6, -v30, v31, 1.0
	v_fmac_f32_e32 v31, v6, v31
	v_div_scale_f32 v6, vcc, 1.0, v23, 1.0
	v_mul_f32_e32 v7, v6, v31
	v_fma_f32 v10, -v30, v7, v6
	v_fmac_f32_e32 v7, v10, v31
	v_div_scale_f32 v10, s[6:7], v22, v22, 1.0
	v_rcp_f32_e32 v11, v10
	v_fma_f32 v6, -v30, v7, v6
	v_div_fmas_f32 v6, v6, v31, v7
	v_div_fixup_f32 v7, v6, v23, 1.0
	v_fma_f32 v6, -v10, v11, 1.0
	v_fmac_f32_e32 v11, v6, v11
	v_div_scale_f32 v6, vcc, 1.0, v22, 1.0
	v_mul_f32_e32 v14, v6, v11
	v_fma_f32 v15, -v10, v14, v6
	v_fmac_f32_e32 v14, v15, v11
	v_fma_f32 v6, -v10, v14, v6
	v_div_fmas_f32 v6, v6, v11, v14
	v_pk_mul_f32 v[10:11], v[20:21], v[42:43]
	v_div_fixup_f32 v6, v6, v22, 1.0
	v_pk_fma_f32 v[10:11], v[24:25], v[46:47], v[10:11]
	v_pk_mul_f32 v[6:7], v[18:19], v[6:7]
	v_pk_fma_f32 v[10:11], v[28:29], v[26:27], v[10:11]
	v_pk_mul_f32 v[2:3], v[2:3], v[6:7]
	v_pk_add_f32 v[10:11], v[10:11], v[32:33]
	v_cvt_pk_bf16_f32 v2, v2, v3
	v_mul_f32_e32 v14, 0xbfb8aa3b, v10
	v_mul_f32_e32 v15, 0xbfb8aa3b, v11
	v_exp_f32_e32 v14, v14
	v_exp_f32_e32 v15, v15
	v_lshlrev_b32_e32 v40, 16, v41
	v_and_b32_e32 v41, 0xffff0000, v41
	v_pk_fma_f32 v[4:5], v[12:13], v[40:41], v[4:5]
	v_pk_add_f32 v[6:7], v[14:15], 1.0 op_sel_hi:[1,0]
	v_pk_add_f32 v[4:5], v[4:5], v[16:17]
	v_div_scale_f32 v3, s[6:7], v7, v7, 1.0
	v_rcp_f32_e32 v14, v3
	s_nop 0
	v_fma_f32 v8, -v3, v14, 1.0
	v_fmac_f32_e32 v14, v8, v14
	v_div_scale_f32 v8, vcc, 1.0, v7, 1.0
	v_mul_f32_e32 v9, v8, v14
	v_fma_f32 v12, -v3, v9, v8
	v_fmac_f32_e32 v9, v12, v14
	v_fma_f32 v3, -v3, v9, v8
	v_div_scale_f32 v8, s[6:7], v6, v6, 1.0
	v_rcp_f32_e32 v12, v8
	v_div_fmas_f32 v3, v3, v14, v9
	v_div_fixup_f32 v7, v3, v7, 1.0
	v_fma_f32 v3, -v8, v12, 1.0
	v_fmac_f32_e32 v12, v3, v12
	v_div_scale_f32 v3, vcc, 1.0, v6, 1.0
	v_mul_f32_e32 v9, v3, v12
	v_fma_f32 v13, -v8, v9, v3
	v_fmac_f32_e32 v9, v13, v12
	v_fma_f32 v3, -v8, v9, v3
	v_div_fmas_f32 v3, v3, v12, v9
	v_div_fixup_f32 v6, v3, v6, 1.0
	v_pk_mul_f32 v[6:7], v[10:11], v[6:7]
	v_cmp_lt_i32_e32 vcc, s39, v1
	v_pk_mul_f32 v[4:5], v[4:5], v[6:7]
	s_or_b64 s[28:29], vcc, s[28:29]
	v_cvt_pk_bf16_f32 v3, v4, v5
	v_mad_i64_i32 v[4:5], s[6:7], v83, s38, v[36:37]
	global_store_dwordx2 v[4:5], v[2:3], off sc1
	s_andn2_b64 exec, exec, s[28:29]
	s_cbranch_execz .LBB0_1011
